# removed the compiler's per-MMA-block s_setprio 1/0 toggles in all GEMM K-loops (DA fast-path priorities kept)
# speedup vs baseline: 1.0086x; 1.0086x over previous
; #define STAGE(P, BASE, br, kt) do { int _so = ((br) * K + (kt) * BK) * 2; \
;     __builtin_amdgcn_raw_ptr_buffer_load_lds(rs_##BASE, (__attribute__((address_space(3))) void*)((char*)(P) + tx * 16), 16, voff0, _so, 0, 0); \
;     __builtin_amdgcn_raw_ptr_buffer_load_lds(rs_##BASE, (__attribute__((address_space(3))) void*)((char*)(P) + tx * 16 + 8192), 16, voff1, _so, 0, 0); } while (0)
; #define LDA(dst, b, h) _Pragma("unroll") for (int m = 0; m < 4; ++m) _Pragma("unroll") for (int k = 0; k < 2; ++k) \
;     dst[m][k] = *reinterpret_cast<const bf16x8*>((char*)SA(b, h) + lds_byte(wr * 64 + m * 16 + fr, k * 32 + fq * 8))
; #define LDB(dst, b, h) _Pragma("unroll") for (int n = 0; n < 2; ++n) _Pragma("unroll") for (int k = 0; k < 2; ++k) \
;     dst[n][k] = *reinterpret_cast<const bf16x8*>((char*)SB(b, h) + lds_byte(wc * 32 + n * 16 + fr, k * 32 + fq * 8))
; #define MMA(ai, bj, At, Bt_) do { __builtin_amdgcn_s_setprio(1); \
;     _Pragma("unroll") for (int m = 0; m < 4; ++m) _Pragma("unroll") for (int n = 0; n < 2; ++n) _Pragma("unroll") for (int k = 0; k < 2; ++k) \
;       acc[ai][bj][m][n] = __builtin_amdgcn_mfma_f32_16x16x32_bf16(At[m][k], Bt_[n][k], acc[ai][bj][m][n], 0, 0, 0); \
;     __builtin_amdgcn_s_setprio(0); } while (0)
; #define WAIT_V(n) asm volatile("s_waitcnt vmcnt(" #n ")" ::: "memory")
; #define WAIT_L(n) asm volatile("s_waitcnt lgkmcnt(" #n ")" ::: "memory")
; template <class Epi> ...
;     ...
;   for (int t = 0; t < nt - 2; t += 2) {
;     LDB(B0, 0, 0); SCHED; LDA(At, 0, 0); STAGE(SA(1, 1), A, brow + HALF, t + 1);
;     WAIT_L(8); BAR; WAIT_L(0); MMA(0, 0, At, B0); BAR; SCHED;
;     LDB(B1, 0, 1); STAGE(SB(0, 0), Bt, bcol, t + 2);
;     BAR; WAIT_L(0); MMA(0, 1, At, B1); BAR;
;     LDA(At, 0, 1); STAGE(SA(0, 0), A, brow, t + 2);
;     BAR; WAIT_L(0); MMA(1, 0, At, B0); BAR; SCHED;
;     STAGE(SB(0, 1), Bt, bcol + HALF, t + 2);
;     WAIT_V(6); BAR; MMA(1, 1, At, B1); BAR;
;     LDB(B0, 1, 0); SCHED; LDA(At, 1, 0); STAGE(SA(0, 1), A, brow + HALF, t + 2);
;     WAIT_L(8); BAR; WAIT_L(0); MMA(0, 0, At, B0); BAR; SCHED;
;     LDB(B1, 1, 1); STAGE(SB(1, 0), Bt, bcol, t + 3);
;     BAR; WAIT_L(0); MMA(0, 1, At, B1); BAR;
;     LDA(At, 1, 1); STAGE(SA(1, 0), A, brow, t + 3);
;     BAR; WAIT_L(0); MMA(1, 0, At, B0); BAR; SCHED;
;     STAGE(SB(1, 1), Bt, bcol + HALF, t + 3);
;     WAIT_V(6); BAR; MMA(1, 1, At, B1); BAR;
;   }
.Lpk0:
	ds_read_b128 v[156:159], v155
	ds_read_b128 v[166:169], v155 offset:1024
	ds_read_b128 v[170:173], v155 offset:2048
	ds_read_b128 v[186:189], v155 offset:3072
	s_add_i32 s35, s21, s34
	v_readfirstlane_b32 s37, v152
	s_add_i32 s36, s35, 0x40080
	s_mov_b32 m0, s37
	v_readfirstlane_b32 s37, v151
	ds_read_b128 v[190:193], v143
	ds_read_b128 v[194:197], v143 offset:1024
	ds_read_b128 v[198:201], v142
	ds_read_b128 v[202:205], v142 offset:1024
	ds_read_b128 v[206:209], v141
	ds_read_b128 v[210:213], v141 offset:1024
	ds_read_b128 v[214:217], v140
	ds_read_b128 v[218:221], v140 offset:1024
	buffer_load_dwordx4 v32, s[4:7], s36 offen lds
	s_mov_b32 m0, s37
	s_nop 0
	buffer_load_dwordx4 v130, s[4:7], s36 offen lds
	s_waitcnt lgkmcnt(8)
	s_barrier
	s_waitcnt lgkmcnt(0)
	s_waitcnt lgkmcnt(7)
	v_mfma_f32_16x16x32_bf16 v[126:129], v[190:193], v[156:159], 0
	v_mfma_f32_16x16x32_bf16 v[122:125], v[190:193], v[170:173], 0
	s_waitcnt lgkmcnt(5)
	v_mfma_f32_16x16x32_bf16 v[118:121], v[198:201], v[156:159], 0
	v_mfma_f32_16x16x32_bf16 v[114:117], v[198:201], v[170:173], 0
	s_waitcnt lgkmcnt(3)
	v_mfma_f32_16x16x32_bf16 v[110:113], v[206:209], v[156:159], 0
	v_mfma_f32_16x16x32_bf16 v[106:109], v[206:209], v[170:173], 0
	s_waitcnt lgkmcnt(1)
	v_mfma_f32_16x16x32_bf16 v[102:105], v[214:217], v[156:159], 0
	v_mfma_f32_16x16x32_bf16 v[98:101], v[214:217], v[170:173], 0
	v_mfma_f32_16x16x32_bf16 v[126:129], v[194:197], v[166:169], v[126:129]
	v_mfma_f32_16x16x32_bf16 v[122:125], v[194:197], v[186:189], v[122:125]
	v_mfma_f32_16x16x32_bf16 v[118:121], v[202:205], v[166:169], v[118:121]
	v_mfma_f32_16x16x32_bf16 v[114:117], v[202:205], v[186:189], v[114:117]
	v_mfma_f32_16x16x32_bf16 v[110:113], v[210:213], v[166:169], v[110:113]
	v_mfma_f32_16x16x32_bf16 v[106:109], v[210:213], v[186:189], v[106:109]
	s_waitcnt lgkmcnt(0)
	v_mfma_f32_16x16x32_bf16 v[102:105], v[218:221], v[166:169], v[102:105]
	v_mfma_f32_16x16x32_bf16 v[98:101], v[218:221], v[186:189], v[98:101]
	s_barrier
	s_add_i32 s36, s20, s34
	v_readfirstlane_b32 s38, v137
	s_add_i32 s37, s36, 0x100
	s_mov_b32 m0, s38
	v_readfirstlane_b32 s38, v139
	ds_read_b128 v[222:225], v149
	ds_read_b128 v[226:229], v149 offset:1024
	ds_read_b128 v[230:233], v149 offset:2048
	ds_read_b128 v[234:237], v149 offset:3072
	buffer_load_dwordx4 v32, s[76:79], s37 offen lds
	s_mov_b32 m0, s38
	s_nop 0
	buffer_load_dwordx4 v130, s[76:79], s37 offen lds
	s_barrier
	s_waitcnt lgkmcnt(0)
	s_waitcnt lgkmcnt(3)
	v_mfma_f32_16x16x32_bf16 v[94:97], v[190:193], v[222:225], 0
	s_waitcnt lgkmcnt(1)
	v_mfma_f32_16x16x32_bf16 v[90:93], v[190:193], v[230:233], 0
	v_mfma_f32_16x16x32_bf16 v[86:89], v[198:201], v[222:225], 0
	v_mfma_f32_16x16x32_bf16 v[82:85], v[198:201], v[230:233], 0
	v_mfma_f32_16x16x32_bf16 v[78:81], v[206:209], v[222:225], 0
	v_mfma_f32_16x16x32_bf16 v[74:77], v[206:209], v[230:233], 0
	v_mfma_f32_16x16x32_bf16 v[70:73], v[214:217], v[222:225], 0
	v_mfma_f32_16x16x32_bf16 v[66:69], v[214:217], v[230:233], 0
	v_mfma_f32_16x16x32_bf16 v[94:97], v[194:197], v[226:229], v[94:97]
	s_waitcnt lgkmcnt(0)
	v_mfma_f32_16x16x32_bf16 v[90:93], v[194:197], v[234:237], v[90:93]
	v_mfma_f32_16x16x32_bf16 v[86:89], v[202:205], v[226:229], v[86:89]
	v_mfma_f32_16x16x32_bf16 v[82:85], v[202:205], v[234:237], v[82:85]
	v_mfma_f32_16x16x32_bf16 v[78:81], v[210:213], v[226:229], v[78:81]
	v_mfma_f32_16x16x32_bf16 v[74:77], v[210:213], v[234:237], v[74:77]
	v_mfma_f32_16x16x32_bf16 v[70:73], v[218:221], v[226:229], v[70:73]
	v_mfma_f32_16x16x32_bf16 v[66:69], v[218:221], v[234:237], v[66:69]
	v_readfirstlane_b32 s38, v136
	s_add_i32 s37, s35, 0x100
	s_mov_b32 m0, s38
	v_readfirstlane_b32 s38, v135
	s_barrier
	ds_read_b128 v[190:193], v143 offset:16384
	ds_read_b128 v[194:197], v143 offset:17408
	ds_read_b128 v[198:201], v142 offset:16384
	ds_read_b128 v[202:205], v142 offset:17408
	ds_read_b128 v[206:209], v141 offset:16384
	ds_read_b128 v[210:213], v141 offset:17408
	ds_read_b128 v[214:217], v140 offset:16384
	ds_read_b128 v[218:221], v140 offset:17408
	buffer_load_dwordx4 v32, s[4:7], s37 offen lds
	s_mov_b32 m0, s38
	s_nop 0
	buffer_load_dwordx4 v130, s[4:7], s37 offen lds
	s_barrier
	s_waitcnt lgkmcnt(0)
	s_waitcnt lgkmcnt(7)
	v_mfma_f32_16x16x32_bf16 v[62:65], v[190:193], v[156:159], 0
	v_mfma_f32_16x16x32_bf16 v[58:61], v[190:193], v[170:173], 0
	s_waitcnt lgkmcnt(5)
	v_mfma_f32_16x16x32_bf16 v[54:57], v[198:201], v[156:159], 0
	v_mfma_f32_16x16x32_bf16 v[50:53], v[198:201], v[170:173], 0
	s_waitcnt lgkmcnt(3)
	v_mfma_f32_16x16x32_bf16 v[46:49], v[206:209], v[156:159], 0
	v_mfma_f32_16x16x32_bf16 v[42:45], v[206:209], v[170:173], 0
	s_waitcnt lgkmcnt(1)
	v_mfma_f32_16x16x32_bf16 v[38:41], v[214:217], v[156:159], 0
	v_mfma_f32_16x16x32_bf16 v[34:37], v[214:217], v[170:173], 0
	v_mfma_f32_16x16x32_bf16 v[62:65], v[194:197], v[166:169], v[62:65]
	v_mfma_f32_16x16x32_bf16 v[58:61], v[194:197], v[186:189], v[58:61]
	v_mfma_f32_16x16x32_bf16 v[54:57], v[202:205], v[166:169], v[54:57]
	v_mfma_f32_16x16x32_bf16 v[50:53], v[202:205], v[186:189], v[50:53]
	v_mfma_f32_16x16x32_bf16 v[46:49], v[210:213], v[166:169], v[46:49]
	v_mfma_f32_16x16x32_bf16 v[42:45], v[210:213], v[186:189], v[42:45]
	s_waitcnt lgkmcnt(0)
	v_mfma_f32_16x16x32_bf16 v[38:41], v[218:221], v[166:169], v[38:41]
	v_mfma_f32_16x16x32_bf16 v[34:37], v[218:221], v[186:189], v[34:37]
	s_barrier
	v_readfirstlane_b32 s38, v134
	s_add_i32 s37, s36, 0x40100
	s_mov_b32 m0, s38
	v_readfirstlane_b32 s38, v138
	buffer_load_dwordx4 v32, s[76:79], s37 offen lds
	s_mov_b32 m0, s38
	s_nop 0
	buffer_load_dwordx4 v130, s[76:79], s37 offen lds
	s_waitcnt vmcnt(6)
	s_barrier
; #define STAGE(P, BASE, br, kt) do { int _so = ((br) * K + (kt) * BK) * 2; \
;     __builtin_amdgcn_raw_ptr_buffer_load_lds(rs_##BASE, (__attribute__((address_space(3))) void*)((char*)(P) + tx * 16), 16, voff0, _so, 0, 0); \
;     __builtin_amdgcn_raw_ptr_buffer_load_lds(rs_##BASE, (__attribute__((address_space(3))) void*)((char*)(P) + tx * 16 + 8192), 16, voff1, _so, 0, 0); } while (0)
; #define LDA(dst, b, h) _Pragma("unroll") for (int m = 0; m < 4; ++m) _Pragma("unroll") for (int k = 0; k < 2; ++k) \
;     dst[m][k] = *reinterpret_cast<const bf16x8*>((char*)SA(b, h) + lds_byte(wr * 64 + m * 16 + fr, k * 32 + fq * 8))
; #define LDB(dst, b, h) _Pragma("unroll") for (int n = 0; n < 2; ++n) _Pragma("unroll") for (int k = 0; k < 2; ++k) \
;     dst[n][k] = *reinterpret_cast<const bf16x8*>((char*)SB(b, h) + lds_byte(wc * 32 + n * 16 + fr, k * 32 + fq * 8))
; #define MMA(ai, bj, At, Bt_) do { __builtin_amdgcn_s_setprio(1); \
;     _Pragma("unroll") for (int m = 0; m < 4; ++m) _Pragma("unroll") for (int n = 0; n < 2; ++n) _Pragma("unroll") for (int k = 0; k < 2; ++k) \
;       acc[ai][bj][m][n] = __builtin_amdgcn_mfma_f32_16x16x32_bf16(At[m][k], Bt_[n][k], acc[ai][bj][m][n], 0, 0, 0); \
;     __builtin_amdgcn_s_setprio(0); } while (0)
; #define WAIT_V(n) asm volatile("s_waitcnt vmcnt(" #n ")" ::: "memory")
; #define WAIT_L(n) asm volatile("s_waitcnt lgkmcnt(" #n ")" ::: "memory")
; template <class Epi> ...
;     ...
;   for (int t = 0; t < nt - 2; t += 2) {
;     LDB(B0, 0, 0); SCHED; LDA(At, 0, 0); STAGE(SA(1, 1), A, brow + HALF, t + 1);
;     WAIT_L(8); BAR; WAIT_L(0); MMA(0, 0, At, B0); BAR; SCHED;
;     LDB(B1, 0, 1); STAGE(SB(0, 0), Bt, bcol, t + 2);
;     BAR; WAIT_L(0); MMA(0, 1, At, B1); BAR;
;     LDA(At, 0, 1); STAGE(SA(0, 0), A, brow, t + 2);
;     BAR; WAIT_L(0); MMA(1, 0, At, B0); BAR; SCHED;
;     STAGE(SB(0, 1), Bt, bcol + HALF, t + 2);
;     WAIT_V(6); BAR; MMA(1, 1, At, B1); BAR;
;     LDB(B0, 1, 0); SCHED; LDA(At, 1, 0); STAGE(SA(0, 1), A, brow + HALF, t + 2);
;     WAIT_L(8); BAR; WAIT_L(0); MMA(0, 0, At, B0); BAR; SCHED;
;     LDB(B1, 1, 1); STAGE(SB(1, 0), Bt, bcol, t + 3);
;     BAR; WAIT_L(0); MMA(0, 1, At, B1); BAR;
;     LDA(At, 1, 1); STAGE(SA(1, 0), A, brow, t + 3);
;     BAR; WAIT_L(0); MMA(1, 0, At, B0); BAR; SCHED;
;     STAGE(SB(1, 1), Bt, bcol + HALF, t + 3);
;     WAIT_V(6); BAR; MMA(1, 1, At, B1); BAR;
;   }
	v_mfma_f32_16x16x32_bf16 v[28:31], v[190:193], v[222:225], 0
	v_mfma_f32_16x16x32_bf16 v[24:27], v[190:193], v[230:233], 0
	v_mfma_f32_16x16x32_bf16 v[20:23], v[198:201], v[222:225], 0
	v_mfma_f32_16x16x32_bf16 v[16:19], v[198:201], v[230:233], 0
	v_mfma_f32_16x16x32_bf16 v[12:15], v[206:209], v[222:225], 0
	v_mfma_f32_16x16x32_bf16 v[8:11], v[206:209], v[230:233], 0
	v_mfma_f32_16x16x32_bf16 v[4:7], v[214:217], v[222:225], 0
	v_mfma_f32_16x16x32_bf16 v[0:3], v[214:217], v[230:233], 0
	v_mfma_f32_16x16x32_bf16 v[28:31], v[194:197], v[226:229], v[28:31]
	v_mfma_f32_16x16x32_bf16 v[24:27], v[194:197], v[234:237], v[24:27]
	v_mfma_f32_16x16x32_bf16 v[20:23], v[202:205], v[226:229], v[20:23]
	v_mfma_f32_16x16x32_bf16 v[16:19], v[202:205], v[234:237], v[16:19]
	v_mfma_f32_16x16x32_bf16 v[12:15], v[210:213], v[226:229], v[12:15]
	v_mfma_f32_16x16x32_bf16 v[8:11], v[210:213], v[234:237], v[8:11]
	v_mfma_f32_16x16x32_bf16 v[4:7], v[218:221], v[226:229], v[4:7]
	v_mfma_f32_16x16x32_bf16 v[0:3], v[218:221], v[234:237], v[0:3]
	s_barrier
	ds_read_b128 v[156:159], v145
	ds_read_b128 v[166:169], v145 offset:1024
	ds_read_b128 v[170:173], v145 offset:2048
	ds_read_b128 v[186:189], v145 offset:3072
	v_readfirstlane_b32 s38, v132
	s_add_i32 s37, s35, 0x40100
	s_mov_b32 m0, s38
	v_readfirstlane_b32 s38, v131
	ds_read_b128 v[190:193], v143 offset:32768
	ds_read_b128 v[194:197], v143 offset:33792
	ds_read_b128 v[198:201], v142 offset:32768
	ds_read_b128 v[202:205], v142 offset:33792
	ds_read_b128 v[206:209], v141 offset:32768
	ds_read_b128 v[210:213], v141 offset:33792
	ds_read_b128 v[214:217], v140 offset:32768
	ds_read_b128 v[218:221], v140 offset:33792
	buffer_load_dwordx4 v32, s[4:7], s37 offen lds
	s_mov_b32 m0, s38
	s_nop 0
	buffer_load_dwordx4 v130, s[4:7], s37 offen lds
	s_waitcnt lgkmcnt(8)
	s_barrier
	s_waitcnt lgkmcnt(0)
	s_waitcnt lgkmcnt(7)
	v_mfma_f32_16x16x32_bf16 v[126:129], v[190:193], v[156:159], v[126:129]
	v_mfma_f32_16x16x32_bf16 v[122:125], v[190:193], v[170:173], v[122:125]
	s_waitcnt lgkmcnt(5)
	v_mfma_f32_16x16x32_bf16 v[118:121], v[198:201], v[156:159], v[118:121]
	v_mfma_f32_16x16x32_bf16 v[114:117], v[198:201], v[170:173], v[114:117]
	s_waitcnt lgkmcnt(3)
	v_mfma_f32_16x16x32_bf16 v[110:113], v[206:209], v[156:159], v[110:113]
	v_mfma_f32_16x16x32_bf16 v[106:109], v[206:209], v[170:173], v[106:109]
	s_waitcnt lgkmcnt(1)
	v_mfma_f32_16x16x32_bf16 v[102:105], v[214:217], v[156:159], v[102:105]
	v_mfma_f32_16x16x32_bf16 v[98:101], v[214:217], v[170:173], v[98:101]
	v_mfma_f32_16x16x32_bf16 v[126:129], v[194:197], v[166:169], v[126:129]
	v_mfma_f32_16x16x32_bf16 v[122:125], v[194:197], v[186:189], v[122:125]
	v_mfma_f32_16x16x32_bf16 v[118:121], v[202:205], v[166:169], v[118:121]
	v_mfma_f32_16x16x32_bf16 v[114:117], v[202:205], v[186:189], v[114:117]
	v_mfma_f32_16x16x32_bf16 v[110:113], v[210:213], v[166:169], v[110:113]
	v_mfma_f32_16x16x32_bf16 v[106:109], v[210:213], v[186:189], v[106:109]
	s_waitcnt lgkmcnt(0)
	v_mfma_f32_16x16x32_bf16 v[102:105], v[218:221], v[166:169], v[102:105]
	v_mfma_f32_16x16x32_bf16 v[98:101], v[218:221], v[186:189], v[98:101]
	s_barrier
	v_readfirstlane_b32 s38, v146
	s_add_i32 s37, s36, 0x180
	s_mov_b32 m0, s38
	v_readfirstlane_b32 s38, v147
	ds_read_b128 v[222:225], v144
	ds_read_b128 v[226:229], v144 offset:1024
	ds_read_b128 v[230:233], v144 offset:2048
	ds_read_b128 v[234:237], v144 offset:3072
	buffer_load_dwordx4 v32, s[76:79], s37 offen lds
	s_mov_b32 m0, s38
	s_nop 0
	buffer_load_dwordx4 v130, s[76:79], s37 offen lds
	s_barrier
	s_waitcnt lgkmcnt(0)
	s_waitcnt lgkmcnt(3)
	v_mfma_f32_16x16x32_bf16 v[94:97], v[190:193], v[222:225], v[94:97]
	s_waitcnt lgkmcnt(1)
	v_mfma_f32_16x16x32_bf16 v[90:93], v[190:193], v[230:233], v[90:93]
	v_mfma_f32_16x16x32_bf16 v[86:89], v[198:201], v[222:225], v[86:89]
	v_mfma_f32_16x16x32_bf16 v[82:85], v[198:201], v[230:233], v[82:85]
	v_mfma_f32_16x16x32_bf16 v[78:81], v[206:209], v[222:225], v[78:81]
	v_mfma_f32_16x16x32_bf16 v[74:77], v[206:209], v[230:233], v[74:77]
	v_mfma_f32_16x16x32_bf16 v[70:73], v[214:217], v[222:225], v[70:73]
	v_mfma_f32_16x16x32_bf16 v[66:69], v[214:217], v[230:233], v[66:69]
	v_mfma_f32_16x16x32_bf16 v[94:97], v[194:197], v[226:229], v[94:97]
	s_waitcnt lgkmcnt(0)
	v_mfma_f32_16x16x32_bf16 v[90:93], v[194:197], v[234:237], v[90:93]
	v_mfma_f32_16x16x32_bf16 v[86:89], v[202:205], v[226:229], v[86:89]
	v_mfma_f32_16x16x32_bf16 v[82:85], v[202:205], v[234:237], v[82:85]
	v_mfma_f32_16x16x32_bf16 v[78:81], v[210:213], v[226:229], v[78:81]
	v_mfma_f32_16x16x32_bf16 v[74:77], v[210:213], v[234:237], v[74:77]
	v_mfma_f32_16x16x32_bf16 v[70:73], v[218:221], v[226:229], v[70:73]
	v_mfma_f32_16x16x32_bf16 v[66:69], v[218:221], v[234:237], v[66:69]
	v_readfirstlane_b32 s37, v148
	s_addk_i32 s35, 0x180
	s_mov_b32 m0, s37
	v_readfirstlane_b32 s37, v150
	s_barrier
	ds_read_b128 v[190:193], v143 offset:49152
	ds_read_b128 v[194:197], v143 offset:50176
	ds_read_b128 v[198:201], v142 offset:49152
	ds_read_b128 v[202:205], v142 offset:50176
	ds_read_b128 v[206:209], v141 offset:49152
	ds_read_b128 v[210:213], v141 offset:50176
	ds_read_b128 v[214:217], v140 offset:49152
	ds_read_b128 v[218:221], v140 offset:50176
	buffer_load_dwordx4 v32, s[4:7], s35 offen lds
	s_mov_b32 m0, s37
	s_nop 0
	buffer_load_dwordx4 v130, s[4:7], s35 offen lds
	s_barrier
; #define STAGE(P, BASE, br, kt) do { int _so = ((br) * K + (kt) * BK) * 2; \
;     __builtin_amdgcn_raw_ptr_buffer_load_lds(rs_##BASE, (__attribute__((address_space(3))) void*)((char*)(P) + tx * 16), 16, voff0, _so, 0, 0); \
;     __builtin_amdgcn_raw_ptr_buffer_load_lds(rs_##BASE, (__attribute__((address_space(3))) void*)((char*)(P) + tx * 16 + 8192), 16, voff1, _so, 0, 0); } while (0)
; #define LDA(dst, b, h) _Pragma("unroll") for (int m = 0; m < 4; ++m) _Pragma("unroll") for (int k = 0; k < 2; ++k) \
;     dst[m][k] = *reinterpret_cast<const bf16x8*>((char*)SA(b, h) + lds_byte(wr * 64 + m * 16 + fr, k * 32 + fq * 8))
; #define LDB(dst, b, h) _Pragma("unroll") for (int n = 0; n < 2; ++n) _Pragma("unroll") for (int k = 0; k < 2; ++k) \
;     dst[n][k] = *reinterpret_cast<const bf16x8*>((char*)SB(b, h) + lds_byte(wc * 32 + n * 16 + fr, k * 32 + fq * 8))
; #define MMA(ai, bj, At, Bt_) do { __builtin_amdgcn_s_setprio(1); \
;     _Pragma("unroll") for (int m = 0; m < 4; ++m) _Pragma("unroll") for (int n = 0; n < 2; ++n) _Pragma("unroll") for (int k = 0; k < 2; ++k) \
;       acc[ai][bj][m][n] = __builtin_amdgcn_mfma_f32_16x16x32_bf16(At[m][k], Bt_[n][k], acc[ai][bj][m][n], 0, 0, 0); \
;     __builtin_amdgcn_s_setprio(0); } while (0)
; #define WAIT_V(n) asm volatile("s_waitcnt vmcnt(" #n ")" ::: "memory")
; #define WAIT_L(n) asm volatile("s_waitcnt lgkmcnt(" #n ")" ::: "memory")
; template <class Epi> ...
;     ...
;   for (int t = 0; t < nt - 2; t += 2) {
;     LDB(B0, 0, 0); SCHED; LDA(At, 0, 0); STAGE(SA(1, 1), A, brow + HALF, t + 1);
;     WAIT_L(8); BAR; WAIT_L(0); MMA(0, 0, At, B0); BAR; SCHED;
;     LDB(B1, 0, 1); STAGE(SB(0, 0), Bt, bcol, t + 2);
;     BAR; WAIT_L(0); MMA(0, 1, At, B1); BAR;
;     LDA(At, 0, 1); STAGE(SA(0, 0), A, brow, t + 2);
;     BAR; WAIT_L(0); MMA(1, 0, At, B0); BAR; SCHED;
;     STAGE(SB(0, 1), Bt, bcol + HALF, t + 2);
;     WAIT_V(6); BAR; MMA(1, 1, At, B1); BAR;
;     LDB(B0, 1, 0); SCHED; LDA(At, 1, 0); STAGE(SA(0, 1), A, brow + HALF, t + 2);
;     WAIT_L(8); BAR; WAIT_L(0); MMA(0, 0, At, B0); BAR; SCHED;
;     LDB(B1, 1, 1); STAGE(SB(1, 0), Bt, bcol, t + 3);
;     BAR; WAIT_L(0); MMA(0, 1, At, B1); BAR;
;     LDA(At, 1, 1); STAGE(SA(1, 0), A, brow, t + 3);
;     BAR; WAIT_L(0); MMA(1, 0, At, B0); BAR; SCHED;
;     STAGE(SB(1, 1), Bt, bcol + HALF, t + 3);
;     WAIT_V(6); BAR; MMA(1, 1, At, B1); BAR;
;   }
	s_waitcnt lgkmcnt(0)
	s_waitcnt lgkmcnt(7)
	v_mfma_f32_16x16x32_bf16 v[62:65], v[190:193], v[156:159], v[62:65]
	v_mfma_f32_16x16x32_bf16 v[58:61], v[190:193], v[170:173], v[58:61]
	s_waitcnt lgkmcnt(5)
	v_mfma_f32_16x16x32_bf16 v[54:57], v[198:201], v[156:159], v[54:57]
	v_mfma_f32_16x16x32_bf16 v[50:53], v[198:201], v[170:173], v[50:53]
	s_waitcnt lgkmcnt(3)
	v_mfma_f32_16x16x32_bf16 v[46:49], v[206:209], v[156:159], v[46:49]
	v_mfma_f32_16x16x32_bf16 v[42:45], v[206:209], v[170:173], v[42:45]
	s_waitcnt lgkmcnt(1)
	v_mfma_f32_16x16x32_bf16 v[38:41], v[214:217], v[156:159], v[38:41]
	v_mfma_f32_16x16x32_bf16 v[34:37], v[214:217], v[170:173], v[34:37]
	v_mfma_f32_16x16x32_bf16 v[62:65], v[194:197], v[166:169], v[62:65]
	v_mfma_f32_16x16x32_bf16 v[58:61], v[194:197], v[186:189], v[58:61]
	v_mfma_f32_16x16x32_bf16 v[54:57], v[202:205], v[166:169], v[54:57]
	v_mfma_f32_16x16x32_bf16 v[50:53], v[202:205], v[186:189], v[50:53]
	v_mfma_f32_16x16x32_bf16 v[46:49], v[210:213], v[166:169], v[46:49]
	v_mfma_f32_16x16x32_bf16 v[42:45], v[210:213], v[186:189], v[42:45]
	s_waitcnt lgkmcnt(0)
	v_mfma_f32_16x16x32_bf16 v[38:41], v[218:221], v[166:169], v[38:41]
	v_mfma_f32_16x16x32_bf16 v[34:37], v[218:221], v[186:189], v[34:37]
	s_barrier
	v_readfirstlane_b32 s35, v153
	s_add_i32 s36, s36, 0x40180
	s_mov_b32 m0, s35
	v_readfirstlane_b32 s35, v154
	buffer_load_dwordx4 v32, s[76:79], s36 offen lds
	s_mov_b32 m0, s35
	s_nop 0
	buffer_load_dwordx4 v130, s[76:79], s36 offen lds
	s_waitcnt vmcnt(6)
	s_barrier
	v_mfma_f32_16x16x32_bf16 v[28:31], v[190:193], v[222:225], v[28:31]
	v_mfma_f32_16x16x32_bf16 v[24:27], v[190:193], v[230:233], v[24:27]
	v_mfma_f32_16x16x32_bf16 v[20:23], v[198:201], v[222:225], v[20:23]
	v_mfma_f32_16x16x32_bf16 v[16:19], v[198:201], v[230:233], v[16:19]
	v_mfma_f32_16x16x32_bf16 v[12:15], v[206:209], v[222:225], v[12:15]
	v_mfma_f32_16x16x32_bf16 v[8:11], v[206:209], v[230:233], v[8:11]
	v_mfma_f32_16x16x32_bf16 v[4:7], v[214:217], v[222:225], v[4:7]
	v_mfma_f32_16x16x32_bf16 v[0:3], v[214:217], v[230:233], v[0:3]
	v_mfma_f32_16x16x32_bf16 v[28:31], v[194:197], v[226:229], v[28:31]
	v_mfma_f32_16x16x32_bf16 v[24:27], v[194:197], v[234:237], v[24:27]
	v_mfma_f32_16x16x32_bf16 v[20:23], v[202:205], v[226:229], v[20:23]
	v_mfma_f32_16x16x32_bf16 v[16:19], v[202:205], v[234:237], v[16:19]
	v_mfma_f32_16x16x32_bf16 v[12:15], v[210:213], v[226:229], v[12:15]
	v_mfma_f32_16x16x32_bf16 v[8:11], v[210:213], v[234:237], v[8:11]
	v_mfma_f32_16x16x32_bf16 v[4:7], v[218:221], v[226:229], v[4:7]
	v_mfma_f32_16x16x32_bf16 v[0:3], v[218:221], v[234:237], v[0:3]
	s_add_i32 s31, s31, 2
	s_addk_i32 s34, 0x100
	s_cmp_lt_u32 s31, 12
	s_barrier
	s_cbranch_scc1 .LBB0_74
	s_branch .Lpx0
.LBB0_74:
	ds_read_b128 v[156:159], v155
	ds_read_b128 v[166:169], v155 offset:1024
	ds_read_b128 v[170:173], v155 offset:2048
	ds_read_b128 v[186:189], v155 offset:3072
	s_add_i32 s35, s21, s34
	v_readfirstlane_b32 s37, v152
	s_add_i32 s36, s35, 0x40080
	s_mov_b32 m0, s37
	v_readfirstlane_b32 s37, v151
	ds_read_b128 v[190:193], v143
	ds_read_b128 v[194:197], v143 offset:1024
	ds_read_b128 v[198:201], v142
	ds_read_b128 v[202:205], v142 offset:1024
	ds_read_b128 v[206:209], v141
	ds_read_b128 v[210:213], v141 offset:1024
	ds_read_b128 v[214:217], v140
	ds_read_b128 v[218:221], v140 offset:1024
	buffer_load_dwordx4 v32, s[4:7], s36 offen lds
	s_mov_b32 m0, s37
	s_nop 0
	buffer_load_dwordx4 v130, s[4:7], s36 offen lds
	s_waitcnt lgkmcnt(8)
	s_barrier
	s_waitcnt lgkmcnt(0)
	s_waitcnt lgkmcnt(7)
	v_mfma_f32_16x16x32_bf16 v[126:129], v[190:193], v[156:159], v[126:129]
	v_mfma_f32_16x16x32_bf16 v[122:125], v[190:193], v[170:173], v[122:125]
	s_waitcnt lgkmcnt(5)
	v_mfma_f32_16x16x32_bf16 v[118:121], v[198:201], v[156:159], v[118:121]
	v_mfma_f32_16x16x32_bf16 v[114:117], v[198:201], v[170:173], v[114:117]
	s_waitcnt lgkmcnt(3)
	v_mfma_f32_16x16x32_bf16 v[110:113], v[206:209], v[156:159], v[110:113]
	v_mfma_f32_16x16x32_bf16 v[106:109], v[206:209], v[170:173], v[106:109]
	s_waitcnt lgkmcnt(1)
	v_mfma_f32_16x16x32_bf16 v[102:105], v[214:217], v[156:159], v[102:105]
	v_mfma_f32_16x16x32_bf16 v[98:101], v[214:217], v[170:173], v[98:101]
	v_mfma_f32_16x16x32_bf16 v[126:129], v[194:197], v[166:169], v[126:129]
	v_mfma_f32_16x16x32_bf16 v[122:125], v[194:197], v[186:189], v[122:125]
	v_mfma_f32_16x16x32_bf16 v[118:121], v[202:205], v[166:169], v[118:121]
	v_mfma_f32_16x16x32_bf16 v[114:117], v[202:205], v[186:189], v[114:117]
	v_mfma_f32_16x16x32_bf16 v[110:113], v[210:213], v[166:169], v[110:113]
	v_mfma_f32_16x16x32_bf16 v[106:109], v[210:213], v[186:189], v[106:109]
	s_waitcnt lgkmcnt(0)
	v_mfma_f32_16x16x32_bf16 v[102:105], v[218:221], v[166:169], v[102:105]
	v_mfma_f32_16x16x32_bf16 v[98:101], v[218:221], v[186:189], v[98:101]
	s_barrier
	s_add_i32 s36, s20, s34
	v_readfirstlane_b32 s38, v137
	s_add_i32 s37, s36, 0x100
	s_mov_b32 m0, s38
	v_readfirstlane_b32 s38, v139
	ds_read_b128 v[222:225], v149
	ds_read_b128 v[226:229], v149 offset:1024
	ds_read_b128 v[230:233], v149 offset:2048
	ds_read_b128 v[234:237], v149 offset:3072
	buffer_load_dwordx4 v32, s[76:79], s37 offen lds
	s_mov_b32 m0, s38
	s_nop 0
	buffer_load_dwordx4 v130, s[76:79], s37 offen lds
	s_barrier
; #define STAGE(P, BASE, br, kt) do { int _so = ((br) * K + (kt) * BK) * 2; \
;     __builtin_amdgcn_raw_ptr_buffer_load_lds(rs_##BASE, (__attribute__((address_space(3))) void*)((char*)(P) + tx * 16), 16, voff0, _so, 0, 0); \
;     __builtin_amdgcn_raw_ptr_buffer_load_lds(rs_##BASE, (__attribute__((address_space(3))) void*)((char*)(P) + tx * 16 + 8192), 16, voff1, _so, 0, 0); } while (0)
; #define LDA(dst, b, h) _Pragma("unroll") for (int m = 0; m < 4; ++m) _Pragma("unroll") for (int k = 0; k < 2; ++k) \
;     dst[m][k] = *reinterpret_cast<const bf16x8*>((char*)SA(b, h) + lds_byte(wr * 64 + m * 16 + fr, k * 32 + fq * 8))
; #define LDB(dst, b, h) _Pragma("unroll") for (int n = 0; n < 2; ++n) _Pragma("unroll") for (int k = 0; k < 2; ++k) \
;     dst[n][k] = *reinterpret_cast<const bf16x8*>((char*)SB(b, h) + lds_byte(wc * 32 + n * 16 + fr, k * 32 + fq * 8))
; #define MMA(ai, bj, At, Bt_) do { __builtin_amdgcn_s_setprio(1); \
;     _Pragma("unroll") for (int m = 0; m < 4; ++m) _Pragma("unroll") for (int n = 0; n < 2; ++n) _Pragma("unroll") for (int k = 0; k < 2; ++k) \
;       acc[ai][bj][m][n] = __builtin_amdgcn_mfma_f32_16x16x32_bf16(At[m][k], Bt_[n][k], acc[ai][bj][m][n], 0, 0, 0); \
;     __builtin_amdgcn_s_setprio(0); } while (0)
; #define WAIT_V(n) asm volatile("s_waitcnt vmcnt(" #n ")" ::: "memory")
; #define WAIT_L(n) asm volatile("s_waitcnt lgkmcnt(" #n ")" ::: "memory")
; template <class Epi> ...
;     ...
;   for (int t = 0; t < nt - 2; t += 2) {
;     LDB(B0, 0, 0); SCHED; LDA(At, 0, 0); STAGE(SA(1, 1), A, brow + HALF, t + 1);
;     WAIT_L(8); BAR; WAIT_L(0); MMA(0, 0, At, B0); BAR; SCHED;
;     LDB(B1, 0, 1); STAGE(SB(0, 0), Bt, bcol, t + 2);
;     BAR; WAIT_L(0); MMA(0, 1, At, B1); BAR;
;     LDA(At, 0, 1); STAGE(SA(0, 0), A, brow, t + 2);
;     BAR; WAIT_L(0); MMA(1, 0, At, B0); BAR; SCHED;
;     STAGE(SB(0, 1), Bt, bcol + HALF, t + 2);
;     WAIT_V(6); BAR; MMA(1, 1, At, B1); BAR;
;     LDB(B0, 1, 0); SCHED; LDA(At, 1, 0); STAGE(SA(0, 1), A, brow + HALF, t + 2);
;     WAIT_L(8); BAR; WAIT_L(0); MMA(0, 0, At, B0); BAR; SCHED;
;     LDB(B1, 1, 1); STAGE(SB(1, 0), Bt, bcol, t + 3);
;     BAR; WAIT_L(0); MMA(0, 1, At, B1); BAR;
;     LDA(At, 1, 1); STAGE(SA(1, 0), A, brow, t + 3);
;     BAR; WAIT_L(0); MMA(1, 0, At, B0); BAR; SCHED;
;     STAGE(SB(1, 1), Bt, bcol + HALF, t + 3);
;     WAIT_V(6); BAR; MMA(1, 1, At, B1); BAR;
;   }
	s_waitcnt lgkmcnt(0)
	s_waitcnt lgkmcnt(3)
	v_mfma_f32_16x16x32_bf16 v[94:97], v[190:193], v[222:225], v[94:97]
	s_waitcnt lgkmcnt(1)
	v_mfma_f32_16x16x32_bf16 v[90:93], v[190:193], v[230:233], v[90:93]
	v_mfma_f32_16x16x32_bf16 v[86:89], v[198:201], v[222:225], v[86:89]
	v_mfma_f32_16x16x32_bf16 v[82:85], v[198:201], v[230:233], v[82:85]
	v_mfma_f32_16x16x32_bf16 v[78:81], v[206:209], v[222:225], v[78:81]
	v_mfma_f32_16x16x32_bf16 v[74:77], v[206:209], v[230:233], v[74:77]
	v_mfma_f32_16x16x32_bf16 v[70:73], v[214:217], v[222:225], v[70:73]
	v_mfma_f32_16x16x32_bf16 v[66:69], v[214:217], v[230:233], v[66:69]
	v_mfma_f32_16x16x32_bf16 v[94:97], v[194:197], v[226:229], v[94:97]
	s_waitcnt lgkmcnt(0)
	v_mfma_f32_16x16x32_bf16 v[90:93], v[194:197], v[234:237], v[90:93]
	v_mfma_f32_16x16x32_bf16 v[86:89], v[202:205], v[226:229], v[86:89]
	v_mfma_f32_16x16x32_bf16 v[82:85], v[202:205], v[234:237], v[82:85]
	v_mfma_f32_16x16x32_bf16 v[78:81], v[210:213], v[226:229], v[78:81]
	v_mfma_f32_16x16x32_bf16 v[74:77], v[210:213], v[234:237], v[74:77]
	v_mfma_f32_16x16x32_bf16 v[70:73], v[218:221], v[226:229], v[70:73]
	v_mfma_f32_16x16x32_bf16 v[66:69], v[218:221], v[234:237], v[66:69]
	v_readfirstlane_b32 s38, v136
	s_add_i32 s37, s35, 0x100
	s_mov_b32 m0, s38
	v_readfirstlane_b32 s38, v135
	s_barrier
	ds_read_b128 v[190:193], v143 offset:16384
	ds_read_b128 v[194:197], v143 offset:17408
	ds_read_b128 v[198:201], v142 offset:16384
	ds_read_b128 v[202:205], v142 offset:17408
	ds_read_b128 v[206:209], v141 offset:16384
	ds_read_b128 v[210:213], v141 offset:17408
	ds_read_b128 v[214:217], v140 offset:16384
	ds_read_b128 v[218:221], v140 offset:17408
	buffer_load_dwordx4 v32, s[4:7], s37 offen lds
	s_mov_b32 m0, s38
	s_nop 0
	buffer_load_dwordx4 v130, s[4:7], s37 offen lds
	s_barrier
	s_waitcnt lgkmcnt(0)
	s_waitcnt lgkmcnt(7)
	v_mfma_f32_16x16x32_bf16 v[62:65], v[190:193], v[156:159], v[62:65]
	v_mfma_f32_16x16x32_bf16 v[58:61], v[190:193], v[170:173], v[58:61]
	s_waitcnt lgkmcnt(5)
	v_mfma_f32_16x16x32_bf16 v[54:57], v[198:201], v[156:159], v[54:57]
	v_mfma_f32_16x16x32_bf16 v[50:53], v[198:201], v[170:173], v[50:53]
	s_waitcnt lgkmcnt(3)
	v_mfma_f32_16x16x32_bf16 v[46:49], v[206:209], v[156:159], v[46:49]
	v_mfma_f32_16x16x32_bf16 v[42:45], v[206:209], v[170:173], v[42:45]
	s_waitcnt lgkmcnt(1)
	v_mfma_f32_16x16x32_bf16 v[38:41], v[214:217], v[156:159], v[38:41]
	v_mfma_f32_16x16x32_bf16 v[34:37], v[214:217], v[170:173], v[34:37]
	v_mfma_f32_16x16x32_bf16 v[62:65], v[194:197], v[166:169], v[62:65]
	v_mfma_f32_16x16x32_bf16 v[58:61], v[194:197], v[186:189], v[58:61]
	v_mfma_f32_16x16x32_bf16 v[54:57], v[202:205], v[166:169], v[54:57]
	v_mfma_f32_16x16x32_bf16 v[50:53], v[202:205], v[186:189], v[50:53]
	v_mfma_f32_16x16x32_bf16 v[46:49], v[210:213], v[166:169], v[46:49]
	v_mfma_f32_16x16x32_bf16 v[42:45], v[210:213], v[186:189], v[42:45]
	s_waitcnt lgkmcnt(0)
	v_mfma_f32_16x16x32_bf16 v[38:41], v[218:221], v[166:169], v[38:41]
	v_mfma_f32_16x16x32_bf16 v[34:37], v[218:221], v[186:189], v[34:37]
	s_barrier
	v_readfirstlane_b32 s38, v134
	s_add_i32 s37, s36, 0x40100
	s_mov_b32 m0, s38
	v_readfirstlane_b32 s38, v138
	buffer_load_dwordx4 v32, s[76:79], s37 offen lds
	s_mov_b32 m0, s38
	s_nop 0
	buffer_load_dwordx4 v130, s[76:79], s37 offen lds
	s_waitcnt vmcnt(6)
	s_barrier
	v_mfma_f32_16x16x32_bf16 v[28:31], v[190:193], v[222:225], v[28:31]
	v_mfma_f32_16x16x32_bf16 v[24:27], v[190:193], v[230:233], v[24:27]
	v_mfma_f32_16x16x32_bf16 v[20:23], v[198:201], v[222:225], v[20:23]
	v_mfma_f32_16x16x32_bf16 v[16:19], v[198:201], v[230:233], v[16:19]
	v_mfma_f32_16x16x32_bf16 v[12:15], v[206:209], v[222:225], v[12:15]
	v_mfma_f32_16x16x32_bf16 v[8:11], v[206:209], v[230:233], v[8:11]
	v_mfma_f32_16x16x32_bf16 v[4:7], v[214:217], v[222:225], v[4:7]
	v_mfma_f32_16x16x32_bf16 v[0:3], v[214:217], v[230:233], v[0:3]
	v_mfma_f32_16x16x32_bf16 v[28:31], v[194:197], v[226:229], v[28:31]
	v_mfma_f32_16x16x32_bf16 v[24:27], v[194:197], v[234:237], v[24:27]
	v_mfma_f32_16x16x32_bf16 v[20:23], v[202:205], v[226:229], v[20:23]
	v_mfma_f32_16x16x32_bf16 v[16:19], v[202:205], v[234:237], v[16:19]
	v_mfma_f32_16x16x32_bf16 v[12:15], v[210:213], v[226:229], v[12:15]
	v_mfma_f32_16x16x32_bf16 v[8:11], v[210:213], v[234:237], v[8:11]
	v_mfma_f32_16x16x32_bf16 v[4:7], v[218:221], v[226:229], v[4:7]
	v_mfma_f32_16x16x32_bf16 v[0:3], v[218:221], v[234:237], v[0:3]
	s_barrier
	ds_read_b128 v[156:159], v145
	ds_read_b128 v[166:169], v145 offset:1024
	ds_read_b128 v[170:173], v145 offset:2048
	ds_read_b128 v[186:189], v145 offset:3072
	v_readfirstlane_b32 s38, v132
	s_add_i32 s37, s35, 0x40100
	s_mov_b32 m0, s38
	v_readfirstlane_b32 s38, v131
	ds_read_b128 v[190:193], v143 offset:32768
	ds_read_b128 v[194:197], v143 offset:33792
	ds_read_b128 v[198:201], v142 offset:32768
	ds_read_b128 v[202:205], v142 offset:33792
	ds_read_b128 v[206:209], v141 offset:32768
	ds_read_b128 v[210:213], v141 offset:33792
	ds_read_b128 v[214:217], v140 offset:32768
	ds_read_b128 v[218:221], v140 offset:33792
	buffer_load_dwordx4 v32, s[4:7], s37 offen lds
	s_mov_b32 m0, s38
	s_nop 0
	buffer_load_dwordx4 v130, s[4:7], s37 offen lds
	s_waitcnt lgkmcnt(8)
	s_barrier
; #define STAGE(P, BASE, br, kt) do { int _so = ((br) * K + (kt) * BK) * 2; \
;     __builtin_amdgcn_raw_ptr_buffer_load_lds(rs_##BASE, (__attribute__((address_space(3))) void*)((char*)(P) + tx * 16), 16, voff0, _so, 0, 0); \
;     __builtin_amdgcn_raw_ptr_buffer_load_lds(rs_##BASE, (__attribute__((address_space(3))) void*)((char*)(P) + tx * 16 + 8192), 16, voff1, _so, 0, 0); } while (0)
; #define LDA(dst, b, h) _Pragma("unroll") for (int m = 0; m < 4; ++m) _Pragma("unroll") for (int k = 0; k < 2; ++k) \
;     dst[m][k] = *reinterpret_cast<const bf16x8*>((char*)SA(b, h) + lds_byte(wr * 64 + m * 16 + fr, k * 32 + fq * 8))
; #define LDB(dst, b, h) _Pragma("unroll") for (int n = 0; n < 2; ++n) _Pragma("unroll") for (int k = 0; k < 2; ++k) \
;     dst[n][k] = *reinterpret_cast<const bf16x8*>((char*)SB(b, h) + lds_byte(wc * 32 + n * 16 + fr, k * 32 + fq * 8))
; #define MMA(ai, bj, At, Bt_) do { __builtin_amdgcn_s_setprio(1); \
;     _Pragma("unroll") for (int m = 0; m < 4; ++m) _Pragma("unroll") for (int n = 0; n < 2; ++n) _Pragma("unroll") for (int k = 0; k < 2; ++k) \
;       acc[ai][bj][m][n] = __builtin_amdgcn_mfma_f32_16x16x32_bf16(At[m][k], Bt_[n][k], acc[ai][bj][m][n], 0, 0, 0); \
;     __builtin_amdgcn_s_setprio(0); } while (0)
; #define WAIT_V(n) asm volatile("s_waitcnt vmcnt(" #n ")" ::: "memory")
; #define WAIT_L(n) asm volatile("s_waitcnt lgkmcnt(" #n ")" ::: "memory")
; template <class Epi> ...
;     ...
;   for (int t = 0; t < nt - 2; t += 2) {
;     LDB(B0, 0, 0); SCHED; LDA(At, 0, 0); STAGE(SA(1, 1), A, brow + HALF, t + 1);
;     WAIT_L(8); BAR; WAIT_L(0); MMA(0, 0, At, B0); BAR; SCHED;
;     LDB(B1, 0, 1); STAGE(SB(0, 0), Bt, bcol, t + 2);
;     BAR; WAIT_L(0); MMA(0, 1, At, B1); BAR;
;     LDA(At, 0, 1); STAGE(SA(0, 0), A, brow, t + 2);
;     BAR; WAIT_L(0); MMA(1, 0, At, B0); BAR; SCHED;
;     STAGE(SB(0, 1), Bt, bcol + HALF, t + 2);
;     WAIT_V(6); BAR; MMA(1, 1, At, B1); BAR;
;     LDB(B0, 1, 0); SCHED; LDA(At, 1, 0); STAGE(SA(0, 1), A, brow + HALF, t + 2);
;     WAIT_L(8); BAR; WAIT_L(0); MMA(0, 0, At, B0); BAR; SCHED;
;     LDB(B1, 1, 1); STAGE(SB(1, 0), Bt, bcol, t + 3);
;     BAR; WAIT_L(0); MMA(0, 1, At, B1); BAR;
;     LDA(At, 1, 1); STAGE(SA(1, 0), A, brow, t + 3);
;     BAR; WAIT_L(0); MMA(1, 0, At, B0); BAR; SCHED;
;     STAGE(SB(1, 1), Bt, bcol + HALF, t + 3);
;     WAIT_V(6); BAR; MMA(1, 1, At, B1); BAR;
;   }
	s_waitcnt lgkmcnt(0)
	s_waitcnt lgkmcnt(7)
	v_mfma_f32_16x16x32_bf16 v[126:129], v[190:193], v[156:159], v[126:129]
	v_mfma_f32_16x16x32_bf16 v[122:125], v[190:193], v[170:173], v[122:125]
	s_waitcnt lgkmcnt(5)
	v_mfma_f32_16x16x32_bf16 v[118:121], v[198:201], v[156:159], v[118:121]
	v_mfma_f32_16x16x32_bf16 v[114:117], v[198:201], v[170:173], v[114:117]
	s_waitcnt lgkmcnt(3)
	v_mfma_f32_16x16x32_bf16 v[110:113], v[206:209], v[156:159], v[110:113]
	v_mfma_f32_16x16x32_bf16 v[106:109], v[206:209], v[170:173], v[106:109]
	s_waitcnt lgkmcnt(1)
	v_mfma_f32_16x16x32_bf16 v[102:105], v[214:217], v[156:159], v[102:105]
	v_mfma_f32_16x16x32_bf16 v[98:101], v[214:217], v[170:173], v[98:101]
	v_mfma_f32_16x16x32_bf16 v[126:129], v[194:197], v[166:169], v[126:129]
	v_mfma_f32_16x16x32_bf16 v[122:125], v[194:197], v[186:189], v[122:125]
	v_mfma_f32_16x16x32_bf16 v[118:121], v[202:205], v[166:169], v[118:121]
	v_mfma_f32_16x16x32_bf16 v[114:117], v[202:205], v[186:189], v[114:117]
	v_mfma_f32_16x16x32_bf16 v[110:113], v[210:213], v[166:169], v[110:113]
	v_mfma_f32_16x16x32_bf16 v[106:109], v[210:213], v[186:189], v[106:109]
	s_waitcnt lgkmcnt(0)
	v_mfma_f32_16x16x32_bf16 v[102:105], v[218:221], v[166:169], v[102:105]
	v_mfma_f32_16x16x32_bf16 v[98:101], v[218:221], v[186:189], v[98:101]
	s_barrier
	v_readfirstlane_b32 s38, v146
	s_add_i32 s37, s36, 0x180
	s_mov_b32 m0, s38
	v_readfirstlane_b32 s38, v147
	ds_read_b128 v[222:225], v144
	ds_read_b128 v[226:229], v144 offset:1024
	ds_read_b128 v[230:233], v144 offset:2048
	ds_read_b128 v[234:237], v144 offset:3072
	buffer_load_dwordx4 v32, s[76:79], s37 offen lds
	s_mov_b32 m0, s38
	s_nop 0
	buffer_load_dwordx4 v130, s[76:79], s37 offen lds
	s_barrier
	s_waitcnt lgkmcnt(0)
	s_waitcnt lgkmcnt(3)
	v_mfma_f32_16x16x32_bf16 v[94:97], v[190:193], v[222:225], v[94:97]
	s_waitcnt lgkmcnt(1)
	v_mfma_f32_16x16x32_bf16 v[90:93], v[190:193], v[230:233], v[90:93]
	v_mfma_f32_16x16x32_bf16 v[86:89], v[198:201], v[222:225], v[86:89]
	v_mfma_f32_16x16x32_bf16 v[82:85], v[198:201], v[230:233], v[82:85]
	v_mfma_f32_16x16x32_bf16 v[78:81], v[206:209], v[222:225], v[78:81]
	v_mfma_f32_16x16x32_bf16 v[74:77], v[206:209], v[230:233], v[74:77]
	v_mfma_f32_16x16x32_bf16 v[70:73], v[214:217], v[222:225], v[70:73]
	v_mfma_f32_16x16x32_bf16 v[66:69], v[214:217], v[230:233], v[66:69]
	v_mfma_f32_16x16x32_bf16 v[94:97], v[194:197], v[226:229], v[94:97]
	s_waitcnt lgkmcnt(0)
	v_mfma_f32_16x16x32_bf16 v[90:93], v[194:197], v[234:237], v[90:93]
	v_mfma_f32_16x16x32_bf16 v[86:89], v[202:205], v[226:229], v[86:89]
	v_mfma_f32_16x16x32_bf16 v[82:85], v[202:205], v[234:237], v[82:85]
	v_mfma_f32_16x16x32_bf16 v[78:81], v[210:213], v[226:229], v[78:81]
	v_mfma_f32_16x16x32_bf16 v[74:77], v[210:213], v[234:237], v[74:77]
	v_mfma_f32_16x16x32_bf16 v[70:73], v[218:221], v[226:229], v[70:73]
	v_mfma_f32_16x16x32_bf16 v[66:69], v[218:221], v[234:237], v[66:69]
	v_readfirstlane_b32 s37, v148
	s_addk_i32 s35, 0x180
	s_mov_b32 m0, s37
	v_readfirstlane_b32 s37, v150
	s_barrier
	ds_read_b128 v[190:193], v143 offset:49152
	ds_read_b128 v[194:197], v143 offset:50176
	ds_read_b128 v[198:201], v142 offset:49152
	ds_read_b128 v[202:205], v142 offset:50176
	ds_read_b128 v[206:209], v141 offset:49152
	ds_read_b128 v[210:213], v141 offset:50176
	ds_read_b128 v[214:217], v140 offset:49152
	ds_read_b128 v[218:221], v140 offset:50176
	buffer_load_dwordx4 v32, s[4:7], s35 offen lds
	s_mov_b32 m0, s37
	s_nop 0
	buffer_load_dwordx4 v130, s[4:7], s35 offen lds
	s_barrier
	s_waitcnt lgkmcnt(0)
	s_waitcnt lgkmcnt(7)
	v_mfma_f32_16x16x32_bf16 v[62:65], v[190:193], v[156:159], v[62:65]
	v_mfma_f32_16x16x32_bf16 v[58:61], v[190:193], v[170:173], v[58:61]
	s_waitcnt lgkmcnt(5)
	v_mfma_f32_16x16x32_bf16 v[54:57], v[198:201], v[156:159], v[54:57]
	v_mfma_f32_16x16x32_bf16 v[50:53], v[198:201], v[170:173], v[50:53]
	s_waitcnt lgkmcnt(3)
	v_mfma_f32_16x16x32_bf16 v[46:49], v[206:209], v[156:159], v[46:49]
	v_mfma_f32_16x16x32_bf16 v[42:45], v[206:209], v[170:173], v[42:45]
	s_waitcnt lgkmcnt(1)
	v_mfma_f32_16x16x32_bf16 v[38:41], v[214:217], v[156:159], v[38:41]
	v_mfma_f32_16x16x32_bf16 v[34:37], v[214:217], v[170:173], v[34:37]
	v_mfma_f32_16x16x32_bf16 v[62:65], v[194:197], v[166:169], v[62:65]
	v_mfma_f32_16x16x32_bf16 v[58:61], v[194:197], v[186:189], v[58:61]
	v_mfma_f32_16x16x32_bf16 v[54:57], v[202:205], v[166:169], v[54:57]
	v_mfma_f32_16x16x32_bf16 v[50:53], v[202:205], v[186:189], v[50:53]
	v_mfma_f32_16x16x32_bf16 v[46:49], v[210:213], v[166:169], v[46:49]
	v_mfma_f32_16x16x32_bf16 v[42:45], v[210:213], v[186:189], v[42:45]
	s_waitcnt lgkmcnt(0)
	v_mfma_f32_16x16x32_bf16 v[38:41], v[218:221], v[166:169], v[38:41]
	v_mfma_f32_16x16x32_bf16 v[34:37], v[218:221], v[186:189], v[34:37]
	s_barrier
	v_readfirstlane_b32 s35, v153
	s_add_i32 s36, s36, 0x40180
	s_mov_b32 m0, s35
	v_readfirstlane_b32 s35, v154
	buffer_load_dwordx4 v32, s[76:79], s36 offen lds
	s_mov_b32 m0, s35
	s_nop 0
	buffer_load_dwordx4 v130, s[76:79], s36 offen lds
	s_waitcnt vmcnt(6)
	s_barrier
	v_mfma_f32_16x16x32_bf16 v[28:31], v[190:193], v[222:225], v[28:31]
	v_mfma_f32_16x16x32_bf16 v[24:27], v[190:193], v[230:233], v[24:27]
	v_mfma_f32_16x16x32_bf16 v[20:23], v[198:201], v[222:225], v[20:23]
	v_mfma_f32_16x16x32_bf16 v[16:19], v[198:201], v[230:233], v[16:19]
	v_mfma_f32_16x16x32_bf16 v[12:15], v[206:209], v[222:225], v[12:15]
	v_mfma_f32_16x16x32_bf16 v[8:11], v[206:209], v[230:233], v[8:11]
	v_mfma_f32_16x16x32_bf16 v[4:7], v[214:217], v[222:225], v[4:7]
	v_mfma_f32_16x16x32_bf16 v[0:3], v[214:217], v[230:233], v[0:3]
	v_mfma_f32_16x16x32_bf16 v[28:31], v[194:197], v[226:229], v[28:31]
	v_mfma_f32_16x16x32_bf16 v[24:27], v[194:197], v[234:237], v[24:27]
	v_mfma_f32_16x16x32_bf16 v[20:23], v[202:205], v[226:229], v[20:23]
	v_mfma_f32_16x16x32_bf16 v[16:19], v[202:205], v[234:237], v[16:19]
	v_mfma_f32_16x16x32_bf16 v[12:15], v[210:213], v[226:229], v[12:15]
	v_mfma_f32_16x16x32_bf16 v[8:11], v[210:213], v[234:237], v[8:11]
	v_mfma_f32_16x16x32_bf16 v[4:7], v[218:221], v[226:229], v[4:7]
	v_mfma_f32_16x16x32_bf16 v[0:3], v[218:221], v[234:237], v[0:3]
	s_add_i32 s31, s31, 2
	s_addk_i32 s34, 0x100
	s_cmp_lt_u32 s31, 12
	s_barrier
	s_cbranch_scc1 .LBB0_74
; #define STAGE(P, BASE, br, kt) do { int _so = ((br) * K + (kt) * BK) * 2; \
;     __builtin_amdgcn_raw_ptr_buffer_load_lds(rs_##BASE, (__attribute__((address_space(3))) void*)((char*)(P) + tx * 16), 16, voff0, _so, 0, 0); \
;     __builtin_amdgcn_raw_ptr_buffer_load_lds(rs_##BASE, (__attribute__((address_space(3))) void*)((char*)(P) + tx * 16 + 8192), 16, voff1, _so, 0, 0); } while (0)
; #define LDA(dst, b, h) _Pragma("unroll") for (int m = 0; m < 4; ++m) _Pragma("unroll") for (int k = 0; k < 2; ++k) \
;     dst[m][k] = *reinterpret_cast<const bf16x8*>((char*)SA(b, h) + lds_byte(wr * 64 + m * 16 + fr, k * 32 + fq * 8))
; #define LDB(dst, b, h) _Pragma("unroll") for (int n = 0; n < 2; ++n) _Pragma("unroll") for (int k = 0; k < 2; ++k) \
;     dst[n][k] = *reinterpret_cast<const bf16x8*>((char*)SB(b, h) + lds_byte(wc * 32 + n * 16 + fr, k * 32 + fq * 8))
; #define MMA(ai, bj, At, Bt_) do { __builtin_amdgcn_s_setprio(1); \
;     _Pragma("unroll") for (int m = 0; m < 4; ++m) _Pragma("unroll") for (int n = 0; n < 2; ++n) _Pragma("unroll") for (int k = 0; k < 2; ++k) \
;       acc[ai][bj][m][n] = __builtin_amdgcn_mfma_f32_16x16x32_bf16(At[m][k], Bt_[n][k], acc[ai][bj][m][n], 0, 0, 0); \
;     __builtin_amdgcn_s_setprio(0); } while (0)
; #define WAIT_V(n) asm volatile("s_waitcnt vmcnt(" #n ")" ::: "memory")
; #define WAIT_L(n) asm volatile("s_waitcnt lgkmcnt(" #n ")" ::: "memory")
; #define BAR __builtin_amdgcn_s_barrier()
; template <class Epi> ...
;     ...
;   { LDB(B0, 0, 0); LDA(At, 0, 0); STAGE(SA(1, 1), A, brow + HALF, nt - 1);
;     BAR; WAIT_L(0); MMA(0, 0, At, B0); BAR;
;     LDB(B1, 0, 1); BAR; WAIT_L(0); MMA(0, 1, At, B1); BAR;
;     LDA(At, 0, 1); WAIT_V(4); BAR; WAIT_L(0); MMA(1, 0, At, B0); MMA(1, 1, At, B1); BAR; }
;   { LDB(B0, 1, 0); LDA(At, 1, 0); WAIT_V(2); BAR; WAIT_L(0); MMA(0, 0, At, B0); BAR;
;     LDB(B1, 1, 1); WAIT_V(0); BAR; WAIT_L(0); MMA(0, 1, At, B1); BAR;
;     LDA(At, 1, 1); BAR; WAIT_L(0); MMA(1, 0, At, B0); MMA(1, 1, At, B1); BAR; }
.Lpx0:
	v_readfirstlane_b32 s20, v152
	s_add_i32 s21, s21, 0x40780
	s_mov_b32 s6, s78
	s_mov_b32 s7, s79
	s_mov_b32 m0, s20
	v_readfirstlane_b32 s20, v151
	ds_read_b128 v[156:159], v155
	ds_read_b128 v[166:169], v155 offset:1024
	ds_read_b128 v[170:173], v155 offset:2048
	ds_read_b128 v[186:189], v155 offset:3072
	ds_read_b128 v[190:193], v143
	ds_read_b128 v[194:197], v143 offset:1024
	ds_read_b128 v[198:201], v142
	ds_read_b128 v[202:205], v142 offset:1024
	ds_read_b128 v[206:209], v141
	ds_read_b128 v[210:213], v141 offset:1024
	ds_read_b128 v[214:217], v140
	ds_read_b128 v[218:221], v140 offset:1024
	buffer_load_dwordx4 v32, s[4:7], s21 offen lds
	s_mov_b32 m0, s20
	s_nop 0
	buffer_load_dwordx4 v130, s[4:7], s21 offen lds
	s_barrier
	s_waitcnt lgkmcnt(0)
	s_waitcnt lgkmcnt(7)
	v_mfma_f32_16x16x32_bf16 v[126:129], v[190:193], v[156:159], v[126:129]
	v_mfma_f32_16x16x32_bf16 v[122:125], v[190:193], v[170:173], v[122:125]
	s_waitcnt lgkmcnt(5)
	v_mfma_f32_16x16x32_bf16 v[118:121], v[198:201], v[156:159], v[118:121]
	v_mfma_f32_16x16x32_bf16 v[114:117], v[198:201], v[170:173], v[114:117]
	s_waitcnt lgkmcnt(3)
	v_mfma_f32_16x16x32_bf16 v[110:113], v[206:209], v[156:159], v[110:113]
	v_mfma_f32_16x16x32_bf16 v[106:109], v[206:209], v[170:173], v[106:109]
	s_waitcnt lgkmcnt(1)
	v_mfma_f32_16x16x32_bf16 v[102:105], v[214:217], v[156:159], v[102:105]
	v_mfma_f32_16x16x32_bf16 v[98:101], v[214:217], v[170:173], v[98:101]
	v_mfma_f32_16x16x32_bf16 v[126:129], v[194:197], v[166:169], v[126:129]
	v_mfma_f32_16x16x32_bf16 v[122:125], v[194:197], v[186:189], v[122:125]
	v_mfma_f32_16x16x32_bf16 v[118:121], v[202:205], v[166:169], v[118:121]
	v_mfma_f32_16x16x32_bf16 v[114:117], v[202:205], v[186:189], v[114:117]
	v_mfma_f32_16x16x32_bf16 v[110:113], v[210:213], v[166:169], v[110:113]
	v_mfma_f32_16x16x32_bf16 v[106:109], v[210:213], v[186:189], v[106:109]
	s_waitcnt lgkmcnt(0)
	v_mfma_f32_16x16x32_bf16 v[102:105], v[218:221], v[166:169], v[102:105]
	v_mfma_f32_16x16x32_bf16 v[98:101], v[218:221], v[186:189], v[98:101]
	s_barrier
	ds_read_b128 v[150:153], v149
	ds_read_b128 v[222:225], v149 offset:1024
	ds_read_b128 v[226:229], v149 offset:2048
	ds_read_b128 v[146:149], v149 offset:3072
	s_barrier
	s_waitcnt lgkmcnt(0)
	s_waitcnt lgkmcnt(3)
	v_mfma_f32_16x16x32_bf16 v[78:81], v[206:209], v[150:153], v[78:81]
	s_waitcnt lgkmcnt(1)
	v_mfma_f32_16x16x32_bf16 v[74:77], v[206:209], v[226:229], v[74:77]
	v_mfma_f32_16x16x32_bf16 v[70:73], v[214:217], v[150:153], v[70:73]
	v_mfma_f32_16x16x32_bf16 v[66:69], v[214:217], v[226:229], v[66:69]
	v_mfma_f32_16x16x32_bf16 v[94:97], v[190:193], v[150:153], v[94:97]
	v_mfma_f32_16x16x32_bf16 v[90:93], v[190:193], v[226:229], v[90:93]
	v_mfma_f32_16x16x32_bf16 v[86:89], v[198:201], v[150:153], v[86:89]
	v_mfma_f32_16x16x32_bf16 v[82:85], v[198:201], v[226:229], v[82:85]
	v_mfma_f32_16x16x32_bf16 v[78:81], v[210:213], v[222:225], v[78:81]
	s_waitcnt lgkmcnt(0)
	v_mfma_f32_16x16x32_bf16 v[74:77], v[210:213], v[146:149], v[74:77]
	v_mfma_f32_16x16x32_bf16 v[70:73], v[218:221], v[222:225], v[70:73]
	v_mfma_f32_16x16x32_bf16 v[66:69], v[218:221], v[146:149], v[66:69]
	v_mfma_f32_16x16x32_bf16 v[230:233], v[194:197], v[222:225], v[94:97]
	v_mfma_f32_16x16x32_bf16 v[190:193], v[194:197], v[146:149], v[90:93]
	v_mfma_f32_16x16x32_bf16 v[194:197], v[202:205], v[222:225], v[86:89]
	v_mfma_f32_16x16x32_bf16 v[198:201], v[202:205], v[146:149], v[82:85]
	s_barrier
	s_nop 0
	ds_read_b128 v[82:85], v143 offset:16384
	ds_read_b128 v[86:89], v143 offset:17408
	ds_read_b128 v[90:93], v142 offset:16384
	ds_read_b128 v[94:97], v142 offset:17408
	ds_read_b128 v[202:205], v141 offset:16384
	ds_read_b128 v[206:209], v141 offset:17408
	ds_read_b128 v[210:213], v140 offset:16384
	ds_read_b128 v[214:217], v140 offset:17408
	s_waitcnt vmcnt(4)
	s_barrier
	s_waitcnt lgkmcnt(0)
	s_waitcnt lgkmcnt(3)
	v_mfma_f32_16x16x32_bf16 v[46:49], v[202:205], v[156:159], v[46:49]
	v_mfma_f32_16x16x32_bf16 v[42:45], v[202:205], v[170:173], v[42:45]
	s_waitcnt lgkmcnt(1)
	v_mfma_f32_16x16x32_bf16 v[38:41], v[210:213], v[156:159], v[38:41]
	v_mfma_f32_16x16x32_bf16 v[34:37], v[210:213], v[170:173], v[34:37]
	v_mfma_f32_16x16x32_bf16 v[62:65], v[82:85], v[156:159], v[62:65]
	v_mfma_f32_16x16x32_bf16 v[58:61], v[82:85], v[170:173], v[58:61]
	v_mfma_f32_16x16x32_bf16 v[54:57], v[90:93], v[156:159], v[54:57]
	v_mfma_f32_16x16x32_bf16 v[50:53], v[90:93], v[170:173], v[50:53]
	v_mfma_f32_16x16x32_bf16 v[46:49], v[206:209], v[166:169], v[46:49]
	v_mfma_f32_16x16x32_bf16 v[42:45], v[206:209], v[186:189], v[42:45]
	s_waitcnt lgkmcnt(0)
	v_mfma_f32_16x16x32_bf16 v[38:41], v[214:217], v[166:169], v[38:41]
	v_mfma_f32_16x16x32_bf16 v[34:37], v[214:217], v[186:189], v[34:37]
	v_mfma_f32_16x16x32_bf16 v[218:221], v[86:89], v[166:169], v[62:65]
	v_mfma_f32_16x16x32_bf16 v[234:237], v[86:89], v[186:189], v[58:61]
	v_mfma_f32_16x16x32_bf16 v[238:241], v[94:97], v[166:169], v[54:57]
	v_mfma_f32_16x16x32_bf16 v[242:245], v[94:97], v[186:189], v[50:53]
	v_mfma_f32_16x16x32_bf16 v[0:3], v[210:213], v[226:229], v[0:3]
	v_mfma_f32_16x16x32_bf16 v[28:31], v[82:85], v[150:153], v[28:31]
	v_mfma_f32_16x16x32_bf16 v[24:27], v[82:85], v[226:229], v[24:27]
	v_mfma_f32_16x16x32_bf16 v[20:23], v[90:93], v[150:153], v[20:23]
	v_mfma_f32_16x16x32_bf16 v[16:19], v[90:93], v[226:229], v[16:19]
	v_mfma_f32_16x16x32_bf16 v[12:15], v[202:205], v[150:153], v[12:15]
	v_mfma_f32_16x16x32_bf16 v[8:11], v[202:205], v[226:229], v[8:11]
	v_mfma_f32_16x16x32_bf16 v[4:7], v[210:213], v[150:153], v[4:7]
	v_mfma_f32_16x16x32_bf16 v[0:3], v[214:217], v[146:149], v[0:3]
	v_mfma_f32_16x16x32_bf16 v[154:157], v[86:89], v[222:225], v[28:31]
	v_mfma_f32_16x16x32_bf16 v[158:161], v[86:89], v[146:149], v[24:27]
	v_mfma_f32_16x16x32_bf16 v[166:169], v[94:97], v[222:225], v[20:23]
	v_mfma_f32_16x16x32_bf16 v[170:173], v[94:97], v[146:149], v[16:19]
	v_mfma_f32_16x16x32_bf16 v[186:189], v[206:209], v[222:225], v[12:15]
	v_mfma_f32_16x16x32_bf16 v[202:205], v[206:209], v[146:149], v[8:11]
	v_mfma_f32_16x16x32_bf16 v[150:153], v[214:217], v[222:225], v[4:7]
	s_barrier
; #define STAGE(P, BASE, br, kt) do { int _so = ((br) * K + (kt) * BK) * 2; \
;     __builtin_amdgcn_raw_ptr_buffer_load_lds(rs_##BASE, (__attribute__((address_space(3))) void*)((char*)(P) + tx * 16), 16, voff0, _so, 0, 0); \
;     __builtin_amdgcn_raw_ptr_buffer_load_lds(rs_##BASE, (__attribute__((address_space(3))) void*)((char*)(P) + tx * 16 + 8192), 16, voff1, _so, 0, 0); } while (0)
; #define LDA(dst, b, h) _Pragma("unroll") for (int m = 0; m < 4; ++m) _Pragma("unroll") for (int k = 0; k < 2; ++k) \
;     dst[m][k] = *reinterpret_cast<const bf16x8*>((char*)SA(b, h) + lds_byte(wr * 64 + m * 16 + fr, k * 32 + fq * 8))
; #define LDB(dst, b, h) _Pragma("unroll") for (int n = 0; n < 2; ++n) _Pragma("unroll") for (int k = 0; k < 2; ++k) \
;     dst[n][k] = *reinterpret_cast<const bf16x8*>((char*)SB(b, h) + lds_byte(wc * 32 + n * 16 + fr, k * 32 + fq * 8))
; #define MMA(ai, bj, At, Bt_) do { __builtin_amdgcn_s_setprio(1); \
;     _Pragma("unroll") for (int m = 0; m < 4; ++m) _Pragma("unroll") for (int n = 0; n < 2; ++n) _Pragma("unroll") for (int k = 0; k < 2; ++k) \
;       acc[ai][bj][m][n] = __builtin_amdgcn_mfma_f32_16x16x32_bf16(At[m][k], Bt_[n][k], acc[ai][bj][m][n], 0, 0, 0); \
;     __builtin_amdgcn_s_setprio(0); } while (0)
; #define WAIT_V(n) asm volatile("s_waitcnt vmcnt(" #n ")" ::: "memory")
; #define WAIT_L(n) asm volatile("s_waitcnt lgkmcnt(" #n ")" ::: "memory")
; #define BAR __builtin_amdgcn_s_barrier()
; template <class Epi> ...
;     ...
;   { LDB(B0, 0, 0); LDA(At, 0, 0); STAGE(SA(1, 1), A, brow + HALF, nt - 1);
;     BAR; WAIT_L(0); MMA(0, 0, At, B0); BAR;
;     LDB(B1, 0, 1); BAR; WAIT_L(0); MMA(0, 1, At, B1); BAR;
;     LDA(At, 0, 1); WAIT_V(4); BAR; WAIT_L(0); MMA(1, 0, At, B0); MMA(1, 1, At, B1); BAR; }
;   { LDB(B0, 1, 0); LDA(At, 1, 0); WAIT_V(2); BAR; WAIT_L(0); MMA(0, 0, At, B0); BAR;
;     LDB(B1, 1, 1); WAIT_V(0); BAR; WAIT_L(0); MMA(0, 1, At, B1); BAR;
;     LDA(At, 1, 1); BAR; WAIT_L(0); MMA(1, 0, At, B0); MMA(1, 1, At, B1); BAR; }
;   if (wr == 0) BAR;
;   if (has_next) {
	s_nop 0
	ds_read_b128 v[4:7], v145
	ds_read_b128 v[8:11], v145 offset:1024
	ds_read_b128 v[12:15], v145 offset:2048
	ds_read_b128 v[146:149], v145 offset:3072
	ds_read_b128 v[16:19], v143 offset:32768
	ds_read_b128 v[20:23], v143 offset:33792
	ds_read_b128 v[24:27], v142 offset:32768
	ds_read_b128 v[50:53], v142 offset:33792
	ds_read_b128 v[206:209], v141 offset:32768
	ds_read_b128 v[210:213], v141 offset:33792
	ds_read_b128 v[214:217], v140 offset:32768
	ds_read_b128 v[222:225], v140 offset:33792
	s_waitcnt vmcnt(2)
	s_barrier
	s_waitcnt lgkmcnt(0)
	s_waitcnt lgkmcnt(7)
	v_mfma_f32_16x16x32_bf16 v[28:31], v[16:19], v[4:7], v[126:129]
	s_waitcnt lgkmcnt(6)
	v_mfma_f32_16x16x32_bf16 v[126:129], v[20:23], v[8:11], v[28:31]
	v_mfma_f32_16x16x32_bf16 v[28:31], v[16:19], v[12:15], v[122:125]
	v_mfma_f32_16x16x32_bf16 v[94:97], v[20:23], v[146:149], v[28:31]
	s_waitcnt lgkmcnt(5)
	v_mfma_f32_16x16x32_bf16 v[28:31], v[24:27], v[4:7], v[118:121]
	s_waitcnt lgkmcnt(4)
	v_mfma_f32_16x16x32_bf16 v[122:125], v[50:53], v[8:11], v[28:31]
	v_mfma_f32_16x16x32_bf16 v[28:31], v[24:27], v[12:15], v[114:117]
	v_mfma_f32_16x16x32_bf16 v[90:93], v[50:53], v[146:149], v[28:31]
	s_waitcnt lgkmcnt(3)
	v_mfma_f32_16x16x32_bf16 v[28:31], v[206:209], v[4:7], v[110:113]
	s_waitcnt lgkmcnt(2)
	v_mfma_f32_16x16x32_bf16 v[118:121], v[210:213], v[8:11], v[28:31]
	v_mfma_f32_16x16x32_bf16 v[28:31], v[206:209], v[12:15], v[106:109]
	v_mfma_f32_16x16x32_bf16 v[86:89], v[210:213], v[146:149], v[28:31]
	s_waitcnt lgkmcnt(1)
	v_mfma_f32_16x16x32_bf16 v[28:31], v[214:217], v[4:7], v[102:105]
	s_waitcnt lgkmcnt(0)
	v_mfma_f32_16x16x32_bf16 v[114:117], v[222:225], v[8:11], v[28:31]
	v_mfma_f32_16x16x32_bf16 v[28:31], v[214:217], v[12:15], v[98:101]
	v_mfma_f32_16x16x32_bf16 v[82:85], v[222:225], v[146:149], v[28:31]
	s_barrier
	ds_read_b128 v[226:229], v144
	ds_read_b128 v[246:249], v144 offset:1024
	ds_read_b128 v[250:253], v144 offset:2048
	ds_read_b128 v[174:177], v144 offset:3072
	s_waitcnt vmcnt(0)
	s_barrier
	s_waitcnt lgkmcnt(0)
	s_waitcnt lgkmcnt(3)
	v_mfma_f32_16x16x32_bf16 v[28:31], v[16:19], v[226:229], v[230:233]
	s_waitcnt lgkmcnt(1)
	v_mfma_f32_16x16x32_bf16 v[16:19], v[16:19], v[250:253], v[190:193]
	v_mfma_f32_16x16x32_bf16 v[62:65], v[20:23], v[246:249], v[28:31]
	s_waitcnt lgkmcnt(0)
	v_mfma_f32_16x16x32_bf16 v[28:31], v[20:23], v[174:177], v[16:19]
	v_mfma_f32_16x16x32_bf16 v[16:19], v[24:27], v[226:229], v[194:197]
	v_mfma_f32_16x16x32_bf16 v[58:61], v[50:53], v[246:249], v[16:19]
	v_mfma_f32_16x16x32_bf16 v[16:19], v[24:27], v[250:253], v[198:201]
	v_mfma_f32_16x16x32_bf16 v[24:27], v[50:53], v[174:177], v[16:19]
	v_mfma_f32_16x16x32_bf16 v[16:19], v[206:209], v[226:229], v[78:81]
	v_mfma_f32_16x16x32_bf16 v[54:57], v[210:213], v[246:249], v[16:19]
	v_mfma_f32_16x16x32_bf16 v[16:19], v[206:209], v[250:253], v[74:77]
	v_mfma_f32_16x16x32_bf16 v[20:23], v[210:213], v[174:177], v[16:19]
	v_mfma_f32_16x16x32_bf16 v[16:19], v[214:217], v[226:229], v[70:73]
	v_mfma_f32_16x16x32_bf16 v[50:53], v[222:225], v[246:249], v[16:19]
	v_mfma_f32_16x16x32_bf16 v[16:19], v[214:217], v[250:253], v[66:69]
	v_mfma_f32_16x16x32_bf16 v[16:19], v[222:225], v[174:177], v[16:19]
	s_barrier
	ds_read_b128 v[190:193], v143 offset:49152
	ds_read_b128 v[194:197], v143 offset:50176
	ds_read_b128 v[198:201], v142 offset:49152
	ds_read_b128 v[142:145], v142 offset:50176
	ds_read_b128 v[206:209], v141 offset:49152
	ds_read_b128 v[210:213], v141 offset:50176
	ds_read_b128 v[214:217], v140 offset:49152
	ds_read_b128 v[222:225], v140 offset:50176
	s_barrier
	s_waitcnt lgkmcnt(0)
	s_waitcnt lgkmcnt(7)
	v_mfma_f32_16x16x32_bf16 v[66:69], v[190:193], v[4:7], v[218:221]
	s_waitcnt lgkmcnt(6)
	v_mfma_f32_16x16x32_bf16 v[110:113], v[194:197], v[8:11], v[66:69]
	v_mfma_f32_16x16x32_bf16 v[66:69], v[190:193], v[12:15], v[234:237]
	v_mfma_f32_16x16x32_bf16 v[78:81], v[194:197], v[146:149], v[66:69]
	s_waitcnt lgkmcnt(5)
	v_mfma_f32_16x16x32_bf16 v[66:69], v[198:201], v[4:7], v[238:241]
	s_waitcnt lgkmcnt(3)
	v_mfma_f32_16x16x32_bf16 v[46:49], v[206:209], v[4:7], v[46:49]
	s_waitcnt lgkmcnt(1)
	v_mfma_f32_16x16x32_bf16 v[4:7], v[214:217], v[4:7], v[38:41]
	v_mfma_f32_16x16x32_bf16 v[106:109], v[142:145], v[8:11], v[66:69]
	v_mfma_f32_16x16x32_bf16 v[66:69], v[198:201], v[12:15], v[242:245]
	v_mfma_f32_16x16x32_bf16 v[42:45], v[206:209], v[12:15], v[42:45]
	s_waitcnt lgkmcnt(0)
	v_mfma_f32_16x16x32_bf16 v[98:101], v[222:225], v[8:11], v[4:7]
	v_mfma_f32_16x16x32_bf16 v[4:7], v[214:217], v[12:15], v[34:37]
	v_mfma_f32_16x16x32_bf16 v[74:77], v[142:145], v[146:149], v[66:69]
	v_mfma_f32_16x16x32_bf16 v[102:105], v[210:213], v[8:11], v[46:49]
	v_mfma_f32_16x16x32_bf16 v[70:73], v[210:213], v[146:149], v[42:45]
	v_mfma_f32_16x16x32_bf16 v[66:69], v[222:225], v[146:149], v[4:7]
	v_mfma_f32_16x16x32_bf16 v[4:7], v[190:193], v[226:229], v[154:157]
	v_mfma_f32_16x16x32_bf16 v[46:49], v[194:197], v[246:249], v[4:7]
	v_mfma_f32_16x16x32_bf16 v[4:7], v[190:193], v[250:253], v[158:161]
	v_mfma_f32_16x16x32_bf16 v[12:15], v[194:197], v[174:177], v[4:7]
	v_mfma_f32_16x16x32_bf16 v[4:7], v[198:201], v[226:229], v[166:169]
	v_mfma_f32_16x16x32_bf16 v[42:45], v[142:145], v[246:249], v[4:7]
	v_mfma_f32_16x16x32_bf16 v[4:7], v[198:201], v[250:253], v[170:173]
	v_mfma_f32_16x16x32_bf16 v[8:11], v[142:145], v[174:177], v[4:7]
	v_mfma_f32_16x16x32_bf16 v[4:7], v[206:209], v[226:229], v[186:189]
	v_mfma_f32_16x16x32_bf16 v[38:41], v[210:213], v[246:249], v[4:7]
	v_mfma_f32_16x16x32_bf16 v[4:7], v[206:209], v[250:253], v[202:205]
	v_mfma_f32_16x16x32_bf16 v[34:37], v[214:217], v[226:229], v[150:153]
	v_mfma_f32_16x16x32_bf16 v[0:3], v[214:217], v[250:253], v[0:3]
	v_mfma_f32_16x16x32_bf16 v[4:7], v[210:213], v[174:177], v[4:7]
	v_mfma_f32_16x16x32_bf16 v[34:37], v[222:225], v[246:249], v[34:37]
	v_mfma_f32_16x16x32_bf16 v[0:3], v[222:225], v[174:177], v[0:3]
	v_cmp_gt_u32_e32 vcc, s59, v133
	s_barrier
	s_and_saveexec_b64 s[4:5], vcc
	s_cbranch_execz .LBB0_77
	s_barrier

; #define STAGE(P, BASE, br, kt) do { int _so = ((br) * K + (kt) * BK) * 2; \
;     __builtin_amdgcn_raw_ptr_buffer_load_lds(rs_##BASE, (__attribute__((address_space(3))) void*)((char*)(P) + tx * 16), 16, voff0, _so, 0, 0); \
;     __builtin_amdgcn_raw_ptr_buffer_load_lds(rs_##BASE, (__attribute__((address_space(3))) void*)((char*)(P) + tx * 16 + 8192), 16, voff1, _so, 0, 0); } while (0)
; #define LDA(dst, b, h) _Pragma("unroll") for (int m = 0; m < 4; ++m) _Pragma("unroll") for (int k = 0; k < 2; ++k) \
;     dst[m][k] = *reinterpret_cast<const bf16x8*>((char*)SA(b, h) + lds_byte(wr * 64 + m * 16 + fr, k * 32 + fq * 8))
; #define LDB(dst, b, h) _Pragma("unroll") for (int n = 0; n < 2; ++n) _Pragma("unroll") for (int k = 0; k < 2; ++k) \
;     dst[n][k] = *reinterpret_cast<const bf16x8*>((char*)SB(b, h) + lds_byte(wc * 32 + n * 16 + fr, k * 32 + fq * 8))
; #define MMA(ai, bj, At, Bt_) do { __builtin_amdgcn_s_setprio(1); \
;     _Pragma("unroll") for (int m = 0; m < 4; ++m) _Pragma("unroll") for (int n = 0; n < 2; ++n) _Pragma("unroll") for (int k = 0; k < 2; ++k) \
;       acc[ai][bj][m][n] = __builtin_amdgcn_mfma_f32_16x16x32_bf16(At[m][k], Bt_[n][k], acc[ai][bj][m][n], 0, 0, 0); \
;     __builtin_amdgcn_s_setprio(0); } while (0)
; #define WAIT_V(n) asm volatile("s_waitcnt vmcnt(" #n ")" ::: "memory")
; #define WAIT_L(n) asm volatile("s_waitcnt lgkmcnt(" #n ")" ::: "memory")
; #define BAR __builtin_amdgcn_s_barrier()
; template <class Epi> ...
;     ...
;   { LDB(B0, 0, 0); LDA(At, 0, 0); STAGE(SA(1, 1), A, brow + HALF, nt - 1);
;     BAR; WAIT_L(0); MMA(0, 0, At, B0); BAR;
;     LDB(B1, 0, 1); BAR; WAIT_L(0); MMA(0, 1, At, B1); BAR;
;     LDA(At, 0, 1); WAIT_V(4); BAR; WAIT_L(0); MMA(1, 0, At, B0); MMA(1, 1, At, B1); BAR; }
;   { LDB(B0, 1, 0); LDA(At, 1, 0); WAIT_V(2); BAR; WAIT_L(0); MMA(0, 0, At, B0); BAR;
;     LDB(B1, 1, 1); WAIT_V(0); BAR; WAIT_L(0); MMA(0, 1, At, B1); BAR;
;     LDA(At, 1, 1); BAR; WAIT_L(0); MMA(1, 0, At, B0); MMA(1, 1, At, B1); BAR; }
.Lpx1:
	v_readfirstlane_b32 s20, v152
	s_add_i32 s21, s21, 0x40780
	s_mov_b32 s6, s78
	s_mov_b32 s7, s79
	s_mov_b32 m0, s20
	v_readfirstlane_b32 s20, v151
	ds_read_b128 v[156:159], v155
	ds_read_b128 v[166:169], v155 offset:1024
	ds_read_b128 v[170:173], v155 offset:2048
	ds_read_b128 v[186:189], v155 offset:3072
	ds_read_b128 v[190:193], v143
	ds_read_b128 v[194:197], v143 offset:1024
	ds_read_b128 v[198:201], v142
	ds_read_b128 v[202:205], v142 offset:1024
	ds_read_b128 v[206:209], v141
	ds_read_b128 v[210:213], v141 offset:1024
	ds_read_b128 v[214:217], v140
	ds_read_b128 v[218:221], v140 offset:1024
	buffer_load_dwordx4 v32, s[4:7], s21 offen lds
	s_mov_b32 m0, s20
	s_nop 0
	buffer_load_dwordx4 v130, s[4:7], s21 offen lds
	s_barrier
	s_waitcnt lgkmcnt(0)
	s_waitcnt lgkmcnt(7)
	v_mfma_f32_16x16x32_bf16 v[126:129], v[190:193], v[156:159], v[126:129]
	v_mfma_f32_16x16x32_bf16 v[122:125], v[190:193], v[170:173], v[122:125]
	s_waitcnt lgkmcnt(5)
	v_mfma_f32_16x16x32_bf16 v[114:117], v[198:201], v[170:173], v[114:117]
	s_waitcnt lgkmcnt(3)
	v_mfma_f32_16x16x32_bf16 v[106:109], v[206:209], v[170:173], v[106:109]
	s_waitcnt lgkmcnt(1)
	v_mfma_f32_16x16x32_bf16 v[102:105], v[214:217], v[156:159], v[102:105]
	v_mfma_f32_16x16x32_bf16 v[126:129], v[194:197], v[166:169], v[126:129]
	v_mfma_f32_16x16x32_bf16 v[122:125], v[194:197], v[186:189], v[122:125]
	v_mfma_f32_16x16x32_bf16 v[118:121], v[198:201], v[156:159], v[118:121]
	v_mfma_f32_16x16x32_bf16 v[114:117], v[202:205], v[186:189], v[114:117]
	v_mfma_f32_16x16x32_bf16 v[110:113], v[206:209], v[156:159], v[110:113]
	v_mfma_f32_16x16x32_bf16 v[106:109], v[210:213], v[186:189], v[106:109]
	s_waitcnt lgkmcnt(0)
	v_mfma_f32_16x16x32_bf16 v[102:105], v[218:221], v[166:169], v[102:105]
	v_mfma_f32_16x16x32_bf16 v[98:101], v[214:217], v[170:173], v[98:101]
	v_mfma_f32_16x16x32_bf16 v[150:153], v[202:205], v[166:169], v[118:121]
	v_mfma_f32_16x16x32_bf16 v[222:225], v[210:213], v[166:169], v[110:113]
	v_mfma_f32_16x16x32_bf16 v[226:229], v[218:221], v[186:189], v[98:101]
	s_barrier
	s_nop 2
	ds_read_b128 v[98:101], v149
	ds_read_b128 v[110:113], v149 offset:1024
	ds_read_b128 v[118:121], v149 offset:2048
	ds_read_b128 v[146:149], v149 offset:3072
	s_barrier
	s_waitcnt lgkmcnt(0)
	s_waitcnt lgkmcnt(1)
	v_mfma_f32_16x16x32_bf16 v[90:93], v[190:193], v[118:121], v[90:93]
	v_mfma_f32_16x16x32_bf16 v[86:89], v[198:201], v[98:101], v[86:89]
	v_mfma_f32_16x16x32_bf16 v[74:77], v[206:209], v[118:121], v[74:77]
	v_mfma_f32_16x16x32_bf16 v[70:73], v[214:217], v[98:101], v[70:73]
	v_mfma_f32_16x16x32_bf16 v[94:97], v[190:193], v[98:101], v[94:97]
	s_waitcnt lgkmcnt(0)
	v_mfma_f32_16x16x32_bf16 v[90:93], v[194:197], v[146:149], v[90:93]
	v_mfma_f32_16x16x32_bf16 v[86:89], v[202:205], v[110:113], v[86:89]
	v_mfma_f32_16x16x32_bf16 v[82:85], v[198:201], v[118:121], v[82:85]
	v_mfma_f32_16x16x32_bf16 v[78:81], v[206:209], v[98:101], v[78:81]
	v_mfma_f32_16x16x32_bf16 v[74:77], v[210:213], v[146:149], v[74:77]
	v_mfma_f32_16x16x32_bf16 v[70:73], v[218:221], v[110:113], v[70:73]
	v_mfma_f32_16x16x32_bf16 v[66:69], v[214:217], v[118:121], v[66:69]
	v_mfma_f32_16x16x32_bf16 v[230:233], v[194:197], v[110:113], v[94:97]
	v_mfma_f32_16x16x32_bf16 v[190:193], v[202:205], v[146:149], v[82:85]
	v_mfma_f32_16x16x32_bf16 v[194:197], v[210:213], v[110:113], v[78:81]
	v_mfma_f32_16x16x32_bf16 v[198:201], v[218:221], v[146:149], v[66:69]
	s_barrier
	s_nop 1
	ds_read_b128 v[66:69], v143 offset:16384
	ds_read_b128 v[78:81], v143 offset:17408
	ds_read_b128 v[82:85], v142 offset:16384
	ds_read_b128 v[94:97], v142 offset:17408
	ds_read_b128 v[202:205], v141 offset:16384
	ds_read_b128 v[206:209], v141 offset:17408
	ds_read_b128 v[210:213], v140 offset:16384
	ds_read_b128 v[214:217], v140 offset:17408
	s_waitcnt vmcnt(4)
	s_barrier
	s_waitcnt lgkmcnt(0)
	s_waitcnt lgkmcnt(7)
	v_mfma_f32_16x16x32_bf16 v[62:65], v[66:69], v[156:159], v[62:65]
	v_mfma_f32_16x16x32_bf16 v[58:61], v[66:69], v[170:173], v[58:61]
	s_waitcnt lgkmcnt(5)
	v_mfma_f32_16x16x32_bf16 v[54:57], v[82:85], v[156:159], v[54:57]
	v_mfma_f32_16x16x32_bf16 v[50:53], v[82:85], v[170:173], v[50:53]
	s_waitcnt lgkmcnt(3)
	v_mfma_f32_16x16x32_bf16 v[42:45], v[202:205], v[170:173], v[42:45]
	s_waitcnt lgkmcnt(1)
	v_mfma_f32_16x16x32_bf16 v[34:37], v[210:213], v[170:173], v[34:37]
	v_mfma_f32_16x16x32_bf16 v[62:65], v[78:81], v[166:169], v[62:65]
	v_mfma_f32_16x16x32_bf16 v[58:61], v[78:81], v[186:189], v[58:61]
	v_mfma_f32_16x16x32_bf16 v[54:57], v[94:97], v[166:169], v[54:57]
	v_mfma_f32_16x16x32_bf16 v[50:53], v[94:97], v[186:189], v[50:53]
	v_mfma_f32_16x16x32_bf16 v[46:49], v[202:205], v[156:159], v[46:49]
	v_mfma_f32_16x16x32_bf16 v[42:45], v[206:209], v[186:189], v[42:45]
	v_mfma_f32_16x16x32_bf16 v[38:41], v[210:213], v[156:159], v[38:41]
	s_waitcnt lgkmcnt(0)
	v_mfma_f32_16x16x32_bf16 v[34:37], v[214:217], v[186:189], v[34:37]
	v_mfma_f32_16x16x32_bf16 v[218:221], v[206:209], v[166:169], v[46:49]
	v_mfma_f32_16x16x32_bf16 v[154:157], v[214:217], v[166:169], v[38:41]
	v_mfma_f32_16x16x32_bf16 v[24:27], v[66:69], v[118:121], v[24:27]
	v_mfma_f32_16x16x32_bf16 v[16:19], v[82:85], v[118:121], v[16:19]
	v_mfma_f32_16x16x32_bf16 v[8:11], v[202:205], v[118:121], v[8:11]
	v_mfma_f32_16x16x32_bf16 v[0:3], v[210:213], v[118:121], v[0:3]
	v_mfma_f32_16x16x32_bf16 v[28:31], v[66:69], v[98:101], v[28:31]
	v_mfma_f32_16x16x32_bf16 v[24:27], v[78:81], v[146:149], v[24:27]
	v_mfma_f32_16x16x32_bf16 v[20:23], v[82:85], v[98:101], v[20:23]
	v_mfma_f32_16x16x32_bf16 v[16:19], v[94:97], v[146:149], v[16:19]
	v_mfma_f32_16x16x32_bf16 v[12:15], v[202:205], v[98:101], v[12:15]
	v_mfma_f32_16x16x32_bf16 v[8:11], v[206:209], v[146:149], v[8:11]
	v_mfma_f32_16x16x32_bf16 v[4:7], v[210:213], v[98:101], v[4:7]
	v_mfma_f32_16x16x32_bf16 v[0:3], v[214:217], v[146:149], v[0:3]
	v_mfma_f32_16x16x32_bf16 v[158:161], v[78:81], v[110:113], v[28:31]
	v_mfma_f32_16x16x32_bf16 v[166:169], v[94:97], v[110:113], v[20:23]
	v_mfma_f32_16x16x32_bf16 v[170:173], v[206:209], v[110:113], v[12:15]
	v_mfma_f32_16x16x32_bf16 v[186:189], v[214:217], v[110:113], v[4:7]
	s_barrier
; #define STAGE(P, BASE, br, kt) do { int _so = ((br) * K + (kt) * BK) * 2; \
;     __builtin_amdgcn_raw_ptr_buffer_load_lds(rs_##BASE, (__attribute__((address_space(3))) void*)((char*)(P) + tx * 16), 16, voff0, _so, 0, 0); \
;     __builtin_amdgcn_raw_ptr_buffer_load_lds(rs_##BASE, (__attribute__((address_space(3))) void*)((char*)(P) + tx * 16 + 8192), 16, voff1, _so, 0, 0); } while (0)
; #define LDA(dst, b, h) _Pragma("unroll") for (int m = 0; m < 4; ++m) _Pragma("unroll") for (int k = 0; k < 2; ++k) \
;     dst[m][k] = *reinterpret_cast<const bf16x8*>((char*)SA(b, h) + lds_byte(wr * 64 + m * 16 + fr, k * 32 + fq * 8))
; #define LDB(dst, b, h) _Pragma("unroll") for (int n = 0; n < 2; ++n) _Pragma("unroll") for (int k = 0; k < 2; ++k) \
;     dst[n][k] = *reinterpret_cast<const bf16x8*>((char*)SB(b, h) + lds_byte(wc * 32 + n * 16 + fr, k * 32 + fq * 8))
; #define MMA(ai, bj, At, Bt_) do { __builtin_amdgcn_s_setprio(1); \
;     _Pragma("unroll") for (int m = 0; m < 4; ++m) _Pragma("unroll") for (int n = 0; n < 2; ++n) _Pragma("unroll") for (int k = 0; k < 2; ++k) \
;       acc[ai][bj][m][n] = __builtin_amdgcn_mfma_f32_16x16x32_bf16(At[m][k], Bt_[n][k], acc[ai][bj][m][n], 0, 0, 0); \
;     __builtin_amdgcn_s_setprio(0); } while (0)
; #define WAIT_V(n) asm volatile("s_waitcnt vmcnt(" #n ")" ::: "memory")
; #define WAIT_L(n) asm volatile("s_waitcnt lgkmcnt(" #n ")" ::: "memory")
; #define BAR __builtin_amdgcn_s_barrier()
; template <class Epi> ...
;     ...
;   { LDB(B0, 0, 0); LDA(At, 0, 0); STAGE(SA(1, 1), A, brow + HALF, nt - 1);
;     BAR; WAIT_L(0); MMA(0, 0, At, B0); BAR;
;     LDB(B1, 0, 1); BAR; WAIT_L(0); MMA(0, 1, At, B1); BAR;
;     LDA(At, 0, 1); WAIT_V(4); BAR; WAIT_L(0); MMA(1, 0, At, B0); MMA(1, 1, At, B1); BAR; }
;   { LDB(B0, 1, 0); LDA(At, 1, 0); WAIT_V(2); BAR; WAIT_L(0); MMA(0, 0, At, B0); BAR;
;     LDB(B1, 1, 1); WAIT_V(0); BAR; WAIT_L(0); MMA(0, 1, At, B1); BAR;
;     LDA(At, 1, 1); BAR; WAIT_L(0); MMA(1, 0, At, B0); MMA(1, 1, At, B1); BAR; }
;   if (wr == 0) BAR;
;   if (has_next) {
	s_nop 0
	ds_read_b128 v[4:7], v145
	ds_read_b128 v[12:15], v145 offset:1024
	ds_read_b128 v[146:149], v145 offset:2048
	ds_read_b128 v[202:205], v145 offset:3072
	ds_read_b128 v[20:23], v143 offset:32768
	ds_read_b128 v[28:31], v143 offset:33792
	ds_read_b128 v[38:41], v142 offset:32768
	ds_read_b128 v[46:49], v142 offset:33792
	ds_read_b128 v[206:209], v141 offset:32768
	ds_read_b128 v[210:213], v141 offset:33792
	ds_read_b128 v[214:217], v140 offset:32768
	ds_read_b128 v[234:237], v140 offset:33792
	s_waitcnt vmcnt(2)
	s_barrier
	s_waitcnt lgkmcnt(0)
	s_waitcnt lgkmcnt(7)
	v_mfma_f32_16x16x32_bf16 v[66:69], v[20:23], v[4:7], v[126:129]
	s_waitcnt lgkmcnt(6)
	v_mfma_f32_16x16x32_bf16 v[126:129], v[28:31], v[12:15], v[66:69]
	v_mfma_f32_16x16x32_bf16 v[66:69], v[20:23], v[146:149], v[122:125]
	v_mfma_f32_16x16x32_bf16 v[118:121], v[28:31], v[202:205], v[66:69]
	s_waitcnt lgkmcnt(5)
	v_mfma_f32_16x16x32_bf16 v[66:69], v[38:41], v[4:7], v[150:153]
	s_waitcnt lgkmcnt(4)
	v_mfma_f32_16x16x32_bf16 v[110:113], v[46:49], v[12:15], v[66:69]
	v_mfma_f32_16x16x32_bf16 v[66:69], v[38:41], v[146:149], v[114:117]
	v_mfma_f32_16x16x32_bf16 v[98:101], v[46:49], v[202:205], v[66:69]
	s_waitcnt lgkmcnt(3)
	v_mfma_f32_16x16x32_bf16 v[66:69], v[206:209], v[4:7], v[222:225]
	s_waitcnt lgkmcnt(2)
	v_mfma_f32_16x16x32_bf16 v[94:97], v[210:213], v[12:15], v[66:69]
	v_mfma_f32_16x16x32_bf16 v[66:69], v[206:209], v[146:149], v[106:109]
	v_mfma_f32_16x16x32_bf16 v[82:85], v[210:213], v[202:205], v[66:69]
	s_waitcnt lgkmcnt(1)
	v_mfma_f32_16x16x32_bf16 v[66:69], v[214:217], v[4:7], v[102:105]
	s_waitcnt lgkmcnt(0)
	v_mfma_f32_16x16x32_bf16 v[78:81], v[234:237], v[12:15], v[66:69]
	v_mfma_f32_16x16x32_bf16 v[66:69], v[214:217], v[146:149], v[226:229]
	v_mfma_f32_16x16x32_bf16 v[66:69], v[234:237], v[202:205], v[66:69]
	s_barrier
	ds_read_b128 v[150:153], v144
	ds_read_b128 v[222:225], v144 offset:1024
	ds_read_b128 v[226:229], v144 offset:2048
	ds_read_b128 v[238:241], v144 offset:3072
	s_waitcnt vmcnt(0)
	s_barrier
	s_waitcnt lgkmcnt(0)
	s_waitcnt lgkmcnt(3)
	v_mfma_f32_16x16x32_bf16 v[102:105], v[20:23], v[150:153], v[230:233]
	s_waitcnt lgkmcnt(1)
	v_mfma_f32_16x16x32_bf16 v[20:23], v[20:23], v[226:229], v[90:93]
	s_waitcnt lgkmcnt(0)
	v_mfma_f32_16x16x32_bf16 v[114:117], v[28:31], v[238:241], v[20:23]
	v_mfma_f32_16x16x32_bf16 v[20:23], v[38:41], v[150:153], v[86:89]
	v_mfma_f32_16x16x32_bf16 v[106:109], v[46:49], v[222:225], v[20:23]
	v_mfma_f32_16x16x32_bf16 v[20:23], v[38:41], v[226:229], v[190:193]
	v_mfma_f32_16x16x32_bf16 v[122:125], v[28:31], v[222:225], v[102:105]
	v_mfma_f32_16x16x32_bf16 v[102:105], v[46:49], v[238:241], v[20:23]
	v_mfma_f32_16x16x32_bf16 v[20:23], v[206:209], v[150:153], v[194:197]
	v_mfma_f32_16x16x32_bf16 v[90:93], v[210:213], v[222:225], v[20:23]
	v_mfma_f32_16x16x32_bf16 v[20:23], v[206:209], v[226:229], v[74:77]
	v_mfma_f32_16x16x32_bf16 v[86:89], v[210:213], v[238:241], v[20:23]
	v_mfma_f32_16x16x32_bf16 v[20:23], v[214:217], v[150:153], v[70:73]
	v_mfma_f32_16x16x32_bf16 v[74:77], v[234:237], v[222:225], v[20:23]
	v_mfma_f32_16x16x32_bf16 v[20:23], v[214:217], v[226:229], v[198:201]
	v_mfma_f32_16x16x32_bf16 v[70:73], v[234:237], v[238:241], v[20:23]
	s_barrier
	ds_read_b128 v[190:193], v143 offset:49152
	ds_read_b128 v[194:197], v143 offset:50176
	ds_read_b128 v[198:201], v142 offset:49152
	ds_read_b128 v[142:145], v142 offset:50176
	ds_read_b128 v[206:209], v141 offset:49152
	ds_read_b128 v[210:213], v141 offset:50176
	ds_read_b128 v[214:217], v140 offset:49152
	ds_read_b128 v[230:233], v140 offset:50176
	s_barrier
	s_waitcnt lgkmcnt(0)
	s_waitcnt lgkmcnt(7)
	v_mfma_f32_16x16x32_bf16 v[20:23], v[190:193], v[4:7], v[62:65]
	s_waitcnt lgkmcnt(6)
	v_mfma_f32_16x16x32_bf16 v[62:65], v[194:197], v[12:15], v[20:23]
	v_mfma_f32_16x16x32_bf16 v[20:23], v[190:193], v[146:149], v[58:61]
	v_mfma_f32_16x16x32_bf16 v[58:61], v[194:197], v[202:205], v[20:23]
	s_waitcnt lgkmcnt(5)
	v_mfma_f32_16x16x32_bf16 v[20:23], v[198:201], v[4:7], v[54:57]
	s_waitcnt lgkmcnt(4)
	v_mfma_f32_16x16x32_bf16 v[46:49], v[142:145], v[12:15], v[20:23]
	v_mfma_f32_16x16x32_bf16 v[20:23], v[198:201], v[146:149], v[50:53]
	v_mfma_f32_16x16x32_bf16 v[38:41], v[142:145], v[202:205], v[20:23]
	s_waitcnt lgkmcnt(3)
	v_mfma_f32_16x16x32_bf16 v[20:23], v[206:209], v[4:7], v[218:221]
	s_waitcnt lgkmcnt(1)
	v_mfma_f32_16x16x32_bf16 v[4:7], v[214:217], v[4:7], v[154:157]
	v_mfma_f32_16x16x32_bf16 v[28:31], v[210:213], v[12:15], v[20:23]
	v_mfma_f32_16x16x32_bf16 v[20:23], v[206:209], v[146:149], v[42:45]
	s_waitcnt lgkmcnt(0)
	v_mfma_f32_16x16x32_bf16 v[12:15], v[230:233], v[12:15], v[4:7]
	v_mfma_f32_16x16x32_bf16 v[4:7], v[214:217], v[146:149], v[34:37]
	v_mfma_f32_16x16x32_bf16 v[20:23], v[210:213], v[202:205], v[20:23]
	v_mfma_f32_16x16x32_bf16 v[4:7], v[230:233], v[202:205], v[4:7]
	v_mfma_f32_16x16x32_bf16 v[34:37], v[190:193], v[150:153], v[158:161]
	v_mfma_f32_16x16x32_bf16 v[24:27], v[190:193], v[226:229], v[24:27]
	v_mfma_f32_16x16x32_bf16 v[16:19], v[198:201], v[226:229], v[16:19]
	v_mfma_f32_16x16x32_bf16 v[54:57], v[194:197], v[222:225], v[34:37]
	v_mfma_f32_16x16x32_bf16 v[50:53], v[194:197], v[238:241], v[24:27]
	v_mfma_f32_16x16x32_bf16 v[24:27], v[198:201], v[150:153], v[166:169]
	v_mfma_f32_16x16x32_bf16 v[34:37], v[142:145], v[238:241], v[16:19]
	v_mfma_f32_16x16x32_bf16 v[16:19], v[206:209], v[150:153], v[170:173]
	v_mfma_f32_16x16x32_bf16 v[8:11], v[206:209], v[226:229], v[8:11]
	v_mfma_f32_16x16x32_bf16 v[42:45], v[142:145], v[222:225], v[24:27]
	v_mfma_f32_16x16x32_bf16 v[24:27], v[210:213], v[222:225], v[16:19]
	v_mfma_f32_16x16x32_bf16 v[16:19], v[210:213], v[238:241], v[8:11]
	v_mfma_f32_16x16x32_bf16 v[8:11], v[214:217], v[150:153], v[186:189]
	v_mfma_f32_16x16x32_bf16 v[0:3], v[214:217], v[226:229], v[0:3]
	v_mfma_f32_16x16x32_bf16 v[8:11], v[230:233], v[222:225], v[8:11]
	v_mfma_f32_16x16x32_bf16 v[0:3], v[230:233], v[238:241], v[0:3]
	v_cmp_gt_u32_e32 vcc, s59, v133
	s_barrier
	s_and_saveexec_b64 s[4:5], vcc
	s_cbranch_execz .LBB0_1370
	s_barrier

; #define STAGE(P, BASE, br, kt) do { int _so = ((br) * K + (kt) * BK) * 2; \
;     __builtin_amdgcn_raw_ptr_buffer_load_lds(rs_##BASE, (__attribute__((address_space(3))) void*)((char*)(P) + tx * 16), 16, voff0, _so, 0, 0); \
;     __builtin_amdgcn_raw_ptr_buffer_load_lds(rs_##BASE, (__attribute__((address_space(3))) void*)((char*)(P) + tx * 16 + 8192), 16, voff1, _so, 0, 0); } while (0)
; #define LDA(dst, b, h) _Pragma("unroll") for (int m = 0; m < 4; ++m) _Pragma("unroll") for (int k = 0; k < 2; ++k) \
;     dst[m][k] = *reinterpret_cast<const bf16x8*>((char*)SA(b, h) + lds_byte(wr * 64 + m * 16 + fr, k * 32 + fq * 8))
; #define LDB(dst, b, h) _Pragma("unroll") for (int n = 0; n < 2; ++n) _Pragma("unroll") for (int k = 0; k < 2; ++k) \
;     dst[n][k] = *reinterpret_cast<const bf16x8*>((char*)SB(b, h) + lds_byte(wc * 32 + n * 16 + fr, k * 32 + fq * 8))
; #define MMA(ai, bj, At, Bt_) do { __builtin_amdgcn_s_setprio(1); \
;     _Pragma("unroll") for (int m = 0; m < 4; ++m) _Pragma("unroll") for (int n = 0; n < 2; ++n) _Pragma("unroll") for (int k = 0; k < 2; ++k) \
;       acc[ai][bj][m][n] = __builtin_amdgcn_mfma_f32_16x16x32_bf16(At[m][k], Bt_[n][k], acc[ai][bj][m][n], 0, 0, 0); \
;     __builtin_amdgcn_s_setprio(0); } while (0)
; #define WAIT_V(n) asm volatile("s_waitcnt vmcnt(" #n ")" ::: "memory")
; #define WAIT_L(n) asm volatile("s_waitcnt lgkmcnt(" #n ")" ::: "memory")
; template <class Epi> ...
;     ...
;   for (int t = 0; t < nt - 2; t += 2) {
;     LDB(B0, 0, 0); SCHED; LDA(At, 0, 0); STAGE(SA(1, 1), A, brow + HALF, t + 1);
;     WAIT_L(8); BAR; WAIT_L(0); MMA(0, 0, At, B0); BAR; SCHED;
;     LDB(B1, 0, 1); STAGE(SB(0, 0), Bt, bcol, t + 2);
;     BAR; WAIT_L(0); MMA(0, 1, At, B1); BAR;
;     LDA(At, 0, 1); STAGE(SA(0, 0), A, brow, t + 2);
;     BAR; WAIT_L(0); MMA(1, 0, At, B0); BAR; SCHED;
;     STAGE(SB(0, 1), Bt, bcol + HALF, t + 2);
;     WAIT_V(6); BAR; MMA(1, 1, At, B1); BAR;
;     LDB(B0, 1, 0); SCHED; LDA(At, 1, 0); STAGE(SA(0, 1), A, brow + HALF, t + 2);
;     WAIT_L(8); BAR; WAIT_L(0); MMA(0, 0, At, B0); BAR; SCHED;
;     LDB(B1, 1, 1); STAGE(SB(1, 0), Bt, bcol, t + 3);
;     BAR; WAIT_L(0); MMA(0, 1, At, B1); BAR;
;     LDA(At, 1, 1); STAGE(SA(1, 0), A, brow, t + 3);
;     BAR; WAIT_L(0); MMA(1, 0, At, B0); BAR; SCHED;
;     STAGE(SB(1, 1), Bt, bcol + HALF, t + 3);
;     WAIT_V(6); BAR; MMA(1, 1, At, B1); BAR;
;   }
.Lpk2:
	ds_read_b128 v[156:159], v153
	ds_read_b128 v[166:169], v153 offset:1024
	ds_read_b128 v[170:173], v153 offset:2048
	ds_read_b128 v[186:189], v153 offset:3072
	s_add_i32 s28, s24, s27
	v_readfirstlane_b32 s30, v155
	s_add_i32 s29, s28, 0x40080
	s_mov_b32 m0, s30
	v_readfirstlane_b32 s30, v154
	ds_read_b128 v[190:193], v133
	ds_read_b128 v[194:197], v133 offset:1024
	ds_read_b128 v[198:201], v132
	ds_read_b128 v[202:205], v132 offset:1024
	ds_read_b128 v[206:209], v131
	ds_read_b128 v[210:213], v131 offset:1024
	ds_read_b128 v[214:217], v130
	ds_read_b128 v[218:221], v130 offset:1024
	buffer_load_dwordx4 v134, s[4:7], s29 offen lds
	s_mov_b32 m0, s30
	s_nop 0
	buffer_load_dwordx4 v135, s[4:7], s29 offen lds
	s_waitcnt lgkmcnt(8)
	s_barrier
	s_waitcnt lgkmcnt(0)
	s_waitcnt lgkmcnt(7)
	v_mfma_f32_16x16x32_bf16 v[126:129], v[190:193], v[156:159], 0
	v_mfma_f32_16x16x32_bf16 v[122:125], v[190:193], v[170:173], 0
	s_waitcnt lgkmcnt(5)
	v_mfma_f32_16x16x32_bf16 v[118:121], v[198:201], v[156:159], 0
	v_mfma_f32_16x16x32_bf16 v[114:117], v[198:201], v[170:173], 0
	s_waitcnt lgkmcnt(3)
	v_mfma_f32_16x16x32_bf16 v[110:113], v[206:209], v[156:159], 0
	v_mfma_f32_16x16x32_bf16 v[106:109], v[206:209], v[170:173], 0
	s_waitcnt lgkmcnt(1)
	v_mfma_f32_16x16x32_bf16 v[102:105], v[214:217], v[156:159], 0
	v_mfma_f32_16x16x32_bf16 v[98:101], v[214:217], v[170:173], 0
	v_mfma_f32_16x16x32_bf16 v[126:129], v[194:197], v[166:169], v[126:129]
	v_mfma_f32_16x16x32_bf16 v[122:125], v[194:197], v[186:189], v[122:125]
	v_mfma_f32_16x16x32_bf16 v[118:121], v[202:205], v[166:169], v[118:121]
	v_mfma_f32_16x16x32_bf16 v[114:117], v[202:205], v[186:189], v[114:117]
	v_mfma_f32_16x16x32_bf16 v[110:113], v[210:213], v[166:169], v[110:113]
	v_mfma_f32_16x16x32_bf16 v[106:109], v[210:213], v[186:189], v[106:109]
	s_waitcnt lgkmcnt(0)
	v_mfma_f32_16x16x32_bf16 v[102:105], v[218:221], v[166:169], v[102:105]
	v_mfma_f32_16x16x32_bf16 v[98:101], v[218:221], v[186:189], v[98:101]
	s_barrier
	s_add_i32 s29, s25, s27
	v_readfirstlane_b32 s31, v138
	s_add_i32 s30, s29, 0x100
	s_mov_b32 m0, s31
	v_readfirstlane_b32 s31, v139
	ds_read_b128 v[222:225], v149
	ds_read_b128 v[226:229], v149 offset:1024
	ds_read_b128 v[230:233], v149 offset:2048
	ds_read_b128 v[234:237], v149 offset:3072
	buffer_load_dwordx4 v134, s[76:79], s30 offen lds
	s_mov_b32 m0, s31
	s_nop 0
	buffer_load_dwordx4 v135, s[76:79], s30 offen lds
	s_barrier
	s_waitcnt lgkmcnt(0)
	s_waitcnt lgkmcnt(3)
	v_mfma_f32_16x16x32_bf16 v[94:97], v[190:193], v[222:225], 0
	s_waitcnt lgkmcnt(1)
	v_mfma_f32_16x16x32_bf16 v[90:93], v[190:193], v[230:233], 0
	v_mfma_f32_16x16x32_bf16 v[86:89], v[198:201], v[222:225], 0
	v_mfma_f32_16x16x32_bf16 v[82:85], v[198:201], v[230:233], 0
	v_mfma_f32_16x16x32_bf16 v[78:81], v[206:209], v[222:225], 0
	v_mfma_f32_16x16x32_bf16 v[74:77], v[206:209], v[230:233], 0
	v_mfma_f32_16x16x32_bf16 v[70:73], v[214:217], v[222:225], 0
	v_mfma_f32_16x16x32_bf16 v[66:69], v[214:217], v[230:233], 0
	v_mfma_f32_16x16x32_bf16 v[94:97], v[194:197], v[226:229], v[94:97]
	s_waitcnt lgkmcnt(0)
	v_mfma_f32_16x16x32_bf16 v[90:93], v[194:197], v[234:237], v[90:93]
	v_mfma_f32_16x16x32_bf16 v[86:89], v[202:205], v[226:229], v[86:89]
	v_mfma_f32_16x16x32_bf16 v[82:85], v[202:205], v[234:237], v[82:85]
	v_mfma_f32_16x16x32_bf16 v[78:81], v[210:213], v[226:229], v[78:81]
	v_mfma_f32_16x16x32_bf16 v[74:77], v[210:213], v[234:237], v[74:77]
	v_mfma_f32_16x16x32_bf16 v[70:73], v[218:221], v[226:229], v[70:73]
	v_mfma_f32_16x16x32_bf16 v[66:69], v[218:221], v[234:237], v[66:69]
	v_readfirstlane_b32 s31, v140
	s_add_i32 s30, s28, 0x100
	s_mov_b32 m0, s31
	v_readfirstlane_b32 s31, v141
	s_barrier
	ds_read_b128 v[190:193], v133 offset:16384
	ds_read_b128 v[194:197], v133 offset:17408
	ds_read_b128 v[198:201], v132 offset:16384
	ds_read_b128 v[202:205], v132 offset:17408
	ds_read_b128 v[206:209], v131 offset:16384
	ds_read_b128 v[210:213], v131 offset:17408
	ds_read_b128 v[214:217], v130 offset:16384
	ds_read_b128 v[218:221], v130 offset:17408
	buffer_load_dwordx4 v134, s[4:7], s30 offen lds
	s_mov_b32 m0, s31
	s_nop 0
	buffer_load_dwordx4 v135, s[4:7], s30 offen lds
	s_barrier
	s_waitcnt lgkmcnt(0)
	s_waitcnt lgkmcnt(7)
	v_mfma_f32_16x16x32_bf16 v[62:65], v[190:193], v[156:159], 0
	v_mfma_f32_16x16x32_bf16 v[58:61], v[190:193], v[170:173], 0
	s_waitcnt lgkmcnt(5)
	v_mfma_f32_16x16x32_bf16 v[54:57], v[198:201], v[156:159], 0
	v_mfma_f32_16x16x32_bf16 v[50:53], v[198:201], v[170:173], 0
	s_waitcnt lgkmcnt(3)
	v_mfma_f32_16x16x32_bf16 v[46:49], v[206:209], v[156:159], 0
	v_mfma_f32_16x16x32_bf16 v[42:45], v[206:209], v[170:173], 0
	s_waitcnt lgkmcnt(1)
	v_mfma_f32_16x16x32_bf16 v[38:41], v[214:217], v[156:159], 0
	v_mfma_f32_16x16x32_bf16 v[34:37], v[214:217], v[170:173], 0
	v_mfma_f32_16x16x32_bf16 v[62:65], v[194:197], v[166:169], v[62:65]
	v_mfma_f32_16x16x32_bf16 v[58:61], v[194:197], v[186:189], v[58:61]
	v_mfma_f32_16x16x32_bf16 v[54:57], v[202:205], v[166:169], v[54:57]
	v_mfma_f32_16x16x32_bf16 v[50:53], v[202:205], v[186:189], v[50:53]
	v_mfma_f32_16x16x32_bf16 v[46:49], v[210:213], v[166:169], v[46:49]
	v_mfma_f32_16x16x32_bf16 v[42:45], v[210:213], v[186:189], v[42:45]
	s_waitcnt lgkmcnt(0)
	v_mfma_f32_16x16x32_bf16 v[38:41], v[218:221], v[166:169], v[38:41]
	v_mfma_f32_16x16x32_bf16 v[34:37], v[218:221], v[186:189], v[34:37]
	s_barrier
	v_readfirstlane_b32 s31, v142
	s_add_i32 s30, s29, 0x40100
	s_mov_b32 m0, s31
	v_readfirstlane_b32 s31, v143
	buffer_load_dwordx4 v134, s[76:79], s30 offen lds
	s_mov_b32 m0, s31
	s_nop 0
	buffer_load_dwordx4 v135, s[76:79], s30 offen lds
	s_waitcnt vmcnt(6)
	s_barrier
; #define STAGE(P, BASE, br, kt) do { int _so = ((br) * K + (kt) * BK) * 2; \
;     __builtin_amdgcn_raw_ptr_buffer_load_lds(rs_##BASE, (__attribute__((address_space(3))) void*)((char*)(P) + tx * 16), 16, voff0, _so, 0, 0); \
;     __builtin_amdgcn_raw_ptr_buffer_load_lds(rs_##BASE, (__attribute__((address_space(3))) void*)((char*)(P) + tx * 16 + 8192), 16, voff1, _so, 0, 0); } while (0)
; #define LDA(dst, b, h) _Pragma("unroll") for (int m = 0; m < 4; ++m) _Pragma("unroll") for (int k = 0; k < 2; ++k) \
;     dst[m][k] = *reinterpret_cast<const bf16x8*>((char*)SA(b, h) + lds_byte(wr * 64 + m * 16 + fr, k * 32 + fq * 8))
; #define LDB(dst, b, h) _Pragma("unroll") for (int n = 0; n < 2; ++n) _Pragma("unroll") for (int k = 0; k < 2; ++k) \
;     dst[n][k] = *reinterpret_cast<const bf16x8*>((char*)SB(b, h) + lds_byte(wc * 32 + n * 16 + fr, k * 32 + fq * 8))
; #define MMA(ai, bj, At, Bt_) do { __builtin_amdgcn_s_setprio(1); \
;     _Pragma("unroll") for (int m = 0; m < 4; ++m) _Pragma("unroll") for (int n = 0; n < 2; ++n) _Pragma("unroll") for (int k = 0; k < 2; ++k) \
;       acc[ai][bj][m][n] = __builtin_amdgcn_mfma_f32_16x16x32_bf16(At[m][k], Bt_[n][k], acc[ai][bj][m][n], 0, 0, 0); \
;     __builtin_amdgcn_s_setprio(0); } while (0)
; #define WAIT_V(n) asm volatile("s_waitcnt vmcnt(" #n ")" ::: "memory")
; #define WAIT_L(n) asm volatile("s_waitcnt lgkmcnt(" #n ")" ::: "memory")
; template <class Epi> ...
;     ...
;   for (int t = 0; t < nt - 2; t += 2) {
;     LDB(B0, 0, 0); SCHED; LDA(At, 0, 0); STAGE(SA(1, 1), A, brow + HALF, t + 1);
;     WAIT_L(8); BAR; WAIT_L(0); MMA(0, 0, At, B0); BAR; SCHED;
;     LDB(B1, 0, 1); STAGE(SB(0, 0), Bt, bcol, t + 2);
;     BAR; WAIT_L(0); MMA(0, 1, At, B1); BAR;
;     LDA(At, 0, 1); STAGE(SA(0, 0), A, brow, t + 2);
;     BAR; WAIT_L(0); MMA(1, 0, At, B0); BAR; SCHED;
;     STAGE(SB(0, 1), Bt, bcol + HALF, t + 2);
;     WAIT_V(6); BAR; MMA(1, 1, At, B1); BAR;
;     LDB(B0, 1, 0); SCHED; LDA(At, 1, 0); STAGE(SA(0, 1), A, brow + HALF, t + 2);
;     WAIT_L(8); BAR; WAIT_L(0); MMA(0, 0, At, B0); BAR; SCHED;
;     LDB(B1, 1, 1); STAGE(SB(1, 0), Bt, bcol, t + 3);
;     BAR; WAIT_L(0); MMA(0, 1, At, B1); BAR;
;     LDA(At, 1, 1); STAGE(SA(1, 0), A, brow, t + 3);
;     BAR; WAIT_L(0); MMA(1, 0, At, B0); BAR; SCHED;
;     STAGE(SB(1, 1), Bt, bcol + HALF, t + 3);
;     WAIT_V(6); BAR; MMA(1, 1, At, B1); BAR;
;   }
	v_mfma_f32_16x16x32_bf16 v[28:31], v[190:193], v[222:225], 0
	v_mfma_f32_16x16x32_bf16 v[24:27], v[190:193], v[230:233], 0
	v_mfma_f32_16x16x32_bf16 v[20:23], v[198:201], v[222:225], 0
	v_mfma_f32_16x16x32_bf16 v[16:19], v[198:201], v[230:233], 0
	v_mfma_f32_16x16x32_bf16 v[12:15], v[206:209], v[222:225], 0
	v_mfma_f32_16x16x32_bf16 v[8:11], v[206:209], v[230:233], 0
	v_mfma_f32_16x16x32_bf16 v[4:7], v[214:217], v[222:225], 0
	v_mfma_f32_16x16x32_bf16 v[0:3], v[214:217], v[230:233], 0
	v_mfma_f32_16x16x32_bf16 v[28:31], v[194:197], v[226:229], v[28:31]
	v_mfma_f32_16x16x32_bf16 v[24:27], v[194:197], v[234:237], v[24:27]
	v_mfma_f32_16x16x32_bf16 v[20:23], v[202:205], v[226:229], v[20:23]
	v_mfma_f32_16x16x32_bf16 v[16:19], v[202:205], v[234:237], v[16:19]
	v_mfma_f32_16x16x32_bf16 v[12:15], v[210:213], v[226:229], v[12:15]
	v_mfma_f32_16x16x32_bf16 v[8:11], v[210:213], v[234:237], v[8:11]
	v_mfma_f32_16x16x32_bf16 v[4:7], v[218:221], v[226:229], v[4:7]
	v_mfma_f32_16x16x32_bf16 v[0:3], v[218:221], v[234:237], v[0:3]
	s_barrier
	ds_read_b128 v[156:159], v137
	ds_read_b128 v[166:169], v137 offset:1024
	ds_read_b128 v[170:173], v137 offset:2048
	ds_read_b128 v[186:189], v137 offset:3072
	v_readfirstlane_b32 s31, v144
	s_add_i32 s30, s28, 0x40100
	s_mov_b32 m0, s31
	v_readfirstlane_b32 s31, v145
	ds_read_b128 v[190:193], v133 offset:32768
	ds_read_b128 v[194:197], v133 offset:33792
	ds_read_b128 v[198:201], v132 offset:32768
	ds_read_b128 v[202:205], v132 offset:33792
	ds_read_b128 v[206:209], v131 offset:32768
	ds_read_b128 v[210:213], v131 offset:33792
	ds_read_b128 v[214:217], v130 offset:32768
	ds_read_b128 v[218:221], v130 offset:33792
	buffer_load_dwordx4 v134, s[4:7], s30 offen lds
	s_mov_b32 m0, s31
	s_nop 0
	buffer_load_dwordx4 v135, s[4:7], s30 offen lds
	s_waitcnt lgkmcnt(8)
	s_barrier
	s_waitcnt lgkmcnt(0)
	s_waitcnt lgkmcnt(7)
	v_mfma_f32_16x16x32_bf16 v[126:129], v[190:193], v[156:159], v[126:129]
	v_mfma_f32_16x16x32_bf16 v[122:125], v[190:193], v[170:173], v[122:125]
	s_waitcnt lgkmcnt(5)
	v_mfma_f32_16x16x32_bf16 v[118:121], v[198:201], v[156:159], v[118:121]
	v_mfma_f32_16x16x32_bf16 v[114:117], v[198:201], v[170:173], v[114:117]
	s_waitcnt lgkmcnt(3)
	v_mfma_f32_16x16x32_bf16 v[110:113], v[206:209], v[156:159], v[110:113]
	v_mfma_f32_16x16x32_bf16 v[106:109], v[206:209], v[170:173], v[106:109]
	s_waitcnt lgkmcnt(1)
	v_mfma_f32_16x16x32_bf16 v[102:105], v[214:217], v[156:159], v[102:105]
	v_mfma_f32_16x16x32_bf16 v[98:101], v[214:217], v[170:173], v[98:101]
	v_mfma_f32_16x16x32_bf16 v[126:129], v[194:197], v[166:169], v[126:129]
	v_mfma_f32_16x16x32_bf16 v[122:125], v[194:197], v[186:189], v[122:125]
	v_mfma_f32_16x16x32_bf16 v[118:121], v[202:205], v[166:169], v[118:121]
	v_mfma_f32_16x16x32_bf16 v[114:117], v[202:205], v[186:189], v[114:117]
	v_mfma_f32_16x16x32_bf16 v[110:113], v[210:213], v[166:169], v[110:113]
	v_mfma_f32_16x16x32_bf16 v[106:109], v[210:213], v[186:189], v[106:109]
	s_waitcnt lgkmcnt(0)
	v_mfma_f32_16x16x32_bf16 v[102:105], v[218:221], v[166:169], v[102:105]
	v_mfma_f32_16x16x32_bf16 v[98:101], v[218:221], v[186:189], v[98:101]
	s_barrier
	v_readfirstlane_b32 s31, v146
	s_add_i32 s30, s29, 0x180
	s_mov_b32 m0, s31
	v_readfirstlane_b32 s31, v147
	ds_read_b128 v[222:225], v136
	ds_read_b128 v[226:229], v136 offset:1024
	ds_read_b128 v[230:233], v136 offset:2048
	ds_read_b128 v[234:237], v136 offset:3072
	buffer_load_dwordx4 v134, s[76:79], s30 offen lds
	s_mov_b32 m0, s31
	s_nop 0
	buffer_load_dwordx4 v135, s[76:79], s30 offen lds
	s_barrier
	s_waitcnt lgkmcnt(0)
	s_waitcnt lgkmcnt(3)
	v_mfma_f32_16x16x32_bf16 v[94:97], v[190:193], v[222:225], v[94:97]
	s_waitcnt lgkmcnt(1)
	v_mfma_f32_16x16x32_bf16 v[90:93], v[190:193], v[230:233], v[90:93]
	v_mfma_f32_16x16x32_bf16 v[86:89], v[198:201], v[222:225], v[86:89]
	v_mfma_f32_16x16x32_bf16 v[82:85], v[198:201], v[230:233], v[82:85]
	v_mfma_f32_16x16x32_bf16 v[78:81], v[206:209], v[222:225], v[78:81]
	v_mfma_f32_16x16x32_bf16 v[74:77], v[206:209], v[230:233], v[74:77]
	v_mfma_f32_16x16x32_bf16 v[70:73], v[214:217], v[222:225], v[70:73]
	v_mfma_f32_16x16x32_bf16 v[66:69], v[214:217], v[230:233], v[66:69]
	v_mfma_f32_16x16x32_bf16 v[94:97], v[194:197], v[226:229], v[94:97]
	s_waitcnt lgkmcnt(0)
	v_mfma_f32_16x16x32_bf16 v[90:93], v[194:197], v[234:237], v[90:93]
	v_mfma_f32_16x16x32_bf16 v[86:89], v[202:205], v[226:229], v[86:89]
	v_mfma_f32_16x16x32_bf16 v[82:85], v[202:205], v[234:237], v[82:85]
	v_mfma_f32_16x16x32_bf16 v[78:81], v[210:213], v[226:229], v[78:81]
	v_mfma_f32_16x16x32_bf16 v[74:77], v[210:213], v[234:237], v[74:77]
	v_mfma_f32_16x16x32_bf16 v[70:73], v[218:221], v[226:229], v[70:73]
	v_mfma_f32_16x16x32_bf16 v[66:69], v[218:221], v[234:237], v[66:69]
	v_readfirstlane_b32 s30, v148
	s_addk_i32 s28, 0x180
	s_mov_b32 m0, s30
	v_readfirstlane_b32 s30, v150
	s_barrier
	ds_read_b128 v[190:193], v133 offset:49152
	ds_read_b128 v[194:197], v133 offset:50176
	ds_read_b128 v[198:201], v132 offset:49152
	ds_read_b128 v[202:205], v132 offset:50176
	ds_read_b128 v[206:209], v131 offset:49152
	ds_read_b128 v[210:213], v131 offset:50176
	ds_read_b128 v[214:217], v130 offset:49152
	ds_read_b128 v[218:221], v130 offset:50176
	buffer_load_dwordx4 v134, s[4:7], s28 offen lds
	s_mov_b32 m0, s30
	s_nop 0
	buffer_load_dwordx4 v135, s[4:7], s28 offen lds
	s_barrier
; #define STAGE(P, BASE, br, kt) do { int _so = ((br) * K + (kt) * BK) * 2; \
;     __builtin_amdgcn_raw_ptr_buffer_load_lds(rs_##BASE, (__attribute__((address_space(3))) void*)((char*)(P) + tx * 16), 16, voff0, _so, 0, 0); \
;     __builtin_amdgcn_raw_ptr_buffer_load_lds(rs_##BASE, (__attribute__((address_space(3))) void*)((char*)(P) + tx * 16 + 8192), 16, voff1, _so, 0, 0); } while (0)
; #define LDA(dst, b, h) _Pragma("unroll") for (int m = 0; m < 4; ++m) _Pragma("unroll") for (int k = 0; k < 2; ++k) \
;     dst[m][k] = *reinterpret_cast<const bf16x8*>((char*)SA(b, h) + lds_byte(wr * 64 + m * 16 + fr, k * 32 + fq * 8))
; #define LDB(dst, b, h) _Pragma("unroll") for (int n = 0; n < 2; ++n) _Pragma("unroll") for (int k = 0; k < 2; ++k) \
;     dst[n][k] = *reinterpret_cast<const bf16x8*>((char*)SB(b, h) + lds_byte(wc * 32 + n * 16 + fr, k * 32 + fq * 8))
; #define MMA(ai, bj, At, Bt_) do { __builtin_amdgcn_s_setprio(1); \
;     _Pragma("unroll") for (int m = 0; m < 4; ++m) _Pragma("unroll") for (int n = 0; n < 2; ++n) _Pragma("unroll") for (int k = 0; k < 2; ++k) \
;       acc[ai][bj][m][n] = __builtin_amdgcn_mfma_f32_16x16x32_bf16(At[m][k], Bt_[n][k], acc[ai][bj][m][n], 0, 0, 0); \
;     __builtin_amdgcn_s_setprio(0); } while (0)
; #define WAIT_V(n) asm volatile("s_waitcnt vmcnt(" #n ")" ::: "memory")
; #define WAIT_L(n) asm volatile("s_waitcnt lgkmcnt(" #n ")" ::: "memory")
; template <class Epi> ...
;     ...
;   for (int t = 0; t < nt - 2; t += 2) {
;     LDB(B0, 0, 0); SCHED; LDA(At, 0, 0); STAGE(SA(1, 1), A, brow + HALF, t + 1);
;     WAIT_L(8); BAR; WAIT_L(0); MMA(0, 0, At, B0); BAR; SCHED;
;     LDB(B1, 0, 1); STAGE(SB(0, 0), Bt, bcol, t + 2);
;     BAR; WAIT_L(0); MMA(0, 1, At, B1); BAR;
;     LDA(At, 0, 1); STAGE(SA(0, 0), A, brow, t + 2);
;     BAR; WAIT_L(0); MMA(1, 0, At, B0); BAR; SCHED;
;     STAGE(SB(0, 1), Bt, bcol + HALF, t + 2);
;     WAIT_V(6); BAR; MMA(1, 1, At, B1); BAR;
;     LDB(B0, 1, 0); SCHED; LDA(At, 1, 0); STAGE(SA(0, 1), A, brow + HALF, t + 2);
;     WAIT_L(8); BAR; WAIT_L(0); MMA(0, 0, At, B0); BAR; SCHED;
;     LDB(B1, 1, 1); STAGE(SB(1, 0), Bt, bcol, t + 3);
;     BAR; WAIT_L(0); MMA(0, 1, At, B1); BAR;
;     LDA(At, 1, 1); STAGE(SA(1, 0), A, brow, t + 3);
;     BAR; WAIT_L(0); MMA(1, 0, At, B0); BAR; SCHED;
;     STAGE(SB(1, 1), Bt, bcol + HALF, t + 3);
;     WAIT_V(6); BAR; MMA(1, 1, At, B1); BAR;
;   }
	s_waitcnt lgkmcnt(0)
	s_waitcnt lgkmcnt(7)
	v_mfma_f32_16x16x32_bf16 v[62:65], v[190:193], v[156:159], v[62:65]
	v_mfma_f32_16x16x32_bf16 v[58:61], v[190:193], v[170:173], v[58:61]
	s_waitcnt lgkmcnt(5)
	v_mfma_f32_16x16x32_bf16 v[54:57], v[198:201], v[156:159], v[54:57]
	v_mfma_f32_16x16x32_bf16 v[50:53], v[198:201], v[170:173], v[50:53]
	s_waitcnt lgkmcnt(3)
	v_mfma_f32_16x16x32_bf16 v[46:49], v[206:209], v[156:159], v[46:49]
	v_mfma_f32_16x16x32_bf16 v[42:45], v[206:209], v[170:173], v[42:45]
	s_waitcnt lgkmcnt(1)
	v_mfma_f32_16x16x32_bf16 v[38:41], v[214:217], v[156:159], v[38:41]
	v_mfma_f32_16x16x32_bf16 v[34:37], v[214:217], v[170:173], v[34:37]
	v_mfma_f32_16x16x32_bf16 v[62:65], v[194:197], v[166:169], v[62:65]
	v_mfma_f32_16x16x32_bf16 v[58:61], v[194:197], v[186:189], v[58:61]
	v_mfma_f32_16x16x32_bf16 v[54:57], v[202:205], v[166:169], v[54:57]
	v_mfma_f32_16x16x32_bf16 v[50:53], v[202:205], v[186:189], v[50:53]
	v_mfma_f32_16x16x32_bf16 v[46:49], v[210:213], v[166:169], v[46:49]
	v_mfma_f32_16x16x32_bf16 v[42:45], v[210:213], v[186:189], v[42:45]
	s_waitcnt lgkmcnt(0)
	v_mfma_f32_16x16x32_bf16 v[38:41], v[218:221], v[166:169], v[38:41]
	v_mfma_f32_16x16x32_bf16 v[34:37], v[218:221], v[186:189], v[34:37]
	s_barrier
	v_readfirstlane_b32 s28, v151
	s_add_i32 s29, s29, 0x40180
	s_mov_b32 m0, s28
	v_readfirstlane_b32 s28, v152
	buffer_load_dwordx4 v134, s[76:79], s29 offen lds
	s_mov_b32 m0, s28
	s_nop 0
	buffer_load_dwordx4 v135, s[76:79], s29 offen lds
	s_waitcnt vmcnt(6)
	s_barrier
	v_mfma_f32_16x16x32_bf16 v[28:31], v[190:193], v[222:225], v[28:31]
	v_mfma_f32_16x16x32_bf16 v[24:27], v[190:193], v[230:233], v[24:27]
	v_mfma_f32_16x16x32_bf16 v[20:23], v[198:201], v[222:225], v[20:23]
	v_mfma_f32_16x16x32_bf16 v[16:19], v[198:201], v[230:233], v[16:19]
	v_mfma_f32_16x16x32_bf16 v[12:15], v[206:209], v[222:225], v[12:15]
	v_mfma_f32_16x16x32_bf16 v[8:11], v[206:209], v[230:233], v[8:11]
	v_mfma_f32_16x16x32_bf16 v[4:7], v[214:217], v[222:225], v[4:7]
	v_mfma_f32_16x16x32_bf16 v[0:3], v[214:217], v[230:233], v[0:3]
	v_mfma_f32_16x16x32_bf16 v[28:31], v[194:197], v[226:229], v[28:31]
	v_mfma_f32_16x16x32_bf16 v[24:27], v[194:197], v[234:237], v[24:27]
	v_mfma_f32_16x16x32_bf16 v[20:23], v[202:205], v[226:229], v[20:23]
	v_mfma_f32_16x16x32_bf16 v[16:19], v[202:205], v[234:237], v[16:19]
	v_mfma_f32_16x16x32_bf16 v[12:15], v[210:213], v[226:229], v[12:15]
	v_mfma_f32_16x16x32_bf16 v[8:11], v[210:213], v[234:237], v[8:11]
	v_mfma_f32_16x16x32_bf16 v[4:7], v[218:221], v[226:229], v[4:7]
	v_mfma_f32_16x16x32_bf16 v[0:3], v[218:221], v[234:237], v[0:3]
	s_add_i32 s26, s26, 2
	s_addk_i32 s27, 0x100
	s_cmp_lt_u32 s26, 12
	s_barrier
	s_cbranch_scc1 .LBB0_1657
	s_branch .Lpx2
.LBB0_1657:
	ds_read_b128 v[156:159], v153
	ds_read_b128 v[166:169], v153 offset:1024
	ds_read_b128 v[170:173], v153 offset:2048
	ds_read_b128 v[186:189], v153 offset:3072
	s_add_i32 s28, s24, s27
	v_readfirstlane_b32 s30, v155
	s_add_i32 s29, s28, 0x40080
	s_mov_b32 m0, s30
	v_readfirstlane_b32 s30, v154
	ds_read_b128 v[190:193], v133
	ds_read_b128 v[194:197], v133 offset:1024
	ds_read_b128 v[198:201], v132
	ds_read_b128 v[202:205], v132 offset:1024
	ds_read_b128 v[206:209], v131
	ds_read_b128 v[210:213], v131 offset:1024
	ds_read_b128 v[214:217], v130
	ds_read_b128 v[218:221], v130 offset:1024
	buffer_load_dwordx4 v134, s[4:7], s29 offen lds
	s_mov_b32 m0, s30
	s_nop 0
	buffer_load_dwordx4 v135, s[4:7], s29 offen lds
	s_waitcnt lgkmcnt(8)
	s_barrier
	s_waitcnt lgkmcnt(0)
	s_waitcnt lgkmcnt(7)
	v_mfma_f32_16x16x32_bf16 v[126:129], v[190:193], v[156:159], v[126:129]
	v_mfma_f32_16x16x32_bf16 v[122:125], v[190:193], v[170:173], v[122:125]
	s_waitcnt lgkmcnt(5)
	v_mfma_f32_16x16x32_bf16 v[118:121], v[198:201], v[156:159], v[118:121]
	v_mfma_f32_16x16x32_bf16 v[114:117], v[198:201], v[170:173], v[114:117]
	s_waitcnt lgkmcnt(3)
	v_mfma_f32_16x16x32_bf16 v[110:113], v[206:209], v[156:159], v[110:113]
	v_mfma_f32_16x16x32_bf16 v[106:109], v[206:209], v[170:173], v[106:109]
	s_waitcnt lgkmcnt(1)
	v_mfma_f32_16x16x32_bf16 v[102:105], v[214:217], v[156:159], v[102:105]
	v_mfma_f32_16x16x32_bf16 v[98:101], v[214:217], v[170:173], v[98:101]
	v_mfma_f32_16x16x32_bf16 v[126:129], v[194:197], v[166:169], v[126:129]
	v_mfma_f32_16x16x32_bf16 v[122:125], v[194:197], v[186:189], v[122:125]
	v_mfma_f32_16x16x32_bf16 v[118:121], v[202:205], v[166:169], v[118:121]
	v_mfma_f32_16x16x32_bf16 v[114:117], v[202:205], v[186:189], v[114:117]
	v_mfma_f32_16x16x32_bf16 v[110:113], v[210:213], v[166:169], v[110:113]
	v_mfma_f32_16x16x32_bf16 v[106:109], v[210:213], v[186:189], v[106:109]
	s_waitcnt lgkmcnt(0)
	v_mfma_f32_16x16x32_bf16 v[102:105], v[218:221], v[166:169], v[102:105]
	v_mfma_f32_16x16x32_bf16 v[98:101], v[218:221], v[186:189], v[98:101]
	s_barrier
	s_add_i32 s29, s25, s27
	v_readfirstlane_b32 s31, v138
	s_add_i32 s30, s29, 0x100
	s_mov_b32 m0, s31
	v_readfirstlane_b32 s31, v139
	ds_read_b128 v[222:225], v149
	ds_read_b128 v[226:229], v149 offset:1024
	ds_read_b128 v[230:233], v149 offset:2048
	ds_read_b128 v[234:237], v149 offset:3072
	buffer_load_dwordx4 v134, s[76:79], s30 offen lds
	s_mov_b32 m0, s31
	s_nop 0
	buffer_load_dwordx4 v135, s[76:79], s30 offen lds
	s_barrier
; #define STAGE(P, BASE, br, kt) do { int _so = ((br) * K + (kt) * BK) * 2; \
;     __builtin_amdgcn_raw_ptr_buffer_load_lds(rs_##BASE, (__attribute__((address_space(3))) void*)((char*)(P) + tx * 16), 16, voff0, _so, 0, 0); \
;     __builtin_amdgcn_raw_ptr_buffer_load_lds(rs_##BASE, (__attribute__((address_space(3))) void*)((char*)(P) + tx * 16 + 8192), 16, voff1, _so, 0, 0); } while (0)
; #define LDA(dst, b, h) _Pragma("unroll") for (int m = 0; m < 4; ++m) _Pragma("unroll") for (int k = 0; k < 2; ++k) \
;     dst[m][k] = *reinterpret_cast<const bf16x8*>((char*)SA(b, h) + lds_byte(wr * 64 + m * 16 + fr, k * 32 + fq * 8))
; #define LDB(dst, b, h) _Pragma("unroll") for (int n = 0; n < 2; ++n) _Pragma("unroll") for (int k = 0; k < 2; ++k) \
;     dst[n][k] = *reinterpret_cast<const bf16x8*>((char*)SB(b, h) + lds_byte(wc * 32 + n * 16 + fr, k * 32 + fq * 8))
; #define MMA(ai, bj, At, Bt_) do { __builtin_amdgcn_s_setprio(1); \
;     _Pragma("unroll") for (int m = 0; m < 4; ++m) _Pragma("unroll") for (int n = 0; n < 2; ++n) _Pragma("unroll") for (int k = 0; k < 2; ++k) \
;       acc[ai][bj][m][n] = __builtin_amdgcn_mfma_f32_16x16x32_bf16(At[m][k], Bt_[n][k], acc[ai][bj][m][n], 0, 0, 0); \
;     __builtin_amdgcn_s_setprio(0); } while (0)
; #define WAIT_V(n) asm volatile("s_waitcnt vmcnt(" #n ")" ::: "memory")
; #define WAIT_L(n) asm volatile("s_waitcnt lgkmcnt(" #n ")" ::: "memory")
; #define BAR __builtin_amdgcn_s_barrier()
; #define SCHED __builtin_amdgcn_sched_barrier(0)
; template <class Epi> ...
;     ...
;     BAR; WAIT_L(0); MMA(0, 1, At, B1); BAR;
;     LDA(At, 0, 1); STAGE(SA(0, 0), A, brow, t + 2);
;     BAR; WAIT_L(0); MMA(1, 0, At, B0); BAR; SCHED;
;     STAGE(SB(0, 1), Bt, bcol + HALF, t + 2);
;     WAIT_V(6); BAR; MMA(1, 1, At, B1); BAR;
;     LDB(B0, 1, 0); SCHED; LDA(At, 1, 0); STAGE(SA(0, 1), A, brow + HALF, t + 2);
	s_waitcnt lgkmcnt(0)
	s_waitcnt lgkmcnt(3)
	v_mfma_f32_16x16x32_bf16 v[94:97], v[190:193], v[222:225], v[94:97]
	s_waitcnt lgkmcnt(1)
	v_mfma_f32_16x16x32_bf16 v[90:93], v[190:193], v[230:233], v[90:93]
	v_mfma_f32_16x16x32_bf16 v[86:89], v[198:201], v[222:225], v[86:89]
	v_mfma_f32_16x16x32_bf16 v[82:85], v[198:201], v[230:233], v[82:85]
	v_mfma_f32_16x16x32_bf16 v[78:81], v[206:209], v[222:225], v[78:81]
	v_mfma_f32_16x16x32_bf16 v[74:77], v[206:209], v[230:233], v[74:77]
	v_mfma_f32_16x16x32_bf16 v[70:73], v[214:217], v[222:225], v[70:73]
	v_mfma_f32_16x16x32_bf16 v[66:69], v[214:217], v[230:233], v[66:69]
	v_mfma_f32_16x16x32_bf16 v[94:97], v[194:197], v[226:229], v[94:97]
	s_waitcnt lgkmcnt(0)
	v_mfma_f32_16x16x32_bf16 v[90:93], v[194:197], v[234:237], v[90:93]
	v_mfma_f32_16x16x32_bf16 v[86:89], v[202:205], v[226:229], v[86:89]
	v_mfma_f32_16x16x32_bf16 v[82:85], v[202:205], v[234:237], v[82:85]
	v_mfma_f32_16x16x32_bf16 v[78:81], v[210:213], v[226:229], v[78:81]
	v_mfma_f32_16x16x32_bf16 v[74:77], v[210:213], v[234:237], v[74:77]
	v_mfma_f32_16x16x32_bf16 v[70:73], v[218:221], v[226:229], v[70:73]
	v_mfma_f32_16x16x32_bf16 v[66:69], v[218:221], v[234:237], v[66:69]
	v_readfirstlane_b32 s31, v140
	s_add_i32 s30, s28, 0x100
	s_mov_b32 m0, s31
	v_readfirstlane_b32 s31, v141
	s_barrier
	ds_read_b128 v[190:193], v133 offset:16384
	ds_read_b128 v[194:197], v133 offset:17408
	ds_read_b128 v[198:201], v132 offset:16384
	ds_read_b128 v[202:205], v132 offset:17408
	ds_read_b128 v[206:209], v131 offset:16384
	ds_read_b128 v[210:213], v131 offset:17408
	ds_read_b128 v[214:217], v130 offset:16384
	ds_read_b128 v[218:221], v130 offset:17408
	buffer_load_dwordx4 v134, s[4:7], s30 offen lds
	s_mov_b32 m0, s31
	s_nop 0
	buffer_load_dwordx4 v135, s[4:7], s30 offen lds
	s_barrier
	s_waitcnt lgkmcnt(0)
	s_waitcnt lgkmcnt(7)
	v_mfma_f32_16x16x32_bf16 v[62:65], v[190:193], v[156:159], v[62:65]
	v_mfma_f32_16x16x32_bf16 v[58:61], v[190:193], v[170:173], v[58:61]
	s_waitcnt lgkmcnt(5)
	v_mfma_f32_16x16x32_bf16 v[54:57], v[198:201], v[156:159], v[54:57]
	v_mfma_f32_16x16x32_bf16 v[50:53], v[198:201], v[170:173], v[50:53]
	s_waitcnt lgkmcnt(3)
	v_mfma_f32_16x16x32_bf16 v[46:49], v[206:209], v[156:159], v[46:49]
	v_mfma_f32_16x16x32_bf16 v[42:45], v[206:209], v[170:173], v[42:45]
	s_waitcnt lgkmcnt(1)
	v_mfma_f32_16x16x32_bf16 v[38:41], v[214:217], v[156:159], v[38:41]
	v_mfma_f32_16x16x32_bf16 v[34:37], v[214:217], v[170:173], v[34:37]
	v_mfma_f32_16x16x32_bf16 v[62:65], v[194:197], v[166:169], v[62:65]
	v_mfma_f32_16x16x32_bf16 v[58:61], v[194:197], v[186:189], v[58:61]
	v_mfma_f32_16x16x32_bf16 v[54:57], v[202:205], v[166:169], v[54:57]
	v_mfma_f32_16x16x32_bf16 v[50:53], v[202:205], v[186:189], v[50:53]
	v_mfma_f32_16x16x32_bf16 v[46:49], v[210:213], v[166:169], v[46:49]
	v_mfma_f32_16x16x32_bf16 v[42:45], v[210:213], v[186:189], v[42:45]
	s_waitcnt lgkmcnt(0)
	v_mfma_f32_16x16x32_bf16 v[38:41], v[218:221], v[166:169], v[38:41]
	v_mfma_f32_16x16x32_bf16 v[34:37], v[218:221], v[186:189], v[34:37]
	s_barrier
	v_readfirstlane_b32 s31, v142
	s_add_i32 s30, s29, 0x40100
	s_mov_b32 m0, s31
	v_readfirstlane_b32 s31, v143
	buffer_load_dwordx4 v134, s[76:79], s30 offen lds
	s_mov_b32 m0, s31
	s_nop 0
	buffer_load_dwordx4 v135, s[76:79], s30 offen lds
	s_waitcnt vmcnt(6)
	s_barrier
	v_mfma_f32_16x16x32_bf16 v[28:31], v[190:193], v[222:225], v[28:31]
	v_mfma_f32_16x16x32_bf16 v[24:27], v[190:193], v[230:233], v[24:27]
	v_mfma_f32_16x16x32_bf16 v[20:23], v[198:201], v[222:225], v[20:23]
	v_mfma_f32_16x16x32_bf16 v[16:19], v[198:201], v[230:233], v[16:19]
	v_mfma_f32_16x16x32_bf16 v[12:15], v[206:209], v[222:225], v[12:15]
	v_mfma_f32_16x16x32_bf16 v[8:11], v[206:209], v[230:233], v[8:11]
	v_mfma_f32_16x16x32_bf16 v[4:7], v[214:217], v[222:225], v[4:7]
	v_mfma_f32_16x16x32_bf16 v[0:3], v[214:217], v[230:233], v[0:3]
	v_mfma_f32_16x16x32_bf16 v[28:31], v[194:197], v[226:229], v[28:31]
	v_mfma_f32_16x16x32_bf16 v[24:27], v[194:197], v[234:237], v[24:27]
	v_mfma_f32_16x16x32_bf16 v[20:23], v[202:205], v[226:229], v[20:23]
	v_mfma_f32_16x16x32_bf16 v[16:19], v[202:205], v[234:237], v[16:19]
	v_mfma_f32_16x16x32_bf16 v[12:15], v[210:213], v[226:229], v[12:15]
	v_mfma_f32_16x16x32_bf16 v[8:11], v[210:213], v[234:237], v[8:11]
	v_mfma_f32_16x16x32_bf16 v[4:7], v[218:221], v[226:229], v[4:7]
	v_mfma_f32_16x16x32_bf16 v[0:3], v[218:221], v[234:237], v[0:3]
	s_barrier
	ds_read_b128 v[156:159], v137
	ds_read_b128 v[166:169], v137 offset:1024
	ds_read_b128 v[170:173], v137 offset:2048
	ds_read_b128 v[186:189], v137 offset:3072
	v_readfirstlane_b32 s31, v144
	s_add_i32 s30, s28, 0x40100
	s_mov_b32 m0, s31
	v_readfirstlane_b32 s31, v145
	ds_read_b128 v[190:193], v133 offset:32768
	ds_read_b128 v[194:197], v133 offset:33792
	ds_read_b128 v[198:201], v132 offset:32768
	ds_read_b128 v[202:205], v132 offset:33792
	ds_read_b128 v[206:209], v131 offset:32768
	ds_read_b128 v[210:213], v131 offset:33792
	ds_read_b128 v[214:217], v130 offset:32768
	ds_read_b128 v[218:221], v130 offset:33792
	buffer_load_dwordx4 v134, s[4:7], s30 offen lds
	s_mov_b32 m0, s31
	s_nop 0
	buffer_load_dwordx4 v135, s[4:7], s30 offen lds
	s_waitcnt lgkmcnt(8)
	s_barrier
; #define STAGE(P, BASE, br, kt) do { int _so = ((br) * K + (kt) * BK) * 2; \
;     __builtin_amdgcn_raw_ptr_buffer_load_lds(rs_##BASE, (__attribute__((address_space(3))) void*)((char*)(P) + tx * 16), 16, voff0, _so, 0, 0); \
;     __builtin_amdgcn_raw_ptr_buffer_load_lds(rs_##BASE, (__attribute__((address_space(3))) void*)((char*)(P) + tx * 16 + 8192), 16, voff1, _so, 0, 0); } while (0)
; #define LDA(dst, b, h) _Pragma("unroll") for (int m = 0; m < 4; ++m) _Pragma("unroll") for (int k = 0; k < 2; ++k) \
;     dst[m][k] = *reinterpret_cast<const bf16x8*>((char*)SA(b, h) + lds_byte(wr * 64 + m * 16 + fr, k * 32 + fq * 8))
; #define LDB(dst, b, h) _Pragma("unroll") for (int n = 0; n < 2; ++n) _Pragma("unroll") for (int k = 0; k < 2; ++k) \
;     dst[n][k] = *reinterpret_cast<const bf16x8*>((char*)SB(b, h) + lds_byte(wc * 32 + n * 16 + fr, k * 32 + fq * 8))
; #define MMA(ai, bj, At, Bt_) do { __builtin_amdgcn_s_setprio(1); \
;     _Pragma("unroll") for (int m = 0; m < 4; ++m) _Pragma("unroll") for (int n = 0; n < 2; ++n) _Pragma("unroll") for (int k = 0; k < 2; ++k) \
;       acc[ai][bj][m][n] = __builtin_amdgcn_mfma_f32_16x16x32_bf16(At[m][k], Bt_[n][k], acc[ai][bj][m][n], 0, 0, 0); \
;     __builtin_amdgcn_s_setprio(0); } while (0)
; #define WAIT_V(n) asm volatile("s_waitcnt vmcnt(" #n ")" ::: "memory")
; #define WAIT_L(n) asm volatile("s_waitcnt lgkmcnt(" #n ")" ::: "memory")
; #define BAR __builtin_amdgcn_s_barrier()
; #define SCHED __builtin_amdgcn_sched_barrier(0)
; template <class Epi> ...
;     ...
;     WAIT_L(8); BAR; WAIT_L(0); MMA(0, 0, At, B0); BAR; SCHED;
;     LDB(B1, 1, 1); STAGE(SB(1, 0), Bt, bcol, t + 3);
;     BAR; WAIT_L(0); MMA(0, 1, At, B1); BAR;
;     LDA(At, 1, 1); STAGE(SA(1, 0), A, brow, t + 3);
;     BAR; WAIT_L(0); MMA(1, 0, At, B0); BAR; SCHED;
;     STAGE(SB(1, 1), Bt, bcol + HALF, t + 3);
;     WAIT_V(6); BAR; MMA(1, 1, At, B1); BAR;
;   }
	s_waitcnt lgkmcnt(0)
	s_waitcnt lgkmcnt(7)
	v_mfma_f32_16x16x32_bf16 v[126:129], v[190:193], v[156:159], v[126:129]
	v_mfma_f32_16x16x32_bf16 v[122:125], v[190:193], v[170:173], v[122:125]
	s_waitcnt lgkmcnt(5)
	v_mfma_f32_16x16x32_bf16 v[118:121], v[198:201], v[156:159], v[118:121]
	v_mfma_f32_16x16x32_bf16 v[114:117], v[198:201], v[170:173], v[114:117]
	s_waitcnt lgkmcnt(3)
	v_mfma_f32_16x16x32_bf16 v[110:113], v[206:209], v[156:159], v[110:113]
	v_mfma_f32_16x16x32_bf16 v[106:109], v[206:209], v[170:173], v[106:109]
	s_waitcnt lgkmcnt(1)
	v_mfma_f32_16x16x32_bf16 v[102:105], v[214:217], v[156:159], v[102:105]
	v_mfma_f32_16x16x32_bf16 v[98:101], v[214:217], v[170:173], v[98:101]
	v_mfma_f32_16x16x32_bf16 v[126:129], v[194:197], v[166:169], v[126:129]
	v_mfma_f32_16x16x32_bf16 v[122:125], v[194:197], v[186:189], v[122:125]
	v_mfma_f32_16x16x32_bf16 v[118:121], v[202:205], v[166:169], v[118:121]
	v_mfma_f32_16x16x32_bf16 v[114:117], v[202:205], v[186:189], v[114:117]
	v_mfma_f32_16x16x32_bf16 v[110:113], v[210:213], v[166:169], v[110:113]
	v_mfma_f32_16x16x32_bf16 v[106:109], v[210:213], v[186:189], v[106:109]
	s_waitcnt lgkmcnt(0)
	v_mfma_f32_16x16x32_bf16 v[102:105], v[218:221], v[166:169], v[102:105]
	v_mfma_f32_16x16x32_bf16 v[98:101], v[218:221], v[186:189], v[98:101]
	s_barrier
	v_readfirstlane_b32 s31, v146
	s_add_i32 s30, s29, 0x180
	s_mov_b32 m0, s31
	v_readfirstlane_b32 s31, v147
	ds_read_b128 v[222:225], v136
	ds_read_b128 v[226:229], v136 offset:1024
	ds_read_b128 v[230:233], v136 offset:2048
	ds_read_b128 v[234:237], v136 offset:3072
	buffer_load_dwordx4 v134, s[76:79], s30 offen lds
	s_mov_b32 m0, s31
	s_nop 0
	buffer_load_dwordx4 v135, s[76:79], s30 offen lds
	s_barrier
	s_waitcnt lgkmcnt(0)
	s_waitcnt lgkmcnt(3)
	v_mfma_f32_16x16x32_bf16 v[94:97], v[190:193], v[222:225], v[94:97]
	s_waitcnt lgkmcnt(1)
	v_mfma_f32_16x16x32_bf16 v[90:93], v[190:193], v[230:233], v[90:93]
	v_mfma_f32_16x16x32_bf16 v[86:89], v[198:201], v[222:225], v[86:89]
	v_mfma_f32_16x16x32_bf16 v[82:85], v[198:201], v[230:233], v[82:85]
	v_mfma_f32_16x16x32_bf16 v[78:81], v[206:209], v[222:225], v[78:81]
	v_mfma_f32_16x16x32_bf16 v[74:77], v[206:209], v[230:233], v[74:77]
	v_mfma_f32_16x16x32_bf16 v[70:73], v[214:217], v[222:225], v[70:73]
	v_mfma_f32_16x16x32_bf16 v[66:69], v[214:217], v[230:233], v[66:69]
	v_mfma_f32_16x16x32_bf16 v[94:97], v[194:197], v[226:229], v[94:97]
	s_waitcnt lgkmcnt(0)
	v_mfma_f32_16x16x32_bf16 v[90:93], v[194:197], v[234:237], v[90:93]
	v_mfma_f32_16x16x32_bf16 v[86:89], v[202:205], v[226:229], v[86:89]
	v_mfma_f32_16x16x32_bf16 v[82:85], v[202:205], v[234:237], v[82:85]
	v_mfma_f32_16x16x32_bf16 v[78:81], v[210:213], v[226:229], v[78:81]
	v_mfma_f32_16x16x32_bf16 v[74:77], v[210:213], v[234:237], v[74:77]
	v_mfma_f32_16x16x32_bf16 v[70:73], v[218:221], v[226:229], v[70:73]
	v_mfma_f32_16x16x32_bf16 v[66:69], v[218:221], v[234:237], v[66:69]
	v_readfirstlane_b32 s30, v148
	s_addk_i32 s28, 0x180
	s_mov_b32 m0, s30
	v_readfirstlane_b32 s30, v150
	s_barrier
	ds_read_b128 v[190:193], v133 offset:49152
	ds_read_b128 v[194:197], v133 offset:50176
	ds_read_b128 v[198:201], v132 offset:49152
	ds_read_b128 v[202:205], v132 offset:50176
	ds_read_b128 v[206:209], v131 offset:49152
	ds_read_b128 v[210:213], v131 offset:50176
	ds_read_b128 v[214:217], v130 offset:49152
	ds_read_b128 v[218:221], v130 offset:50176
	buffer_load_dwordx4 v134, s[4:7], s28 offen lds
	s_mov_b32 m0, s30
	s_nop 0
	buffer_load_dwordx4 v135, s[4:7], s28 offen lds
	s_barrier
	s_waitcnt lgkmcnt(0)
	s_waitcnt lgkmcnt(7)
	v_mfma_f32_16x16x32_bf16 v[62:65], v[190:193], v[156:159], v[62:65]
	v_mfma_f32_16x16x32_bf16 v[58:61], v[190:193], v[170:173], v[58:61]
	s_waitcnt lgkmcnt(5)
	v_mfma_f32_16x16x32_bf16 v[54:57], v[198:201], v[156:159], v[54:57]
	v_mfma_f32_16x16x32_bf16 v[50:53], v[198:201], v[170:173], v[50:53]
	s_waitcnt lgkmcnt(3)
	v_mfma_f32_16x16x32_bf16 v[46:49], v[206:209], v[156:159], v[46:49]
	v_mfma_f32_16x16x32_bf16 v[42:45], v[206:209], v[170:173], v[42:45]
	s_waitcnt lgkmcnt(1)
	v_mfma_f32_16x16x32_bf16 v[38:41], v[214:217], v[156:159], v[38:41]
	v_mfma_f32_16x16x32_bf16 v[34:37], v[214:217], v[170:173], v[34:37]
	v_mfma_f32_16x16x32_bf16 v[62:65], v[194:197], v[166:169], v[62:65]
	v_mfma_f32_16x16x32_bf16 v[58:61], v[194:197], v[186:189], v[58:61]
	v_mfma_f32_16x16x32_bf16 v[54:57], v[202:205], v[166:169], v[54:57]
	v_mfma_f32_16x16x32_bf16 v[50:53], v[202:205], v[186:189], v[50:53]
	v_mfma_f32_16x16x32_bf16 v[46:49], v[210:213], v[166:169], v[46:49]
	v_mfma_f32_16x16x32_bf16 v[42:45], v[210:213], v[186:189], v[42:45]
	s_waitcnt lgkmcnt(0)
	v_mfma_f32_16x16x32_bf16 v[38:41], v[218:221], v[166:169], v[38:41]
	v_mfma_f32_16x16x32_bf16 v[34:37], v[218:221], v[186:189], v[34:37]
	s_barrier
	v_readfirstlane_b32 s28, v151
	s_add_i32 s29, s29, 0x40180
	s_mov_b32 m0, s28
	v_readfirstlane_b32 s28, v152
	buffer_load_dwordx4 v134, s[76:79], s29 offen lds
	s_mov_b32 m0, s28
	s_nop 0
	buffer_load_dwordx4 v135, s[76:79], s29 offen lds
	s_waitcnt vmcnt(6)
	s_barrier
	v_mfma_f32_16x16x32_bf16 v[28:31], v[190:193], v[222:225], v[28:31]
	v_mfma_f32_16x16x32_bf16 v[24:27], v[190:193], v[230:233], v[24:27]
	v_mfma_f32_16x16x32_bf16 v[20:23], v[198:201], v[222:225], v[20:23]
	v_mfma_f32_16x16x32_bf16 v[16:19], v[198:201], v[230:233], v[16:19]
	v_mfma_f32_16x16x32_bf16 v[12:15], v[206:209], v[222:225], v[12:15]
	v_mfma_f32_16x16x32_bf16 v[8:11], v[206:209], v[230:233], v[8:11]
	v_mfma_f32_16x16x32_bf16 v[4:7], v[214:217], v[222:225], v[4:7]
	v_mfma_f32_16x16x32_bf16 v[0:3], v[214:217], v[230:233], v[0:3]
	v_mfma_f32_16x16x32_bf16 v[28:31], v[194:197], v[226:229], v[28:31]
	v_mfma_f32_16x16x32_bf16 v[24:27], v[194:197], v[234:237], v[24:27]
	v_mfma_f32_16x16x32_bf16 v[20:23], v[202:205], v[226:229], v[20:23]
	v_mfma_f32_16x16x32_bf16 v[16:19], v[202:205], v[234:237], v[16:19]
	v_mfma_f32_16x16x32_bf16 v[12:15], v[210:213], v[226:229], v[12:15]
	v_mfma_f32_16x16x32_bf16 v[8:11], v[210:213], v[234:237], v[8:11]
	v_mfma_f32_16x16x32_bf16 v[4:7], v[218:221], v[226:229], v[4:7]
	v_mfma_f32_16x16x32_bf16 v[0:3], v[218:221], v[234:237], v[0:3]
	s_add_i32 s26, s26, 2
	s_addk_i32 s27, 0x100
	s_cmp_lt_u32 s26, 12
	s_barrier
	s_cbranch_scc1 .LBB0_1657
; #define STAGE(P, BASE, br, kt) do { int _so = ((br) * K + (kt) * BK) * 2; \
;     __builtin_amdgcn_raw_ptr_buffer_load_lds(rs_##BASE, (__attribute__((address_space(3))) void*)((char*)(P) + tx * 16), 16, voff0, _so, 0, 0); \
;     __builtin_amdgcn_raw_ptr_buffer_load_lds(rs_##BASE, (__attribute__((address_space(3))) void*)((char*)(P) + tx * 16 + 8192), 16, voff1, _so, 0, 0); } while (0)
; #define LDA(dst, b, h) _Pragma("unroll") for (int m = 0; m < 4; ++m) _Pragma("unroll") for (int k = 0; k < 2; ++k) \
;     dst[m][k] = *reinterpret_cast<const bf16x8*>((char*)SA(b, h) + lds_byte(wr * 64 + m * 16 + fr, k * 32 + fq * 8))
; #define LDB(dst, b, h) _Pragma("unroll") for (int n = 0; n < 2; ++n) _Pragma("unroll") for (int k = 0; k < 2; ++k) \
;     dst[n][k] = *reinterpret_cast<const bf16x8*>((char*)SB(b, h) + lds_byte(wc * 32 + n * 16 + fr, k * 32 + fq * 8))
; #define MMA(ai, bj, At, Bt_) do { __builtin_amdgcn_s_setprio(1); \
;     _Pragma("unroll") for (int m = 0; m < 4; ++m) _Pragma("unroll") for (int n = 0; n < 2; ++n) _Pragma("unroll") for (int k = 0; k < 2; ++k) \
;       acc[ai][bj][m][n] = __builtin_amdgcn_mfma_f32_16x16x32_bf16(At[m][k], Bt_[n][k], acc[ai][bj][m][n], 0, 0, 0); \
;     __builtin_amdgcn_s_setprio(0); } while (0)
; #define WAIT_V(n) asm volatile("s_waitcnt vmcnt(" #n ")" ::: "memory")
; #define WAIT_L(n) asm volatile("s_waitcnt lgkmcnt(" #n ")" ::: "memory")
; #define BAR __builtin_amdgcn_s_barrier()
; template <class Epi> ...
;     ...
;   { LDB(B0, 0, 0); LDA(At, 0, 0); STAGE(SA(1, 1), A, brow + HALF, nt - 1);
;     BAR; WAIT_L(0); MMA(0, 0, At, B0); BAR;
;     LDB(B1, 0, 1); BAR; WAIT_L(0); MMA(0, 1, At, B1); BAR;
;     LDA(At, 0, 1); WAIT_V(4); BAR; WAIT_L(0); MMA(1, 0, At, B0); MMA(1, 1, At, B1); BAR; }
.Lpx2:
	v_readfirstlane_b32 s25, v155
	s_or_b32 s24, s24, 0x40780
	s_mov_b32 s6, s78
	s_mov_b32 s7, s79
	s_mov_b32 m0, s25
	v_readfirstlane_b32 s25, v154
	ds_read_b128 v[138:141], v153
	ds_read_b128 v[142:145], v153 offset:1024
	ds_read_b128 v[156:159], v153 offset:2048
	ds_read_b128 v[150:153], v153 offset:3072
	ds_read_b128 v[166:169], v133
	ds_read_b128 v[170:173], v133 offset:1024
	ds_read_b128 v[186:189], v132
	ds_read_b128 v[190:193], v132 offset:1024
	ds_read_b128 v[194:197], v131
	ds_read_b128 v[198:201], v131 offset:1024
	ds_read_b128 v[202:205], v130
	ds_read_b128 v[206:209], v130 offset:1024
	buffer_load_dwordx4 v134, s[4:7], s24 offen lds
	s_mov_b32 m0, s25
	s_nop 0
	buffer_load_dwordx4 v135, s[4:7], s24 offen lds
	s_barrier
	s_waitcnt lgkmcnt(0)
	s_waitcnt lgkmcnt(7)
	v_mfma_f32_16x16x32_bf16 v[126:129], v[166:169], v[138:141], v[126:129]
	v_mfma_f32_16x16x32_bf16 v[122:125], v[166:169], v[156:159], v[122:125]
	s_waitcnt lgkmcnt(5)
	v_mfma_f32_16x16x32_bf16 v[118:121], v[186:189], v[138:141], v[118:121]
	v_mfma_f32_16x16x32_bf16 v[114:117], v[186:189], v[156:159], v[114:117]
	s_waitcnt lgkmcnt(3)
	v_mfma_f32_16x16x32_bf16 v[110:113], v[194:197], v[138:141], v[110:113]
	v_mfma_f32_16x16x32_bf16 v[106:109], v[194:197], v[156:159], v[106:109]
	s_waitcnt lgkmcnt(1)
	v_mfma_f32_16x16x32_bf16 v[102:105], v[202:205], v[138:141], v[102:105]
	v_mfma_f32_16x16x32_bf16 v[98:101], v[202:205], v[156:159], v[98:101]
	v_mfma_f32_16x16x32_bf16 v[126:129], v[170:173], v[142:145], v[126:129]
	v_mfma_f32_16x16x32_bf16 v[122:125], v[170:173], v[150:153], v[122:125]
	v_mfma_f32_16x16x32_bf16 v[118:121], v[190:193], v[142:145], v[118:121]
	v_mfma_f32_16x16x32_bf16 v[114:117], v[190:193], v[150:153], v[114:117]
	v_mfma_f32_16x16x32_bf16 v[110:113], v[198:201], v[142:145], v[110:113]
	v_mfma_f32_16x16x32_bf16 v[106:109], v[198:201], v[150:153], v[106:109]
	s_waitcnt lgkmcnt(0)
	v_mfma_f32_16x16x32_bf16 v[102:105], v[206:209], v[142:145], v[102:105]
	v_mfma_f32_16x16x32_bf16 v[98:101], v[206:209], v[150:153], v[98:101]
	s_barrier
	ds_read_b128 v[210:213], v149
	ds_read_b128 v[214:217], v149 offset:1024
	ds_read_b128 v[218:221], v149 offset:2048
	ds_read_b128 v[146:149], v149 offset:3072
	s_barrier
	s_waitcnt lgkmcnt(0)
	s_waitcnt lgkmcnt(3)
	v_mfma_f32_16x16x32_bf16 v[94:97], v[166:169], v[210:213], v[94:97]
	s_waitcnt lgkmcnt(1)
	v_mfma_f32_16x16x32_bf16 v[90:93], v[166:169], v[218:221], v[90:93]
	v_mfma_f32_16x16x32_bf16 v[82:85], v[186:189], v[218:221], v[82:85]
	v_mfma_f32_16x16x32_bf16 v[78:81], v[194:197], v[210:213], v[78:81]
	v_mfma_f32_16x16x32_bf16 v[66:69], v[202:205], v[218:221], v[66:69]
	v_mfma_f32_16x16x32_bf16 v[94:97], v[170:173], v[214:217], v[94:97]
	s_waitcnt lgkmcnt(0)
	v_mfma_f32_16x16x32_bf16 v[90:93], v[170:173], v[146:149], v[90:93]
	v_mfma_f32_16x16x32_bf16 v[86:89], v[186:189], v[210:213], v[86:89]
	v_mfma_f32_16x16x32_bf16 v[82:85], v[190:193], v[146:149], v[82:85]
	v_mfma_f32_16x16x32_bf16 v[78:81], v[198:201], v[214:217], v[78:81]
	v_mfma_f32_16x16x32_bf16 v[74:77], v[194:197], v[218:221], v[74:77]
	v_mfma_f32_16x16x32_bf16 v[70:73], v[202:205], v[210:213], v[70:73]
	v_mfma_f32_16x16x32_bf16 v[66:69], v[206:209], v[146:149], v[66:69]
	v_mfma_f32_16x16x32_bf16 v[166:169], v[190:193], v[214:217], v[86:89]
	v_mfma_f32_16x16x32_bf16 v[170:173], v[198:201], v[146:149], v[74:77]
	v_mfma_f32_16x16x32_bf16 v[186:189], v[206:209], v[214:217], v[70:73]
	s_barrier
	s_nop 1
	ds_read_b128 v[70:73], v133 offset:16384
	ds_read_b128 v[74:77], v133 offset:17408
	ds_read_b128 v[86:89], v132 offset:16384
	ds_read_b128 v[190:193], v132 offset:17408
	ds_read_b128 v[194:197], v131 offset:16384
	ds_read_b128 v[198:201], v131 offset:17408
	ds_read_b128 v[202:205], v130 offset:16384
	ds_read_b128 v[206:209], v130 offset:17408
	s_waitcnt vmcnt(4)
	s_barrier
	s_waitcnt lgkmcnt(0)
	s_waitcnt lgkmcnt(7)
	v_mfma_f32_16x16x32_bf16 v[62:65], v[70:73], v[138:141], v[62:65]
	s_waitcnt lgkmcnt(5)
	v_mfma_f32_16x16x32_bf16 v[50:53], v[86:89], v[156:159], v[50:53]
	s_waitcnt lgkmcnt(3)
	v_mfma_f32_16x16x32_bf16 v[46:49], v[194:197], v[138:141], v[46:49]
	v_mfma_f32_16x16x32_bf16 v[62:65], v[74:77], v[142:145], v[62:65]
	v_mfma_f32_16x16x32_bf16 v[58:61], v[70:73], v[156:159], v[58:61]
	v_mfma_f32_16x16x32_bf16 v[54:57], v[86:89], v[138:141], v[54:57]
	v_mfma_f32_16x16x32_bf16 v[50:53], v[190:193], v[150:153], v[50:53]
	s_waitcnt lgkmcnt(2)
	v_mfma_f32_16x16x32_bf16 v[46:49], v[198:201], v[142:145], v[46:49]
	v_mfma_f32_16x16x32_bf16 v[42:45], v[194:197], v[156:159], v[42:45]
	s_waitcnt lgkmcnt(1)
	v_mfma_f32_16x16x32_bf16 v[38:41], v[202:205], v[138:141], v[38:41]
	v_mfma_f32_16x16x32_bf16 v[34:37], v[202:205], v[156:159], v[34:37]
	v_mfma_f32_16x16x32_bf16 v[222:225], v[74:77], v[150:153], v[58:61]
	v_mfma_f32_16x16x32_bf16 v[226:229], v[190:193], v[142:145], v[54:57]
	v_mfma_f32_16x16x32_bf16 v[230:233], v[198:201], v[150:153], v[42:45]
	s_waitcnt lgkmcnt(0)
	v_mfma_f32_16x16x32_bf16 v[138:141], v[206:209], v[142:145], v[38:41]
	v_mfma_f32_16x16x32_bf16 v[142:145], v[206:209], v[150:153], v[34:37]
	v_mfma_f32_16x16x32_bf16 v[0:3], v[202:205], v[218:221], v[0:3]
	v_mfma_f32_16x16x32_bf16 v[28:31], v[70:73], v[210:213], v[28:31]
	v_mfma_f32_16x16x32_bf16 v[24:27], v[70:73], v[218:221], v[24:27]
	v_mfma_f32_16x16x32_bf16 v[20:23], v[86:89], v[210:213], v[20:23]
	v_mfma_f32_16x16x32_bf16 v[16:19], v[86:89], v[218:221], v[16:19]
	v_mfma_f32_16x16x32_bf16 v[12:15], v[194:197], v[210:213], v[12:15]
	v_mfma_f32_16x16x32_bf16 v[8:11], v[194:197], v[218:221], v[8:11]
	v_mfma_f32_16x16x32_bf16 v[4:7], v[202:205], v[210:213], v[4:7]
	v_mfma_f32_16x16x32_bf16 v[0:3], v[206:209], v[146:149], v[0:3]
	v_mfma_f32_16x16x32_bf16 v[150:153], v[74:77], v[214:217], v[28:31]
	v_mfma_f32_16x16x32_bf16 v[154:157], v[74:77], v[146:149], v[24:27]
	v_mfma_f32_16x16x32_bf16 v[158:161], v[190:193], v[214:217], v[20:23]
	v_mfma_f32_16x16x32_bf16 v[190:193], v[190:193], v[146:149], v[16:19]
	v_mfma_f32_16x16x32_bf16 v[234:237], v[198:201], v[214:217], v[12:15]
	v_mfma_f32_16x16x32_bf16 v[194:197], v[198:201], v[146:149], v[8:11]
	v_mfma_f32_16x16x32_bf16 v[198:201], v[206:209], v[214:217], v[4:7]
	s_barrier
; #define LDA(dst, b, h) _Pragma("unroll") for (int m = 0; m < 4; ++m) _Pragma("unroll") for (int k = 0; k < 2; ++k) \
;     dst[m][k] = *reinterpret_cast<const bf16x8*>((char*)SA(b, h) + lds_byte(wr * 64 + m * 16 + fr, k * 32 + fq * 8))
; #define LDB(dst, b, h) _Pragma("unroll") for (int n = 0; n < 2; ++n) _Pragma("unroll") for (int k = 0; k < 2; ++k) \
;     dst[n][k] = *reinterpret_cast<const bf16x8*>((char*)SB(b, h) + lds_byte(wc * 32 + n * 16 + fr, k * 32 + fq * 8))
; #define MMA(ai, bj, At, Bt_) do { __builtin_amdgcn_s_setprio(1); \
;     _Pragma("unroll") for (int m = 0; m < 4; ++m) _Pragma("unroll") for (int n = 0; n < 2; ++n) _Pragma("unroll") for (int k = 0; k < 2; ++k) \
;       acc[ai][bj][m][n] = __builtin_amdgcn_mfma_f32_16x16x32_bf16(At[m][k], Bt_[n][k], acc[ai][bj][m][n], 0, 0, 0); \
;     __builtin_amdgcn_s_setprio(0); } while (0)
; #define WAIT_V(n) asm volatile("s_waitcnt vmcnt(" #n ")" ::: "memory")
; #define WAIT_L(n) asm volatile("s_waitcnt lgkmcnt(" #n ")" ::: "memory")
; #define BAR __builtin_amdgcn_s_barrier()
; template <class Epi> ...
;     ...
;   { LDB(B0, 1, 0); LDA(At, 1, 0); WAIT_V(2); BAR; WAIT_L(0); MMA(0, 0, At, B0); BAR;
;     LDB(B1, 1, 1); WAIT_V(0); BAR; WAIT_L(0); MMA(0, 1, At, B1); BAR;
;     LDA(At, 1, 1); BAR; WAIT_L(0); MMA(1, 0, At, B0); MMA(1, 1, At, B1); BAR; }
;   if (wr == 0) BAR;
	ds_read_b128 v[146:149], v137
	ds_read_b128 v[202:205], v137 offset:1024
	ds_read_b128 v[206:209], v137 offset:2048
	ds_read_b128 v[210:213], v137 offset:3072
	ds_read_b128 v[38:41], v133 offset:32768
	ds_read_b128 v[42:45], v133 offset:33792
	ds_read_b128 v[54:57], v132 offset:32768
	ds_read_b128 v[58:61], v132 offset:33792
	ds_read_b128 v[214:217], v131 offset:32768
	ds_read_b128 v[218:221], v131 offset:33792
	ds_read_b128 v[238:241], v130 offset:32768
	ds_read_b128 v[242:245], v130 offset:33792
	s_waitcnt vmcnt(2)
	s_barrier
	s_waitcnt lgkmcnt(0)
	s_waitcnt lgkmcnt(7)
	v_mfma_f32_16x16x32_bf16 v[4:7], v[38:41], v[146:149], v[126:129]
	s_waitcnt lgkmcnt(6)
	v_mfma_f32_16x16x32_bf16 v[28:31], v[42:45], v[202:205], v[4:7]
	v_mfma_f32_16x16x32_bf16 v[4:7], v[38:41], v[206:209], v[122:125]
	v_mfma_f32_16x16x32_bf16 v[34:37], v[42:45], v[210:213], v[4:7]
	s_waitcnt lgkmcnt(5)
	v_mfma_f32_16x16x32_bf16 v[4:7], v[54:57], v[146:149], v[118:121]
	s_waitcnt lgkmcnt(4)
	v_mfma_f32_16x16x32_bf16 v[20:23], v[58:61], v[202:205], v[4:7]
	v_mfma_f32_16x16x32_bf16 v[4:7], v[54:57], v[206:209], v[114:117]
	v_mfma_f32_16x16x32_bf16 v[24:27], v[58:61], v[210:213], v[4:7]
	s_waitcnt lgkmcnt(3)
	v_mfma_f32_16x16x32_bf16 v[4:7], v[214:217], v[146:149], v[110:113]
	s_waitcnt lgkmcnt(2)
	v_mfma_f32_16x16x32_bf16 v[12:15], v[218:221], v[202:205], v[4:7]
	v_mfma_f32_16x16x32_bf16 v[4:7], v[214:217], v[206:209], v[106:109]
	v_mfma_f32_16x16x32_bf16 v[16:19], v[218:221], v[210:213], v[4:7]
	s_waitcnt lgkmcnt(1)
	v_mfma_f32_16x16x32_bf16 v[4:7], v[238:241], v[146:149], v[102:105]
	v_mfma_f32_16x16x32_bf16 v[8:11], v[238:241], v[206:209], v[98:101]
	s_waitcnt lgkmcnt(0)
	v_mfma_f32_16x16x32_bf16 v[4:7], v[242:245], v[202:205], v[4:7]
	v_mfma_f32_16x16x32_bf16 v[8:11], v[242:245], v[210:213], v[8:11]
	s_barrier
	ds_read_b128 v[102:105], v136
	ds_read_b128 v[246:249], v136 offset:1024
	ds_read_b128 v[250:253], v136 offset:2048
	ds_read_b128 v[134:137], v136 offset:3072
	s_waitcnt vmcnt(0)
	s_barrier
	s_waitcnt lgkmcnt(0)
	s_waitcnt lgkmcnt(3)
	v_mfma_f32_16x16x32_bf16 v[70:73], v[38:41], v[102:105], v[94:97]
	s_waitcnt lgkmcnt(1)
	v_mfma_f32_16x16x32_bf16 v[38:41], v[38:41], v[250:253], v[90:93]
	s_waitcnt lgkmcnt(0)
	v_mfma_f32_16x16x32_bf16 v[90:93], v[42:45], v[134:137], v[38:41]
	v_mfma_f32_16x16x32_bf16 v[38:41], v[54:57], v[102:105], v[166:169]
	v_mfma_f32_16x16x32_bf16 v[86:89], v[42:45], v[246:249], v[70:73]
	v_mfma_f32_16x16x32_bf16 v[70:73], v[58:61], v[246:249], v[38:41]
	v_mfma_f32_16x16x32_bf16 v[38:41], v[54:57], v[250:253], v[82:85]
	v_mfma_f32_16x16x32_bf16 v[74:77], v[58:61], v[134:137], v[38:41]
	v_mfma_f32_16x16x32_bf16 v[38:41], v[214:217], v[102:105], v[78:81]
	v_mfma_f32_16x16x32_bf16 v[54:57], v[218:221], v[246:249], v[38:41]
	v_mfma_f32_16x16x32_bf16 v[38:41], v[214:217], v[250:253], v[170:173]
	v_mfma_f32_16x16x32_bf16 v[58:61], v[218:221], v[134:137], v[38:41]
	v_mfma_f32_16x16x32_bf16 v[38:41], v[238:241], v[102:105], v[186:189]
	v_mfma_f32_16x16x32_bf16 v[42:45], v[238:241], v[250:253], v[66:69]
	v_mfma_f32_16x16x32_bf16 v[38:41], v[242:245], v[246:249], v[38:41]
	v_mfma_f32_16x16x32_bf16 v[42:45], v[242:245], v[134:137], v[42:45]
	s_barrier
	ds_read_b128 v[106:109], v133 offset:49152
	ds_read_b128 v[110:113], v133 offset:50176
	ds_read_b128 v[118:121], v132 offset:49152
	ds_read_b128 v[166:169], v132 offset:50176
	ds_read_b128 v[170:173], v131 offset:49152
	ds_read_b128 v[186:189], v131 offset:50176
	ds_read_b128 v[214:217], v130 offset:49152
	ds_read_b128 v[130:133], v130 offset:50176
	s_barrier
	s_waitcnt lgkmcnt(0)
	s_waitcnt lgkmcnt(7)
	v_mfma_f32_16x16x32_bf16 v[62:65], v[106:109], v[146:149], v[62:65]
	s_waitcnt lgkmcnt(6)
	v_mfma_f32_16x16x32_bf16 v[94:97], v[110:113], v[202:205], v[62:65]
	v_mfma_f32_16x16x32_bf16 v[62:65], v[106:109], v[206:209], v[222:225]
	v_mfma_f32_16x16x32_bf16 v[98:101], v[110:113], v[210:213], v[62:65]
	s_waitcnt lgkmcnt(5)
	v_mfma_f32_16x16x32_bf16 v[62:65], v[118:121], v[146:149], v[226:229]
	s_waitcnt lgkmcnt(3)
	v_mfma_f32_16x16x32_bf16 v[46:49], v[170:173], v[146:149], v[46:49]
	v_mfma_f32_16x16x32_bf16 v[78:81], v[166:169], v[202:205], v[62:65]
	v_mfma_f32_16x16x32_bf16 v[50:53], v[118:121], v[206:209], v[50:53]
	s_waitcnt lgkmcnt(2)
	v_mfma_f32_16x16x32_bf16 v[62:65], v[186:189], v[202:205], v[46:49]
	v_mfma_f32_16x16x32_bf16 v[46:49], v[170:173], v[206:209], v[230:233]
	v_mfma_f32_16x16x32_bf16 v[82:85], v[166:169], v[210:213], v[50:53]
	v_mfma_f32_16x16x32_bf16 v[66:69], v[186:189], v[210:213], v[46:49]
	s_waitcnt lgkmcnt(1)
	v_mfma_f32_16x16x32_bf16 v[46:49], v[214:217], v[146:149], v[138:141]
	v_mfma_f32_16x16x32_bf16 v[50:53], v[214:217], v[206:209], v[142:145]
	s_waitcnt lgkmcnt(0)
	v_mfma_f32_16x16x32_bf16 v[46:49], v[130:133], v[202:205], v[46:49]
	v_mfma_f32_16x16x32_bf16 v[50:53], v[130:133], v[210:213], v[50:53]
	v_mfma_f32_16x16x32_bf16 v[114:117], v[106:109], v[102:105], v[150:153]
	v_mfma_f32_16x16x32_bf16 v[106:109], v[106:109], v[250:253], v[154:157]
	v_mfma_f32_16x16x32_bf16 v[126:129], v[110:113], v[134:137], v[106:109]
	v_mfma_f32_16x16x32_bf16 v[106:109], v[118:121], v[102:105], v[158:161]
	v_mfma_f32_16x16x32_bf16 v[122:125], v[110:113], v[246:249], v[114:117]
	v_mfma_f32_16x16x32_bf16 v[114:117], v[166:169], v[246:249], v[106:109]
	v_mfma_f32_16x16x32_bf16 v[106:109], v[118:121], v[250:253], v[190:193]
	v_mfma_f32_16x16x32_bf16 v[118:121], v[166:169], v[134:137], v[106:109]
	v_mfma_f32_16x16x32_bf16 v[106:109], v[170:173], v[102:105], v[234:237]
	v_mfma_f32_16x16x32_bf16 v[110:113], v[170:173], v[250:253], v[194:197]
	v_mfma_f32_16x16x32_bf16 v[102:105], v[214:217], v[102:105], v[198:201]
	v_mfma_f32_16x16x32_bf16 v[0:3], v[214:217], v[250:253], v[0:3]
	v_mfma_f32_16x16x32_bf16 v[106:109], v[186:189], v[246:249], v[106:109]
	v_mfma_f32_16x16x32_bf16 v[110:113], v[186:189], v[134:137], v[110:113]
	v_mfma_f32_16x16x32_bf16 v[102:105], v[130:133], v[246:249], v[102:105]
	v_mfma_f32_16x16x32_bf16 v[0:3], v[130:133], v[134:137], v[0:3]
	v_cmp_gt_u32_e32 vcc, s59, v32
	s_barrier
	s_and_saveexec_b64 s[4:5], vcc
	s_cbranch_execz .LBB0_1660
	s_barrier

; #define STAGE(P, BASE, br, kt) do { int _so = ((br) * K + (kt) * BK) * 2; \
;     __builtin_amdgcn_raw_ptr_buffer_load_lds(rs_##BASE, (__attribute__((address_space(3))) void*)((char*)(P) + tx * 16), 16, voff0, _so, 0, 0); \
;     __builtin_amdgcn_raw_ptr_buffer_load_lds(rs_##BASE, (__attribute__((address_space(3))) void*)((char*)(P) + tx * 16 + 8192), 16, voff1, _so, 0, 0); } while (0)
; #define LDA(dst, b, h) _Pragma("unroll") for (int m = 0; m < 4; ++m) _Pragma("unroll") for (int k = 0; k < 2; ++k) \
;     dst[m][k] = *reinterpret_cast<const bf16x8*>((char*)SA(b, h) + lds_byte(wr * 64 + m * 16 + fr, k * 32 + fq * 8))
; #define LDB(dst, b, h) _Pragma("unroll") for (int n = 0; n < 2; ++n) _Pragma("unroll") for (int k = 0; k < 2; ++k) \
;     dst[n][k] = *reinterpret_cast<const bf16x8*>((char*)SB(b, h) + lds_byte(wc * 32 + n * 16 + fr, k * 32 + fq * 8))
; #define MMA(ai, bj, At, Bt_) do { __builtin_amdgcn_s_setprio(1); \
;     _Pragma("unroll") for (int m = 0; m < 4; ++m) _Pragma("unroll") for (int n = 0; n < 2; ++n) _Pragma("unroll") for (int k = 0; k < 2; ++k) \
;       acc[ai][bj][m][n] = __builtin_amdgcn_mfma_f32_16x16x32_bf16(At[m][k], Bt_[n][k], acc[ai][bj][m][n], 0, 0, 0); \
;     __builtin_amdgcn_s_setprio(0); } while (0)
; #define WAIT_V(n) asm volatile("s_waitcnt vmcnt(" #n ")" ::: "memory")
; #define WAIT_L(n) asm volatile("s_waitcnt lgkmcnt(" #n ")" ::: "memory")
; #define BAR __builtin_amdgcn_s_barrier()
; #define SCHED __builtin_amdgcn_sched_barrier(0)
; template <class Epi> ...
;     ...
;     LDB(B0, 0, 0); SCHED; LDA(At, 0, 0); STAGE(SA(1, 1), A, brow + HALF, t + 1);
;     WAIT_L(8); BAR; WAIT_L(0); MMA(0, 0, At, B0); BAR; SCHED;
;     LDB(B1, 0, 1); STAGE(SB(0, 0), Bt, bcol, t + 2);
;     BAR; WAIT_L(0); MMA(0, 1, At, B1); BAR;
;     LDA(At, 0, 1); STAGE(SA(0, 0), A, brow, t + 2);
;     BAR; WAIT_L(0); MMA(1, 0, At, B0); BAR; SCHED;
;     STAGE(SB(0, 1), Bt, bcol + HALF, t + 2);
;     WAIT_V(6); BAR; MMA(1, 1, At, B1); BAR;
.Lpk3:
	ds_read_b128 v[156:159], v155
	ds_read_b128 v[166:169], v155 offset:1024
	ds_read_b128 v[170:173], v155 offset:2048
	ds_read_b128 v[186:189], v155 offset:3072
	s_add_i32 s29, s19, s28
	v_readfirstlane_b32 s31, v152
	s_add_i32 s30, s29, 0x40080
	s_mov_b32 m0, s31
	v_readfirstlane_b32 s31, v151
	ds_read_b128 v[190:193], v143
	ds_read_b128 v[194:197], v143 offset:1024
	ds_read_b128 v[198:201], v142
	ds_read_b128 v[202:205], v142 offset:1024
	ds_read_b128 v[206:209], v141
	ds_read_b128 v[210:213], v141 offset:1024
	ds_read_b128 v[214:217], v140
	ds_read_b128 v[218:221], v140 offset:1024
	buffer_load_dwordx4 v32, s[4:7], s30 offen lds
	s_mov_b32 m0, s31
	s_nop 0
	buffer_load_dwordx4 v130, s[4:7], s30 offen lds
	s_waitcnt lgkmcnt(8)
	s_barrier
	s_waitcnt lgkmcnt(0)
	s_waitcnt lgkmcnt(7)
	v_mfma_f32_16x16x32_bf16 v[126:129], v[190:193], v[156:159], 0
	v_mfma_f32_16x16x32_bf16 v[122:125], v[190:193], v[170:173], 0
	s_waitcnt lgkmcnt(5)
	v_mfma_f32_16x16x32_bf16 v[118:121], v[198:201], v[156:159], 0
	v_mfma_f32_16x16x32_bf16 v[114:117], v[198:201], v[170:173], 0
	s_waitcnt lgkmcnt(3)
	v_mfma_f32_16x16x32_bf16 v[110:113], v[206:209], v[156:159], 0
	v_mfma_f32_16x16x32_bf16 v[106:109], v[206:209], v[170:173], 0
	s_waitcnt lgkmcnt(1)
	v_mfma_f32_16x16x32_bf16 v[102:105], v[214:217], v[156:159], 0
	v_mfma_f32_16x16x32_bf16 v[98:101], v[214:217], v[170:173], 0
	v_mfma_f32_16x16x32_bf16 v[126:129], v[194:197], v[166:169], v[126:129]
	v_mfma_f32_16x16x32_bf16 v[122:125], v[194:197], v[186:189], v[122:125]
	v_mfma_f32_16x16x32_bf16 v[118:121], v[202:205], v[166:169], v[118:121]
	v_mfma_f32_16x16x32_bf16 v[114:117], v[202:205], v[186:189], v[114:117]
	v_mfma_f32_16x16x32_bf16 v[110:113], v[210:213], v[166:169], v[110:113]
	v_mfma_f32_16x16x32_bf16 v[106:109], v[210:213], v[186:189], v[106:109]
	s_waitcnt lgkmcnt(0)
	v_mfma_f32_16x16x32_bf16 v[102:105], v[218:221], v[166:169], v[102:105]
	v_mfma_f32_16x16x32_bf16 v[98:101], v[218:221], v[186:189], v[98:101]
	s_barrier
	s_add_i32 s30, s18, s28
	v_readfirstlane_b32 s34, v137
	s_add_i32 s31, s30, 0x100
	s_mov_b32 m0, s34
	v_readfirstlane_b32 s34, v139
	ds_read_b128 v[222:225], v149
	ds_read_b128 v[226:229], v149 offset:1024
	ds_read_b128 v[230:233], v149 offset:2048
	ds_read_b128 v[234:237], v149 offset:3072
	buffer_load_dwordx4 v32, s[76:79], s31 offen lds
	s_mov_b32 m0, s34
	s_nop 0
	buffer_load_dwordx4 v130, s[76:79], s31 offen lds
	s_barrier
	s_waitcnt lgkmcnt(0)
	s_waitcnt lgkmcnt(3)
	v_mfma_f32_16x16x32_bf16 v[94:97], v[190:193], v[222:225], 0
	s_waitcnt lgkmcnt(1)
	v_mfma_f32_16x16x32_bf16 v[90:93], v[190:193], v[230:233], 0
	v_mfma_f32_16x16x32_bf16 v[86:89], v[198:201], v[222:225], 0
	v_mfma_f32_16x16x32_bf16 v[82:85], v[198:201], v[230:233], 0
	v_mfma_f32_16x16x32_bf16 v[78:81], v[206:209], v[222:225], 0
	v_mfma_f32_16x16x32_bf16 v[74:77], v[206:209], v[230:233], 0
	v_mfma_f32_16x16x32_bf16 v[70:73], v[214:217], v[222:225], 0
	v_mfma_f32_16x16x32_bf16 v[66:69], v[214:217], v[230:233], 0
	v_mfma_f32_16x16x32_bf16 v[94:97], v[194:197], v[226:229], v[94:97]
	s_waitcnt lgkmcnt(0)
	v_mfma_f32_16x16x32_bf16 v[90:93], v[194:197], v[234:237], v[90:93]
	v_mfma_f32_16x16x32_bf16 v[86:89], v[202:205], v[226:229], v[86:89]
	v_mfma_f32_16x16x32_bf16 v[82:85], v[202:205], v[234:237], v[82:85]
	v_mfma_f32_16x16x32_bf16 v[78:81], v[210:213], v[226:229], v[78:81]
	v_mfma_f32_16x16x32_bf16 v[74:77], v[210:213], v[234:237], v[74:77]
	v_mfma_f32_16x16x32_bf16 v[70:73], v[218:221], v[226:229], v[70:73]
	v_mfma_f32_16x16x32_bf16 v[66:69], v[218:221], v[234:237], v[66:69]
	v_readfirstlane_b32 s34, v136
	s_add_i32 s31, s29, 0x100
	s_mov_b32 m0, s34
	v_readfirstlane_b32 s34, v135
	s_barrier
	ds_read_b128 v[190:193], v143 offset:16384
	ds_read_b128 v[194:197], v143 offset:17408
	ds_read_b128 v[198:201], v142 offset:16384
	ds_read_b128 v[202:205], v142 offset:17408
	ds_read_b128 v[206:209], v141 offset:16384
	ds_read_b128 v[210:213], v141 offset:17408
	ds_read_b128 v[214:217], v140 offset:16384
	ds_read_b128 v[218:221], v140 offset:17408
	buffer_load_dwordx4 v32, s[4:7], s31 offen lds
	s_mov_b32 m0, s34
	s_nop 0
	buffer_load_dwordx4 v130, s[4:7], s31 offen lds
	s_barrier
	s_waitcnt lgkmcnt(0)
	s_waitcnt lgkmcnt(7)
	v_mfma_f32_16x16x32_bf16 v[62:65], v[190:193], v[156:159], 0
	v_mfma_f32_16x16x32_bf16 v[58:61], v[190:193], v[170:173], 0
	s_waitcnt lgkmcnt(5)
	v_mfma_f32_16x16x32_bf16 v[54:57], v[198:201], v[156:159], 0
	v_mfma_f32_16x16x32_bf16 v[50:53], v[198:201], v[170:173], 0
	s_waitcnt lgkmcnt(3)
	v_mfma_f32_16x16x32_bf16 v[46:49], v[206:209], v[156:159], 0
	v_mfma_f32_16x16x32_bf16 v[42:45], v[206:209], v[170:173], 0
	s_waitcnt lgkmcnt(1)
	v_mfma_f32_16x16x32_bf16 v[38:41], v[214:217], v[156:159], 0
	v_mfma_f32_16x16x32_bf16 v[34:37], v[214:217], v[170:173], 0
	v_mfma_f32_16x16x32_bf16 v[62:65], v[194:197], v[166:169], v[62:65]
	v_mfma_f32_16x16x32_bf16 v[58:61], v[194:197], v[186:189], v[58:61]
	v_mfma_f32_16x16x32_bf16 v[54:57], v[202:205], v[166:169], v[54:57]
	v_mfma_f32_16x16x32_bf16 v[50:53], v[202:205], v[186:189], v[50:53]
	v_mfma_f32_16x16x32_bf16 v[46:49], v[210:213], v[166:169], v[46:49]
	v_mfma_f32_16x16x32_bf16 v[42:45], v[210:213], v[186:189], v[42:45]
	s_waitcnt lgkmcnt(0)
	v_mfma_f32_16x16x32_bf16 v[38:41], v[218:221], v[166:169], v[38:41]
	v_mfma_f32_16x16x32_bf16 v[34:37], v[218:221], v[186:189], v[34:37]
	s_barrier
	v_readfirstlane_b32 s34, v134
	s_add_i32 s31, s30, 0x40100
	s_mov_b32 m0, s34
	v_readfirstlane_b32 s34, v138
	buffer_load_dwordx4 v32, s[76:79], s31 offen lds
	s_mov_b32 m0, s34
	s_nop 0
	buffer_load_dwordx4 v130, s[76:79], s31 offen lds
	s_waitcnt vmcnt(6)
	s_barrier
; #define STAGE(P, BASE, br, kt) do { int _so = ((br) * K + (kt) * BK) * 2; \
;     __builtin_amdgcn_raw_ptr_buffer_load_lds(rs_##BASE, (__attribute__((address_space(3))) void*)((char*)(P) + tx * 16), 16, voff0, _so, 0, 0); \
;     __builtin_amdgcn_raw_ptr_buffer_load_lds(rs_##BASE, (__attribute__((address_space(3))) void*)((char*)(P) + tx * 16 + 8192), 16, voff1, _so, 0, 0); } while (0)
; #define LDA(dst, b, h) _Pragma("unroll") for (int m = 0; m < 4; ++m) _Pragma("unroll") for (int k = 0; k < 2; ++k) \
;     dst[m][k] = *reinterpret_cast<const bf16x8*>((char*)SA(b, h) + lds_byte(wr * 64 + m * 16 + fr, k * 32 + fq * 8))
; #define LDB(dst, b, h) _Pragma("unroll") for (int n = 0; n < 2; ++n) _Pragma("unroll") for (int k = 0; k < 2; ++k) \
;     dst[n][k] = *reinterpret_cast<const bf16x8*>((char*)SB(b, h) + lds_byte(wc * 32 + n * 16 + fr, k * 32 + fq * 8))
; #define MMA(ai, bj, At, Bt_) do { __builtin_amdgcn_s_setprio(1); \
;     _Pragma("unroll") for (int m = 0; m < 4; ++m) _Pragma("unroll") for (int n = 0; n < 2; ++n) _Pragma("unroll") for (int k = 0; k < 2; ++k) \
;       acc[ai][bj][m][n] = __builtin_amdgcn_mfma_f32_16x16x32_bf16(At[m][k], Bt_[n][k], acc[ai][bj][m][n], 0, 0, 0); \
;     __builtin_amdgcn_s_setprio(0); } while (0)
; #define WAIT_V(n) asm volatile("s_waitcnt vmcnt(" #n ")" ::: "memory")
; #define WAIT_L(n) asm volatile("s_waitcnt lgkmcnt(" #n ")" ::: "memory")
; #define BAR __builtin_amdgcn_s_barrier()
; #define SCHED __builtin_amdgcn_sched_barrier(0)
; template <class Epi> ...
;     ...
;     WAIT_V(6); BAR; MMA(1, 1, At, B1); BAR;
;     LDB(B0, 1, 0); SCHED; LDA(At, 1, 0); STAGE(SA(0, 1), A, brow + HALF, t + 2);
;     WAIT_L(8); BAR; WAIT_L(0); MMA(0, 0, At, B0); BAR; SCHED;
;     LDB(B1, 1, 1); STAGE(SB(1, 0), Bt, bcol, t + 3);
;     BAR; WAIT_L(0); MMA(0, 1, At, B1); BAR;
;     LDA(At, 1, 1); STAGE(SA(1, 0), A, brow, t + 3);
	v_mfma_f32_16x16x32_bf16 v[28:31], v[190:193], v[222:225], 0
	v_mfma_f32_16x16x32_bf16 v[24:27], v[190:193], v[230:233], 0
	v_mfma_f32_16x16x32_bf16 v[20:23], v[198:201], v[222:225], 0
	v_mfma_f32_16x16x32_bf16 v[16:19], v[198:201], v[230:233], 0
	v_mfma_f32_16x16x32_bf16 v[12:15], v[206:209], v[222:225], 0
	v_mfma_f32_16x16x32_bf16 v[8:11], v[206:209], v[230:233], 0
	v_mfma_f32_16x16x32_bf16 v[4:7], v[214:217], v[222:225], 0
	v_mfma_f32_16x16x32_bf16 v[0:3], v[214:217], v[230:233], 0
	v_mfma_f32_16x16x32_bf16 v[28:31], v[194:197], v[226:229], v[28:31]
	v_mfma_f32_16x16x32_bf16 v[24:27], v[194:197], v[234:237], v[24:27]
	v_mfma_f32_16x16x32_bf16 v[20:23], v[202:205], v[226:229], v[20:23]
	v_mfma_f32_16x16x32_bf16 v[16:19], v[202:205], v[234:237], v[16:19]
	v_mfma_f32_16x16x32_bf16 v[12:15], v[210:213], v[226:229], v[12:15]
	v_mfma_f32_16x16x32_bf16 v[8:11], v[210:213], v[234:237], v[8:11]
	v_mfma_f32_16x16x32_bf16 v[4:7], v[218:221], v[226:229], v[4:7]
	v_mfma_f32_16x16x32_bf16 v[0:3], v[218:221], v[234:237], v[0:3]
	s_barrier
	ds_read_b128 v[156:159], v145
	ds_read_b128 v[166:169], v145 offset:1024
	ds_read_b128 v[170:173], v145 offset:2048
	ds_read_b128 v[186:189], v145 offset:3072
	v_readfirstlane_b32 s34, v132
	s_add_i32 s31, s29, 0x40100
	s_mov_b32 m0, s34
	v_readfirstlane_b32 s34, v131
	ds_read_b128 v[190:193], v143 offset:32768
	ds_read_b128 v[194:197], v143 offset:33792
	ds_read_b128 v[198:201], v142 offset:32768
	ds_read_b128 v[202:205], v142 offset:33792
	ds_read_b128 v[206:209], v141 offset:32768
	ds_read_b128 v[210:213], v141 offset:33792
	ds_read_b128 v[214:217], v140 offset:32768
	ds_read_b128 v[218:221], v140 offset:33792
	buffer_load_dwordx4 v32, s[4:7], s31 offen lds
	s_mov_b32 m0, s34
	s_nop 0
	buffer_load_dwordx4 v130, s[4:7], s31 offen lds
	s_waitcnt lgkmcnt(8)
	s_barrier
	s_waitcnt lgkmcnt(0)
	s_waitcnt lgkmcnt(7)
	v_mfma_f32_16x16x32_bf16 v[126:129], v[190:193], v[156:159], v[126:129]
	v_mfma_f32_16x16x32_bf16 v[122:125], v[190:193], v[170:173], v[122:125]
	s_waitcnt lgkmcnt(5)
	v_mfma_f32_16x16x32_bf16 v[118:121], v[198:201], v[156:159], v[118:121]
	v_mfma_f32_16x16x32_bf16 v[114:117], v[198:201], v[170:173], v[114:117]
	s_waitcnt lgkmcnt(3)
	v_mfma_f32_16x16x32_bf16 v[110:113], v[206:209], v[156:159], v[110:113]
	v_mfma_f32_16x16x32_bf16 v[106:109], v[206:209], v[170:173], v[106:109]
	s_waitcnt lgkmcnt(1)
	v_mfma_f32_16x16x32_bf16 v[102:105], v[214:217], v[156:159], v[102:105]
	v_mfma_f32_16x16x32_bf16 v[98:101], v[214:217], v[170:173], v[98:101]
	v_mfma_f32_16x16x32_bf16 v[126:129], v[194:197], v[166:169], v[126:129]
	v_mfma_f32_16x16x32_bf16 v[122:125], v[194:197], v[186:189], v[122:125]
	v_mfma_f32_16x16x32_bf16 v[118:121], v[202:205], v[166:169], v[118:121]
	v_mfma_f32_16x16x32_bf16 v[114:117], v[202:205], v[186:189], v[114:117]
	v_mfma_f32_16x16x32_bf16 v[110:113], v[210:213], v[166:169], v[110:113]
	v_mfma_f32_16x16x32_bf16 v[106:109], v[210:213], v[186:189], v[106:109]
	s_waitcnt lgkmcnt(0)
	v_mfma_f32_16x16x32_bf16 v[102:105], v[218:221], v[166:169], v[102:105]
	v_mfma_f32_16x16x32_bf16 v[98:101], v[218:221], v[186:189], v[98:101]
	s_barrier
	v_readfirstlane_b32 s34, v146
	s_add_i32 s31, s30, 0x180
	s_mov_b32 m0, s34
	v_readfirstlane_b32 s34, v147
	ds_read_b128 v[222:225], v144
	ds_read_b128 v[226:229], v144 offset:1024
	ds_read_b128 v[230:233], v144 offset:2048
	ds_read_b128 v[234:237], v144 offset:3072
	buffer_load_dwordx4 v32, s[76:79], s31 offen lds
	s_mov_b32 m0, s34
	s_nop 0
	buffer_load_dwordx4 v130, s[76:79], s31 offen lds
	s_barrier
	s_waitcnt lgkmcnt(0)
	s_waitcnt lgkmcnt(3)
	v_mfma_f32_16x16x32_bf16 v[94:97], v[190:193], v[222:225], v[94:97]
	s_waitcnt lgkmcnt(1)
	v_mfma_f32_16x16x32_bf16 v[90:93], v[190:193], v[230:233], v[90:93]
	v_mfma_f32_16x16x32_bf16 v[86:89], v[198:201], v[222:225], v[86:89]
	v_mfma_f32_16x16x32_bf16 v[82:85], v[198:201], v[230:233], v[82:85]
	v_mfma_f32_16x16x32_bf16 v[78:81], v[206:209], v[222:225], v[78:81]
	v_mfma_f32_16x16x32_bf16 v[74:77], v[206:209], v[230:233], v[74:77]
	v_mfma_f32_16x16x32_bf16 v[70:73], v[214:217], v[222:225], v[70:73]
	v_mfma_f32_16x16x32_bf16 v[66:69], v[214:217], v[230:233], v[66:69]
	v_mfma_f32_16x16x32_bf16 v[94:97], v[194:197], v[226:229], v[94:97]
	s_waitcnt lgkmcnt(0)
	v_mfma_f32_16x16x32_bf16 v[90:93], v[194:197], v[234:237], v[90:93]
	v_mfma_f32_16x16x32_bf16 v[86:89], v[202:205], v[226:229], v[86:89]
	v_mfma_f32_16x16x32_bf16 v[82:85], v[202:205], v[234:237], v[82:85]
	v_mfma_f32_16x16x32_bf16 v[78:81], v[210:213], v[226:229], v[78:81]
	v_mfma_f32_16x16x32_bf16 v[74:77], v[210:213], v[234:237], v[74:77]
	v_mfma_f32_16x16x32_bf16 v[70:73], v[218:221], v[226:229], v[70:73]
	v_mfma_f32_16x16x32_bf16 v[66:69], v[218:221], v[234:237], v[66:69]
	v_readfirstlane_b32 s31, v148
	s_addk_i32 s29, 0x180
	s_mov_b32 m0, s31
	v_readfirstlane_b32 s31, v150
	s_barrier
	ds_read_b128 v[190:193], v143 offset:49152
	ds_read_b128 v[194:197], v143 offset:50176
	ds_read_b128 v[198:201], v142 offset:49152
	ds_read_b128 v[202:205], v142 offset:50176
	ds_read_b128 v[206:209], v141 offset:49152
	ds_read_b128 v[210:213], v141 offset:50176
	ds_read_b128 v[214:217], v140 offset:49152
	ds_read_b128 v[218:221], v140 offset:50176
	buffer_load_dwordx4 v32, s[4:7], s29 offen lds
	s_mov_b32 m0, s31
	s_nop 0
	buffer_load_dwordx4 v130, s[4:7], s29 offen lds
	s_barrier
; #define STAGE(P, BASE, br, kt) do { int _so = ((br) * K + (kt) * BK) * 2; \
;     __builtin_amdgcn_raw_ptr_buffer_load_lds(rs_##BASE, (__attribute__((address_space(3))) void*)((char*)(P) + tx * 16), 16, voff0, _so, 0, 0); \
;     __builtin_amdgcn_raw_ptr_buffer_load_lds(rs_##BASE, (__attribute__((address_space(3))) void*)((char*)(P) + tx * 16 + 8192), 16, voff1, _so, 0, 0); } while (0)
; #define LDA(dst, b, h) _Pragma("unroll") for (int m = 0; m < 4; ++m) _Pragma("unroll") for (int k = 0; k < 2; ++k) \
;     dst[m][k] = *reinterpret_cast<const bf16x8*>((char*)SA(b, h) + lds_byte(wr * 64 + m * 16 + fr, k * 32 + fq * 8))
; #define LDB(dst, b, h) _Pragma("unroll") for (int n = 0; n < 2; ++n) _Pragma("unroll") for (int k = 0; k < 2; ++k) \
;     dst[n][k] = *reinterpret_cast<const bf16x8*>((char*)SB(b, h) + lds_byte(wc * 32 + n * 16 + fr, k * 32 + fq * 8))
; #define MMA(ai, bj, At, Bt_) do { __builtin_amdgcn_s_setprio(1); \
;     _Pragma("unroll") for (int m = 0; m < 4; ++m) _Pragma("unroll") for (int n = 0; n < 2; ++n) _Pragma("unroll") for (int k = 0; k < 2; ++k) \
;       acc[ai][bj][m][n] = __builtin_amdgcn_mfma_f32_16x16x32_bf16(At[m][k], Bt_[n][k], acc[ai][bj][m][n], 0, 0, 0); \
;     __builtin_amdgcn_s_setprio(0); } while (0)
; #define WAIT_V(n) asm volatile("s_waitcnt vmcnt(" #n ")" ::: "memory")
; #define WAIT_L(n) asm volatile("s_waitcnt lgkmcnt(" #n ")" ::: "memory")
; #define BAR __builtin_amdgcn_s_barrier()
; #define SCHED __builtin_amdgcn_sched_barrier(0)
; template <class Epi> ...
;     ...
;   for (int t = 0; t < nt - 2; t += 2) {
;     LDB(B0, 0, 0); SCHED; LDA(At, 0, 0); STAGE(SA(1, 1), A, brow + HALF, t + 1);
;     WAIT_L(8); BAR; WAIT_L(0); MMA(0, 0, At, B0); BAR; SCHED;
;     LDB(B1, 0, 1); STAGE(SB(0, 0), Bt, bcol, t + 2);
;     ...
;     BAR; WAIT_L(0); MMA(1, 0, At, B0); BAR; SCHED;
;     STAGE(SB(1, 1), Bt, bcol + HALF, t + 3);
;     WAIT_V(6); BAR; MMA(1, 1, At, B1); BAR;
;   }
	s_waitcnt lgkmcnt(0)
	s_waitcnt lgkmcnt(7)
	v_mfma_f32_16x16x32_bf16 v[62:65], v[190:193], v[156:159], v[62:65]
	v_mfma_f32_16x16x32_bf16 v[58:61], v[190:193], v[170:173], v[58:61]
	s_waitcnt lgkmcnt(5)
	v_mfma_f32_16x16x32_bf16 v[54:57], v[198:201], v[156:159], v[54:57]
	v_mfma_f32_16x16x32_bf16 v[50:53], v[198:201], v[170:173], v[50:53]
	s_waitcnt lgkmcnt(3)
	v_mfma_f32_16x16x32_bf16 v[46:49], v[206:209], v[156:159], v[46:49]
	v_mfma_f32_16x16x32_bf16 v[42:45], v[206:209], v[170:173], v[42:45]
	s_waitcnt lgkmcnt(1)
	v_mfma_f32_16x16x32_bf16 v[38:41], v[214:217], v[156:159], v[38:41]
	v_mfma_f32_16x16x32_bf16 v[34:37], v[214:217], v[170:173], v[34:37]
	v_mfma_f32_16x16x32_bf16 v[62:65], v[194:197], v[166:169], v[62:65]
	v_mfma_f32_16x16x32_bf16 v[58:61], v[194:197], v[186:189], v[58:61]
	v_mfma_f32_16x16x32_bf16 v[54:57], v[202:205], v[166:169], v[54:57]
	v_mfma_f32_16x16x32_bf16 v[50:53], v[202:205], v[186:189], v[50:53]
	v_mfma_f32_16x16x32_bf16 v[46:49], v[210:213], v[166:169], v[46:49]
	v_mfma_f32_16x16x32_bf16 v[42:45], v[210:213], v[186:189], v[42:45]
	s_waitcnt lgkmcnt(0)
	v_mfma_f32_16x16x32_bf16 v[38:41], v[218:221], v[166:169], v[38:41]
	v_mfma_f32_16x16x32_bf16 v[34:37], v[218:221], v[186:189], v[34:37]
	s_barrier
	v_readfirstlane_b32 s29, v153
	s_add_i32 s30, s30, 0x40180
	s_mov_b32 m0, s29
	v_readfirstlane_b32 s29, v154
	buffer_load_dwordx4 v32, s[76:79], s30 offen lds
	s_mov_b32 m0, s29
	s_nop 0
	buffer_load_dwordx4 v130, s[76:79], s30 offen lds
	s_waitcnt vmcnt(6)
	s_barrier
	v_mfma_f32_16x16x32_bf16 v[28:31], v[190:193], v[222:225], v[28:31]
	v_mfma_f32_16x16x32_bf16 v[24:27], v[190:193], v[230:233], v[24:27]
	v_mfma_f32_16x16x32_bf16 v[20:23], v[198:201], v[222:225], v[20:23]
	v_mfma_f32_16x16x32_bf16 v[16:19], v[198:201], v[230:233], v[16:19]
	v_mfma_f32_16x16x32_bf16 v[12:15], v[206:209], v[222:225], v[12:15]
	v_mfma_f32_16x16x32_bf16 v[8:11], v[206:209], v[230:233], v[8:11]
	v_mfma_f32_16x16x32_bf16 v[4:7], v[214:217], v[222:225], v[4:7]
	v_mfma_f32_16x16x32_bf16 v[0:3], v[214:217], v[230:233], v[0:3]
	v_mfma_f32_16x16x32_bf16 v[28:31], v[194:197], v[226:229], v[28:31]
	v_mfma_f32_16x16x32_bf16 v[24:27], v[194:197], v[234:237], v[24:27]
	v_mfma_f32_16x16x32_bf16 v[20:23], v[202:205], v[226:229], v[20:23]
	v_mfma_f32_16x16x32_bf16 v[16:19], v[202:205], v[234:237], v[16:19]
	v_mfma_f32_16x16x32_bf16 v[12:15], v[210:213], v[226:229], v[12:15]
	v_mfma_f32_16x16x32_bf16 v[8:11], v[210:213], v[234:237], v[8:11]
	v_mfma_f32_16x16x32_bf16 v[4:7], v[218:221], v[226:229], v[4:7]
	v_mfma_f32_16x16x32_bf16 v[0:3], v[218:221], v[234:237], v[0:3]
	s_add_i32 s27, s27, 2
	s_addk_i32 s28, 0x100
	s_cmp_lt_u32 s27, 12
	s_barrier
	s_cbranch_scc1 .LBB0_1682
	s_branch .Lpx3
.LBB0_1682:
	ds_read_b128 v[156:159], v155
	ds_read_b128 v[166:169], v155 offset:1024
	ds_read_b128 v[170:173], v155 offset:2048
	ds_read_b128 v[186:189], v155 offset:3072
	s_add_i32 s29, s19, s28
	v_readfirstlane_b32 s31, v152
	s_add_i32 s30, s29, 0x40080
	s_mov_b32 m0, s31
	v_readfirstlane_b32 s31, v151
	ds_read_b128 v[190:193], v143
	ds_read_b128 v[194:197], v143 offset:1024
	ds_read_b128 v[198:201], v142
	ds_read_b128 v[202:205], v142 offset:1024
	ds_read_b128 v[206:209], v141
	ds_read_b128 v[210:213], v141 offset:1024
	ds_read_b128 v[214:217], v140
	ds_read_b128 v[218:221], v140 offset:1024
	buffer_load_dwordx4 v32, s[4:7], s30 offen lds
	s_mov_b32 m0, s31
	s_nop 0
	buffer_load_dwordx4 v130, s[4:7], s30 offen lds
	s_waitcnt lgkmcnt(8)
	s_barrier
	s_waitcnt lgkmcnt(0)
	s_waitcnt lgkmcnt(7)
	v_mfma_f32_16x16x32_bf16 v[126:129], v[190:193], v[156:159], v[126:129]
	v_mfma_f32_16x16x32_bf16 v[122:125], v[190:193], v[170:173], v[122:125]
	s_waitcnt lgkmcnt(5)
	v_mfma_f32_16x16x32_bf16 v[118:121], v[198:201], v[156:159], v[118:121]
	v_mfma_f32_16x16x32_bf16 v[114:117], v[198:201], v[170:173], v[114:117]
	s_waitcnt lgkmcnt(3)
	v_mfma_f32_16x16x32_bf16 v[110:113], v[206:209], v[156:159], v[110:113]
	v_mfma_f32_16x16x32_bf16 v[106:109], v[206:209], v[170:173], v[106:109]
	s_waitcnt lgkmcnt(1)
	v_mfma_f32_16x16x32_bf16 v[102:105], v[214:217], v[156:159], v[102:105]
	v_mfma_f32_16x16x32_bf16 v[98:101], v[214:217], v[170:173], v[98:101]
	v_mfma_f32_16x16x32_bf16 v[126:129], v[194:197], v[166:169], v[126:129]
	v_mfma_f32_16x16x32_bf16 v[122:125], v[194:197], v[186:189], v[122:125]
	v_mfma_f32_16x16x32_bf16 v[118:121], v[202:205], v[166:169], v[118:121]
	v_mfma_f32_16x16x32_bf16 v[114:117], v[202:205], v[186:189], v[114:117]
	v_mfma_f32_16x16x32_bf16 v[110:113], v[210:213], v[166:169], v[110:113]
	v_mfma_f32_16x16x32_bf16 v[106:109], v[210:213], v[186:189], v[106:109]
	s_waitcnt lgkmcnt(0)
	v_mfma_f32_16x16x32_bf16 v[102:105], v[218:221], v[166:169], v[102:105]
	v_mfma_f32_16x16x32_bf16 v[98:101], v[218:221], v[186:189], v[98:101]
	s_barrier
	s_add_i32 s30, s18, s28
	v_readfirstlane_b32 s34, v137
	s_add_i32 s31, s30, 0x100
	s_mov_b32 m0, s34
	v_readfirstlane_b32 s34, v139
	ds_read_b128 v[222:225], v149
	ds_read_b128 v[226:229], v149 offset:1024
	ds_read_b128 v[230:233], v149 offset:2048
	ds_read_b128 v[234:237], v149 offset:3072
	buffer_load_dwordx4 v32, s[76:79], s31 offen lds
	s_mov_b32 m0, s34
	s_nop 0
	buffer_load_dwordx4 v130, s[76:79], s31 offen lds
	s_barrier
; #define STAGE(P, BASE, br, kt) do { int _so = ((br) * K + (kt) * BK) * 2; \
;     __builtin_amdgcn_raw_ptr_buffer_load_lds(rs_##BASE, (__attribute__((address_space(3))) void*)((char*)(P) + tx * 16), 16, voff0, _so, 0, 0); \
;     __builtin_amdgcn_raw_ptr_buffer_load_lds(rs_##BASE, (__attribute__((address_space(3))) void*)((char*)(P) + tx * 16 + 8192), 16, voff1, _so, 0, 0); } while (0)
; #define LDA(dst, b, h) _Pragma("unroll") for (int m = 0; m < 4; ++m) _Pragma("unroll") for (int k = 0; k < 2; ++k) \
;     dst[m][k] = *reinterpret_cast<const bf16x8*>((char*)SA(b, h) + lds_byte(wr * 64 + m * 16 + fr, k * 32 + fq * 8))
; #define LDB(dst, b, h) _Pragma("unroll") for (int n = 0; n < 2; ++n) _Pragma("unroll") for (int k = 0; k < 2; ++k) \
;     dst[n][k] = *reinterpret_cast<const bf16x8*>((char*)SB(b, h) + lds_byte(wc * 32 + n * 16 + fr, k * 32 + fq * 8))
; #define MMA(ai, bj, At, Bt_) do { __builtin_amdgcn_s_setprio(1); \
;     _Pragma("unroll") for (int m = 0; m < 4; ++m) _Pragma("unroll") for (int n = 0; n < 2; ++n) _Pragma("unroll") for (int k = 0; k < 2; ++k) \
;       acc[ai][bj][m][n] = __builtin_amdgcn_mfma_f32_16x16x32_bf16(At[m][k], Bt_[n][k], acc[ai][bj][m][n], 0, 0, 0); \
;     __builtin_amdgcn_s_setprio(0); } while (0)
; #define WAIT_V(n) asm volatile("s_waitcnt vmcnt(" #n ")" ::: "memory")
; #define WAIT_L(n) asm volatile("s_waitcnt lgkmcnt(" #n ")" ::: "memory")
; #define BAR __builtin_amdgcn_s_barrier()
; #define SCHED __builtin_amdgcn_sched_barrier(0)
; template <class Epi> ...
;     ...
;     BAR; WAIT_L(0); MMA(0, 1, At, B1); BAR;
;     LDA(At, 0, 1); STAGE(SA(0, 0), A, brow, t + 2);
;     BAR; WAIT_L(0); MMA(1, 0, At, B0); BAR; SCHED;
;     STAGE(SB(0, 1), Bt, bcol + HALF, t + 2);
;     WAIT_V(6); BAR; MMA(1, 1, At, B1); BAR;
;     LDB(B0, 1, 0); SCHED; LDA(At, 1, 0); STAGE(SA(0, 1), A, brow + HALF, t + 2);
	s_waitcnt lgkmcnt(0)
	s_waitcnt lgkmcnt(3)
	v_mfma_f32_16x16x32_bf16 v[94:97], v[190:193], v[222:225], v[94:97]
	s_waitcnt lgkmcnt(1)
	v_mfma_f32_16x16x32_bf16 v[90:93], v[190:193], v[230:233], v[90:93]
	v_mfma_f32_16x16x32_bf16 v[86:89], v[198:201], v[222:225], v[86:89]
	v_mfma_f32_16x16x32_bf16 v[82:85], v[198:201], v[230:233], v[82:85]
	v_mfma_f32_16x16x32_bf16 v[78:81], v[206:209], v[222:225], v[78:81]
	v_mfma_f32_16x16x32_bf16 v[74:77], v[206:209], v[230:233], v[74:77]
	v_mfma_f32_16x16x32_bf16 v[70:73], v[214:217], v[222:225], v[70:73]
	v_mfma_f32_16x16x32_bf16 v[66:69], v[214:217], v[230:233], v[66:69]
	v_mfma_f32_16x16x32_bf16 v[94:97], v[194:197], v[226:229], v[94:97]
	s_waitcnt lgkmcnt(0)
	v_mfma_f32_16x16x32_bf16 v[90:93], v[194:197], v[234:237], v[90:93]
	v_mfma_f32_16x16x32_bf16 v[86:89], v[202:205], v[226:229], v[86:89]
	v_mfma_f32_16x16x32_bf16 v[82:85], v[202:205], v[234:237], v[82:85]
	v_mfma_f32_16x16x32_bf16 v[78:81], v[210:213], v[226:229], v[78:81]
	v_mfma_f32_16x16x32_bf16 v[74:77], v[210:213], v[234:237], v[74:77]
	v_mfma_f32_16x16x32_bf16 v[70:73], v[218:221], v[226:229], v[70:73]
	v_mfma_f32_16x16x32_bf16 v[66:69], v[218:221], v[234:237], v[66:69]
	v_readfirstlane_b32 s34, v136
	s_add_i32 s31, s29, 0x100
	s_mov_b32 m0, s34
	v_readfirstlane_b32 s34, v135
	s_barrier
	ds_read_b128 v[190:193], v143 offset:16384
	ds_read_b128 v[194:197], v143 offset:17408
	ds_read_b128 v[198:201], v142 offset:16384
	ds_read_b128 v[202:205], v142 offset:17408
	ds_read_b128 v[206:209], v141 offset:16384
	ds_read_b128 v[210:213], v141 offset:17408
	ds_read_b128 v[214:217], v140 offset:16384
	ds_read_b128 v[218:221], v140 offset:17408
	buffer_load_dwordx4 v32, s[4:7], s31 offen lds
	s_mov_b32 m0, s34
	s_nop 0
	buffer_load_dwordx4 v130, s[4:7], s31 offen lds
	s_barrier
	s_waitcnt lgkmcnt(0)
	s_waitcnt lgkmcnt(7)
	v_mfma_f32_16x16x32_bf16 v[62:65], v[190:193], v[156:159], v[62:65]
	v_mfma_f32_16x16x32_bf16 v[58:61], v[190:193], v[170:173], v[58:61]
	s_waitcnt lgkmcnt(5)
	v_mfma_f32_16x16x32_bf16 v[54:57], v[198:201], v[156:159], v[54:57]
	v_mfma_f32_16x16x32_bf16 v[50:53], v[198:201], v[170:173], v[50:53]
	s_waitcnt lgkmcnt(3)
	v_mfma_f32_16x16x32_bf16 v[46:49], v[206:209], v[156:159], v[46:49]
	v_mfma_f32_16x16x32_bf16 v[42:45], v[206:209], v[170:173], v[42:45]
	s_waitcnt lgkmcnt(1)
	v_mfma_f32_16x16x32_bf16 v[38:41], v[214:217], v[156:159], v[38:41]
	v_mfma_f32_16x16x32_bf16 v[34:37], v[214:217], v[170:173], v[34:37]
	v_mfma_f32_16x16x32_bf16 v[62:65], v[194:197], v[166:169], v[62:65]
	v_mfma_f32_16x16x32_bf16 v[58:61], v[194:197], v[186:189], v[58:61]
	v_mfma_f32_16x16x32_bf16 v[54:57], v[202:205], v[166:169], v[54:57]
	v_mfma_f32_16x16x32_bf16 v[50:53], v[202:205], v[186:189], v[50:53]
	v_mfma_f32_16x16x32_bf16 v[46:49], v[210:213], v[166:169], v[46:49]
	v_mfma_f32_16x16x32_bf16 v[42:45], v[210:213], v[186:189], v[42:45]
	s_waitcnt lgkmcnt(0)
	v_mfma_f32_16x16x32_bf16 v[38:41], v[218:221], v[166:169], v[38:41]
	v_mfma_f32_16x16x32_bf16 v[34:37], v[218:221], v[186:189], v[34:37]
	s_barrier
	v_readfirstlane_b32 s34, v134
	s_add_i32 s31, s30, 0x40100
	s_mov_b32 m0, s34
	v_readfirstlane_b32 s34, v138
	buffer_load_dwordx4 v32, s[76:79], s31 offen lds
	s_mov_b32 m0, s34
	s_nop 0
	buffer_load_dwordx4 v130, s[76:79], s31 offen lds
	s_waitcnt vmcnt(6)
	s_barrier
	v_mfma_f32_16x16x32_bf16 v[28:31], v[190:193], v[222:225], v[28:31]
	v_mfma_f32_16x16x32_bf16 v[24:27], v[190:193], v[230:233], v[24:27]
	v_mfma_f32_16x16x32_bf16 v[20:23], v[198:201], v[222:225], v[20:23]
	v_mfma_f32_16x16x32_bf16 v[16:19], v[198:201], v[230:233], v[16:19]
	v_mfma_f32_16x16x32_bf16 v[12:15], v[206:209], v[222:225], v[12:15]
	v_mfma_f32_16x16x32_bf16 v[8:11], v[206:209], v[230:233], v[8:11]
	v_mfma_f32_16x16x32_bf16 v[4:7], v[214:217], v[222:225], v[4:7]
	v_mfma_f32_16x16x32_bf16 v[0:3], v[214:217], v[230:233], v[0:3]
	v_mfma_f32_16x16x32_bf16 v[28:31], v[194:197], v[226:229], v[28:31]
	v_mfma_f32_16x16x32_bf16 v[24:27], v[194:197], v[234:237], v[24:27]
	v_mfma_f32_16x16x32_bf16 v[20:23], v[202:205], v[226:229], v[20:23]
	v_mfma_f32_16x16x32_bf16 v[16:19], v[202:205], v[234:237], v[16:19]
	v_mfma_f32_16x16x32_bf16 v[12:15], v[210:213], v[226:229], v[12:15]
	v_mfma_f32_16x16x32_bf16 v[8:11], v[210:213], v[234:237], v[8:11]
	v_mfma_f32_16x16x32_bf16 v[4:7], v[218:221], v[226:229], v[4:7]
	v_mfma_f32_16x16x32_bf16 v[0:3], v[218:221], v[234:237], v[0:3]
	s_barrier
	ds_read_b128 v[156:159], v145
	ds_read_b128 v[166:169], v145 offset:1024
	ds_read_b128 v[170:173], v145 offset:2048
	ds_read_b128 v[186:189], v145 offset:3072
	v_readfirstlane_b32 s34, v132
	s_add_i32 s31, s29, 0x40100
	s_mov_b32 m0, s34
	v_readfirstlane_b32 s34, v131
	ds_read_b128 v[190:193], v143 offset:32768
	ds_read_b128 v[194:197], v143 offset:33792
	ds_read_b128 v[198:201], v142 offset:32768
	ds_read_b128 v[202:205], v142 offset:33792
	ds_read_b128 v[206:209], v141 offset:32768
	ds_read_b128 v[210:213], v141 offset:33792
	ds_read_b128 v[214:217], v140 offset:32768
	ds_read_b128 v[218:221], v140 offset:33792
	buffer_load_dwordx4 v32, s[4:7], s31 offen lds
	s_mov_b32 m0, s34
	s_nop 0
	buffer_load_dwordx4 v130, s[4:7], s31 offen lds
	s_waitcnt lgkmcnt(8)
	s_barrier
; #define STAGE(P, BASE, br, kt) do { int _so = ((br) * K + (kt) * BK) * 2; \
;     __builtin_amdgcn_raw_ptr_buffer_load_lds(rs_##BASE, (__attribute__((address_space(3))) void*)((char*)(P) + tx * 16), 16, voff0, _so, 0, 0); \
;     __builtin_amdgcn_raw_ptr_buffer_load_lds(rs_##BASE, (__attribute__((address_space(3))) void*)((char*)(P) + tx * 16 + 8192), 16, voff1, _so, 0, 0); } while (0)
; #define LDA(dst, b, h) _Pragma("unroll") for (int m = 0; m < 4; ++m) _Pragma("unroll") for (int k = 0; k < 2; ++k) \
;     dst[m][k] = *reinterpret_cast<const bf16x8*>((char*)SA(b, h) + lds_byte(wr * 64 + m * 16 + fr, k * 32 + fq * 8))
; #define LDB(dst, b, h) _Pragma("unroll") for (int n = 0; n < 2; ++n) _Pragma("unroll") for (int k = 0; k < 2; ++k) \
;     dst[n][k] = *reinterpret_cast<const bf16x8*>((char*)SB(b, h) + lds_byte(wc * 32 + n * 16 + fr, k * 32 + fq * 8))
; #define MMA(ai, bj, At, Bt_) do { __builtin_amdgcn_s_setprio(1); \
;     _Pragma("unroll") for (int m = 0; m < 4; ++m) _Pragma("unroll") for (int n = 0; n < 2; ++n) _Pragma("unroll") for (int k = 0; k < 2; ++k) \
;       acc[ai][bj][m][n] = __builtin_amdgcn_mfma_f32_16x16x32_bf16(At[m][k], Bt_[n][k], acc[ai][bj][m][n], 0, 0, 0); \
;     __builtin_amdgcn_s_setprio(0); } while (0)
; #define WAIT_V(n) asm volatile("s_waitcnt vmcnt(" #n ")" ::: "memory")
; #define WAIT_L(n) asm volatile("s_waitcnt lgkmcnt(" #n ")" ::: "memory")
; #define BAR __builtin_amdgcn_s_barrier()
; #define SCHED __builtin_amdgcn_sched_barrier(0)
; template <class Epi> ...
;     ...
;     WAIT_L(8); BAR; WAIT_L(0); MMA(0, 0, At, B0); BAR; SCHED;
;     LDB(B1, 1, 1); STAGE(SB(1, 0), Bt, bcol, t + 3);
;     BAR; WAIT_L(0); MMA(0, 1, At, B1); BAR;
;     LDA(At, 1, 1); STAGE(SA(1, 0), A, brow, t + 3);
;     BAR; WAIT_L(0); MMA(1, 0, At, B0); BAR; SCHED;
;     STAGE(SB(1, 1), Bt, bcol + HALF, t + 3);
;     WAIT_V(6); BAR; MMA(1, 1, At, B1); BAR;
;   }
	s_waitcnt lgkmcnt(0)
	s_waitcnt lgkmcnt(7)
	v_mfma_f32_16x16x32_bf16 v[126:129], v[190:193], v[156:159], v[126:129]
	v_mfma_f32_16x16x32_bf16 v[122:125], v[190:193], v[170:173], v[122:125]
	s_waitcnt lgkmcnt(5)
	v_mfma_f32_16x16x32_bf16 v[118:121], v[198:201], v[156:159], v[118:121]
	v_mfma_f32_16x16x32_bf16 v[114:117], v[198:201], v[170:173], v[114:117]
	s_waitcnt lgkmcnt(3)
	v_mfma_f32_16x16x32_bf16 v[110:113], v[206:209], v[156:159], v[110:113]
	v_mfma_f32_16x16x32_bf16 v[106:109], v[206:209], v[170:173], v[106:109]
	s_waitcnt lgkmcnt(1)
	v_mfma_f32_16x16x32_bf16 v[102:105], v[214:217], v[156:159], v[102:105]
	v_mfma_f32_16x16x32_bf16 v[98:101], v[214:217], v[170:173], v[98:101]
	v_mfma_f32_16x16x32_bf16 v[126:129], v[194:197], v[166:169], v[126:129]
	v_mfma_f32_16x16x32_bf16 v[122:125], v[194:197], v[186:189], v[122:125]
	v_mfma_f32_16x16x32_bf16 v[118:121], v[202:205], v[166:169], v[118:121]
	v_mfma_f32_16x16x32_bf16 v[114:117], v[202:205], v[186:189], v[114:117]
	v_mfma_f32_16x16x32_bf16 v[110:113], v[210:213], v[166:169], v[110:113]
	v_mfma_f32_16x16x32_bf16 v[106:109], v[210:213], v[186:189], v[106:109]
	s_waitcnt lgkmcnt(0)
	v_mfma_f32_16x16x32_bf16 v[102:105], v[218:221], v[166:169], v[102:105]
	v_mfma_f32_16x16x32_bf16 v[98:101], v[218:221], v[186:189], v[98:101]
	s_barrier
	v_readfirstlane_b32 s34, v146
	s_add_i32 s31, s30, 0x180
	s_mov_b32 m0, s34
	v_readfirstlane_b32 s34, v147
	ds_read_b128 v[222:225], v144
	ds_read_b128 v[226:229], v144 offset:1024
	ds_read_b128 v[230:233], v144 offset:2048
	ds_read_b128 v[234:237], v144 offset:3072
	buffer_load_dwordx4 v32, s[76:79], s31 offen lds
	s_mov_b32 m0, s34
	s_nop 0
	buffer_load_dwordx4 v130, s[76:79], s31 offen lds
	s_barrier
	s_waitcnt lgkmcnt(0)
	s_waitcnt lgkmcnt(3)
	v_mfma_f32_16x16x32_bf16 v[94:97], v[190:193], v[222:225], v[94:97]
	s_waitcnt lgkmcnt(1)
	v_mfma_f32_16x16x32_bf16 v[90:93], v[190:193], v[230:233], v[90:93]
	v_mfma_f32_16x16x32_bf16 v[86:89], v[198:201], v[222:225], v[86:89]
	v_mfma_f32_16x16x32_bf16 v[82:85], v[198:201], v[230:233], v[82:85]
	v_mfma_f32_16x16x32_bf16 v[78:81], v[206:209], v[222:225], v[78:81]
	v_mfma_f32_16x16x32_bf16 v[74:77], v[206:209], v[230:233], v[74:77]
	v_mfma_f32_16x16x32_bf16 v[70:73], v[214:217], v[222:225], v[70:73]
	v_mfma_f32_16x16x32_bf16 v[66:69], v[214:217], v[230:233], v[66:69]
	v_mfma_f32_16x16x32_bf16 v[94:97], v[194:197], v[226:229], v[94:97]
	s_waitcnt lgkmcnt(0)
	v_mfma_f32_16x16x32_bf16 v[90:93], v[194:197], v[234:237], v[90:93]
	v_mfma_f32_16x16x32_bf16 v[86:89], v[202:205], v[226:229], v[86:89]
	v_mfma_f32_16x16x32_bf16 v[82:85], v[202:205], v[234:237], v[82:85]
	v_mfma_f32_16x16x32_bf16 v[78:81], v[210:213], v[226:229], v[78:81]
	v_mfma_f32_16x16x32_bf16 v[74:77], v[210:213], v[234:237], v[74:77]
	v_mfma_f32_16x16x32_bf16 v[70:73], v[218:221], v[226:229], v[70:73]
	v_mfma_f32_16x16x32_bf16 v[66:69], v[218:221], v[234:237], v[66:69]
	v_readfirstlane_b32 s31, v148
	s_addk_i32 s29, 0x180
	s_mov_b32 m0, s31
	v_readfirstlane_b32 s31, v150
	s_barrier
	ds_read_b128 v[190:193], v143 offset:49152
	ds_read_b128 v[194:197], v143 offset:50176
	ds_read_b128 v[198:201], v142 offset:49152
	ds_read_b128 v[202:205], v142 offset:50176
	ds_read_b128 v[206:209], v141 offset:49152
	ds_read_b128 v[210:213], v141 offset:50176
	ds_read_b128 v[214:217], v140 offset:49152
	ds_read_b128 v[218:221], v140 offset:50176
	buffer_load_dwordx4 v32, s[4:7], s29 offen lds
	s_mov_b32 m0, s31
	s_nop 0
	buffer_load_dwordx4 v130, s[4:7], s29 offen lds
	s_barrier
	s_waitcnt lgkmcnt(0)
	s_waitcnt lgkmcnt(7)
	v_mfma_f32_16x16x32_bf16 v[62:65], v[190:193], v[156:159], v[62:65]
	v_mfma_f32_16x16x32_bf16 v[58:61], v[190:193], v[170:173], v[58:61]
	s_waitcnt lgkmcnt(5)
	v_mfma_f32_16x16x32_bf16 v[54:57], v[198:201], v[156:159], v[54:57]
	v_mfma_f32_16x16x32_bf16 v[50:53], v[198:201], v[170:173], v[50:53]
	s_waitcnt lgkmcnt(3)
	v_mfma_f32_16x16x32_bf16 v[46:49], v[206:209], v[156:159], v[46:49]
	v_mfma_f32_16x16x32_bf16 v[42:45], v[206:209], v[170:173], v[42:45]
	s_waitcnt lgkmcnt(1)
	v_mfma_f32_16x16x32_bf16 v[38:41], v[214:217], v[156:159], v[38:41]
	v_mfma_f32_16x16x32_bf16 v[34:37], v[214:217], v[170:173], v[34:37]
	v_mfma_f32_16x16x32_bf16 v[62:65], v[194:197], v[166:169], v[62:65]
	v_mfma_f32_16x16x32_bf16 v[58:61], v[194:197], v[186:189], v[58:61]
	v_mfma_f32_16x16x32_bf16 v[54:57], v[202:205], v[166:169], v[54:57]
	v_mfma_f32_16x16x32_bf16 v[50:53], v[202:205], v[186:189], v[50:53]
	v_mfma_f32_16x16x32_bf16 v[46:49], v[210:213], v[166:169], v[46:49]
	v_mfma_f32_16x16x32_bf16 v[42:45], v[210:213], v[186:189], v[42:45]
	s_waitcnt lgkmcnt(0)
	v_mfma_f32_16x16x32_bf16 v[38:41], v[218:221], v[166:169], v[38:41]
	v_mfma_f32_16x16x32_bf16 v[34:37], v[218:221], v[186:189], v[34:37]
	s_barrier
	v_readfirstlane_b32 s29, v153
	s_add_i32 s30, s30, 0x40180
	s_mov_b32 m0, s29
	v_readfirstlane_b32 s29, v154
	buffer_load_dwordx4 v32, s[76:79], s30 offen lds
	s_mov_b32 m0, s29
	s_nop 0
	buffer_load_dwordx4 v130, s[76:79], s30 offen lds
	s_waitcnt vmcnt(6)
	s_barrier
	v_mfma_f32_16x16x32_bf16 v[28:31], v[190:193], v[222:225], v[28:31]
	v_mfma_f32_16x16x32_bf16 v[24:27], v[190:193], v[230:233], v[24:27]
	v_mfma_f32_16x16x32_bf16 v[20:23], v[198:201], v[222:225], v[20:23]
	v_mfma_f32_16x16x32_bf16 v[16:19], v[198:201], v[230:233], v[16:19]
	v_mfma_f32_16x16x32_bf16 v[12:15], v[206:209], v[222:225], v[12:15]
	v_mfma_f32_16x16x32_bf16 v[8:11], v[206:209], v[230:233], v[8:11]
	v_mfma_f32_16x16x32_bf16 v[4:7], v[214:217], v[222:225], v[4:7]
	v_mfma_f32_16x16x32_bf16 v[0:3], v[214:217], v[230:233], v[0:3]
	v_mfma_f32_16x16x32_bf16 v[28:31], v[194:197], v[226:229], v[28:31]
	v_mfma_f32_16x16x32_bf16 v[24:27], v[194:197], v[234:237], v[24:27]
	v_mfma_f32_16x16x32_bf16 v[20:23], v[202:205], v[226:229], v[20:23]
	v_mfma_f32_16x16x32_bf16 v[16:19], v[202:205], v[234:237], v[16:19]
	v_mfma_f32_16x16x32_bf16 v[12:15], v[210:213], v[226:229], v[12:15]
	v_mfma_f32_16x16x32_bf16 v[8:11], v[210:213], v[234:237], v[8:11]
	v_mfma_f32_16x16x32_bf16 v[4:7], v[218:221], v[226:229], v[4:7]
	v_mfma_f32_16x16x32_bf16 v[0:3], v[218:221], v[234:237], v[0:3]
	s_add_i32 s27, s27, 2
	s_addk_i32 s28, 0x100
	s_cmp_lt_u32 s27, 12
	s_barrier
	s_cbranch_scc1 .LBB0_1682
; #define STAGE(P, BASE, br, kt) do { int _so = ((br) * K + (kt) * BK) * 2; \
;     __builtin_amdgcn_raw_ptr_buffer_load_lds(rs_##BASE, (__attribute__((address_space(3))) void*)((char*)(P) + tx * 16), 16, voff0, _so, 0, 0); \
;     __builtin_amdgcn_raw_ptr_buffer_load_lds(rs_##BASE, (__attribute__((address_space(3))) void*)((char*)(P) + tx * 16 + 8192), 16, voff1, _so, 0, 0); } while (0)
; #define LDA(dst, b, h) _Pragma("unroll") for (int m = 0; m < 4; ++m) _Pragma("unroll") for (int k = 0; k < 2; ++k) \
;     dst[m][k] = *reinterpret_cast<const bf16x8*>((char*)SA(b, h) + lds_byte(wr * 64 + m * 16 + fr, k * 32 + fq * 8))
; #define LDB(dst, b, h) _Pragma("unroll") for (int n = 0; n < 2; ++n) _Pragma("unroll") for (int k = 0; k < 2; ++k) \
;     dst[n][k] = *reinterpret_cast<const bf16x8*>((char*)SB(b, h) + lds_byte(wc * 32 + n * 16 + fr, k * 32 + fq * 8))
; #define MMA(ai, bj, At, Bt_) do { __builtin_amdgcn_s_setprio(1); \
;     _Pragma("unroll") for (int m = 0; m < 4; ++m) _Pragma("unroll") for (int n = 0; n < 2; ++n) _Pragma("unroll") for (int k = 0; k < 2; ++k) \
;       acc[ai][bj][m][n] = __builtin_amdgcn_mfma_f32_16x16x32_bf16(At[m][k], Bt_[n][k], acc[ai][bj][m][n], 0, 0, 0); \
;     __builtin_amdgcn_s_setprio(0); } while (0)
; #define WAIT_V(n) asm volatile("s_waitcnt vmcnt(" #n ")" ::: "memory")
; #define WAIT_L(n) asm volatile("s_waitcnt lgkmcnt(" #n ")" ::: "memory")
; #define BAR __builtin_amdgcn_s_barrier()
; template <class Epi> ...
;     ...
;   { LDB(B0, 0, 0); LDA(At, 0, 0); STAGE(SA(1, 1), A, brow + HALF, nt - 1);
;     BAR; WAIT_L(0); MMA(0, 0, At, B0); BAR;
;     LDB(B1, 0, 1); BAR; WAIT_L(0); MMA(0, 1, At, B1); BAR;
;     LDA(At, 0, 1); WAIT_V(4); BAR; WAIT_L(0); MMA(1, 0, At, B0); MMA(1, 1, At, B1); BAR; }
.Lpx3:
	v_readfirstlane_b32 s18, v152
	s_add_i32 s19, s19, 0x40780
	s_mov_b32 s6, s78
	s_mov_b32 s7, s79
	s_mov_b32 m0, s18
	v_readfirstlane_b32 s18, v151
	ds_read_b128 v[156:159], v155
	ds_read_b128 v[166:169], v155 offset:1024
	ds_read_b128 v[170:173], v155 offset:2048
	ds_read_b128 v[186:189], v155 offset:3072
	ds_read_b128 v[190:193], v143
	ds_read_b128 v[194:197], v143 offset:1024
	ds_read_b128 v[198:201], v142
	ds_read_b128 v[202:205], v142 offset:1024
	ds_read_b128 v[206:209], v141
	ds_read_b128 v[210:213], v141 offset:1024
	ds_read_b128 v[214:217], v140
	ds_read_b128 v[218:221], v140 offset:1024
	buffer_load_dwordx4 v32, s[4:7], s19 offen lds
	s_mov_b32 m0, s18
	s_nop 0
	buffer_load_dwordx4 v130, s[4:7], s19 offen lds
	s_barrier
	s_waitcnt lgkmcnt(0)
	s_waitcnt lgkmcnt(7)
	v_mfma_f32_16x16x32_bf16 v[126:129], v[190:193], v[156:159], v[126:129]
	v_mfma_f32_16x16x32_bf16 v[122:125], v[190:193], v[170:173], v[122:125]
	s_waitcnt lgkmcnt(5)
	v_mfma_f32_16x16x32_bf16 v[118:121], v[198:201], v[156:159], v[118:121]
	v_mfma_f32_16x16x32_bf16 v[114:117], v[198:201], v[170:173], v[114:117]
	s_waitcnt lgkmcnt(3)
	v_mfma_f32_16x16x32_bf16 v[110:113], v[206:209], v[156:159], v[110:113]
	v_mfma_f32_16x16x32_bf16 v[126:129], v[194:197], v[166:169], v[126:129]
	v_mfma_f32_16x16x32_bf16 v[122:125], v[194:197], v[186:189], v[122:125]
	v_mfma_f32_16x16x32_bf16 v[118:121], v[202:205], v[166:169], v[118:121]
	v_mfma_f32_16x16x32_bf16 v[114:117], v[202:205], v[186:189], v[114:117]
	s_waitcnt lgkmcnt(2)
	v_mfma_f32_16x16x32_bf16 v[110:113], v[210:213], v[166:169], v[110:113]
	v_mfma_f32_16x16x32_bf16 v[106:109], v[206:209], v[170:173], v[106:109]
	s_waitcnt lgkmcnt(1)
	v_mfma_f32_16x16x32_bf16 v[102:105], v[214:217], v[156:159], v[102:105]
	v_mfma_f32_16x16x32_bf16 v[98:101], v[214:217], v[170:173], v[98:101]
	v_mfma_f32_16x16x32_bf16 v[150:153], v[210:213], v[186:189], v[106:109]
	s_waitcnt lgkmcnt(0)
	v_mfma_f32_16x16x32_bf16 v[222:225], v[218:221], v[166:169], v[102:105]
	v_mfma_f32_16x16x32_bf16 v[226:229], v[218:221], v[186:189], v[98:101]
	s_barrier
	s_nop 1
	ds_read_b128 v[98:101], v149
	ds_read_b128 v[102:105], v149 offset:1024
	ds_read_b128 v[106:109], v149 offset:2048
	ds_read_b128 v[146:149], v149 offset:3072
	s_barrier
	s_waitcnt lgkmcnt(0)
	s_waitcnt lgkmcnt(3)
	v_mfma_f32_16x16x32_bf16 v[94:97], v[190:193], v[98:101], v[94:97]
	s_waitcnt lgkmcnt(1)
	v_mfma_f32_16x16x32_bf16 v[90:93], v[190:193], v[106:109], v[90:93]
	v_mfma_f32_16x16x32_bf16 v[86:89], v[198:201], v[98:101], v[86:89]
	v_mfma_f32_16x16x32_bf16 v[82:85], v[198:201], v[106:109], v[82:85]
	v_mfma_f32_16x16x32_bf16 v[94:97], v[194:197], v[102:105], v[94:97]
	s_waitcnt lgkmcnt(0)
	v_mfma_f32_16x16x32_bf16 v[90:93], v[194:197], v[146:149], v[90:93]
	v_mfma_f32_16x16x32_bf16 v[86:89], v[202:205], v[102:105], v[86:89]
	v_mfma_f32_16x16x32_bf16 v[82:85], v[202:205], v[146:149], v[82:85]
	v_mfma_f32_16x16x32_bf16 v[78:81], v[206:209], v[98:101], v[78:81]
	v_mfma_f32_16x16x32_bf16 v[74:77], v[206:209], v[106:109], v[74:77]
	v_mfma_f32_16x16x32_bf16 v[70:73], v[214:217], v[98:101], v[70:73]
	v_mfma_f32_16x16x32_bf16 v[66:69], v[214:217], v[106:109], v[66:69]
	v_mfma_f32_16x16x32_bf16 v[190:193], v[210:213], v[102:105], v[78:81]
	v_mfma_f32_16x16x32_bf16 v[194:197], v[210:213], v[146:149], v[74:77]
	v_mfma_f32_16x16x32_bf16 v[198:201], v[218:221], v[102:105], v[70:73]
	v_mfma_f32_16x16x32_bf16 v[202:205], v[218:221], v[146:149], v[66:69]
	s_barrier
	s_nop 1
	ds_read_b128 v[66:69], v143 offset:16384
	ds_read_b128 v[70:73], v143 offset:17408
	ds_read_b128 v[74:77], v142 offset:16384
	ds_read_b128 v[78:81], v142 offset:17408
	ds_read_b128 v[206:209], v141 offset:16384
	ds_read_b128 v[210:213], v141 offset:17408
	ds_read_b128 v[214:217], v140 offset:16384
	ds_read_b128 v[218:221], v140 offset:17408
	s_waitcnt vmcnt(4)
	s_barrier
	s_waitcnt lgkmcnt(0)
	s_waitcnt lgkmcnt(7)
	v_mfma_f32_16x16x32_bf16 v[62:65], v[66:69], v[156:159], v[62:65]
	v_mfma_f32_16x16x32_bf16 v[58:61], v[66:69], v[170:173], v[58:61]
	s_waitcnt lgkmcnt(5)
	v_mfma_f32_16x16x32_bf16 v[54:57], v[74:77], v[156:159], v[54:57]
	v_mfma_f32_16x16x32_bf16 v[50:53], v[74:77], v[170:173], v[50:53]
	v_mfma_f32_16x16x32_bf16 v[62:65], v[70:73], v[166:169], v[62:65]
	v_mfma_f32_16x16x32_bf16 v[58:61], v[70:73], v[186:189], v[58:61]
	s_waitcnt lgkmcnt(4)
	v_mfma_f32_16x16x32_bf16 v[54:57], v[78:81], v[166:169], v[54:57]
	v_mfma_f32_16x16x32_bf16 v[50:53], v[78:81], v[186:189], v[50:53]
	s_waitcnt lgkmcnt(3)
	v_mfma_f32_16x16x32_bf16 v[46:49], v[206:209], v[156:159], v[46:49]
	v_mfma_f32_16x16x32_bf16 v[42:45], v[206:209], v[170:173], v[42:45]
	s_waitcnt lgkmcnt(1)
	v_mfma_f32_16x16x32_bf16 v[38:41], v[214:217], v[156:159], v[38:41]
	v_mfma_f32_16x16x32_bf16 v[34:37], v[214:217], v[170:173], v[34:37]
	v_mfma_f32_16x16x32_bf16 v[230:233], v[210:213], v[166:169], v[46:49]
	v_mfma_f32_16x16x32_bf16 v[234:237], v[210:213], v[186:189], v[42:45]
	s_waitcnt lgkmcnt(0)
	v_mfma_f32_16x16x32_bf16 v[154:157], v[218:221], v[166:169], v[38:41]
	v_mfma_f32_16x16x32_bf16 v[158:161], v[218:221], v[186:189], v[34:37]
	v_mfma_f32_16x16x32_bf16 v[28:31], v[66:69], v[98:101], v[28:31]
	v_mfma_f32_16x16x32_bf16 v[24:27], v[66:69], v[106:109], v[24:27]
	v_mfma_f32_16x16x32_bf16 v[20:23], v[74:77], v[98:101], v[20:23]
	v_mfma_f32_16x16x32_bf16 v[12:15], v[206:209], v[98:101], v[12:15]
	v_mfma_f32_16x16x32_bf16 v[28:31], v[70:73], v[102:105], v[28:31]
	v_mfma_f32_16x16x32_bf16 v[24:27], v[70:73], v[146:149], v[24:27]
	v_mfma_f32_16x16x32_bf16 v[20:23], v[78:81], v[102:105], v[20:23]
	v_mfma_f32_16x16x32_bf16 v[16:19], v[74:77], v[106:109], v[16:19]
	v_mfma_f32_16x16x32_bf16 v[12:15], v[210:213], v[102:105], v[12:15]
	v_mfma_f32_16x16x32_bf16 v[8:11], v[206:209], v[106:109], v[8:11]
	v_mfma_f32_16x16x32_bf16 v[4:7], v[214:217], v[98:101], v[4:7]
	v_mfma_f32_16x16x32_bf16 v[0:3], v[214:217], v[106:109], v[0:3]
	v_mfma_f32_16x16x32_bf16 v[166:169], v[78:81], v[146:149], v[16:19]
	v_mfma_f32_16x16x32_bf16 v[170:173], v[210:213], v[146:149], v[8:11]
	v_mfma_f32_16x16x32_bf16 v[186:189], v[218:221], v[102:105], v[4:7]
	v_mfma_f32_16x16x32_bf16 v[146:149], v[218:221], v[146:149], v[0:3]
	s_barrier
; #define LDA(dst, b, h) _Pragma("unroll") for (int m = 0; m < 4; ++m) _Pragma("unroll") for (int k = 0; k < 2; ++k) \
;     dst[m][k] = *reinterpret_cast<const bf16x8*>((char*)SA(b, h) + lds_byte(wr * 64 + m * 16 + fr, k * 32 + fq * 8))
; #define LDB(dst, b, h) _Pragma("unroll") for (int n = 0; n < 2; ++n) _Pragma("unroll") for (int k = 0; k < 2; ++k) \
;     dst[n][k] = *reinterpret_cast<const bf16x8*>((char*)SB(b, h) + lds_byte(wc * 32 + n * 16 + fr, k * 32 + fq * 8))
; #define MMA(ai, bj, At, Bt_) do { __builtin_amdgcn_s_setprio(1); \
;     _Pragma("unroll") for (int m = 0; m < 4; ++m) _Pragma("unroll") for (int n = 0; n < 2; ++n) _Pragma("unroll") for (int k = 0; k < 2; ++k) \
;       acc[ai][bj][m][n] = __builtin_amdgcn_mfma_f32_16x16x32_bf16(At[m][k], Bt_[n][k], acc[ai][bj][m][n], 0, 0, 0); \
;     __builtin_amdgcn_s_setprio(0); } while (0)
; #define WAIT_V(n) asm volatile("s_waitcnt vmcnt(" #n ")" ::: "memory")
; #define WAIT_L(n) asm volatile("s_waitcnt lgkmcnt(" #n ")" ::: "memory")
; #define BAR __builtin_amdgcn_s_barrier()
; template <class Epi> ...
;     ...
;   { LDB(B0, 1, 0); LDA(At, 1, 0); WAIT_V(2); BAR; WAIT_L(0); MMA(0, 0, At, B0); BAR;
;     LDB(B1, 1, 1); WAIT_V(0); BAR; WAIT_L(0); MMA(0, 1, At, B1); BAR;
;     LDA(At, 1, 1); BAR; WAIT_L(0); MMA(1, 0, At, B0); MMA(1, 1, At, B1); BAR; }
;   if (wr == 0) BAR;
	ds_read_b128 v[206:209], v145
	ds_read_b128 v[210:213], v145 offset:1024
	ds_read_b128 v[214:217], v145 offset:2048
	ds_read_b128 v[218:221], v145 offset:3072
	ds_read_b128 v[0:3], v143 offset:32768
	ds_read_b128 v[4:7], v143 offset:33792
	ds_read_b128 v[8:11], v142 offset:32768
	ds_read_b128 v[42:45], v142 offset:33792
	ds_read_b128 v[46:49], v141 offset:32768
	ds_read_b128 v[238:241], v141 offset:33792
	ds_read_b128 v[242:245], v140 offset:32768
	ds_read_b128 v[246:249], v140 offset:33792
	s_waitcnt vmcnt(2)
	s_barrier
	s_waitcnt lgkmcnt(0)
	s_waitcnt lgkmcnt(7)
	v_mfma_f32_16x16x32_bf16 v[16:19], v[0:3], v[206:209], v[126:129]
	s_waitcnt lgkmcnt(6)
	v_mfma_f32_16x16x32_bf16 v[98:101], v[4:7], v[210:213], v[16:19]
	v_mfma_f32_16x16x32_bf16 v[16:19], v[0:3], v[214:217], v[122:125]
	v_mfma_f32_16x16x32_bf16 v[66:69], v[4:7], v[218:221], v[16:19]
	s_waitcnt lgkmcnt(5)
	v_mfma_f32_16x16x32_bf16 v[16:19], v[8:11], v[206:209], v[118:121]
	s_waitcnt lgkmcnt(4)
	v_mfma_f32_16x16x32_bf16 v[102:105], v[42:45], v[210:213], v[16:19]
	v_mfma_f32_16x16x32_bf16 v[16:19], v[8:11], v[214:217], v[114:117]
	v_mfma_f32_16x16x32_bf16 v[70:73], v[42:45], v[218:221], v[16:19]
	s_waitcnt lgkmcnt(3)
	v_mfma_f32_16x16x32_bf16 v[16:19], v[46:49], v[206:209], v[110:113]
	s_waitcnt lgkmcnt(2)
	v_mfma_f32_16x16x32_bf16 v[106:109], v[238:241], v[210:213], v[16:19]
	v_mfma_f32_16x16x32_bf16 v[16:19], v[46:49], v[214:217], v[150:153]
	v_mfma_f32_16x16x32_bf16 v[74:77], v[238:241], v[218:221], v[16:19]
	s_waitcnt lgkmcnt(1)
	v_mfma_f32_16x16x32_bf16 v[16:19], v[242:245], v[206:209], v[222:225]
	s_waitcnt lgkmcnt(0)
	v_mfma_f32_16x16x32_bf16 v[110:113], v[246:249], v[210:213], v[16:19]
	v_mfma_f32_16x16x32_bf16 v[16:19], v[242:245], v[214:217], v[226:229]
	v_mfma_f32_16x16x32_bf16 v[78:81], v[246:249], v[218:221], v[16:19]
	s_barrier
	ds_read_b128 v[150:153], v144
	ds_read_b128 v[222:225], v144 offset:1024
	ds_read_b128 v[226:229], v144 offset:2048
	ds_read_b128 v[250:253], v144 offset:3072
	s_waitcnt vmcnt(0)
	s_barrier
	s_waitcnt lgkmcnt(0)
	s_waitcnt lgkmcnt(3)
	v_mfma_f32_16x16x32_bf16 v[16:19], v[0:3], v[150:153], v[94:97]
	s_waitcnt lgkmcnt(1)
	v_mfma_f32_16x16x32_bf16 v[0:3], v[0:3], v[226:229], v[90:93]
	v_mfma_f32_16x16x32_bf16 v[34:37], v[4:7], v[222:225], v[16:19]
	s_waitcnt lgkmcnt(0)
	v_mfma_f32_16x16x32_bf16 v[16:19], v[4:7], v[250:253], v[0:3]
	v_mfma_f32_16x16x32_bf16 v[0:3], v[8:11], v[150:153], v[86:89]
	v_mfma_f32_16x16x32_bf16 v[38:41], v[42:45], v[222:225], v[0:3]
	v_mfma_f32_16x16x32_bf16 v[0:3], v[8:11], v[226:229], v[82:85]
	v_mfma_f32_16x16x32_bf16 v[8:11], v[42:45], v[250:253], v[0:3]
	v_mfma_f32_16x16x32_bf16 v[0:3], v[46:49], v[150:153], v[190:193]
	v_mfma_f32_16x16x32_bf16 v[42:45], v[238:241], v[222:225], v[0:3]
	v_mfma_f32_16x16x32_bf16 v[0:3], v[46:49], v[226:229], v[194:197]
	v_mfma_f32_16x16x32_bf16 v[4:7], v[238:241], v[250:253], v[0:3]
	v_mfma_f32_16x16x32_bf16 v[0:3], v[242:245], v[150:153], v[198:201]
	v_mfma_f32_16x16x32_bf16 v[46:49], v[246:249], v[222:225], v[0:3]
	v_mfma_f32_16x16x32_bf16 v[0:3], v[242:245], v[226:229], v[202:205]
	v_mfma_f32_16x16x32_bf16 v[0:3], v[246:249], v[250:253], v[0:3]
	s_barrier
	ds_read_b128 v[190:193], v143 offset:49152
	ds_read_b128 v[194:197], v143 offset:50176
	ds_read_b128 v[198:201], v142 offset:49152
	ds_read_b128 v[142:145], v142 offset:50176
	ds_read_b128 v[202:205], v141 offset:49152
	ds_read_b128 v[238:241], v141 offset:50176
	ds_read_b128 v[242:245], v140 offset:49152
	ds_read_b128 v[246:249], v140 offset:50176
	s_barrier
	s_waitcnt lgkmcnt(0)
	s_waitcnt lgkmcnt(5)
	v_mfma_f32_16x16x32_bf16 v[50:53], v[198:201], v[214:217], v[50:53]
	s_waitcnt lgkmcnt(4)
	v_mfma_f32_16x16x32_bf16 v[86:89], v[142:145], v[218:221], v[50:53]
	s_waitcnt lgkmcnt(3)
	v_mfma_f32_16x16x32_bf16 v[50:53], v[202:205], v[206:209], v[230:233]
	s_waitcnt lgkmcnt(2)
	v_mfma_f32_16x16x32_bf16 v[122:125], v[238:241], v[210:213], v[50:53]
	v_mfma_f32_16x16x32_bf16 v[50:53], v[202:205], v[214:217], v[234:237]
	v_mfma_f32_16x16x32_bf16 v[90:93], v[238:241], v[218:221], v[50:53]
	s_waitcnt lgkmcnt(1)
	v_mfma_f32_16x16x32_bf16 v[50:53], v[242:245], v[206:209], v[154:157]
	v_mfma_f32_16x16x32_bf16 v[62:65], v[190:193], v[206:209], v[62:65]
	v_mfma_f32_16x16x32_bf16 v[58:61], v[190:193], v[214:217], v[58:61]
	v_mfma_f32_16x16x32_bf16 v[54:57], v[198:201], v[206:209], v[54:57]
	s_waitcnt lgkmcnt(0)
	v_mfma_f32_16x16x32_bf16 v[126:129], v[246:249], v[210:213], v[50:53]
	v_mfma_f32_16x16x32_bf16 v[50:53], v[242:245], v[214:217], v[158:161]
	v_mfma_f32_16x16x32_bf16 v[114:117], v[194:197], v[210:213], v[62:65]
	v_mfma_f32_16x16x32_bf16 v[82:85], v[194:197], v[218:221], v[58:61]
	v_mfma_f32_16x16x32_bf16 v[118:121], v[142:145], v[210:213], v[54:57]
	v_mfma_f32_16x16x32_bf16 v[94:97], v[246:249], v[218:221], v[50:53]
	v_mfma_f32_16x16x32_bf16 v[20:23], v[198:201], v[150:153], v[20:23]
	v_mfma_f32_16x16x32_bf16 v[12:15], v[202:205], v[150:153], v[12:15]
	v_mfma_f32_16x16x32_bf16 v[28:31], v[190:193], v[150:153], v[28:31]
	v_mfma_f32_16x16x32_bf16 v[24:27], v[190:193], v[226:229], v[24:27]
	v_mfma_f32_16x16x32_bf16 v[54:57], v[142:145], v[222:225], v[20:23]
	v_mfma_f32_16x16x32_bf16 v[20:23], v[198:201], v[226:229], v[166:169]
	v_mfma_f32_16x16x32_bf16 v[58:61], v[238:241], v[222:225], v[12:15]
	v_mfma_f32_16x16x32_bf16 v[12:15], v[202:205], v[226:229], v[170:173]
	v_mfma_f32_16x16x32_bf16 v[50:53], v[194:197], v[222:225], v[28:31]
	v_mfma_f32_16x16x32_bf16 v[28:31], v[194:197], v[250:253], v[24:27]
	v_mfma_f32_16x16x32_bf16 v[24:27], v[142:145], v[250:253], v[20:23]
	v_mfma_f32_16x16x32_bf16 v[20:23], v[238:241], v[250:253], v[12:15]
	v_mfma_f32_16x16x32_bf16 v[12:15], v[242:245], v[150:153], v[186:189]
	v_mfma_f32_16x16x32_bf16 v[62:65], v[246:249], v[222:225], v[12:15]
	v_mfma_f32_16x16x32_bf16 v[12:15], v[242:245], v[226:229], v[146:149]
	v_mfma_f32_16x16x32_bf16 v[12:15], v[246:249], v[250:253], v[12:15]
	v_cmp_gt_u32_e32 vcc, s59, v133
	s_barrier
	s_and_saveexec_b64 s[4:5], vcc
	s_cbranch_execz .LBB0_1685
	s_barrier

; #define STAGE(P, BASE, br, kt) do { int _so = ((br) * K + (kt) * BK) * 2; \
;     __builtin_amdgcn_raw_ptr_buffer_load_lds(rs_##BASE, (__attribute__((address_space(3))) void*)((char*)(P) + tx * 16), 16, voff0, _so, 0, 0); \
;     __builtin_amdgcn_raw_ptr_buffer_load_lds(rs_##BASE, (__attribute__((address_space(3))) void*)((char*)(P) + tx * 16 + 8192), 16, voff1, _so, 0, 0); } while (0)
; #define LDA(dst, b, h) _Pragma("unroll") for (int m = 0; m < 4; ++m) _Pragma("unroll") for (int k = 0; k < 2; ++k) \
;     dst[m][k] = *reinterpret_cast<const bf16x8*>((char*)SA(b, h) + lds_byte(wr * 64 + m * 16 + fr, k * 32 + fq * 8))
; #define LDB(dst, b, h) _Pragma("unroll") for (int n = 0; n < 2; ++n) _Pragma("unroll") for (int k = 0; k < 2; ++k) \
;     dst[n][k] = *reinterpret_cast<const bf16x8*>((char*)SB(b, h) + lds_byte(wc * 32 + n * 16 + fr, k * 32 + fq * 8))
; #define MMA(ai, bj, At, Bt_) do { __builtin_amdgcn_s_setprio(1); \
;     _Pragma("unroll") for (int m = 0; m < 4; ++m) _Pragma("unroll") for (int n = 0; n < 2; ++n) _Pragma("unroll") for (int k = 0; k < 2; ++k) \
;       acc[ai][bj][m][n] = __builtin_amdgcn_mfma_f32_16x16x32_bf16(At[m][k], Bt_[n][k], acc[ai][bj][m][n], 0, 0, 0); \
;     __builtin_amdgcn_s_setprio(0); } while (0)
; #define WAIT_V(n) asm volatile("s_waitcnt vmcnt(" #n ")" ::: "memory")
; #define WAIT_L(n) asm volatile("s_waitcnt lgkmcnt(" #n ")" ::: "memory")
; #define BAR __builtin_amdgcn_s_barrier()
; #define SCHED __builtin_amdgcn_sched_barrier(0)
; template <class Epi> ...
;     ...
;     LDB(B0, 0, 0); SCHED; LDA(At, 0, 0); STAGE(SA(1, 1), A, brow + HALF, t + 1);
;     WAIT_L(8); BAR; WAIT_L(0); MMA(0, 0, At, B0); BAR; SCHED;
;     LDB(B1, 0, 1); STAGE(SB(0, 0), Bt, bcol, t + 2);
;     BAR; WAIT_L(0); MMA(0, 1, At, B1); BAR;
;     LDA(At, 0, 1); STAGE(SA(0, 0), A, brow, t + 2);
;     BAR; WAIT_L(0); MMA(1, 0, At, B0); BAR; SCHED;
;     STAGE(SB(0, 1), Bt, bcol + HALF, t + 2);
;     WAIT_V(6); BAR; MMA(1, 1, At, B1); BAR;
.Lpk4:
	ds_read_b128 v[156:159], v155
	ds_read_b128 v[166:169], v155 offset:1024
	ds_read_b128 v[170:173], v155 offset:2048
	ds_read_b128 v[174:177], v155 offset:3072
	s_add_i32 s25, s17, s24
	v_readfirstlane_b32 s27, v152
	s_add_i32 s26, s25, 0x40080
	s_mov_b32 m0, s27
	v_readfirstlane_b32 s27, v151
	ds_read_b128 v[186:189], v143
	ds_read_b128 v[190:193], v143 offset:1024
	ds_read_b128 v[194:197], v142
	ds_read_b128 v[198:201], v142 offset:1024
	ds_read_b128 v[202:205], v141
	ds_read_b128 v[206:209], v141 offset:1024
	ds_read_b128 v[210:213], v140
	ds_read_b128 v[214:217], v140 offset:1024
	buffer_load_dwordx4 v32, s[8:11], s26 offen lds
	s_mov_b32 m0, s27
	s_nop 0
	buffer_load_dwordx4 v131, s[8:11], s26 offen lds
	s_waitcnt lgkmcnt(8)
	s_barrier
	s_waitcnt lgkmcnt(0)
	s_waitcnt lgkmcnt(7)
	v_mfma_f32_16x16x32_bf16 v[126:129], v[186:189], v[156:159], 0
	v_mfma_f32_16x16x32_bf16 v[122:125], v[186:189], v[170:173], 0
	s_waitcnt lgkmcnt(5)
	v_mfma_f32_16x16x32_bf16 v[118:121], v[194:197], v[156:159], 0
	v_mfma_f32_16x16x32_bf16 v[114:117], v[194:197], v[170:173], 0
	s_waitcnt lgkmcnt(3)
	v_mfma_f32_16x16x32_bf16 v[110:113], v[202:205], v[156:159], 0
	v_mfma_f32_16x16x32_bf16 v[106:109], v[202:205], v[170:173], 0
	s_waitcnt lgkmcnt(1)
	v_mfma_f32_16x16x32_bf16 v[102:105], v[210:213], v[156:159], 0
	v_mfma_f32_16x16x32_bf16 v[98:101], v[210:213], v[170:173], 0
	v_mfma_f32_16x16x32_bf16 v[126:129], v[190:193], v[166:169], v[126:129]
	v_mfma_f32_16x16x32_bf16 v[122:125], v[190:193], v[174:177], v[122:125]
	v_mfma_f32_16x16x32_bf16 v[118:121], v[198:201], v[166:169], v[118:121]
	v_mfma_f32_16x16x32_bf16 v[114:117], v[198:201], v[174:177], v[114:117]
	v_mfma_f32_16x16x32_bf16 v[110:113], v[206:209], v[166:169], v[110:113]
	v_mfma_f32_16x16x32_bf16 v[106:109], v[206:209], v[174:177], v[106:109]
	s_waitcnt lgkmcnt(0)
	v_mfma_f32_16x16x32_bf16 v[102:105], v[214:217], v[166:169], v[102:105]
	v_mfma_f32_16x16x32_bf16 v[98:101], v[214:217], v[174:177], v[98:101]
	s_barrier
	s_add_i32 s26, s16, s24
	v_readfirstlane_b32 s28, v137
	s_add_i32 s27, s26, 0x100
	s_mov_b32 m0, s28
	v_readfirstlane_b32 s28, v139
	ds_read_b128 v[218:221], v149
	ds_read_b128 v[222:225], v149 offset:1024
	ds_read_b128 v[226:229], v149 offset:2048
	ds_read_b128 v[230:233], v149 offset:3072
	buffer_load_dwordx4 v32, s[76:79], s27 offen lds
	s_mov_b32 m0, s28
	s_nop 0
	buffer_load_dwordx4 v131, s[76:79], s27 offen lds
	s_barrier
	s_waitcnt lgkmcnt(0)
	s_waitcnt lgkmcnt(3)
	v_mfma_f32_16x16x32_bf16 v[94:97], v[186:189], v[218:221], 0
	s_waitcnt lgkmcnt(1)
	v_mfma_f32_16x16x32_bf16 v[90:93], v[186:189], v[226:229], 0
	v_mfma_f32_16x16x32_bf16 v[86:89], v[194:197], v[218:221], 0
	v_mfma_f32_16x16x32_bf16 v[82:85], v[194:197], v[226:229], 0
	v_mfma_f32_16x16x32_bf16 v[78:81], v[202:205], v[218:221], 0
	v_mfma_f32_16x16x32_bf16 v[74:77], v[202:205], v[226:229], 0
	v_mfma_f32_16x16x32_bf16 v[70:73], v[210:213], v[218:221], 0
	v_mfma_f32_16x16x32_bf16 v[66:69], v[210:213], v[226:229], 0
	v_mfma_f32_16x16x32_bf16 v[94:97], v[190:193], v[222:225], v[94:97]
	s_waitcnt lgkmcnt(0)
	v_mfma_f32_16x16x32_bf16 v[90:93], v[190:193], v[230:233], v[90:93]
	v_mfma_f32_16x16x32_bf16 v[86:89], v[198:201], v[222:225], v[86:89]
	v_mfma_f32_16x16x32_bf16 v[82:85], v[198:201], v[230:233], v[82:85]
	v_mfma_f32_16x16x32_bf16 v[78:81], v[206:209], v[222:225], v[78:81]
	v_mfma_f32_16x16x32_bf16 v[74:77], v[206:209], v[230:233], v[74:77]
	v_mfma_f32_16x16x32_bf16 v[70:73], v[214:217], v[222:225], v[70:73]
	v_mfma_f32_16x16x32_bf16 v[66:69], v[214:217], v[230:233], v[66:69]
	v_readfirstlane_b32 s28, v136
	s_add_i32 s27, s25, 0x100
	s_mov_b32 m0, s28
	v_readfirstlane_b32 s28, v135
	s_barrier
	ds_read_b128 v[186:189], v143 offset:16384
	ds_read_b128 v[190:193], v143 offset:17408
	ds_read_b128 v[194:197], v142 offset:16384
	ds_read_b128 v[198:201], v142 offset:17408
	ds_read_b128 v[202:205], v141 offset:16384
	ds_read_b128 v[206:209], v141 offset:17408
	ds_read_b128 v[210:213], v140 offset:16384
	ds_read_b128 v[214:217], v140 offset:17408
	buffer_load_dwordx4 v32, s[8:11], s27 offen lds
	s_mov_b32 m0, s28
	s_nop 0
	buffer_load_dwordx4 v131, s[8:11], s27 offen lds
	s_barrier
	s_waitcnt lgkmcnt(0)
	s_waitcnt lgkmcnt(7)
	v_mfma_f32_16x16x32_bf16 v[62:65], v[186:189], v[156:159], 0
	v_mfma_f32_16x16x32_bf16 v[58:61], v[186:189], v[170:173], 0
	s_waitcnt lgkmcnt(5)
	v_mfma_f32_16x16x32_bf16 v[54:57], v[194:197], v[156:159], 0
	v_mfma_f32_16x16x32_bf16 v[50:53], v[194:197], v[170:173], 0
	s_waitcnt lgkmcnt(3)
	v_mfma_f32_16x16x32_bf16 v[46:49], v[202:205], v[156:159], 0
	v_mfma_f32_16x16x32_bf16 v[42:45], v[202:205], v[170:173], 0
	s_waitcnt lgkmcnt(1)
	v_mfma_f32_16x16x32_bf16 v[38:41], v[210:213], v[156:159], 0
	v_mfma_f32_16x16x32_bf16 v[34:37], v[210:213], v[170:173], 0
	v_mfma_f32_16x16x32_bf16 v[62:65], v[190:193], v[166:169], v[62:65]
	v_mfma_f32_16x16x32_bf16 v[58:61], v[190:193], v[174:177], v[58:61]
	v_mfma_f32_16x16x32_bf16 v[54:57], v[198:201], v[166:169], v[54:57]
	v_mfma_f32_16x16x32_bf16 v[50:53], v[198:201], v[174:177], v[50:53]
	v_mfma_f32_16x16x32_bf16 v[46:49], v[206:209], v[166:169], v[46:49]
	v_mfma_f32_16x16x32_bf16 v[42:45], v[206:209], v[174:177], v[42:45]
	s_waitcnt lgkmcnt(0)
	v_mfma_f32_16x16x32_bf16 v[38:41], v[214:217], v[166:169], v[38:41]
	v_mfma_f32_16x16x32_bf16 v[34:37], v[214:217], v[174:177], v[34:37]
	s_barrier
	v_readfirstlane_b32 s28, v134
	s_add_i32 s27, s26, 0x40100
	s_mov_b32 m0, s28
	v_readfirstlane_b32 s28, v138
	buffer_load_dwordx4 v32, s[76:79], s27 offen lds
	s_mov_b32 m0, s28
	s_nop 0
	buffer_load_dwordx4 v131, s[76:79], s27 offen lds
	s_waitcnt vmcnt(6)
	s_barrier
; #define STAGE(P, BASE, br, kt) do { int _so = ((br) * K + (kt) * BK) * 2; \
;     __builtin_amdgcn_raw_ptr_buffer_load_lds(rs_##BASE, (__attribute__((address_space(3))) void*)((char*)(P) + tx * 16), 16, voff0, _so, 0, 0); \
;     __builtin_amdgcn_raw_ptr_buffer_load_lds(rs_##BASE, (__attribute__((address_space(3))) void*)((char*)(P) + tx * 16 + 8192), 16, voff1, _so, 0, 0); } while (0)
; #define LDA(dst, b, h) _Pragma("unroll") for (int m = 0; m < 4; ++m) _Pragma("unroll") for (int k = 0; k < 2; ++k) \
;     dst[m][k] = *reinterpret_cast<const bf16x8*>((char*)SA(b, h) + lds_byte(wr * 64 + m * 16 + fr, k * 32 + fq * 8))
; #define LDB(dst, b, h) _Pragma("unroll") for (int n = 0; n < 2; ++n) _Pragma("unroll") for (int k = 0; k < 2; ++k) \
;     dst[n][k] = *reinterpret_cast<const bf16x8*>((char*)SB(b, h) + lds_byte(wc * 32 + n * 16 + fr, k * 32 + fq * 8))
; #define MMA(ai, bj, At, Bt_) do { __builtin_amdgcn_s_setprio(1); \
;     _Pragma("unroll") for (int m = 0; m < 4; ++m) _Pragma("unroll") for (int n = 0; n < 2; ++n) _Pragma("unroll") for (int k = 0; k < 2; ++k) \
;       acc[ai][bj][m][n] = __builtin_amdgcn_mfma_f32_16x16x32_bf16(At[m][k], Bt_[n][k], acc[ai][bj][m][n], 0, 0, 0); \
;     __builtin_amdgcn_s_setprio(0); } while (0)
; #define WAIT_V(n) asm volatile("s_waitcnt vmcnt(" #n ")" ::: "memory")
; #define WAIT_L(n) asm volatile("s_waitcnt lgkmcnt(" #n ")" ::: "memory")
; #define BAR __builtin_amdgcn_s_barrier()
; #define SCHED __builtin_amdgcn_sched_barrier(0)
; template <class Epi> ...
;     ...
;     WAIT_V(6); BAR; MMA(1, 1, At, B1); BAR;
;     LDB(B0, 1, 0); SCHED; LDA(At, 1, 0); STAGE(SA(0, 1), A, brow + HALF, t + 2);
;     WAIT_L(8); BAR; WAIT_L(0); MMA(0, 0, At, B0); BAR; SCHED;
;     LDB(B1, 1, 1); STAGE(SB(1, 0), Bt, bcol, t + 3);
;     BAR; WAIT_L(0); MMA(0, 1, At, B1); BAR;
;     LDA(At, 1, 1); STAGE(SA(1, 0), A, brow, t + 3);
	v_mfma_f32_16x16x32_bf16 v[28:31], v[186:189], v[218:221], 0
	v_mfma_f32_16x16x32_bf16 v[24:27], v[186:189], v[226:229], 0
	v_mfma_f32_16x16x32_bf16 v[20:23], v[194:197], v[218:221], 0
	v_mfma_f32_16x16x32_bf16 v[16:19], v[194:197], v[226:229], 0
	v_mfma_f32_16x16x32_bf16 v[12:15], v[202:205], v[218:221], 0
	v_mfma_f32_16x16x32_bf16 v[8:11], v[202:205], v[226:229], 0
	v_mfma_f32_16x16x32_bf16 v[4:7], v[210:213], v[218:221], 0
	v_mfma_f32_16x16x32_bf16 v[0:3], v[210:213], v[226:229], 0
	v_mfma_f32_16x16x32_bf16 v[28:31], v[190:193], v[222:225], v[28:31]
	v_mfma_f32_16x16x32_bf16 v[24:27], v[190:193], v[230:233], v[24:27]
	v_mfma_f32_16x16x32_bf16 v[20:23], v[198:201], v[222:225], v[20:23]
	v_mfma_f32_16x16x32_bf16 v[16:19], v[198:201], v[230:233], v[16:19]
	v_mfma_f32_16x16x32_bf16 v[12:15], v[206:209], v[222:225], v[12:15]
	v_mfma_f32_16x16x32_bf16 v[8:11], v[206:209], v[230:233], v[8:11]
	v_mfma_f32_16x16x32_bf16 v[4:7], v[214:217], v[222:225], v[4:7]
	v_mfma_f32_16x16x32_bf16 v[0:3], v[214:217], v[230:233], v[0:3]
	s_barrier
	ds_read_b128 v[156:159], v145
	ds_read_b128 v[166:169], v145 offset:1024
	ds_read_b128 v[170:173], v145 offset:2048
	ds_read_b128 v[174:177], v145 offset:3072
	v_readfirstlane_b32 s28, v133
	s_add_i32 s27, s25, 0x40100
	s_mov_b32 m0, s28
	v_readfirstlane_b32 s28, v132
	ds_read_b128 v[186:189], v143 offset:32768
	ds_read_b128 v[190:193], v143 offset:33792
	ds_read_b128 v[194:197], v142 offset:32768
	ds_read_b128 v[198:201], v142 offset:33792
	ds_read_b128 v[202:205], v141 offset:32768
	ds_read_b128 v[206:209], v141 offset:33792
	ds_read_b128 v[210:213], v140 offset:32768
	ds_read_b128 v[214:217], v140 offset:33792
	buffer_load_dwordx4 v32, s[8:11], s27 offen lds
	s_mov_b32 m0, s28
	s_nop 0
	buffer_load_dwordx4 v131, s[8:11], s27 offen lds
	s_waitcnt lgkmcnt(8)
	s_barrier
	s_waitcnt lgkmcnt(0)
	s_waitcnt lgkmcnt(7)
	v_mfma_f32_16x16x32_bf16 v[126:129], v[186:189], v[156:159], v[126:129]
	v_mfma_f32_16x16x32_bf16 v[122:125], v[186:189], v[170:173], v[122:125]
	s_waitcnt lgkmcnt(5)
	v_mfma_f32_16x16x32_bf16 v[118:121], v[194:197], v[156:159], v[118:121]
	v_mfma_f32_16x16x32_bf16 v[114:117], v[194:197], v[170:173], v[114:117]
	s_waitcnt lgkmcnt(3)
	v_mfma_f32_16x16x32_bf16 v[110:113], v[202:205], v[156:159], v[110:113]
	v_mfma_f32_16x16x32_bf16 v[106:109], v[202:205], v[170:173], v[106:109]
	s_waitcnt lgkmcnt(1)
	v_mfma_f32_16x16x32_bf16 v[102:105], v[210:213], v[156:159], v[102:105]
	v_mfma_f32_16x16x32_bf16 v[98:101], v[210:213], v[170:173], v[98:101]
	v_mfma_f32_16x16x32_bf16 v[126:129], v[190:193], v[166:169], v[126:129]
	v_mfma_f32_16x16x32_bf16 v[122:125], v[190:193], v[174:177], v[122:125]
	v_mfma_f32_16x16x32_bf16 v[118:121], v[198:201], v[166:169], v[118:121]
	v_mfma_f32_16x16x32_bf16 v[114:117], v[198:201], v[174:177], v[114:117]
	v_mfma_f32_16x16x32_bf16 v[110:113], v[206:209], v[166:169], v[110:113]
	v_mfma_f32_16x16x32_bf16 v[106:109], v[206:209], v[174:177], v[106:109]
	s_waitcnt lgkmcnt(0)
	v_mfma_f32_16x16x32_bf16 v[102:105], v[214:217], v[166:169], v[102:105]
	v_mfma_f32_16x16x32_bf16 v[98:101], v[214:217], v[174:177], v[98:101]
	s_barrier
	v_readfirstlane_b32 s28, v146
	s_add_i32 s27, s26, 0x180
	s_mov_b32 m0, s28
	v_readfirstlane_b32 s28, v147
	ds_read_b128 v[218:221], v144
	ds_read_b128 v[222:225], v144 offset:1024
	ds_read_b128 v[226:229], v144 offset:2048
	ds_read_b128 v[230:233], v144 offset:3072
	buffer_load_dwordx4 v32, s[76:79], s27 offen lds
	s_mov_b32 m0, s28
	s_nop 0
	buffer_load_dwordx4 v131, s[76:79], s27 offen lds
	s_barrier
	s_waitcnt lgkmcnt(0)
	s_waitcnt lgkmcnt(3)
	v_mfma_f32_16x16x32_bf16 v[94:97], v[186:189], v[218:221], v[94:97]
	s_waitcnt lgkmcnt(1)
	v_mfma_f32_16x16x32_bf16 v[90:93], v[186:189], v[226:229], v[90:93]
	v_mfma_f32_16x16x32_bf16 v[86:89], v[194:197], v[218:221], v[86:89]
	v_mfma_f32_16x16x32_bf16 v[82:85], v[194:197], v[226:229], v[82:85]
	v_mfma_f32_16x16x32_bf16 v[78:81], v[202:205], v[218:221], v[78:81]
	v_mfma_f32_16x16x32_bf16 v[74:77], v[202:205], v[226:229], v[74:77]
	v_mfma_f32_16x16x32_bf16 v[70:73], v[210:213], v[218:221], v[70:73]
	v_mfma_f32_16x16x32_bf16 v[66:69], v[210:213], v[226:229], v[66:69]
	v_mfma_f32_16x16x32_bf16 v[94:97], v[190:193], v[222:225], v[94:97]
	s_waitcnt lgkmcnt(0)
	v_mfma_f32_16x16x32_bf16 v[90:93], v[190:193], v[230:233], v[90:93]
	v_mfma_f32_16x16x32_bf16 v[86:89], v[198:201], v[222:225], v[86:89]
	v_mfma_f32_16x16x32_bf16 v[82:85], v[198:201], v[230:233], v[82:85]
	v_mfma_f32_16x16x32_bf16 v[78:81], v[206:209], v[222:225], v[78:81]
	v_mfma_f32_16x16x32_bf16 v[74:77], v[206:209], v[230:233], v[74:77]
	v_mfma_f32_16x16x32_bf16 v[70:73], v[214:217], v[222:225], v[70:73]
	v_mfma_f32_16x16x32_bf16 v[66:69], v[214:217], v[230:233], v[66:69]
	v_readfirstlane_b32 s27, v148
	s_addk_i32 s25, 0x180
	s_mov_b32 m0, s27
	v_readfirstlane_b32 s27, v150
	s_barrier
	ds_read_b128 v[186:189], v143 offset:49152
	ds_read_b128 v[190:193], v143 offset:50176
	ds_read_b128 v[194:197], v142 offset:49152
	ds_read_b128 v[198:201], v142 offset:50176
	ds_read_b128 v[202:205], v141 offset:49152
	ds_read_b128 v[206:209], v141 offset:50176
	ds_read_b128 v[210:213], v140 offset:49152
	ds_read_b128 v[214:217], v140 offset:50176
	buffer_load_dwordx4 v32, s[8:11], s25 offen lds
	s_mov_b32 m0, s27
	s_nop 0
	buffer_load_dwordx4 v131, s[8:11], s25 offen lds
	s_barrier
; #define STAGE(P, BASE, br, kt) do { int _so = ((br) * K + (kt) * BK) * 2; \
;     __builtin_amdgcn_raw_ptr_buffer_load_lds(rs_##BASE, (__attribute__((address_space(3))) void*)((char*)(P) + tx * 16), 16, voff0, _so, 0, 0); \
;     __builtin_amdgcn_raw_ptr_buffer_load_lds(rs_##BASE, (__attribute__((address_space(3))) void*)((char*)(P) + tx * 16 + 8192), 16, voff1, _so, 0, 0); } while (0)
; #define LDA(dst, b, h) _Pragma("unroll") for (int m = 0; m < 4; ++m) _Pragma("unroll") for (int k = 0; k < 2; ++k) \
;     dst[m][k] = *reinterpret_cast<const bf16x8*>((char*)SA(b, h) + lds_byte(wr * 64 + m * 16 + fr, k * 32 + fq * 8))
; #define LDB(dst, b, h) _Pragma("unroll") for (int n = 0; n < 2; ++n) _Pragma("unroll") for (int k = 0; k < 2; ++k) \
;     dst[n][k] = *reinterpret_cast<const bf16x8*>((char*)SB(b, h) + lds_byte(wc * 32 + n * 16 + fr, k * 32 + fq * 8))
; #define MMA(ai, bj, At, Bt_) do { __builtin_amdgcn_s_setprio(1); \
;     _Pragma("unroll") for (int m = 0; m < 4; ++m) _Pragma("unroll") for (int n = 0; n < 2; ++n) _Pragma("unroll") for (int k = 0; k < 2; ++k) \
;       acc[ai][bj][m][n] = __builtin_amdgcn_mfma_f32_16x16x32_bf16(At[m][k], Bt_[n][k], acc[ai][bj][m][n], 0, 0, 0); \
;     __builtin_amdgcn_s_setprio(0); } while (0)
; #define WAIT_V(n) asm volatile("s_waitcnt vmcnt(" #n ")" ::: "memory")
; #define WAIT_L(n) asm volatile("s_waitcnt lgkmcnt(" #n ")" ::: "memory")
; #define BAR __builtin_amdgcn_s_barrier()
; #define SCHED __builtin_amdgcn_sched_barrier(0)
; template <class Epi> ...
;     ...
;   for (int t = 0; t < nt - 2; t += 2) {
;     LDB(B0, 0, 0); SCHED; LDA(At, 0, 0); STAGE(SA(1, 1), A, brow + HALF, t + 1);
;     WAIT_L(8); BAR; WAIT_L(0); MMA(0, 0, At, B0); BAR; SCHED;
;     LDB(B1, 0, 1); STAGE(SB(0, 0), Bt, bcol, t + 2);
;     ...
;     BAR; WAIT_L(0); MMA(1, 0, At, B0); BAR; SCHED;
;     STAGE(SB(1, 1), Bt, bcol + HALF, t + 3);
;     WAIT_V(6); BAR; MMA(1, 1, At, B1); BAR;
;   }
	s_waitcnt lgkmcnt(0)
	s_waitcnt lgkmcnt(7)
	v_mfma_f32_16x16x32_bf16 v[62:65], v[186:189], v[156:159], v[62:65]
	v_mfma_f32_16x16x32_bf16 v[58:61], v[186:189], v[170:173], v[58:61]
	s_waitcnt lgkmcnt(5)
	v_mfma_f32_16x16x32_bf16 v[54:57], v[194:197], v[156:159], v[54:57]
	v_mfma_f32_16x16x32_bf16 v[50:53], v[194:197], v[170:173], v[50:53]
	s_waitcnt lgkmcnt(3)
	v_mfma_f32_16x16x32_bf16 v[46:49], v[202:205], v[156:159], v[46:49]
	v_mfma_f32_16x16x32_bf16 v[42:45], v[202:205], v[170:173], v[42:45]
	s_waitcnt lgkmcnt(1)
	v_mfma_f32_16x16x32_bf16 v[38:41], v[210:213], v[156:159], v[38:41]
	v_mfma_f32_16x16x32_bf16 v[34:37], v[210:213], v[170:173], v[34:37]
	v_mfma_f32_16x16x32_bf16 v[62:65], v[190:193], v[166:169], v[62:65]
	v_mfma_f32_16x16x32_bf16 v[58:61], v[190:193], v[174:177], v[58:61]
	v_mfma_f32_16x16x32_bf16 v[54:57], v[198:201], v[166:169], v[54:57]
	v_mfma_f32_16x16x32_bf16 v[50:53], v[198:201], v[174:177], v[50:53]
	v_mfma_f32_16x16x32_bf16 v[46:49], v[206:209], v[166:169], v[46:49]
	v_mfma_f32_16x16x32_bf16 v[42:45], v[206:209], v[174:177], v[42:45]
	s_waitcnt lgkmcnt(0)
	v_mfma_f32_16x16x32_bf16 v[38:41], v[214:217], v[166:169], v[38:41]
	v_mfma_f32_16x16x32_bf16 v[34:37], v[214:217], v[174:177], v[34:37]
	s_barrier
	v_readfirstlane_b32 s25, v153
	s_add_i32 s26, s26, 0x40180
	s_mov_b32 m0, s25
	v_readfirstlane_b32 s25, v154
	buffer_load_dwordx4 v32, s[76:79], s26 offen lds
	s_mov_b32 m0, s25
	s_nop 0
	buffer_load_dwordx4 v131, s[76:79], s26 offen lds
	s_waitcnt vmcnt(6)
	s_barrier
	v_mfma_f32_16x16x32_bf16 v[28:31], v[186:189], v[218:221], v[28:31]
	v_mfma_f32_16x16x32_bf16 v[24:27], v[186:189], v[226:229], v[24:27]
	v_mfma_f32_16x16x32_bf16 v[20:23], v[194:197], v[218:221], v[20:23]
	v_mfma_f32_16x16x32_bf16 v[16:19], v[194:197], v[226:229], v[16:19]
	v_mfma_f32_16x16x32_bf16 v[12:15], v[202:205], v[218:221], v[12:15]
	v_mfma_f32_16x16x32_bf16 v[8:11], v[202:205], v[226:229], v[8:11]
	v_mfma_f32_16x16x32_bf16 v[4:7], v[210:213], v[218:221], v[4:7]
	v_mfma_f32_16x16x32_bf16 v[0:3], v[210:213], v[226:229], v[0:3]
	v_mfma_f32_16x16x32_bf16 v[28:31], v[190:193], v[222:225], v[28:31]
	v_mfma_f32_16x16x32_bf16 v[24:27], v[190:193], v[230:233], v[24:27]
	v_mfma_f32_16x16x32_bf16 v[20:23], v[198:201], v[222:225], v[20:23]
	v_mfma_f32_16x16x32_bf16 v[16:19], v[198:201], v[230:233], v[16:19]
	v_mfma_f32_16x16x32_bf16 v[12:15], v[206:209], v[222:225], v[12:15]
	v_mfma_f32_16x16x32_bf16 v[8:11], v[206:209], v[230:233], v[8:11]
	v_mfma_f32_16x16x32_bf16 v[4:7], v[214:217], v[222:225], v[4:7]
	v_mfma_f32_16x16x32_bf16 v[0:3], v[214:217], v[230:233], v[0:3]
	s_add_i32 s23, s23, 2
	s_addk_i32 s24, 0x100
	s_cmp_lt_u32 s23, 12
	s_barrier
	s_cbranch_scc1 .LBB0_1927
	s_branch .Lpx4
.LBB0_1927:
	ds_read_b128 v[156:159], v155
	ds_read_b128 v[166:169], v155 offset:1024
	ds_read_b128 v[170:173], v155 offset:2048
	ds_read_b128 v[174:177], v155 offset:3072
	s_add_i32 s25, s17, s24
	v_readfirstlane_b32 s27, v152
	s_add_i32 s26, s25, 0x40080
	s_mov_b32 m0, s27
	v_readfirstlane_b32 s27, v151
	ds_read_b128 v[186:189], v143
	ds_read_b128 v[190:193], v143 offset:1024
	ds_read_b128 v[194:197], v142
	ds_read_b128 v[198:201], v142 offset:1024
	ds_read_b128 v[202:205], v141
	ds_read_b128 v[206:209], v141 offset:1024
	ds_read_b128 v[210:213], v140
	ds_read_b128 v[214:217], v140 offset:1024
	buffer_load_dwordx4 v32, s[8:11], s26 offen lds
	s_mov_b32 m0, s27
	s_nop 0
	buffer_load_dwordx4 v131, s[8:11], s26 offen lds
	s_waitcnt lgkmcnt(8)
	s_barrier
	s_waitcnt lgkmcnt(0)
	s_waitcnt lgkmcnt(7)
	v_mfma_f32_16x16x32_bf16 v[126:129], v[186:189], v[156:159], v[126:129]
	v_mfma_f32_16x16x32_bf16 v[122:125], v[186:189], v[170:173], v[122:125]
	s_waitcnt lgkmcnt(5)
	v_mfma_f32_16x16x32_bf16 v[118:121], v[194:197], v[156:159], v[118:121]
	v_mfma_f32_16x16x32_bf16 v[114:117], v[194:197], v[170:173], v[114:117]
	s_waitcnt lgkmcnt(3)
	v_mfma_f32_16x16x32_bf16 v[110:113], v[202:205], v[156:159], v[110:113]
	v_mfma_f32_16x16x32_bf16 v[106:109], v[202:205], v[170:173], v[106:109]
	s_waitcnt lgkmcnt(1)
	v_mfma_f32_16x16x32_bf16 v[102:105], v[210:213], v[156:159], v[102:105]
	v_mfma_f32_16x16x32_bf16 v[98:101], v[210:213], v[170:173], v[98:101]
	v_mfma_f32_16x16x32_bf16 v[126:129], v[190:193], v[166:169], v[126:129]
	v_mfma_f32_16x16x32_bf16 v[122:125], v[190:193], v[174:177], v[122:125]
	v_mfma_f32_16x16x32_bf16 v[118:121], v[198:201], v[166:169], v[118:121]
	v_mfma_f32_16x16x32_bf16 v[114:117], v[198:201], v[174:177], v[114:117]
	v_mfma_f32_16x16x32_bf16 v[110:113], v[206:209], v[166:169], v[110:113]
	v_mfma_f32_16x16x32_bf16 v[106:109], v[206:209], v[174:177], v[106:109]
	s_waitcnt lgkmcnt(0)
	v_mfma_f32_16x16x32_bf16 v[102:105], v[214:217], v[166:169], v[102:105]
	v_mfma_f32_16x16x32_bf16 v[98:101], v[214:217], v[174:177], v[98:101]
	s_barrier
	s_add_i32 s26, s16, s24
	v_readfirstlane_b32 s28, v137
	s_add_i32 s27, s26, 0x100
	s_mov_b32 m0, s28
	v_readfirstlane_b32 s28, v139
	ds_read_b128 v[218:221], v149
	ds_read_b128 v[222:225], v149 offset:1024
	ds_read_b128 v[226:229], v149 offset:2048
	ds_read_b128 v[230:233], v149 offset:3072
	buffer_load_dwordx4 v32, s[76:79], s27 offen lds
	s_mov_b32 m0, s28
	s_nop 0
	buffer_load_dwordx4 v131, s[76:79], s27 offen lds
	s_barrier
; #define STAGE(P, BASE, br, kt) do { int _so = ((br) * K + (kt) * BK) * 2; \
;     __builtin_amdgcn_raw_ptr_buffer_load_lds(rs_##BASE, (__attribute__((address_space(3))) void*)((char*)(P) + tx * 16), 16, voff0, _so, 0, 0); \
;     __builtin_amdgcn_raw_ptr_buffer_load_lds(rs_##BASE, (__attribute__((address_space(3))) void*)((char*)(P) + tx * 16 + 8192), 16, voff1, _so, 0, 0); } while (0)
; #define LDA(dst, b, h) _Pragma("unroll") for (int m = 0; m < 4; ++m) _Pragma("unroll") for (int k = 0; k < 2; ++k) \
;     dst[m][k] = *reinterpret_cast<const bf16x8*>((char*)SA(b, h) + lds_byte(wr * 64 + m * 16 + fr, k * 32 + fq * 8))
; #define LDB(dst, b, h) _Pragma("unroll") for (int n = 0; n < 2; ++n) _Pragma("unroll") for (int k = 0; k < 2; ++k) \
;     dst[n][k] = *reinterpret_cast<const bf16x8*>((char*)SB(b, h) + lds_byte(wc * 32 + n * 16 + fr, k * 32 + fq * 8))
; #define MMA(ai, bj, At, Bt_) do { __builtin_amdgcn_s_setprio(1); \
;     _Pragma("unroll") for (int m = 0; m < 4; ++m) _Pragma("unroll") for (int n = 0; n < 2; ++n) _Pragma("unroll") for (int k = 0; k < 2; ++k) \
;       acc[ai][bj][m][n] = __builtin_amdgcn_mfma_f32_16x16x32_bf16(At[m][k], Bt_[n][k], acc[ai][bj][m][n], 0, 0, 0); \
;     __builtin_amdgcn_s_setprio(0); } while (0)
; #define WAIT_V(n) asm volatile("s_waitcnt vmcnt(" #n ")" ::: "memory")
; #define WAIT_L(n) asm volatile("s_waitcnt lgkmcnt(" #n ")" ::: "memory")
; #define BAR __builtin_amdgcn_s_barrier()
; #define SCHED __builtin_amdgcn_sched_barrier(0)
; template <class Epi> ...
;     ...
;     BAR; WAIT_L(0); MMA(0, 1, At, B1); BAR;
;     LDA(At, 0, 1); STAGE(SA(0, 0), A, brow, t + 2);
;     BAR; WAIT_L(0); MMA(1, 0, At, B0); BAR; SCHED;
;     STAGE(SB(0, 1), Bt, bcol + HALF, t + 2);
;     WAIT_V(6); BAR; MMA(1, 1, At, B1); BAR;
;     LDB(B0, 1, 0); SCHED; LDA(At, 1, 0); STAGE(SA(0, 1), A, brow + HALF, t + 2);
	s_waitcnt lgkmcnt(0)
	s_waitcnt lgkmcnt(3)
	v_mfma_f32_16x16x32_bf16 v[94:97], v[186:189], v[218:221], v[94:97]
	s_waitcnt lgkmcnt(1)
	v_mfma_f32_16x16x32_bf16 v[90:93], v[186:189], v[226:229], v[90:93]
	v_mfma_f32_16x16x32_bf16 v[86:89], v[194:197], v[218:221], v[86:89]
	v_mfma_f32_16x16x32_bf16 v[82:85], v[194:197], v[226:229], v[82:85]
	v_mfma_f32_16x16x32_bf16 v[78:81], v[202:205], v[218:221], v[78:81]
	v_mfma_f32_16x16x32_bf16 v[74:77], v[202:205], v[226:229], v[74:77]
	v_mfma_f32_16x16x32_bf16 v[70:73], v[210:213], v[218:221], v[70:73]
	v_mfma_f32_16x16x32_bf16 v[66:69], v[210:213], v[226:229], v[66:69]
	v_mfma_f32_16x16x32_bf16 v[94:97], v[190:193], v[222:225], v[94:97]
	s_waitcnt lgkmcnt(0)
	v_mfma_f32_16x16x32_bf16 v[90:93], v[190:193], v[230:233], v[90:93]
	v_mfma_f32_16x16x32_bf16 v[86:89], v[198:201], v[222:225], v[86:89]
	v_mfma_f32_16x16x32_bf16 v[82:85], v[198:201], v[230:233], v[82:85]
	v_mfma_f32_16x16x32_bf16 v[78:81], v[206:209], v[222:225], v[78:81]
	v_mfma_f32_16x16x32_bf16 v[74:77], v[206:209], v[230:233], v[74:77]
	v_mfma_f32_16x16x32_bf16 v[70:73], v[214:217], v[222:225], v[70:73]
	v_mfma_f32_16x16x32_bf16 v[66:69], v[214:217], v[230:233], v[66:69]
	v_readfirstlane_b32 s28, v136
	s_add_i32 s27, s25, 0x100
	s_mov_b32 m0, s28
	v_readfirstlane_b32 s28, v135
	s_barrier
	ds_read_b128 v[186:189], v143 offset:16384
	ds_read_b128 v[190:193], v143 offset:17408
	ds_read_b128 v[194:197], v142 offset:16384
	ds_read_b128 v[198:201], v142 offset:17408
	ds_read_b128 v[202:205], v141 offset:16384
	ds_read_b128 v[206:209], v141 offset:17408
	ds_read_b128 v[210:213], v140 offset:16384
	ds_read_b128 v[214:217], v140 offset:17408
	buffer_load_dwordx4 v32, s[8:11], s27 offen lds
	s_mov_b32 m0, s28
	s_nop 0
	buffer_load_dwordx4 v131, s[8:11], s27 offen lds
	s_barrier
	s_waitcnt lgkmcnt(0)
	s_waitcnt lgkmcnt(7)
	v_mfma_f32_16x16x32_bf16 v[62:65], v[186:189], v[156:159], v[62:65]
	v_mfma_f32_16x16x32_bf16 v[58:61], v[186:189], v[170:173], v[58:61]
	s_waitcnt lgkmcnt(5)
	v_mfma_f32_16x16x32_bf16 v[54:57], v[194:197], v[156:159], v[54:57]
	v_mfma_f32_16x16x32_bf16 v[50:53], v[194:197], v[170:173], v[50:53]
	s_waitcnt lgkmcnt(3)
	v_mfma_f32_16x16x32_bf16 v[46:49], v[202:205], v[156:159], v[46:49]
	v_mfma_f32_16x16x32_bf16 v[42:45], v[202:205], v[170:173], v[42:45]
	s_waitcnt lgkmcnt(1)
	v_mfma_f32_16x16x32_bf16 v[38:41], v[210:213], v[156:159], v[38:41]
	v_mfma_f32_16x16x32_bf16 v[34:37], v[210:213], v[170:173], v[34:37]
	v_mfma_f32_16x16x32_bf16 v[62:65], v[190:193], v[166:169], v[62:65]
	v_mfma_f32_16x16x32_bf16 v[58:61], v[190:193], v[174:177], v[58:61]
	v_mfma_f32_16x16x32_bf16 v[54:57], v[198:201], v[166:169], v[54:57]
	v_mfma_f32_16x16x32_bf16 v[50:53], v[198:201], v[174:177], v[50:53]
	v_mfma_f32_16x16x32_bf16 v[46:49], v[206:209], v[166:169], v[46:49]
	v_mfma_f32_16x16x32_bf16 v[42:45], v[206:209], v[174:177], v[42:45]
	s_waitcnt lgkmcnt(0)
	v_mfma_f32_16x16x32_bf16 v[38:41], v[214:217], v[166:169], v[38:41]
	v_mfma_f32_16x16x32_bf16 v[34:37], v[214:217], v[174:177], v[34:37]
	s_barrier
	v_readfirstlane_b32 s28, v134
	s_add_i32 s27, s26, 0x40100
	s_mov_b32 m0, s28
	v_readfirstlane_b32 s28, v138
	buffer_load_dwordx4 v32, s[76:79], s27 offen lds
	s_mov_b32 m0, s28
	s_nop 0
	buffer_load_dwordx4 v131, s[76:79], s27 offen lds
	s_waitcnt vmcnt(6)
	s_barrier
	v_mfma_f32_16x16x32_bf16 v[28:31], v[186:189], v[218:221], v[28:31]
	v_mfma_f32_16x16x32_bf16 v[24:27], v[186:189], v[226:229], v[24:27]
	v_mfma_f32_16x16x32_bf16 v[20:23], v[194:197], v[218:221], v[20:23]
	v_mfma_f32_16x16x32_bf16 v[16:19], v[194:197], v[226:229], v[16:19]
	v_mfma_f32_16x16x32_bf16 v[12:15], v[202:205], v[218:221], v[12:15]
	v_mfma_f32_16x16x32_bf16 v[8:11], v[202:205], v[226:229], v[8:11]
	v_mfma_f32_16x16x32_bf16 v[4:7], v[210:213], v[218:221], v[4:7]
	v_mfma_f32_16x16x32_bf16 v[0:3], v[210:213], v[226:229], v[0:3]
	v_mfma_f32_16x16x32_bf16 v[28:31], v[190:193], v[222:225], v[28:31]
	v_mfma_f32_16x16x32_bf16 v[24:27], v[190:193], v[230:233], v[24:27]
	v_mfma_f32_16x16x32_bf16 v[20:23], v[198:201], v[222:225], v[20:23]
	v_mfma_f32_16x16x32_bf16 v[16:19], v[198:201], v[230:233], v[16:19]
	v_mfma_f32_16x16x32_bf16 v[12:15], v[206:209], v[222:225], v[12:15]
	v_mfma_f32_16x16x32_bf16 v[8:11], v[206:209], v[230:233], v[8:11]
	v_mfma_f32_16x16x32_bf16 v[4:7], v[214:217], v[222:225], v[4:7]
	v_mfma_f32_16x16x32_bf16 v[0:3], v[214:217], v[230:233], v[0:3]
	s_barrier
	ds_read_b128 v[156:159], v145
	ds_read_b128 v[166:169], v145 offset:1024
	ds_read_b128 v[170:173], v145 offset:2048
	ds_read_b128 v[174:177], v145 offset:3072
	v_readfirstlane_b32 s28, v133
	s_add_i32 s27, s25, 0x40100
	s_mov_b32 m0, s28
	v_readfirstlane_b32 s28, v132
	ds_read_b128 v[186:189], v143 offset:32768
	ds_read_b128 v[190:193], v143 offset:33792
	ds_read_b128 v[194:197], v142 offset:32768
	ds_read_b128 v[198:201], v142 offset:33792
	ds_read_b128 v[202:205], v141 offset:32768
	ds_read_b128 v[206:209], v141 offset:33792
	ds_read_b128 v[210:213], v140 offset:32768
	ds_read_b128 v[214:217], v140 offset:33792
	buffer_load_dwordx4 v32, s[8:11], s27 offen lds
	s_mov_b32 m0, s28
	s_nop 0
	buffer_load_dwordx4 v131, s[8:11], s27 offen lds
	s_waitcnt lgkmcnt(8)
	s_barrier
; #define STAGE(P, BASE, br, kt) do { int _so = ((br) * K + (kt) * BK) * 2; \
;     __builtin_amdgcn_raw_ptr_buffer_load_lds(rs_##BASE, (__attribute__((address_space(3))) void*)((char*)(P) + tx * 16), 16, voff0, _so, 0, 0); \
;     __builtin_amdgcn_raw_ptr_buffer_load_lds(rs_##BASE, (__attribute__((address_space(3))) void*)((char*)(P) + tx * 16 + 8192), 16, voff1, _so, 0, 0); } while (0)
; #define LDA(dst, b, h) _Pragma("unroll") for (int m = 0; m < 4; ++m) _Pragma("unroll") for (int k = 0; k < 2; ++k) \
;     dst[m][k] = *reinterpret_cast<const bf16x8*>((char*)SA(b, h) + lds_byte(wr * 64 + m * 16 + fr, k * 32 + fq * 8))
; #define LDB(dst, b, h) _Pragma("unroll") for (int n = 0; n < 2; ++n) _Pragma("unroll") for (int k = 0; k < 2; ++k) \
;     dst[n][k] = *reinterpret_cast<const bf16x8*>((char*)SB(b, h) + lds_byte(wc * 32 + n * 16 + fr, k * 32 + fq * 8))
; #define MMA(ai, bj, At, Bt_) do { __builtin_amdgcn_s_setprio(1); \
;     _Pragma("unroll") for (int m = 0; m < 4; ++m) _Pragma("unroll") for (int n = 0; n < 2; ++n) _Pragma("unroll") for (int k = 0; k < 2; ++k) \
;       acc[ai][bj][m][n] = __builtin_amdgcn_mfma_f32_16x16x32_bf16(At[m][k], Bt_[n][k], acc[ai][bj][m][n], 0, 0, 0); \
;     __builtin_amdgcn_s_setprio(0); } while (0)
; #define WAIT_V(n) asm volatile("s_waitcnt vmcnt(" #n ")" ::: "memory")
; #define WAIT_L(n) asm volatile("s_waitcnt lgkmcnt(" #n ")" ::: "memory")
; #define BAR __builtin_amdgcn_s_barrier()
; #define SCHED __builtin_amdgcn_sched_barrier(0)
; template <class Epi> ...
;     ...
;     WAIT_L(8); BAR; WAIT_L(0); MMA(0, 0, At, B0); BAR; SCHED;
;     LDB(B1, 1, 1); STAGE(SB(1, 0), Bt, bcol, t + 3);
;     BAR; WAIT_L(0); MMA(0, 1, At, B1); BAR;
;     LDA(At, 1, 1); STAGE(SA(1, 0), A, brow, t + 3);
;     BAR; WAIT_L(0); MMA(1, 0, At, B0); BAR; SCHED;
;     STAGE(SB(1, 1), Bt, bcol + HALF, t + 3);
;     WAIT_V(6); BAR; MMA(1, 1, At, B1); BAR;
;   }
	s_waitcnt lgkmcnt(0)
	s_waitcnt lgkmcnt(7)
	v_mfma_f32_16x16x32_bf16 v[126:129], v[186:189], v[156:159], v[126:129]
	v_mfma_f32_16x16x32_bf16 v[122:125], v[186:189], v[170:173], v[122:125]
	s_waitcnt lgkmcnt(5)
	v_mfma_f32_16x16x32_bf16 v[118:121], v[194:197], v[156:159], v[118:121]
	v_mfma_f32_16x16x32_bf16 v[114:117], v[194:197], v[170:173], v[114:117]
	s_waitcnt lgkmcnt(3)
	v_mfma_f32_16x16x32_bf16 v[110:113], v[202:205], v[156:159], v[110:113]
	v_mfma_f32_16x16x32_bf16 v[106:109], v[202:205], v[170:173], v[106:109]
	s_waitcnt lgkmcnt(1)
	v_mfma_f32_16x16x32_bf16 v[102:105], v[210:213], v[156:159], v[102:105]
	v_mfma_f32_16x16x32_bf16 v[98:101], v[210:213], v[170:173], v[98:101]
	v_mfma_f32_16x16x32_bf16 v[126:129], v[190:193], v[166:169], v[126:129]
	v_mfma_f32_16x16x32_bf16 v[122:125], v[190:193], v[174:177], v[122:125]
	v_mfma_f32_16x16x32_bf16 v[118:121], v[198:201], v[166:169], v[118:121]
	v_mfma_f32_16x16x32_bf16 v[114:117], v[198:201], v[174:177], v[114:117]
	v_mfma_f32_16x16x32_bf16 v[110:113], v[206:209], v[166:169], v[110:113]
	v_mfma_f32_16x16x32_bf16 v[106:109], v[206:209], v[174:177], v[106:109]
	s_waitcnt lgkmcnt(0)
	v_mfma_f32_16x16x32_bf16 v[102:105], v[214:217], v[166:169], v[102:105]
	v_mfma_f32_16x16x32_bf16 v[98:101], v[214:217], v[174:177], v[98:101]
	s_barrier
	v_readfirstlane_b32 s28, v146
	s_add_i32 s27, s26, 0x180
	s_mov_b32 m0, s28
	v_readfirstlane_b32 s28, v147
	ds_read_b128 v[218:221], v144
	ds_read_b128 v[222:225], v144 offset:1024
	ds_read_b128 v[226:229], v144 offset:2048
	ds_read_b128 v[230:233], v144 offset:3072
	buffer_load_dwordx4 v32, s[76:79], s27 offen lds
	s_mov_b32 m0, s28
	s_nop 0
	buffer_load_dwordx4 v131, s[76:79], s27 offen lds
	s_barrier
	s_waitcnt lgkmcnt(0)
	s_waitcnt lgkmcnt(3)
	v_mfma_f32_16x16x32_bf16 v[94:97], v[186:189], v[218:221], v[94:97]
	s_waitcnt lgkmcnt(1)
	v_mfma_f32_16x16x32_bf16 v[90:93], v[186:189], v[226:229], v[90:93]
	v_mfma_f32_16x16x32_bf16 v[86:89], v[194:197], v[218:221], v[86:89]
	v_mfma_f32_16x16x32_bf16 v[82:85], v[194:197], v[226:229], v[82:85]
	v_mfma_f32_16x16x32_bf16 v[78:81], v[202:205], v[218:221], v[78:81]
	v_mfma_f32_16x16x32_bf16 v[74:77], v[202:205], v[226:229], v[74:77]
	v_mfma_f32_16x16x32_bf16 v[70:73], v[210:213], v[218:221], v[70:73]
	v_mfma_f32_16x16x32_bf16 v[66:69], v[210:213], v[226:229], v[66:69]
	v_mfma_f32_16x16x32_bf16 v[94:97], v[190:193], v[222:225], v[94:97]
	s_waitcnt lgkmcnt(0)
	v_mfma_f32_16x16x32_bf16 v[90:93], v[190:193], v[230:233], v[90:93]
	v_mfma_f32_16x16x32_bf16 v[86:89], v[198:201], v[222:225], v[86:89]
	v_mfma_f32_16x16x32_bf16 v[82:85], v[198:201], v[230:233], v[82:85]
	v_mfma_f32_16x16x32_bf16 v[78:81], v[206:209], v[222:225], v[78:81]
	v_mfma_f32_16x16x32_bf16 v[74:77], v[206:209], v[230:233], v[74:77]
	v_mfma_f32_16x16x32_bf16 v[70:73], v[214:217], v[222:225], v[70:73]
	v_mfma_f32_16x16x32_bf16 v[66:69], v[214:217], v[230:233], v[66:69]
	v_readfirstlane_b32 s27, v148
	s_addk_i32 s25, 0x180
	s_mov_b32 m0, s27
	v_readfirstlane_b32 s27, v150
	s_barrier
	ds_read_b128 v[186:189], v143 offset:49152
	ds_read_b128 v[190:193], v143 offset:50176
	ds_read_b128 v[194:197], v142 offset:49152
	ds_read_b128 v[198:201], v142 offset:50176
	ds_read_b128 v[202:205], v141 offset:49152
	ds_read_b128 v[206:209], v141 offset:50176
	ds_read_b128 v[210:213], v140 offset:49152
	ds_read_b128 v[214:217], v140 offset:50176
	buffer_load_dwordx4 v32, s[8:11], s25 offen lds
	s_mov_b32 m0, s27
	s_nop 0
	buffer_load_dwordx4 v131, s[8:11], s25 offen lds
	s_barrier
	s_waitcnt lgkmcnt(0)
	s_waitcnt lgkmcnt(7)
	v_mfma_f32_16x16x32_bf16 v[62:65], v[186:189], v[156:159], v[62:65]
	v_mfma_f32_16x16x32_bf16 v[58:61], v[186:189], v[170:173], v[58:61]
	s_waitcnt lgkmcnt(5)
	v_mfma_f32_16x16x32_bf16 v[54:57], v[194:197], v[156:159], v[54:57]
	v_mfma_f32_16x16x32_bf16 v[50:53], v[194:197], v[170:173], v[50:53]
	s_waitcnt lgkmcnt(3)
	v_mfma_f32_16x16x32_bf16 v[46:49], v[202:205], v[156:159], v[46:49]
	v_mfma_f32_16x16x32_bf16 v[42:45], v[202:205], v[170:173], v[42:45]
	s_waitcnt lgkmcnt(1)
	v_mfma_f32_16x16x32_bf16 v[38:41], v[210:213], v[156:159], v[38:41]
	v_mfma_f32_16x16x32_bf16 v[34:37], v[210:213], v[170:173], v[34:37]
	v_mfma_f32_16x16x32_bf16 v[62:65], v[190:193], v[166:169], v[62:65]
	v_mfma_f32_16x16x32_bf16 v[58:61], v[190:193], v[174:177], v[58:61]
	v_mfma_f32_16x16x32_bf16 v[54:57], v[198:201], v[166:169], v[54:57]
	v_mfma_f32_16x16x32_bf16 v[50:53], v[198:201], v[174:177], v[50:53]
	v_mfma_f32_16x16x32_bf16 v[46:49], v[206:209], v[166:169], v[46:49]
	v_mfma_f32_16x16x32_bf16 v[42:45], v[206:209], v[174:177], v[42:45]
	s_waitcnt lgkmcnt(0)
	v_mfma_f32_16x16x32_bf16 v[38:41], v[214:217], v[166:169], v[38:41]
	v_mfma_f32_16x16x32_bf16 v[34:37], v[214:217], v[174:177], v[34:37]
	s_barrier
	v_readfirstlane_b32 s25, v153
	s_add_i32 s26, s26, 0x40180
	s_mov_b32 m0, s25
	v_readfirstlane_b32 s25, v154
	buffer_load_dwordx4 v32, s[76:79], s26 offen lds
	s_mov_b32 m0, s25
	s_nop 0
	buffer_load_dwordx4 v131, s[76:79], s26 offen lds
	s_waitcnt vmcnt(6)
	s_barrier
	v_mfma_f32_16x16x32_bf16 v[28:31], v[186:189], v[218:221], v[28:31]
	v_mfma_f32_16x16x32_bf16 v[24:27], v[186:189], v[226:229], v[24:27]
	v_mfma_f32_16x16x32_bf16 v[20:23], v[194:197], v[218:221], v[20:23]
	v_mfma_f32_16x16x32_bf16 v[16:19], v[194:197], v[226:229], v[16:19]
	v_mfma_f32_16x16x32_bf16 v[12:15], v[202:205], v[218:221], v[12:15]
	v_mfma_f32_16x16x32_bf16 v[8:11], v[202:205], v[226:229], v[8:11]
	v_mfma_f32_16x16x32_bf16 v[4:7], v[210:213], v[218:221], v[4:7]
	v_mfma_f32_16x16x32_bf16 v[0:3], v[210:213], v[226:229], v[0:3]
	v_mfma_f32_16x16x32_bf16 v[28:31], v[190:193], v[222:225], v[28:31]
	v_mfma_f32_16x16x32_bf16 v[24:27], v[190:193], v[230:233], v[24:27]
	v_mfma_f32_16x16x32_bf16 v[20:23], v[198:201], v[222:225], v[20:23]
	v_mfma_f32_16x16x32_bf16 v[16:19], v[198:201], v[230:233], v[16:19]
	v_mfma_f32_16x16x32_bf16 v[12:15], v[206:209], v[222:225], v[12:15]
	v_mfma_f32_16x16x32_bf16 v[8:11], v[206:209], v[230:233], v[8:11]
	v_mfma_f32_16x16x32_bf16 v[4:7], v[214:217], v[222:225], v[4:7]
	v_mfma_f32_16x16x32_bf16 v[0:3], v[214:217], v[230:233], v[0:3]
	s_add_i32 s23, s23, 2
	s_addk_i32 s24, 0x100
	s_cmp_lt_u32 s23, 12
	s_barrier
	s_cbranch_scc1 .LBB0_1927
; #define STAGE(P, BASE, br, kt) do { int _so = ((br) * K + (kt) * BK) * 2; \
;     __builtin_amdgcn_raw_ptr_buffer_load_lds(rs_##BASE, (__attribute__((address_space(3))) void*)((char*)(P) + tx * 16), 16, voff0, _so, 0, 0); \
;     __builtin_amdgcn_raw_ptr_buffer_load_lds(rs_##BASE, (__attribute__((address_space(3))) void*)((char*)(P) + tx * 16 + 8192), 16, voff1, _so, 0, 0); } while (0)
; #define LDA(dst, b, h) _Pragma("unroll") for (int m = 0; m < 4; ++m) _Pragma("unroll") for (int k = 0; k < 2; ++k) \
;     dst[m][k] = *reinterpret_cast<const bf16x8*>((char*)SA(b, h) + lds_byte(wr * 64 + m * 16 + fr, k * 32 + fq * 8))
; #define LDB(dst, b, h) _Pragma("unroll") for (int n = 0; n < 2; ++n) _Pragma("unroll") for (int k = 0; k < 2; ++k) \
;     dst[n][k] = *reinterpret_cast<const bf16x8*>((char*)SB(b, h) + lds_byte(wc * 32 + n * 16 + fr, k * 32 + fq * 8))
; #define MMA(ai, bj, At, Bt_) do { __builtin_amdgcn_s_setprio(1); \
;     _Pragma("unroll") for (int m = 0; m < 4; ++m) _Pragma("unroll") for (int n = 0; n < 2; ++n) _Pragma("unroll") for (int k = 0; k < 2; ++k) \
;       acc[ai][bj][m][n] = __builtin_amdgcn_mfma_f32_16x16x32_bf16(At[m][k], Bt_[n][k], acc[ai][bj][m][n], 0, 0, 0); \
;     __builtin_amdgcn_s_setprio(0); } while (0)
; #define WAIT_V(n) asm volatile("s_waitcnt vmcnt(" #n ")" ::: "memory")
; #define WAIT_L(n) asm volatile("s_waitcnt lgkmcnt(" #n ")" ::: "memory")
; #define BAR __builtin_amdgcn_s_barrier()
; template <class Epi> ...
;     ...
;   { LDB(B0, 0, 0); LDA(At, 0, 0); STAGE(SA(1, 1), A, brow + HALF, nt - 1);
;     BAR; WAIT_L(0); MMA(0, 0, At, B0); BAR;
;     LDB(B1, 0, 1); BAR; WAIT_L(0); MMA(0, 1, At, B1); BAR;
;     LDA(At, 0, 1); WAIT_V(4); BAR; WAIT_L(0); MMA(1, 0, At, B0); MMA(1, 1, At, B1); BAR; }
.Lpx4:
	s_or_b32 s16, s17, 0x40780
	v_readfirstlane_b32 s17, v152
	s_mov_b32 s10, s78
	s_mov_b32 s11, s79
	s_mov_b32 m0, s17
	v_readfirstlane_b32 s17, v151
	ds_read_b128 v[156:159], v155
	ds_read_b128 v[166:169], v155 offset:1024
	ds_read_b128 v[170:173], v155 offset:2048
	ds_read_b128 v[174:177], v155 offset:3072
	ds_read_b128 v[186:189], v143
	ds_read_b128 v[190:193], v143 offset:1024
	ds_read_b128 v[194:197], v142
	ds_read_b128 v[198:201], v142 offset:1024
	ds_read_b128 v[202:205], v141
	ds_read_b128 v[206:209], v141 offset:1024
	ds_read_b128 v[210:213], v140
	ds_read_b128 v[214:217], v140 offset:1024
	buffer_load_dwordx4 v32, s[8:11], s16 offen lds
	s_mov_b32 m0, s17
	s_nop 0
	buffer_load_dwordx4 v131, s[8:11], s16 offen lds
	s_barrier
	s_waitcnt lgkmcnt(0)
	s_waitcnt lgkmcnt(7)
	v_mfma_f32_16x16x32_bf16 v[126:129], v[186:189], v[156:159], v[126:129]
	v_mfma_f32_16x16x32_bf16 v[122:125], v[186:189], v[170:173], v[122:125]
	s_waitcnt lgkmcnt(5)
	v_mfma_f32_16x16x32_bf16 v[118:121], v[194:197], v[156:159], v[118:121]
	v_mfma_f32_16x16x32_bf16 v[114:117], v[194:197], v[170:173], v[114:117]
	s_waitcnt lgkmcnt(3)
	v_mfma_f32_16x16x32_bf16 v[110:113], v[202:205], v[156:159], v[110:113]
	v_mfma_f32_16x16x32_bf16 v[106:109], v[202:205], v[170:173], v[106:109]
	s_waitcnt lgkmcnt(1)
	v_mfma_f32_16x16x32_bf16 v[102:105], v[210:213], v[156:159], v[102:105]
	v_mfma_f32_16x16x32_bf16 v[98:101], v[210:213], v[170:173], v[98:101]
	v_mfma_f32_16x16x32_bf16 v[126:129], v[190:193], v[166:169], v[126:129]
	v_mfma_f32_16x16x32_bf16 v[122:125], v[190:193], v[174:177], v[122:125]
	v_mfma_f32_16x16x32_bf16 v[118:121], v[198:201], v[166:169], v[118:121]
	v_mfma_f32_16x16x32_bf16 v[114:117], v[198:201], v[174:177], v[114:117]
	v_mfma_f32_16x16x32_bf16 v[110:113], v[206:209], v[166:169], v[110:113]
	v_mfma_f32_16x16x32_bf16 v[106:109], v[206:209], v[174:177], v[106:109]
	s_waitcnt lgkmcnt(0)
	v_mfma_f32_16x16x32_bf16 v[102:105], v[214:217], v[166:169], v[102:105]
	v_mfma_f32_16x16x32_bf16 v[98:101], v[214:217], v[174:177], v[98:101]
	s_barrier
	ds_read_b128 v[150:153], v149
	ds_read_b128 v[218:221], v149 offset:1024
	ds_read_b128 v[222:225], v149 offset:2048
	ds_read_b128 v[146:149], v149 offset:3072
	s_barrier
	s_waitcnt lgkmcnt(0)
	s_waitcnt lgkmcnt(3)
	v_mfma_f32_16x16x32_bf16 v[78:81], v[202:205], v[150:153], v[78:81]
	s_waitcnt lgkmcnt(1)
	v_mfma_f32_16x16x32_bf16 v[74:77], v[202:205], v[222:225], v[74:77]
	v_mfma_f32_16x16x32_bf16 v[70:73], v[210:213], v[150:153], v[70:73]
	v_mfma_f32_16x16x32_bf16 v[66:69], v[210:213], v[222:225], v[66:69]
	v_mfma_f32_16x16x32_bf16 v[94:97], v[186:189], v[150:153], v[94:97]
	v_mfma_f32_16x16x32_bf16 v[90:93], v[186:189], v[222:225], v[90:93]
	v_mfma_f32_16x16x32_bf16 v[86:89], v[194:197], v[150:153], v[86:89]
	v_mfma_f32_16x16x32_bf16 v[82:85], v[194:197], v[222:225], v[82:85]
	v_mfma_f32_16x16x32_bf16 v[78:81], v[206:209], v[218:221], v[78:81]
	s_waitcnt lgkmcnt(0)
	v_mfma_f32_16x16x32_bf16 v[74:77], v[206:209], v[146:149], v[74:77]
	v_mfma_f32_16x16x32_bf16 v[70:73], v[214:217], v[218:221], v[70:73]
	v_mfma_f32_16x16x32_bf16 v[66:69], v[214:217], v[146:149], v[66:69]
	v_mfma_f32_16x16x32_bf16 v[226:229], v[190:193], v[218:221], v[94:97]
	v_mfma_f32_16x16x32_bf16 v[186:189], v[190:193], v[146:149], v[90:93]
	v_mfma_f32_16x16x32_bf16 v[190:193], v[198:201], v[218:221], v[86:89]
	v_mfma_f32_16x16x32_bf16 v[194:197], v[198:201], v[146:149], v[82:85]
	s_barrier
	s_nop 0
	ds_read_b128 v[82:85], v143 offset:16384
	ds_read_b128 v[86:89], v143 offset:17408
	ds_read_b128 v[90:93], v142 offset:16384
	ds_read_b128 v[94:97], v142 offset:17408
	ds_read_b128 v[198:201], v141 offset:16384
	ds_read_b128 v[202:205], v141 offset:17408
	ds_read_b128 v[206:209], v140 offset:16384
	ds_read_b128 v[210:213], v140 offset:17408
	s_waitcnt vmcnt(4)
	s_barrier
	s_waitcnt lgkmcnt(0)
	s_waitcnt lgkmcnt(3)
	v_mfma_f32_16x16x32_bf16 v[46:49], v[198:201], v[156:159], v[46:49]
	v_mfma_f32_16x16x32_bf16 v[42:45], v[198:201], v[170:173], v[42:45]
	s_waitcnt lgkmcnt(1)
	v_mfma_f32_16x16x32_bf16 v[38:41], v[206:209], v[156:159], v[38:41]
	v_mfma_f32_16x16x32_bf16 v[34:37], v[206:209], v[170:173], v[34:37]
	v_mfma_f32_16x16x32_bf16 v[62:65], v[82:85], v[156:159], v[62:65]
	v_mfma_f32_16x16x32_bf16 v[58:61], v[82:85], v[170:173], v[58:61]
	v_mfma_f32_16x16x32_bf16 v[54:57], v[90:93], v[156:159], v[54:57]
	v_mfma_f32_16x16x32_bf16 v[50:53], v[90:93], v[170:173], v[50:53]
	v_mfma_f32_16x16x32_bf16 v[46:49], v[202:205], v[166:169], v[46:49]
	v_mfma_f32_16x16x32_bf16 v[42:45], v[202:205], v[174:177], v[42:45]
	s_waitcnt lgkmcnt(0)
	v_mfma_f32_16x16x32_bf16 v[38:41], v[210:213], v[166:169], v[38:41]
	v_mfma_f32_16x16x32_bf16 v[34:37], v[210:213], v[174:177], v[34:37]
	v_mfma_f32_16x16x32_bf16 v[214:217], v[86:89], v[166:169], v[62:65]
	v_mfma_f32_16x16x32_bf16 v[230:233], v[86:89], v[174:177], v[58:61]
	v_mfma_f32_16x16x32_bf16 v[234:237], v[94:97], v[166:169], v[54:57]
	v_mfma_f32_16x16x32_bf16 v[238:241], v[94:97], v[174:177], v[50:53]
	v_mfma_f32_16x16x32_bf16 v[0:3], v[206:209], v[222:225], v[0:3]
	v_mfma_f32_16x16x32_bf16 v[28:31], v[82:85], v[150:153], v[28:31]
	v_mfma_f32_16x16x32_bf16 v[24:27], v[82:85], v[222:225], v[24:27]
	v_mfma_f32_16x16x32_bf16 v[20:23], v[90:93], v[150:153], v[20:23]
	v_mfma_f32_16x16x32_bf16 v[16:19], v[90:93], v[222:225], v[16:19]
	v_mfma_f32_16x16x32_bf16 v[12:15], v[198:201], v[150:153], v[12:15]
	v_mfma_f32_16x16x32_bf16 v[8:11], v[198:201], v[222:225], v[8:11]
	v_mfma_f32_16x16x32_bf16 v[4:7], v[206:209], v[150:153], v[4:7]
	v_mfma_f32_16x16x32_bf16 v[0:3], v[210:213], v[146:149], v[0:3]
	v_mfma_f32_16x16x32_bf16 v[154:157], v[86:89], v[218:221], v[28:31]
	v_mfma_f32_16x16x32_bf16 v[158:161], v[86:89], v[146:149], v[24:27]
	v_mfma_f32_16x16x32_bf16 v[166:169], v[94:97], v[218:221], v[20:23]
	v_mfma_f32_16x16x32_bf16 v[170:173], v[94:97], v[146:149], v[16:19]
	v_mfma_f32_16x16x32_bf16 v[174:177], v[202:205], v[218:221], v[12:15]
	v_mfma_f32_16x16x32_bf16 v[198:201], v[202:205], v[146:149], v[8:11]
	v_mfma_f32_16x16x32_bf16 v[150:153], v[210:213], v[218:221], v[4:7]
	s_barrier
; #define LDA(dst, b, h) _Pragma("unroll") for (int m = 0; m < 4; ++m) _Pragma("unroll") for (int k = 0; k < 2; ++k) \
;     dst[m][k] = *reinterpret_cast<const bf16x8*>((char*)SA(b, h) + lds_byte(wr * 64 + m * 16 + fr, k * 32 + fq * 8))
; #define LDB(dst, b, h) _Pragma("unroll") for (int n = 0; n < 2; ++n) _Pragma("unroll") for (int k = 0; k < 2; ++k) \
;     dst[n][k] = *reinterpret_cast<const bf16x8*>((char*)SB(b, h) + lds_byte(wc * 32 + n * 16 + fr, k * 32 + fq * 8))
; #define MMA(ai, bj, At, Bt_) do { __builtin_amdgcn_s_setprio(1); \
;     _Pragma("unroll") for (int m = 0; m < 4; ++m) _Pragma("unroll") for (int n = 0; n < 2; ++n) _Pragma("unroll") for (int k = 0; k < 2; ++k) \
;       acc[ai][bj][m][n] = __builtin_amdgcn_mfma_f32_16x16x32_bf16(At[m][k], Bt_[n][k], acc[ai][bj][m][n], 0, 0, 0); \
;     __builtin_amdgcn_s_setprio(0); } while (0)
; #define WAIT_V(n) asm volatile("s_waitcnt vmcnt(" #n ")" ::: "memory")
; #define WAIT_L(n) asm volatile("s_waitcnt lgkmcnt(" #n ")" ::: "memory")
; #define BAR __builtin_amdgcn_s_barrier()
; template <class Epi> ...
;     ...
;   { LDB(B0, 1, 0); LDA(At, 1, 0); WAIT_V(2); BAR; WAIT_L(0); MMA(0, 0, At, B0); BAR;
;     LDB(B1, 1, 1); WAIT_V(0); BAR; WAIT_L(0); MMA(0, 1, At, B1); BAR;
;     LDA(At, 1, 1); BAR; WAIT_L(0); MMA(1, 0, At, B0); MMA(1, 1, At, B1); BAR; }
;   if (wr == 0) BAR;
	s_nop 0
	ds_read_b128 v[4:7], v145
	ds_read_b128 v[8:11], v145 offset:1024
	ds_read_b128 v[12:15], v145 offset:2048
	ds_read_b128 v[146:149], v145 offset:3072
	ds_read_b128 v[16:19], v143 offset:32768
	ds_read_b128 v[20:23], v143 offset:33792
	ds_read_b128 v[24:27], v142 offset:32768
	ds_read_b128 v[50:53], v142 offset:33792
	ds_read_b128 v[202:205], v141 offset:32768
	ds_read_b128 v[206:209], v141 offset:33792
	ds_read_b128 v[210:213], v140 offset:32768
	ds_read_b128 v[218:221], v140 offset:33792
	s_waitcnt vmcnt(2)
	s_barrier
	s_waitcnt lgkmcnt(0)
	s_waitcnt lgkmcnt(7)
	v_mfma_f32_16x16x32_bf16 v[28:31], v[16:19], v[4:7], v[126:129]
	s_waitcnt lgkmcnt(6)
	v_mfma_f32_16x16x32_bf16 v[126:129], v[20:23], v[8:11], v[28:31]
	v_mfma_f32_16x16x32_bf16 v[28:31], v[16:19], v[12:15], v[122:125]
	v_mfma_f32_16x16x32_bf16 v[94:97], v[20:23], v[146:149], v[28:31]
	s_waitcnt lgkmcnt(5)
	v_mfma_f32_16x16x32_bf16 v[28:31], v[24:27], v[4:7], v[118:121]
	s_waitcnt lgkmcnt(4)
	v_mfma_f32_16x16x32_bf16 v[122:125], v[50:53], v[8:11], v[28:31]
	v_mfma_f32_16x16x32_bf16 v[28:31], v[24:27], v[12:15], v[114:117]
	v_mfma_f32_16x16x32_bf16 v[90:93], v[50:53], v[146:149], v[28:31]
	s_waitcnt lgkmcnt(3)
	v_mfma_f32_16x16x32_bf16 v[28:31], v[202:205], v[4:7], v[110:113]
	s_waitcnt lgkmcnt(2)
	v_mfma_f32_16x16x32_bf16 v[118:121], v[206:209], v[8:11], v[28:31]
	v_mfma_f32_16x16x32_bf16 v[28:31], v[202:205], v[12:15], v[106:109]
	v_mfma_f32_16x16x32_bf16 v[86:89], v[206:209], v[146:149], v[28:31]
	s_waitcnt lgkmcnt(1)
	v_mfma_f32_16x16x32_bf16 v[28:31], v[210:213], v[4:7], v[102:105]
	s_waitcnt lgkmcnt(0)
	v_mfma_f32_16x16x32_bf16 v[114:117], v[218:221], v[8:11], v[28:31]
	v_mfma_f32_16x16x32_bf16 v[28:31], v[210:213], v[12:15], v[98:101]
	v_mfma_f32_16x16x32_bf16 v[82:85], v[218:221], v[146:149], v[28:31]
	s_barrier
	ds_read_b128 v[222:225], v144
	ds_read_b128 v[242:245], v144 offset:1024
	ds_read_b128 v[246:249], v144 offset:2048
	ds_read_b128 v[250:253], v144 offset:3072
	s_waitcnt vmcnt(0)
	s_barrier
	s_waitcnt lgkmcnt(0)
	s_waitcnt lgkmcnt(3)
	v_mfma_f32_16x16x32_bf16 v[28:31], v[16:19], v[222:225], v[226:229]
	s_waitcnt lgkmcnt(1)
	v_mfma_f32_16x16x32_bf16 v[16:19], v[16:19], v[246:249], v[186:189]
	v_mfma_f32_16x16x32_bf16 v[62:65], v[20:23], v[242:245], v[28:31]
	s_waitcnt lgkmcnt(0)
	v_mfma_f32_16x16x32_bf16 v[28:31], v[20:23], v[250:253], v[16:19]
	v_mfma_f32_16x16x32_bf16 v[16:19], v[24:27], v[222:225], v[190:193]
	v_mfma_f32_16x16x32_bf16 v[58:61], v[50:53], v[242:245], v[16:19]
	v_mfma_f32_16x16x32_bf16 v[16:19], v[24:27], v[246:249], v[194:197]
	v_mfma_f32_16x16x32_bf16 v[24:27], v[50:53], v[250:253], v[16:19]
	v_mfma_f32_16x16x32_bf16 v[16:19], v[202:205], v[222:225], v[78:81]
	v_mfma_f32_16x16x32_bf16 v[54:57], v[206:209], v[242:245], v[16:19]
	v_mfma_f32_16x16x32_bf16 v[16:19], v[202:205], v[246:249], v[74:77]
	v_mfma_f32_16x16x32_bf16 v[20:23], v[206:209], v[250:253], v[16:19]
	v_mfma_f32_16x16x32_bf16 v[16:19], v[210:213], v[222:225], v[70:73]
	v_mfma_f32_16x16x32_bf16 v[50:53], v[218:221], v[242:245], v[16:19]
	v_mfma_f32_16x16x32_bf16 v[16:19], v[210:213], v[246:249], v[66:69]
	v_mfma_f32_16x16x32_bf16 v[16:19], v[218:221], v[250:253], v[16:19]
	s_barrier
	ds_read_b128 v[186:189], v143 offset:49152
	ds_read_b128 v[190:193], v143 offset:50176
	ds_read_b128 v[194:197], v142 offset:49152
	ds_read_b128 v[142:145], v142 offset:50176
	ds_read_b128 v[202:205], v141 offset:49152
	ds_read_b128 v[206:209], v141 offset:50176
	ds_read_b128 v[210:213], v140 offset:49152
	ds_read_b128 v[218:221], v140 offset:50176
	s_barrier
	s_waitcnt lgkmcnt(0)
	s_waitcnt lgkmcnt(7)
	v_mfma_f32_16x16x32_bf16 v[66:69], v[186:189], v[4:7], v[214:217]
	s_waitcnt lgkmcnt(6)
	v_mfma_f32_16x16x32_bf16 v[110:113], v[190:193], v[8:11], v[66:69]
	v_mfma_f32_16x16x32_bf16 v[66:69], v[186:189], v[12:15], v[230:233]
	v_mfma_f32_16x16x32_bf16 v[78:81], v[190:193], v[146:149], v[66:69]
	s_waitcnt lgkmcnt(5)
	v_mfma_f32_16x16x32_bf16 v[66:69], v[194:197], v[4:7], v[234:237]
	s_waitcnt lgkmcnt(3)
	v_mfma_f32_16x16x32_bf16 v[46:49], v[202:205], v[4:7], v[46:49]
	s_waitcnt lgkmcnt(1)
	v_mfma_f32_16x16x32_bf16 v[4:7], v[210:213], v[4:7], v[38:41]
	v_mfma_f32_16x16x32_bf16 v[106:109], v[142:145], v[8:11], v[66:69]
	v_mfma_f32_16x16x32_bf16 v[66:69], v[194:197], v[12:15], v[238:241]
	v_mfma_f32_16x16x32_bf16 v[42:45], v[202:205], v[12:15], v[42:45]
	s_waitcnt lgkmcnt(0)
	v_mfma_f32_16x16x32_bf16 v[98:101], v[218:221], v[8:11], v[4:7]
	v_mfma_f32_16x16x32_bf16 v[4:7], v[210:213], v[12:15], v[34:37]
	v_mfma_f32_16x16x32_bf16 v[74:77], v[142:145], v[146:149], v[66:69]
	v_mfma_f32_16x16x32_bf16 v[102:105], v[206:209], v[8:11], v[46:49]
	v_mfma_f32_16x16x32_bf16 v[70:73], v[206:209], v[146:149], v[42:45]
	v_mfma_f32_16x16x32_bf16 v[66:69], v[218:221], v[146:149], v[4:7]
	v_mfma_f32_16x16x32_bf16 v[4:7], v[186:189], v[222:225], v[154:157]
	v_mfma_f32_16x16x32_bf16 v[46:49], v[190:193], v[242:245], v[4:7]
	v_mfma_f32_16x16x32_bf16 v[4:7], v[186:189], v[246:249], v[158:161]
	v_mfma_f32_16x16x32_bf16 v[12:15], v[190:193], v[250:253], v[4:7]
	v_mfma_f32_16x16x32_bf16 v[4:7], v[194:197], v[222:225], v[166:169]
	v_mfma_f32_16x16x32_bf16 v[42:45], v[142:145], v[242:245], v[4:7]
	v_mfma_f32_16x16x32_bf16 v[4:7], v[194:197], v[246:249], v[170:173]
	v_mfma_f32_16x16x32_bf16 v[8:11], v[142:145], v[250:253], v[4:7]
	v_mfma_f32_16x16x32_bf16 v[4:7], v[202:205], v[222:225], v[174:177]
	v_mfma_f32_16x16x32_bf16 v[38:41], v[206:209], v[242:245], v[4:7]
	v_mfma_f32_16x16x32_bf16 v[4:7], v[202:205], v[246:249], v[198:201]
	v_mfma_f32_16x16x32_bf16 v[34:37], v[210:213], v[222:225], v[150:153]
	v_mfma_f32_16x16x32_bf16 v[0:3], v[210:213], v[246:249], v[0:3]
	v_mfma_f32_16x16x32_bf16 v[4:7], v[206:209], v[250:253], v[4:7]
	v_mfma_f32_16x16x32_bf16 v[34:37], v[218:221], v[242:245], v[34:37]
	v_mfma_f32_16x16x32_bf16 v[0:3], v[218:221], v[250:253], v[0:3]
	v_cmp_gt_u32_e32 vcc, s59, v130
	s_barrier
	s_and_saveexec_b64 s[10:11], vcc
	s_cbranch_execz .LBB0_1930
	s_barrier

; #define STAGE(P, BASE, br, kt) do { int _so = ((br) * K + (kt) * BK) * 2; \
;     __builtin_amdgcn_raw_ptr_buffer_load_lds(rs_##BASE, (__attribute__((address_space(3))) void*)((char*)(P) + tx * 16), 16, voff0, _so, 0, 0); \
;     __builtin_amdgcn_raw_ptr_buffer_load_lds(rs_##BASE, (__attribute__((address_space(3))) void*)((char*)(P) + tx * 16 + 8192), 16, voff1, _so, 0, 0); } while (0)
; #define LDA(dst, b, h) _Pragma("unroll") for (int m = 0; m < 4; ++m) _Pragma("unroll") for (int k = 0; k < 2; ++k) \
;     dst[m][k] = *reinterpret_cast<const bf16x8*>((char*)SA(b, h) + lds_byte(wr * 64 + m * 16 + fr, k * 32 + fq * 8))
; #define LDB(dst, b, h) _Pragma("unroll") for (int n = 0; n < 2; ++n) _Pragma("unroll") for (int k = 0; k < 2; ++k) \
;     dst[n][k] = *reinterpret_cast<const bf16x8*>((char*)SB(b, h) + lds_byte(wc * 32 + n * 16 + fr, k * 32 + fq * 8))
; #define MMA(ai, bj, At, Bt_) do { __builtin_amdgcn_s_setprio(1); \
;     _Pragma("unroll") for (int m = 0; m < 4; ++m) _Pragma("unroll") for (int n = 0; n < 2; ++n) _Pragma("unroll") for (int k = 0; k < 2; ++k) \
;       acc[ai][bj][m][n] = __builtin_amdgcn_mfma_f32_16x16x32_bf16(At[m][k], Bt_[n][k], acc[ai][bj][m][n], 0, 0, 0); \
;     __builtin_amdgcn_s_setprio(0); } while (0)
; #define WAIT_V(n) asm volatile("s_waitcnt vmcnt(" #n ")" ::: "memory")
; #define WAIT_L(n) asm volatile("s_waitcnt lgkmcnt(" #n ")" ::: "memory")
; #define BAR __builtin_amdgcn_s_barrier()
; template <class Epi> ...
;     ...
;   { LDB(B0, 0, 0); LDA(At, 0, 0); STAGE(SA(1, 1), A, brow + HALF, nt - 1);
;     BAR; WAIT_L(0); MMA(0, 0, At, B0); BAR;
;     LDB(B1, 0, 1); BAR; WAIT_L(0); MMA(0, 1, At, B1); BAR;
;     LDA(At, 0, 1); WAIT_V(4); BAR; WAIT_L(0); MMA(1, 0, At, B0); MMA(1, 1, At, B1); BAR; }
.Lpx5:
	s_or_b32 s16, s17, 0x40780
	v_readfirstlane_b32 s17, v152
	s_mov_b32 s10, s78
	s_mov_b32 s11, s79
	s_mov_b32 m0, s17
	v_readfirstlane_b32 s17, v151
	ds_read_b128 v[156:159], v155
	ds_read_b128 v[166:169], v155 offset:1024
	ds_read_b128 v[170:173], v155 offset:2048
	ds_read_b128 v[174:177], v155 offset:3072
	ds_read_b128 v[186:189], v143
	ds_read_b128 v[190:193], v143 offset:1024
	ds_read_b128 v[194:197], v142
	ds_read_b128 v[198:201], v142 offset:1024
	ds_read_b128 v[202:205], v141
	ds_read_b128 v[206:209], v141 offset:1024
	ds_read_b128 v[210:213], v140
	ds_read_b128 v[214:217], v140 offset:1024
	buffer_load_dwordx4 v32, s[8:11], s16 offen lds
	s_mov_b32 m0, s17
	s_nop 0
	buffer_load_dwordx4 v131, s[8:11], s16 offen lds
	s_barrier
	s_waitcnt lgkmcnt(0)
	s_waitcnt lgkmcnt(7)
	v_mfma_f32_16x16x32_bf16 v[126:129], v[186:189], v[156:159], v[126:129]
	v_mfma_f32_16x16x32_bf16 v[122:125], v[186:189], v[170:173], v[122:125]
	s_waitcnt lgkmcnt(5)
	v_mfma_f32_16x16x32_bf16 v[118:121], v[194:197], v[156:159], v[118:121]
	v_mfma_f32_16x16x32_bf16 v[114:117], v[194:197], v[170:173], v[114:117]
	v_mfma_f32_16x16x32_bf16 v[126:129], v[190:193], v[166:169], v[126:129]
	v_mfma_f32_16x16x32_bf16 v[122:125], v[190:193], v[174:177], v[122:125]
	s_waitcnt lgkmcnt(4)
	v_mfma_f32_16x16x32_bf16 v[118:121], v[198:201], v[166:169], v[118:121]
	v_mfma_f32_16x16x32_bf16 v[114:117], v[198:201], v[174:177], v[114:117]
	s_waitcnt lgkmcnt(3)
	v_mfma_f32_16x16x32_bf16 v[110:113], v[202:205], v[156:159], v[110:113]
	v_mfma_f32_16x16x32_bf16 v[106:109], v[202:205], v[170:173], v[106:109]
	s_waitcnt lgkmcnt(1)
	v_mfma_f32_16x16x32_bf16 v[102:105], v[210:213], v[156:159], v[102:105]
	v_mfma_f32_16x16x32_bf16 v[98:101], v[210:213], v[170:173], v[98:101]
	v_mfma_f32_16x16x32_bf16 v[150:153], v[206:209], v[166:169], v[110:113]
	v_mfma_f32_16x16x32_bf16 v[218:221], v[206:209], v[174:177], v[106:109]
	s_waitcnt lgkmcnt(0)
	v_mfma_f32_16x16x32_bf16 v[222:225], v[214:217], v[166:169], v[102:105]
	v_mfma_f32_16x16x32_bf16 v[226:229], v[214:217], v[174:177], v[98:101]
	s_barrier
	s_nop 0
	ds_read_b128 v[98:101], v149
	ds_read_b128 v[102:105], v149 offset:1024
	ds_read_b128 v[106:109], v149 offset:2048
	ds_read_b128 v[110:113], v149 offset:3072
	s_barrier
	s_waitcnt lgkmcnt(0)
	s_waitcnt lgkmcnt(3)
	v_mfma_f32_16x16x32_bf16 v[94:97], v[186:189], v[98:101], v[94:97]
	s_waitcnt lgkmcnt(1)
	v_mfma_f32_16x16x32_bf16 v[90:93], v[186:189], v[106:109], v[90:93]
	v_mfma_f32_16x16x32_bf16 v[86:89], v[194:197], v[98:101], v[86:89]
	v_mfma_f32_16x16x32_bf16 v[82:85], v[194:197], v[106:109], v[82:85]
	v_mfma_f32_16x16x32_bf16 v[94:97], v[190:193], v[102:105], v[94:97]
	s_waitcnt lgkmcnt(0)
	v_mfma_f32_16x16x32_bf16 v[90:93], v[190:193], v[110:113], v[90:93]
	v_mfma_f32_16x16x32_bf16 v[86:89], v[198:201], v[102:105], v[86:89]
	v_mfma_f32_16x16x32_bf16 v[82:85], v[198:201], v[110:113], v[82:85]
	v_mfma_f32_16x16x32_bf16 v[78:81], v[202:205], v[98:101], v[78:81]
	v_mfma_f32_16x16x32_bf16 v[74:77], v[202:205], v[106:109], v[74:77]
	v_mfma_f32_16x16x32_bf16 v[70:73], v[210:213], v[98:101], v[70:73]
	v_mfma_f32_16x16x32_bf16 v[66:69], v[210:213], v[106:109], v[66:69]
	v_mfma_f32_16x16x32_bf16 v[146:149], v[206:209], v[102:105], v[78:81]
	v_mfma_f32_16x16x32_bf16 v[186:189], v[206:209], v[110:113], v[74:77]
	v_mfma_f32_16x16x32_bf16 v[190:193], v[214:217], v[102:105], v[70:73]
	v_mfma_f32_16x16x32_bf16 v[194:197], v[214:217], v[110:113], v[66:69]
	s_barrier
	s_nop 1
	ds_read_b128 v[66:69], v143 offset:16384
	ds_read_b128 v[70:73], v143 offset:17408
	ds_read_b128 v[74:77], v142 offset:16384
	ds_read_b128 v[78:81], v142 offset:17408
	ds_read_b128 v[198:201], v141 offset:16384
	ds_read_b128 v[202:205], v141 offset:17408
	ds_read_b128 v[206:209], v140 offset:16384
	ds_read_b128 v[210:213], v140 offset:17408
	s_waitcnt vmcnt(4)
	s_barrier
	s_waitcnt lgkmcnt(0)
	s_waitcnt lgkmcnt(7)
	v_mfma_f32_16x16x32_bf16 v[62:65], v[66:69], v[156:159], v[62:65]
	v_mfma_f32_16x16x32_bf16 v[58:61], v[66:69], v[170:173], v[58:61]
	s_waitcnt lgkmcnt(5)
	v_mfma_f32_16x16x32_bf16 v[54:57], v[74:77], v[156:159], v[54:57]
	v_mfma_f32_16x16x32_bf16 v[50:53], v[74:77], v[170:173], v[50:53]
	v_mfma_f32_16x16x32_bf16 v[62:65], v[70:73], v[166:169], v[62:65]
	v_mfma_f32_16x16x32_bf16 v[58:61], v[70:73], v[174:177], v[58:61]
	s_waitcnt lgkmcnt(4)
	v_mfma_f32_16x16x32_bf16 v[54:57], v[78:81], v[166:169], v[54:57]
	v_mfma_f32_16x16x32_bf16 v[50:53], v[78:81], v[174:177], v[50:53]
	s_waitcnt lgkmcnt(3)
	v_mfma_f32_16x16x32_bf16 v[46:49], v[198:201], v[156:159], v[46:49]
	v_mfma_f32_16x16x32_bf16 v[42:45], v[198:201], v[170:173], v[42:45]
	s_waitcnt lgkmcnt(1)
	v_mfma_f32_16x16x32_bf16 v[38:41], v[206:209], v[156:159], v[38:41]
	v_mfma_f32_16x16x32_bf16 v[34:37], v[206:209], v[170:173], v[34:37]
	v_mfma_f32_16x16x32_bf16 v[214:217], v[202:205], v[166:169], v[46:49]
	v_mfma_f32_16x16x32_bf16 v[230:233], v[202:205], v[174:177], v[42:45]
	s_waitcnt lgkmcnt(0)
	v_mfma_f32_16x16x32_bf16 v[154:157], v[210:213], v[166:169], v[38:41]
	v_mfma_f32_16x16x32_bf16 v[158:161], v[210:213], v[174:177], v[34:37]
	v_mfma_f32_16x16x32_bf16 v[28:31], v[66:69], v[98:101], v[28:31]
	v_mfma_f32_16x16x32_bf16 v[24:27], v[66:69], v[106:109], v[24:27]
	v_mfma_f32_16x16x32_bf16 v[20:23], v[74:77], v[98:101], v[20:23]
	v_mfma_f32_16x16x32_bf16 v[16:19], v[74:77], v[106:109], v[16:19]
	v_mfma_f32_16x16x32_bf16 v[28:31], v[70:73], v[102:105], v[28:31]
	v_mfma_f32_16x16x32_bf16 v[24:27], v[70:73], v[110:113], v[24:27]
	v_mfma_f32_16x16x32_bf16 v[20:23], v[78:81], v[102:105], v[20:23]
	v_mfma_f32_16x16x32_bf16 v[16:19], v[78:81], v[110:113], v[16:19]
	v_mfma_f32_16x16x32_bf16 v[12:15], v[198:201], v[98:101], v[12:15]
	v_mfma_f32_16x16x32_bf16 v[8:11], v[198:201], v[106:109], v[8:11]
	v_mfma_f32_16x16x32_bf16 v[4:7], v[206:209], v[98:101], v[4:7]
	v_mfma_f32_16x16x32_bf16 v[0:3], v[206:209], v[106:109], v[0:3]
	v_mfma_f32_16x16x32_bf16 v[166:169], v[202:205], v[102:105], v[12:15]
	v_mfma_f32_16x16x32_bf16 v[170:173], v[202:205], v[110:113], v[8:11]
	v_mfma_f32_16x16x32_bf16 v[174:177], v[210:213], v[102:105], v[4:7]
	v_mfma_f32_16x16x32_bf16 v[198:201], v[210:213], v[110:113], v[0:3]
	s_barrier
; #define LDA(dst, b, h) _Pragma("unroll") for (int m = 0; m < 4; ++m) _Pragma("unroll") for (int k = 0; k < 2; ++k) \
;     dst[m][k] = *reinterpret_cast<const bf16x8*>((char*)SA(b, h) + lds_byte(wr * 64 + m * 16 + fr, k * 32 + fq * 8))
; #define LDB(dst, b, h) _Pragma("unroll") for (int n = 0; n < 2; ++n) _Pragma("unroll") for (int k = 0; k < 2; ++k) \
;     dst[n][k] = *reinterpret_cast<const bf16x8*>((char*)SB(b, h) + lds_byte(wc * 32 + n * 16 + fr, k * 32 + fq * 8))
; #define MMA(ai, bj, At, Bt_) do { __builtin_amdgcn_s_setprio(1); \
;     _Pragma("unroll") for (int m = 0; m < 4; ++m) _Pragma("unroll") for (int n = 0; n < 2; ++n) _Pragma("unroll") for (int k = 0; k < 2; ++k) \
;       acc[ai][bj][m][n] = __builtin_amdgcn_mfma_f32_16x16x32_bf16(At[m][k], Bt_[n][k], acc[ai][bj][m][n], 0, 0, 0); \
;     __builtin_amdgcn_s_setprio(0); } while (0)
; #define WAIT_V(n) asm volatile("s_waitcnt vmcnt(" #n ")" ::: "memory")
; #define WAIT_L(n) asm volatile("s_waitcnt lgkmcnt(" #n ")" ::: "memory")
; #define BAR __builtin_amdgcn_s_barrier()
; template <class Epi> ...
;     ...
;   { LDB(B0, 1, 0); LDA(At, 1, 0); WAIT_V(2); BAR; WAIT_L(0); MMA(0, 0, At, B0); BAR;
;     LDB(B1, 1, 1); WAIT_V(0); BAR; WAIT_L(0); MMA(0, 1, At, B1); BAR;
;     LDA(At, 1, 1); BAR; WAIT_L(0); MMA(1, 0, At, B0); MMA(1, 1, At, B1); BAR; }
;   if (wr == 0) BAR;
	ds_read_b128 v[202:205], v145
	ds_read_b128 v[206:209], v145 offset:1024
	ds_read_b128 v[210:213], v145 offset:2048
	ds_read_b128 v[234:237], v145 offset:3072
	ds_read_b128 v[0:3], v143 offset:32768
	ds_read_b128 v[4:7], v143 offset:33792
	ds_read_b128 v[8:11], v142 offset:32768
	ds_read_b128 v[34:37], v142 offset:33792
	ds_read_b128 v[238:241], v141 offset:32768
	ds_read_b128 v[242:245], v141 offset:33792
	ds_read_b128 v[246:249], v140 offset:32768
	ds_read_b128 v[250:253], v140 offset:33792
	s_waitcnt vmcnt(2)
	s_barrier
	s_waitcnt lgkmcnt(0)
	s_waitcnt lgkmcnt(7)
	v_mfma_f32_16x16x32_bf16 v[12:15], v[0:3], v[202:205], v[126:129]
	s_waitcnt lgkmcnt(6)
	v_mfma_f32_16x16x32_bf16 v[110:113], v[4:7], v[206:209], v[12:15]
	v_mfma_f32_16x16x32_bf16 v[12:15], v[0:3], v[210:213], v[122:125]
	v_mfma_f32_16x16x32_bf16 v[78:81], v[4:7], v[234:237], v[12:15]
	s_waitcnt lgkmcnt(5)
	v_mfma_f32_16x16x32_bf16 v[12:15], v[8:11], v[202:205], v[118:121]
	s_waitcnt lgkmcnt(4)
	v_mfma_f32_16x16x32_bf16 v[106:109], v[34:37], v[206:209], v[12:15]
	v_mfma_f32_16x16x32_bf16 v[12:15], v[8:11], v[210:213], v[114:117]
	v_mfma_f32_16x16x32_bf16 v[74:77], v[34:37], v[234:237], v[12:15]
	s_waitcnt lgkmcnt(3)
	v_mfma_f32_16x16x32_bf16 v[12:15], v[238:241], v[202:205], v[150:153]
	s_waitcnt lgkmcnt(2)
	v_mfma_f32_16x16x32_bf16 v[102:105], v[242:245], v[206:209], v[12:15]
	v_mfma_f32_16x16x32_bf16 v[12:15], v[238:241], v[210:213], v[218:221]
	v_mfma_f32_16x16x32_bf16 v[70:73], v[242:245], v[234:237], v[12:15]
	s_waitcnt lgkmcnt(1)
	v_mfma_f32_16x16x32_bf16 v[12:15], v[246:249], v[202:205], v[222:225]
	s_waitcnt lgkmcnt(0)
	v_mfma_f32_16x16x32_bf16 v[98:101], v[250:253], v[206:209], v[12:15]
	v_mfma_f32_16x16x32_bf16 v[12:15], v[246:249], v[210:213], v[226:229]
	v_mfma_f32_16x16x32_bf16 v[66:69], v[250:253], v[234:237], v[12:15]
	s_barrier
	ds_read_b128 v[150:153], v144
	ds_read_b128 v[218:221], v144 offset:1024
	ds_read_b128 v[222:225], v144 offset:2048
	ds_read_b128 v[226:229], v144 offset:3072
	s_waitcnt vmcnt(0)
	s_barrier
	s_waitcnt lgkmcnt(0)
	s_waitcnt lgkmcnt(3)
	v_mfma_f32_16x16x32_bf16 v[12:15], v[0:3], v[150:153], v[94:97]
	s_waitcnt lgkmcnt(1)
	v_mfma_f32_16x16x32_bf16 v[0:3], v[0:3], v[222:225], v[90:93]
	v_mfma_f32_16x16x32_bf16 v[46:49], v[4:7], v[218:221], v[12:15]
	s_waitcnt lgkmcnt(0)
	v_mfma_f32_16x16x32_bf16 v[12:15], v[4:7], v[226:229], v[0:3]
	v_mfma_f32_16x16x32_bf16 v[0:3], v[8:11], v[150:153], v[86:89]
	v_mfma_f32_16x16x32_bf16 v[42:45], v[34:37], v[218:221], v[0:3]
	v_mfma_f32_16x16x32_bf16 v[0:3], v[8:11], v[222:225], v[82:85]
	v_mfma_f32_16x16x32_bf16 v[8:11], v[34:37], v[226:229], v[0:3]
	v_mfma_f32_16x16x32_bf16 v[0:3], v[238:241], v[150:153], v[146:149]
	v_mfma_f32_16x16x32_bf16 v[38:41], v[242:245], v[218:221], v[0:3]
	v_mfma_f32_16x16x32_bf16 v[0:3], v[238:241], v[222:225], v[186:189]
	v_mfma_f32_16x16x32_bf16 v[4:7], v[242:245], v[226:229], v[0:3]
	v_mfma_f32_16x16x32_bf16 v[0:3], v[246:249], v[150:153], v[190:193]
	v_mfma_f32_16x16x32_bf16 v[34:37], v[250:253], v[218:221], v[0:3]
	v_mfma_f32_16x16x32_bf16 v[0:3], v[246:249], v[222:225], v[194:197]
	v_mfma_f32_16x16x32_bf16 v[0:3], v[250:253], v[226:229], v[0:3]
	s_barrier
	ds_read_b128 v[144:147], v143 offset:49152
	ds_read_b128 v[186:189], v143 offset:50176
	ds_read_b128 v[190:193], v142 offset:49152
	ds_read_b128 v[194:197], v142 offset:50176
	ds_read_b128 v[238:241], v141 offset:49152
	ds_read_b128 v[242:245], v141 offset:50176
	ds_read_b128 v[246:249], v140 offset:49152
	ds_read_b128 v[140:143], v140 offset:50176
	s_barrier
	s_waitcnt lgkmcnt(0)
	s_waitcnt lgkmcnt(5)
	v_mfma_f32_16x16x32_bf16 v[50:53], v[190:193], v[210:213], v[50:53]
	s_waitcnt lgkmcnt(4)
	v_mfma_f32_16x16x32_bf16 v[90:93], v[194:197], v[234:237], v[50:53]
	s_waitcnt lgkmcnt(3)
	v_mfma_f32_16x16x32_bf16 v[50:53], v[238:241], v[202:205], v[214:217]
	s_waitcnt lgkmcnt(2)
	v_mfma_f32_16x16x32_bf16 v[118:121], v[242:245], v[206:209], v[50:53]
	v_mfma_f32_16x16x32_bf16 v[50:53], v[238:241], v[210:213], v[230:233]
	v_mfma_f32_16x16x32_bf16 v[86:89], v[242:245], v[234:237], v[50:53]
	s_waitcnt lgkmcnt(1)
	v_mfma_f32_16x16x32_bf16 v[50:53], v[246:249], v[202:205], v[154:157]
	v_mfma_f32_16x16x32_bf16 v[62:65], v[144:147], v[202:205], v[62:65]
	v_mfma_f32_16x16x32_bf16 v[58:61], v[144:147], v[210:213], v[58:61]
	v_mfma_f32_16x16x32_bf16 v[54:57], v[190:193], v[202:205], v[54:57]
	s_waitcnt lgkmcnt(0)
	v_mfma_f32_16x16x32_bf16 v[114:117], v[140:143], v[206:209], v[50:53]
	v_mfma_f32_16x16x32_bf16 v[50:53], v[246:249], v[210:213], v[158:161]
	v_mfma_f32_16x16x32_bf16 v[126:129], v[186:189], v[206:209], v[62:65]
	v_mfma_f32_16x16x32_bf16 v[94:97], v[186:189], v[234:237], v[58:61]
	v_mfma_f32_16x16x32_bf16 v[122:125], v[194:197], v[206:209], v[54:57]
	v_mfma_f32_16x16x32_bf16 v[82:85], v[140:143], v[234:237], v[50:53]
	v_mfma_f32_16x16x32_bf16 v[28:31], v[144:147], v[150:153], v[28:31]
	v_mfma_f32_16x16x32_bf16 v[24:27], v[144:147], v[222:225], v[24:27]
	v_mfma_f32_16x16x32_bf16 v[16:19], v[190:193], v[222:225], v[16:19]
	v_mfma_f32_16x16x32_bf16 v[62:65], v[186:189], v[218:221], v[28:31]
	v_mfma_f32_16x16x32_bf16 v[28:31], v[186:189], v[226:229], v[24:27]
	v_mfma_f32_16x16x32_bf16 v[24:27], v[194:197], v[226:229], v[16:19]
	v_mfma_f32_16x16x32_bf16 v[16:19], v[238:241], v[150:153], v[166:169]
	v_mfma_f32_16x16x32_bf16 v[20:23], v[190:193], v[150:153], v[20:23]
	v_mfma_f32_16x16x32_bf16 v[54:57], v[242:245], v[218:221], v[16:19]
	v_mfma_f32_16x16x32_bf16 v[16:19], v[238:241], v[222:225], v[170:173]
	v_mfma_f32_16x16x32_bf16 v[58:61], v[194:197], v[218:221], v[20:23]
	v_mfma_f32_16x16x32_bf16 v[20:23], v[242:245], v[226:229], v[16:19]
	v_mfma_f32_16x16x32_bf16 v[16:19], v[246:249], v[150:153], v[174:177]
	v_mfma_f32_16x16x32_bf16 v[50:53], v[140:143], v[218:221], v[16:19]
	v_mfma_f32_16x16x32_bf16 v[16:19], v[246:249], v[222:225], v[198:201]
	v_mfma_f32_16x16x32_bf16 v[16:19], v[140:143], v[226:229], v[16:19]
	v_cmp_gt_u32_e32 vcc, s59, v130
	s_barrier
	s_and_saveexec_b64 s[10:11], vcc
	s_cbranch_execz .LBB0_2021
	s_barrier

; #define STAGE(P, BASE, br, kt) do { int _so = ((br) * K + (kt) * BK) * 2; \
;     __builtin_amdgcn_raw_ptr_buffer_load_lds(rs_##BASE, (__attribute__((address_space(3))) void*)((char*)(P) + tx * 16), 16, voff0, _so, 0, 0); \
;     __builtin_amdgcn_raw_ptr_buffer_load_lds(rs_##BASE, (__attribute__((address_space(3))) void*)((char*)(P) + tx * 16 + 8192), 16, voff1, _so, 0, 0); } while (0)
; #define LDA(dst, b, h) _Pragma("unroll") for (int m = 0; m < 4; ++m) _Pragma("unroll") for (int k = 0; k < 2; ++k) \
;     dst[m][k] = *reinterpret_cast<const bf16x8*>((char*)SA(b, h) + lds_byte(wr * 64 + m * 16 + fr, k * 32 + fq * 8))
; #define LDB(dst, b, h) _Pragma("unroll") for (int n = 0; n < 2; ++n) _Pragma("unroll") for (int k = 0; k < 2; ++k) \
;     dst[n][k] = *reinterpret_cast<const bf16x8*>((char*)SB(b, h) + lds_byte(wc * 32 + n * 16 + fr, k * 32 + fq * 8))
; #define MMA(ai, bj, At, Bt_) do { __builtin_amdgcn_s_setprio(1); \
;     _Pragma("unroll") for (int m = 0; m < 4; ++m) _Pragma("unroll") for (int n = 0; n < 2; ++n) _Pragma("unroll") for (int k = 0; k < 2; ++k) \
;       acc[ai][bj][m][n] = __builtin_amdgcn_mfma_f32_16x16x32_bf16(At[m][k], Bt_[n][k], acc[ai][bj][m][n], 0, 0, 0); \
;     __builtin_amdgcn_s_setprio(0); } while (0)
; #define WAIT_V(n) asm volatile("s_waitcnt vmcnt(" #n ")" ::: "memory")
; #define WAIT_L(n) asm volatile("s_waitcnt lgkmcnt(" #n ")" ::: "memory")
; #define BAR __builtin_amdgcn_s_barrier()
; template <class Epi> ...
;     ...
;   { LDB(B0, 0, 0); LDA(At, 0, 0); STAGE(SA(1, 1), A, brow + HALF, nt - 1);
;     BAR; WAIT_L(0); MMA(0, 0, At, B0); BAR;
;     LDB(B1, 0, 1); BAR; WAIT_L(0); MMA(0, 1, At, B1); BAR;
;     LDA(At, 0, 1); WAIT_V(4); BAR; WAIT_L(0); MMA(1, 0, At, B0); MMA(1, 1, At, B1); BAR; }
.Lpx7:
	s_or_b32 s16, s17, 0x40780
	v_readfirstlane_b32 s17, v152
	s_mov_b32 s10, s78
	s_mov_b32 s11, s79
	s_mov_b32 m0, s17
	v_readfirstlane_b32 s17, v151
	ds_read_b128 v[156:159], v155
	ds_read_b128 v[166:169], v155 offset:1024
	ds_read_b128 v[170:173], v155 offset:2048
	ds_read_b128 v[174:177], v155 offset:3072
	ds_read_b128 v[186:189], v143
	ds_read_b128 v[190:193], v143 offset:1024
	ds_read_b128 v[194:197], v142
	ds_read_b128 v[198:201], v142 offset:1024
	ds_read_b128 v[202:205], v141
	ds_read_b128 v[206:209], v141 offset:1024
	ds_read_b128 v[210:213], v140
	ds_read_b128 v[214:217], v140 offset:1024
	buffer_load_dwordx4 v32, s[8:11], s16 offen lds
	s_mov_b32 m0, s17
	s_nop 0
	buffer_load_dwordx4 v131, s[8:11], s16 offen lds
	s_barrier
	s_waitcnt lgkmcnt(0)
	s_waitcnt lgkmcnt(7)
	v_mfma_f32_16x16x32_bf16 v[126:129], v[186:189], v[156:159], v[126:129]
	s_waitcnt lgkmcnt(5)
	v_mfma_f32_16x16x32_bf16 v[118:121], v[194:197], v[156:159], v[118:121]
	s_waitcnt lgkmcnt(3)
	v_mfma_f32_16x16x32_bf16 v[110:113], v[202:205], v[156:159], v[110:113]
	v_mfma_f32_16x16x32_bf16 v[106:109], v[202:205], v[170:173], v[106:109]
	s_waitcnt lgkmcnt(1)
	v_mfma_f32_16x16x32_bf16 v[102:105], v[210:213], v[156:159], v[102:105]
	v_mfma_f32_16x16x32_bf16 v[126:129], v[190:193], v[166:169], v[126:129]
	v_mfma_f32_16x16x32_bf16 v[122:125], v[186:189], v[170:173], v[122:125]
	v_mfma_f32_16x16x32_bf16 v[118:121], v[198:201], v[166:169], v[118:121]
	v_mfma_f32_16x16x32_bf16 v[114:117], v[194:197], v[170:173], v[114:117]
	v_mfma_f32_16x16x32_bf16 v[110:113], v[206:209], v[166:169], v[110:113]
	v_mfma_f32_16x16x32_bf16 v[106:109], v[206:209], v[174:177], v[106:109]
	s_waitcnt lgkmcnt(0)
	v_mfma_f32_16x16x32_bf16 v[102:105], v[214:217], v[166:169], v[102:105]
	v_mfma_f32_16x16x32_bf16 v[98:101], v[210:213], v[170:173], v[98:101]
	v_mfma_f32_16x16x32_bf16 v[150:153], v[190:193], v[174:177], v[122:125]
	v_mfma_f32_16x16x32_bf16 v[218:221], v[198:201], v[174:177], v[114:117]
	v_mfma_f32_16x16x32_bf16 v[222:225], v[214:217], v[174:177], v[98:101]
	s_barrier
	s_nop 2
	ds_read_b128 v[98:101], v149
	ds_read_b128 v[114:117], v149 offset:1024
	ds_read_b128 v[122:125], v149 offset:2048
	ds_read_b128 v[146:149], v149 offset:3072
	s_barrier
	s_waitcnt lgkmcnt(0)
	s_waitcnt lgkmcnt(3)
	v_mfma_f32_16x16x32_bf16 v[94:97], v[186:189], v[98:101], v[94:97]
	s_waitcnt lgkmcnt(1)
	v_mfma_f32_16x16x32_bf16 v[82:85], v[194:197], v[122:125], v[82:85]
	v_mfma_f32_16x16x32_bf16 v[78:81], v[202:205], v[98:101], v[78:81]
	v_mfma_f32_16x16x32_bf16 v[70:73], v[210:213], v[98:101], v[70:73]
	v_mfma_f32_16x16x32_bf16 v[94:97], v[190:193], v[114:117], v[94:97]
	v_mfma_f32_16x16x32_bf16 v[90:93], v[186:189], v[122:125], v[90:93]
	v_mfma_f32_16x16x32_bf16 v[86:89], v[194:197], v[98:101], v[86:89]
	s_waitcnt lgkmcnt(0)
	v_mfma_f32_16x16x32_bf16 v[82:85], v[198:201], v[146:149], v[82:85]
	v_mfma_f32_16x16x32_bf16 v[78:81], v[206:209], v[114:117], v[78:81]
	v_mfma_f32_16x16x32_bf16 v[74:77], v[202:205], v[122:125], v[74:77]
	v_mfma_f32_16x16x32_bf16 v[70:73], v[214:217], v[114:117], v[70:73]
	v_mfma_f32_16x16x32_bf16 v[66:69], v[210:213], v[122:125], v[66:69]
	v_mfma_f32_16x16x32_bf16 v[186:189], v[190:193], v[146:149], v[90:93]
	v_mfma_f32_16x16x32_bf16 v[190:193], v[198:201], v[114:117], v[86:89]
	v_mfma_f32_16x16x32_bf16 v[194:197], v[206:209], v[146:149], v[74:77]
	v_mfma_f32_16x16x32_bf16 v[198:201], v[214:217], v[146:149], v[66:69]
	s_barrier
	s_nop 1
	ds_read_b128 v[66:69], v143 offset:16384
	ds_read_b128 v[74:77], v143 offset:17408
	ds_read_b128 v[86:89], v142 offset:16384
	ds_read_b128 v[90:93], v142 offset:17408
	ds_read_b128 v[202:205], v141 offset:16384
	ds_read_b128 v[206:209], v141 offset:17408
	ds_read_b128 v[210:213], v140 offset:16384
	ds_read_b128 v[214:217], v140 offset:17408
	s_waitcnt vmcnt(4)
	s_barrier
	s_waitcnt lgkmcnt(0)
	s_waitcnt lgkmcnt(7)
	v_mfma_f32_16x16x32_bf16 v[58:61], v[66:69], v[170:173], v[58:61]
	s_waitcnt lgkmcnt(5)
	v_mfma_f32_16x16x32_bf16 v[54:57], v[86:89], v[156:159], v[54:57]
	s_waitcnt lgkmcnt(3)
	v_mfma_f32_16x16x32_bf16 v[46:49], v[202:205], v[156:159], v[46:49]
	s_waitcnt lgkmcnt(1)
	v_mfma_f32_16x16x32_bf16 v[38:41], v[210:213], v[156:159], v[38:41]
	v_mfma_f32_16x16x32_bf16 v[62:65], v[66:69], v[156:159], v[62:65]
	v_mfma_f32_16x16x32_bf16 v[58:61], v[74:77], v[174:177], v[58:61]
	v_mfma_f32_16x16x32_bf16 v[54:57], v[90:93], v[166:169], v[54:57]
	v_mfma_f32_16x16x32_bf16 v[50:53], v[86:89], v[170:173], v[50:53]
	v_mfma_f32_16x16x32_bf16 v[46:49], v[206:209], v[166:169], v[46:49]
	v_mfma_f32_16x16x32_bf16 v[42:45], v[202:205], v[170:173], v[42:45]
	s_waitcnt lgkmcnt(0)
	v_mfma_f32_16x16x32_bf16 v[38:41], v[214:217], v[166:169], v[38:41]
	v_mfma_f32_16x16x32_bf16 v[34:37], v[210:213], v[170:173], v[34:37]
	v_mfma_f32_16x16x32_bf16 v[226:229], v[74:77], v[166:169], v[62:65]
	v_mfma_f32_16x16x32_bf16 v[230:233], v[90:93], v[174:177], v[50:53]
	v_mfma_f32_16x16x32_bf16 v[234:237], v[206:209], v[174:177], v[42:45]
	v_mfma_f32_16x16x32_bf16 v[154:157], v[214:217], v[174:177], v[34:37]
	v_mfma_f32_16x16x32_bf16 v[28:31], v[66:69], v[98:101], v[28:31]
	v_mfma_f32_16x16x32_bf16 v[20:23], v[86:89], v[98:101], v[20:23]
	v_mfma_f32_16x16x32_bf16 v[12:15], v[202:205], v[98:101], v[12:15]
	v_mfma_f32_16x16x32_bf16 v[4:7], v[210:213], v[98:101], v[4:7]
	v_mfma_f32_16x16x32_bf16 v[28:31], v[74:77], v[114:117], v[28:31]
	v_mfma_f32_16x16x32_bf16 v[24:27], v[66:69], v[122:125], v[24:27]
	v_mfma_f32_16x16x32_bf16 v[20:23], v[90:93], v[114:117], v[20:23]
	v_mfma_f32_16x16x32_bf16 v[16:19], v[86:89], v[122:125], v[16:19]
	v_mfma_f32_16x16x32_bf16 v[12:15], v[206:209], v[114:117], v[12:15]
	v_mfma_f32_16x16x32_bf16 v[8:11], v[202:205], v[122:125], v[8:11]
	v_mfma_f32_16x16x32_bf16 v[4:7], v[214:217], v[114:117], v[4:7]
	v_mfma_f32_16x16x32_bf16 v[0:3], v[210:213], v[122:125], v[0:3]
	v_mfma_f32_16x16x32_bf16 v[158:161], v[74:77], v[146:149], v[24:27]
	v_mfma_f32_16x16x32_bf16 v[166:169], v[90:93], v[146:149], v[16:19]
	v_mfma_f32_16x16x32_bf16 v[170:173], v[206:209], v[146:149], v[8:11]
	v_mfma_f32_16x16x32_bf16 v[146:149], v[214:217], v[146:149], v[0:3]
	s_barrier
; #define LDA(dst, b, h) _Pragma("unroll") for (int m = 0; m < 4; ++m) _Pragma("unroll") for (int k = 0; k < 2; ++k) \
;     dst[m][k] = *reinterpret_cast<const bf16x8*>((char*)SA(b, h) + lds_byte(wr * 64 + m * 16 + fr, k * 32 + fq * 8))
; #define LDB(dst, b, h) _Pragma("unroll") for (int n = 0; n < 2; ++n) _Pragma("unroll") for (int k = 0; k < 2; ++k) \
;     dst[n][k] = *reinterpret_cast<const bf16x8*>((char*)SB(b, h) + lds_byte(wc * 32 + n * 16 + fr, k * 32 + fq * 8))
; #define MMA(ai, bj, At, Bt_) do { __builtin_amdgcn_s_setprio(1); \
;     _Pragma("unroll") for (int m = 0; m < 4; ++m) _Pragma("unroll") for (int n = 0; n < 2; ++n) _Pragma("unroll") for (int k = 0; k < 2; ++k) \
;       acc[ai][bj][m][n] = __builtin_amdgcn_mfma_f32_16x16x32_bf16(At[m][k], Bt_[n][k], acc[ai][bj][m][n], 0, 0, 0); \
;     __builtin_amdgcn_s_setprio(0); } while (0)
; #define WAIT_V(n) asm volatile("s_waitcnt vmcnt(" #n ")" ::: "memory")
; #define WAIT_L(n) asm volatile("s_waitcnt lgkmcnt(" #n ")" ::: "memory")
; #define BAR __builtin_amdgcn_s_barrier()
; template <class Epi> ...
;     ...
;   { LDB(B0, 1, 0); LDA(At, 1, 0); WAIT_V(2); BAR; WAIT_L(0); MMA(0, 0, At, B0); BAR;
;     LDB(B1, 1, 1); WAIT_V(0); BAR; WAIT_L(0); MMA(0, 1, At, B1); BAR;
;     LDA(At, 1, 1); BAR; WAIT_L(0); MMA(1, 0, At, B0); MMA(1, 1, At, B1); BAR; }
;   if (wr == 0) BAR;
	ds_read_b128 v[174:177], v145
	ds_read_b128 v[202:205], v145 offset:1024
	ds_read_b128 v[206:209], v145 offset:2048
	ds_read_b128 v[210:213], v145 offset:3072
	ds_read_b128 v[0:3], v143 offset:32768
	ds_read_b128 v[8:11], v143 offset:33792
	ds_read_b128 v[16:19], v142 offset:32768
	ds_read_b128 v[34:37], v142 offset:33792
	ds_read_b128 v[214:217], v141 offset:32768
	ds_read_b128 v[238:241], v141 offset:33792
	ds_read_b128 v[242:245], v140 offset:32768
	ds_read_b128 v[246:249], v140 offset:33792
	s_waitcnt vmcnt(2)
	s_barrier
	s_waitcnt lgkmcnt(0)
	s_waitcnt lgkmcnt(7)
	v_mfma_f32_16x16x32_bf16 v[24:27], v[0:3], v[174:177], v[126:129]
	s_waitcnt lgkmcnt(6)
	v_mfma_f32_16x16x32_bf16 v[122:125], v[8:11], v[202:205], v[24:27]
	v_mfma_f32_16x16x32_bf16 v[24:27], v[0:3], v[206:209], v[150:153]
	v_mfma_f32_16x16x32_bf16 v[90:93], v[8:11], v[210:213], v[24:27]
	s_waitcnt lgkmcnt(5)
	v_mfma_f32_16x16x32_bf16 v[24:27], v[16:19], v[174:177], v[118:121]
	s_waitcnt lgkmcnt(4)
	v_mfma_f32_16x16x32_bf16 v[114:117], v[34:37], v[202:205], v[24:27]
	v_mfma_f32_16x16x32_bf16 v[24:27], v[16:19], v[206:209], v[218:221]
	v_mfma_f32_16x16x32_bf16 v[86:89], v[34:37], v[210:213], v[24:27]
	s_waitcnt lgkmcnt(3)
	v_mfma_f32_16x16x32_bf16 v[24:27], v[214:217], v[174:177], v[110:113]
	s_waitcnt lgkmcnt(2)
	v_mfma_f32_16x16x32_bf16 v[110:113], v[238:241], v[202:205], v[24:27]
	v_mfma_f32_16x16x32_bf16 v[24:27], v[214:217], v[206:209], v[106:109]
	v_mfma_f32_16x16x32_bf16 v[74:77], v[238:241], v[210:213], v[24:27]
	s_waitcnt lgkmcnt(1)
	v_mfma_f32_16x16x32_bf16 v[24:27], v[242:245], v[174:177], v[102:105]
	s_waitcnt lgkmcnt(0)
	v_mfma_f32_16x16x32_bf16 v[98:101], v[246:249], v[202:205], v[24:27]
	v_mfma_f32_16x16x32_bf16 v[24:27], v[242:245], v[206:209], v[222:225]
	v_mfma_f32_16x16x32_bf16 v[66:69], v[246:249], v[210:213], v[24:27]
	s_barrier
	ds_read_b128 v[150:153], v144
	ds_read_b128 v[218:221], v144 offset:1024
	ds_read_b128 v[222:225], v144 offset:2048
	ds_read_b128 v[250:253], v144 offset:3072
	s_waitcnt vmcnt(0)
	s_barrier
	s_waitcnt lgkmcnt(0)
	s_waitcnt lgkmcnt(3)
	v_mfma_f32_16x16x32_bf16 v[24:27], v[0:3], v[150:153], v[94:97]
	s_waitcnt lgkmcnt(1)
	v_mfma_f32_16x16x32_bf16 v[0:3], v[0:3], v[222:225], v[186:189]
	v_mfma_f32_16x16x32_bf16 v[62:65], v[8:11], v[218:221], v[24:27]
	s_waitcnt lgkmcnt(0)
	v_mfma_f32_16x16x32_bf16 v[24:27], v[8:11], v[250:253], v[0:3]
	v_mfma_f32_16x16x32_bf16 v[0:3], v[16:19], v[150:153], v[190:193]
	v_mfma_f32_16x16x32_bf16 v[50:53], v[34:37], v[218:221], v[0:3]
	v_mfma_f32_16x16x32_bf16 v[0:3], v[16:19], v[222:225], v[82:85]
	v_mfma_f32_16x16x32_bf16 v[16:19], v[34:37], v[250:253], v[0:3]
	v_mfma_f32_16x16x32_bf16 v[0:3], v[214:217], v[150:153], v[78:81]
	v_mfma_f32_16x16x32_bf16 v[42:45], v[238:241], v[218:221], v[0:3]
	v_mfma_f32_16x16x32_bf16 v[0:3], v[214:217], v[222:225], v[194:197]
	v_mfma_f32_16x16x32_bf16 v[8:11], v[238:241], v[250:253], v[0:3]
	v_mfma_f32_16x16x32_bf16 v[0:3], v[242:245], v[150:153], v[70:73]
	v_mfma_f32_16x16x32_bf16 v[34:37], v[246:249], v[218:221], v[0:3]
	v_mfma_f32_16x16x32_bf16 v[0:3], v[242:245], v[222:225], v[198:201]
	v_mfma_f32_16x16x32_bf16 v[0:3], v[246:249], v[250:253], v[0:3]
	s_barrier
	ds_read_b128 v[186:189], v143 offset:49152
	ds_read_b128 v[190:193], v143 offset:50176
	ds_read_b128 v[194:197], v142 offset:49152
	ds_read_b128 v[142:145], v142 offset:50176
	ds_read_b128 v[198:201], v141 offset:49152
	ds_read_b128 v[214:217], v141 offset:50176
	ds_read_b128 v[238:241], v140 offset:49152
	ds_read_b128 v[242:245], v140 offset:50176
	s_barrier
	s_waitcnt lgkmcnt(0)
	s_waitcnt lgkmcnt(5)
	v_mfma_f32_16x16x32_bf16 v[54:57], v[194:197], v[174:177], v[54:57]
	s_waitcnt lgkmcnt(3)
	v_mfma_f32_16x16x32_bf16 v[46:49], v[198:201], v[174:177], v[46:49]
	s_waitcnt lgkmcnt(1)
	v_mfma_f32_16x16x32_bf16 v[38:41], v[238:241], v[174:177], v[38:41]
	v_mfma_f32_16x16x32_bf16 v[70:73], v[186:189], v[174:177], v[226:229]
	v_mfma_f32_16x16x32_bf16 v[58:61], v[186:189], v[206:209], v[58:61]
	v_mfma_f32_16x16x32_bf16 v[118:121], v[142:145], v[202:205], v[54:57]
	v_mfma_f32_16x16x32_bf16 v[54:57], v[194:197], v[206:209], v[230:233]
	v_mfma_f32_16x16x32_bf16 v[106:109], v[214:217], v[202:205], v[46:49]
	v_mfma_f32_16x16x32_bf16 v[46:49], v[198:201], v[206:209], v[234:237]
	s_waitcnt lgkmcnt(0)
	v_mfma_f32_16x16x32_bf16 v[102:105], v[242:245], v[202:205], v[38:41]
	v_mfma_f32_16x16x32_bf16 v[38:41], v[238:241], v[206:209], v[154:157]
	v_mfma_f32_16x16x32_bf16 v[126:129], v[190:193], v[202:205], v[70:73]
	v_mfma_f32_16x16x32_bf16 v[94:97], v[190:193], v[210:213], v[58:61]
	v_mfma_f32_16x16x32_bf16 v[82:85], v[142:145], v[210:213], v[54:57]
	v_mfma_f32_16x16x32_bf16 v[78:81], v[214:217], v[210:213], v[46:49]
	v_mfma_f32_16x16x32_bf16 v[70:73], v[242:245], v[210:213], v[38:41]
	v_mfma_f32_16x16x32_bf16 v[28:31], v[186:189], v[150:153], v[28:31]
	v_mfma_f32_16x16x32_bf16 v[20:23], v[194:197], v[150:153], v[20:23]
	v_mfma_f32_16x16x32_bf16 v[12:15], v[198:201], v[150:153], v[12:15]
	v_mfma_f32_16x16x32_bf16 v[4:7], v[238:241], v[150:153], v[4:7]
	v_mfma_f32_16x16x32_bf16 v[58:61], v[190:193], v[218:221], v[28:31]
	v_mfma_f32_16x16x32_bf16 v[28:31], v[186:189], v[222:225], v[158:161]
	v_mfma_f32_16x16x32_bf16 v[54:57], v[142:145], v[218:221], v[20:23]
	v_mfma_f32_16x16x32_bf16 v[20:23], v[194:197], v[222:225], v[166:169]
	v_mfma_f32_16x16x32_bf16 v[46:49], v[214:217], v[218:221], v[12:15]
	v_mfma_f32_16x16x32_bf16 v[12:15], v[198:201], v[222:225], v[170:173]
	v_mfma_f32_16x16x32_bf16 v[38:41], v[242:245], v[218:221], v[4:7]
	v_mfma_f32_16x16x32_bf16 v[4:7], v[238:241], v[222:225], v[146:149]
	v_mfma_f32_16x16x32_bf16 v[28:31], v[190:193], v[250:253], v[28:31]
	v_mfma_f32_16x16x32_bf16 v[20:23], v[142:145], v[250:253], v[20:23]
	v_mfma_f32_16x16x32_bf16 v[12:15], v[214:217], v[250:253], v[12:15]
	v_mfma_f32_16x16x32_bf16 v[4:7], v[242:245], v[250:253], v[4:7]
	v_cmp_gt_u32_e32 vcc, s59, v130
	s_barrier
	s_and_saveexec_b64 s[10:11], vcc
	s_cbranch_execz .LBB0_2256
	s_barrier

; #define STAGE(P, BASE, br, kt) do { int _so = ((br) * K + (kt) * BK) * 2; \
;     __builtin_amdgcn_raw_ptr_buffer_load_lds(rs_##BASE, (__attribute__((address_space(3))) void*)((char*)(P) + tx * 16), 16, voff0, _so, 0, 0); \
;     __builtin_amdgcn_raw_ptr_buffer_load_lds(rs_##BASE, (__attribute__((address_space(3))) void*)((char*)(P) + tx * 16 + 8192), 16, voff1, _so, 0, 0); } while (0)
; #define LDA(dst, b, h) _Pragma("unroll") for (int m = 0; m < 4; ++m) _Pragma("unroll") for (int k = 0; k < 2; ++k) \
;     dst[m][k] = *reinterpret_cast<const bf16x8*>((char*)SA(b, h) + lds_byte(wr * 64 + m * 16 + fr, k * 32 + fq * 8))
; #define LDB(dst, b, h) _Pragma("unroll") for (int n = 0; n < 2; ++n) _Pragma("unroll") for (int k = 0; k < 2; ++k) \
;     dst[n][k] = *reinterpret_cast<const bf16x8*>((char*)SB(b, h) + lds_byte(wc * 32 + n * 16 + fr, k * 32 + fq * 8))
; #define MMA(ai, bj, At, Bt_) do { __builtin_amdgcn_s_setprio(1); \
;     _Pragma("unroll") for (int m = 0; m < 4; ++m) _Pragma("unroll") for (int n = 0; n < 2; ++n) _Pragma("unroll") for (int k = 0; k < 2; ++k) \
;       acc[ai][bj][m][n] = __builtin_amdgcn_mfma_f32_16x16x32_bf16(At[m][k], Bt_[n][k], acc[ai][bj][m][n], 0, 0, 0); \
;     __builtin_amdgcn_s_setprio(0); } while (0)
; #define WAIT_V(n) asm volatile("s_waitcnt vmcnt(" #n ")" ::: "memory")
; #define WAIT_L(n) asm volatile("s_waitcnt lgkmcnt(" #n ")" ::: "memory")
; #define BAR __builtin_amdgcn_s_barrier()
; #define SCHED __builtin_amdgcn_sched_barrier(0)
; template <class Epi> ...
;     ...
;     LDB(B0, 0, 0); SCHED; LDA(At, 0, 0); STAGE(SA(1, 1), A, brow + HALF, t + 1);
;     WAIT_L(8); BAR; WAIT_L(0); MMA(0, 0, At, B0); BAR; SCHED;
;     LDB(B1, 0, 1); STAGE(SB(0, 0), Bt, bcol, t + 2);
;     BAR; WAIT_L(0); MMA(0, 1, At, B1); BAR;
;     LDA(At, 0, 1); STAGE(SA(0, 0), A, brow, t + 2);
;     BAR; WAIT_L(0); MMA(1, 0, At, B0); BAR; SCHED;
;     STAGE(SB(0, 1), Bt, bcol + HALF, t + 2);
;     WAIT_V(6); BAR; MMA(1, 1, At, B1); BAR;
.Lpk8:
	ds_read_b128 v[156:159], v155
	ds_read_b128 v[166:169], v155 offset:1024
	ds_read_b128 v[170:173], v155 offset:2048
	ds_read_b128 v[174:177], v155 offset:3072
	s_add_i32 s23, s21, s15
	v_readfirstlane_b32 s25, v152
	s_add_i32 s24, s23, 0xb0080
	s_mov_b32 m0, s25
	v_readfirstlane_b32 s25, v151
	ds_read_b128 v[186:189], v143
	ds_read_b128 v[190:193], v143 offset:1024
	ds_read_b128 v[194:197], v142
	ds_read_b128 v[198:201], v142 offset:1024
	ds_read_b128 v[202:205], v141
	ds_read_b128 v[206:209], v141 offset:1024
	ds_read_b128 v[210:213], v140
	ds_read_b128 v[214:217], v140 offset:1024
	buffer_load_dwordx4 v32, s[4:7], s24 offen lds
	s_mov_b32 m0, s25
	s_nop 0
	buffer_load_dwordx4 v131, s[4:7], s24 offen lds
	s_waitcnt lgkmcnt(8)
	s_barrier
	s_waitcnt lgkmcnt(0)
	s_waitcnt lgkmcnt(7)
	v_mfma_f32_16x16x32_bf16 v[126:129], v[186:189], v[156:159], 0
	v_mfma_f32_16x16x32_bf16 v[122:125], v[186:189], v[170:173], 0
	s_waitcnt lgkmcnt(5)
	v_mfma_f32_16x16x32_bf16 v[118:121], v[194:197], v[156:159], 0
	v_mfma_f32_16x16x32_bf16 v[114:117], v[194:197], v[170:173], 0
	s_waitcnt lgkmcnt(3)
	v_mfma_f32_16x16x32_bf16 v[110:113], v[202:205], v[156:159], 0
	v_mfma_f32_16x16x32_bf16 v[106:109], v[202:205], v[170:173], 0
	s_waitcnt lgkmcnt(1)
	v_mfma_f32_16x16x32_bf16 v[102:105], v[210:213], v[156:159], 0
	v_mfma_f32_16x16x32_bf16 v[98:101], v[210:213], v[170:173], 0
	v_mfma_f32_16x16x32_bf16 v[126:129], v[190:193], v[166:169], v[126:129]
	v_mfma_f32_16x16x32_bf16 v[122:125], v[190:193], v[174:177], v[122:125]
	v_mfma_f32_16x16x32_bf16 v[118:121], v[198:201], v[166:169], v[118:121]
	v_mfma_f32_16x16x32_bf16 v[114:117], v[198:201], v[174:177], v[114:117]
	v_mfma_f32_16x16x32_bf16 v[110:113], v[206:209], v[166:169], v[110:113]
	v_mfma_f32_16x16x32_bf16 v[106:109], v[206:209], v[174:177], v[106:109]
	s_waitcnt lgkmcnt(0)
	v_mfma_f32_16x16x32_bf16 v[102:105], v[214:217], v[166:169], v[102:105]
	v_mfma_f32_16x16x32_bf16 v[98:101], v[214:217], v[174:177], v[98:101]
	s_barrier
	s_add_i32 s24, s22, s15
	v_readfirstlane_b32 s26, v137
	s_add_i32 s25, s24, 0x100
	s_mov_b32 m0, s26
	v_readfirstlane_b32 s26, v139
	ds_read_b128 v[218:221], v149
	ds_read_b128 v[222:225], v149 offset:1024
	ds_read_b128 v[226:229], v149 offset:2048
	ds_read_b128 v[230:233], v149 offset:3072
	buffer_load_dwordx4 v32, s[76:79], s25 offen lds
	s_mov_b32 m0, s26
	s_nop 0
	buffer_load_dwordx4 v131, s[76:79], s25 offen lds
	s_barrier
	s_waitcnt lgkmcnt(0)
	s_waitcnt lgkmcnt(3)
	v_mfma_f32_16x16x32_bf16 v[94:97], v[186:189], v[218:221], 0
	s_waitcnt lgkmcnt(1)
	v_mfma_f32_16x16x32_bf16 v[90:93], v[186:189], v[226:229], 0
	v_mfma_f32_16x16x32_bf16 v[86:89], v[194:197], v[218:221], 0
	v_mfma_f32_16x16x32_bf16 v[82:85], v[194:197], v[226:229], 0
	v_mfma_f32_16x16x32_bf16 v[78:81], v[202:205], v[218:221], 0
	v_mfma_f32_16x16x32_bf16 v[74:77], v[202:205], v[226:229], 0
	v_mfma_f32_16x16x32_bf16 v[70:73], v[210:213], v[218:221], 0
	v_mfma_f32_16x16x32_bf16 v[66:69], v[210:213], v[226:229], 0
	v_mfma_f32_16x16x32_bf16 v[94:97], v[190:193], v[222:225], v[94:97]
	s_waitcnt lgkmcnt(0)
	v_mfma_f32_16x16x32_bf16 v[90:93], v[190:193], v[230:233], v[90:93]
	v_mfma_f32_16x16x32_bf16 v[86:89], v[198:201], v[222:225], v[86:89]
	v_mfma_f32_16x16x32_bf16 v[82:85], v[198:201], v[230:233], v[82:85]
	v_mfma_f32_16x16x32_bf16 v[78:81], v[206:209], v[222:225], v[78:81]
	v_mfma_f32_16x16x32_bf16 v[74:77], v[206:209], v[230:233], v[74:77]
	v_mfma_f32_16x16x32_bf16 v[70:73], v[214:217], v[222:225], v[70:73]
	v_mfma_f32_16x16x32_bf16 v[66:69], v[214:217], v[230:233], v[66:69]
	v_readfirstlane_b32 s26, v136
	s_add_i32 s25, s23, 0x100
	s_mov_b32 m0, s26
	v_readfirstlane_b32 s26, v135
	s_barrier
	ds_read_b128 v[186:189], v143 offset:16384
	ds_read_b128 v[190:193], v143 offset:17408
	ds_read_b128 v[194:197], v142 offset:16384
	ds_read_b128 v[198:201], v142 offset:17408
	ds_read_b128 v[202:205], v141 offset:16384
	ds_read_b128 v[206:209], v141 offset:17408
	ds_read_b128 v[210:213], v140 offset:16384
	ds_read_b128 v[214:217], v140 offset:17408
	buffer_load_dwordx4 v32, s[4:7], s25 offen lds
	s_mov_b32 m0, s26
	s_nop 0
	buffer_load_dwordx4 v131, s[4:7], s25 offen lds
	s_barrier
	s_waitcnt lgkmcnt(0)
	s_waitcnt lgkmcnt(7)
	v_mfma_f32_16x16x32_bf16 v[62:65], v[186:189], v[156:159], 0
	v_mfma_f32_16x16x32_bf16 v[58:61], v[186:189], v[170:173], 0
	s_waitcnt lgkmcnt(5)
	v_mfma_f32_16x16x32_bf16 v[54:57], v[194:197], v[156:159], 0
	v_mfma_f32_16x16x32_bf16 v[50:53], v[194:197], v[170:173], 0
	s_waitcnt lgkmcnt(3)
	v_mfma_f32_16x16x32_bf16 v[46:49], v[202:205], v[156:159], 0
	v_mfma_f32_16x16x32_bf16 v[42:45], v[202:205], v[170:173], 0
	s_waitcnt lgkmcnt(1)
	v_mfma_f32_16x16x32_bf16 v[38:41], v[210:213], v[156:159], 0
	v_mfma_f32_16x16x32_bf16 v[34:37], v[210:213], v[170:173], 0
	v_mfma_f32_16x16x32_bf16 v[62:65], v[190:193], v[166:169], v[62:65]
	v_mfma_f32_16x16x32_bf16 v[58:61], v[190:193], v[174:177], v[58:61]
	v_mfma_f32_16x16x32_bf16 v[54:57], v[198:201], v[166:169], v[54:57]
	v_mfma_f32_16x16x32_bf16 v[50:53], v[198:201], v[174:177], v[50:53]
	v_mfma_f32_16x16x32_bf16 v[46:49], v[206:209], v[166:169], v[46:49]
	v_mfma_f32_16x16x32_bf16 v[42:45], v[206:209], v[174:177], v[42:45]
	s_waitcnt lgkmcnt(0)
	v_mfma_f32_16x16x32_bf16 v[38:41], v[214:217], v[166:169], v[38:41]
	v_mfma_f32_16x16x32_bf16 v[34:37], v[214:217], v[174:177], v[34:37]
	s_barrier
	v_readfirstlane_b32 s26, v134
	s_add_i32 s25, s24, 0xb0100
	s_mov_b32 m0, s26
	v_readfirstlane_b32 s26, v138
	buffer_load_dwordx4 v32, s[76:79], s25 offen lds
	s_mov_b32 m0, s26
	s_nop 0
	buffer_load_dwordx4 v131, s[76:79], s25 offen lds
	s_waitcnt vmcnt(6)
	s_barrier
; #define STAGE(P, BASE, br, kt) do { int _so = ((br) * K + (kt) * BK) * 2; \
;     __builtin_amdgcn_raw_ptr_buffer_load_lds(rs_##BASE, (__attribute__((address_space(3))) void*)((char*)(P) + tx * 16), 16, voff0, _so, 0, 0); \
;     __builtin_amdgcn_raw_ptr_buffer_load_lds(rs_##BASE, (__attribute__((address_space(3))) void*)((char*)(P) + tx * 16 + 8192), 16, voff1, _so, 0, 0); } while (0)
; #define LDA(dst, b, h) _Pragma("unroll") for (int m = 0; m < 4; ++m) _Pragma("unroll") for (int k = 0; k < 2; ++k) \
;     dst[m][k] = *reinterpret_cast<const bf16x8*>((char*)SA(b, h) + lds_byte(wr * 64 + m * 16 + fr, k * 32 + fq * 8))
; #define LDB(dst, b, h) _Pragma("unroll") for (int n = 0; n < 2; ++n) _Pragma("unroll") for (int k = 0; k < 2; ++k) \
;     dst[n][k] = *reinterpret_cast<const bf16x8*>((char*)SB(b, h) + lds_byte(wc * 32 + n * 16 + fr, k * 32 + fq * 8))
; #define MMA(ai, bj, At, Bt_) do { __builtin_amdgcn_s_setprio(1); \
;     _Pragma("unroll") for (int m = 0; m < 4; ++m) _Pragma("unroll") for (int n = 0; n < 2; ++n) _Pragma("unroll") for (int k = 0; k < 2; ++k) \
;       acc[ai][bj][m][n] = __builtin_amdgcn_mfma_f32_16x16x32_bf16(At[m][k], Bt_[n][k], acc[ai][bj][m][n], 0, 0, 0); \
;     __builtin_amdgcn_s_setprio(0); } while (0)
; #define WAIT_V(n) asm volatile("s_waitcnt vmcnt(" #n ")" ::: "memory")
; #define WAIT_L(n) asm volatile("s_waitcnt lgkmcnt(" #n ")" ::: "memory")
; #define BAR __builtin_amdgcn_s_barrier()
; #define SCHED __builtin_amdgcn_sched_barrier(0)
; template <class Epi> ...
;     ...
;     WAIT_V(6); BAR; MMA(1, 1, At, B1); BAR;
;     LDB(B0, 1, 0); SCHED; LDA(At, 1, 0); STAGE(SA(0, 1), A, brow + HALF, t + 2);
;     WAIT_L(8); BAR; WAIT_L(0); MMA(0, 0, At, B0); BAR; SCHED;
;     LDB(B1, 1, 1); STAGE(SB(1, 0), Bt, bcol, t + 3);
;     BAR; WAIT_L(0); MMA(0, 1, At, B1); BAR;
;     LDA(At, 1, 1); STAGE(SA(1, 0), A, brow, t + 3);
;     BAR; WAIT_L(0); MMA(1, 0, At, B0); BAR; SCHED;
;     STAGE(SB(1, 1), Bt, bcol + HALF, t + 3);
;     WAIT_V(6); BAR; MMA(1, 1, At, B1); BAR;
	v_mfma_f32_16x16x32_bf16 v[28:31], v[186:189], v[218:221], 0
	v_mfma_f32_16x16x32_bf16 v[24:27], v[186:189], v[226:229], 0
	v_mfma_f32_16x16x32_bf16 v[20:23], v[194:197], v[218:221], 0
	v_mfma_f32_16x16x32_bf16 v[16:19], v[194:197], v[226:229], 0
	v_mfma_f32_16x16x32_bf16 v[12:15], v[202:205], v[218:221], 0
	v_mfma_f32_16x16x32_bf16 v[8:11], v[202:205], v[226:229], 0
	v_mfma_f32_16x16x32_bf16 v[4:7], v[210:213], v[218:221], 0
	v_mfma_f32_16x16x32_bf16 v[0:3], v[210:213], v[226:229], 0
	v_mfma_f32_16x16x32_bf16 v[28:31], v[190:193], v[222:225], v[28:31]
	v_mfma_f32_16x16x32_bf16 v[24:27], v[190:193], v[230:233], v[24:27]
	v_mfma_f32_16x16x32_bf16 v[20:23], v[198:201], v[222:225], v[20:23]
	v_mfma_f32_16x16x32_bf16 v[16:19], v[198:201], v[230:233], v[16:19]
	v_mfma_f32_16x16x32_bf16 v[12:15], v[206:209], v[222:225], v[12:15]
	v_mfma_f32_16x16x32_bf16 v[8:11], v[206:209], v[230:233], v[8:11]
	v_mfma_f32_16x16x32_bf16 v[4:7], v[214:217], v[222:225], v[4:7]
	v_mfma_f32_16x16x32_bf16 v[0:3], v[214:217], v[230:233], v[0:3]
	s_barrier
	ds_read_b128 v[156:159], v145
	ds_read_b128 v[166:169], v145 offset:1024
	ds_read_b128 v[170:173], v145 offset:2048
	ds_read_b128 v[174:177], v145 offset:3072
	v_readfirstlane_b32 s26, v133
	s_add_i32 s25, s23, 0xb0100
	s_mov_b32 m0, s26
	v_readfirstlane_b32 s26, v132
	ds_read_b128 v[186:189], v143 offset:32768
	ds_read_b128 v[190:193], v143 offset:33792
	ds_read_b128 v[194:197], v142 offset:32768
	ds_read_b128 v[198:201], v142 offset:33792
	ds_read_b128 v[202:205], v141 offset:32768
	ds_read_b128 v[206:209], v141 offset:33792
	ds_read_b128 v[210:213], v140 offset:32768
	ds_read_b128 v[214:217], v140 offset:33792
	buffer_load_dwordx4 v32, s[4:7], s25 offen lds
	s_mov_b32 m0, s26
	s_nop 0
	buffer_load_dwordx4 v131, s[4:7], s25 offen lds
	s_waitcnt lgkmcnt(8)
	s_barrier
	s_waitcnt lgkmcnt(0)
	s_waitcnt lgkmcnt(7)
	v_mfma_f32_16x16x32_bf16 v[126:129], v[186:189], v[156:159], v[126:129]
	v_mfma_f32_16x16x32_bf16 v[122:125], v[186:189], v[170:173], v[122:125]
	s_waitcnt lgkmcnt(5)
	v_mfma_f32_16x16x32_bf16 v[118:121], v[194:197], v[156:159], v[118:121]
	v_mfma_f32_16x16x32_bf16 v[114:117], v[194:197], v[170:173], v[114:117]
	s_waitcnt lgkmcnt(3)
	v_mfma_f32_16x16x32_bf16 v[110:113], v[202:205], v[156:159], v[110:113]
	v_mfma_f32_16x16x32_bf16 v[106:109], v[202:205], v[170:173], v[106:109]
	s_waitcnt lgkmcnt(1)
	v_mfma_f32_16x16x32_bf16 v[102:105], v[210:213], v[156:159], v[102:105]
	v_mfma_f32_16x16x32_bf16 v[98:101], v[210:213], v[170:173], v[98:101]
	v_mfma_f32_16x16x32_bf16 v[126:129], v[190:193], v[166:169], v[126:129]
	v_mfma_f32_16x16x32_bf16 v[122:125], v[190:193], v[174:177], v[122:125]
	v_mfma_f32_16x16x32_bf16 v[118:121], v[198:201], v[166:169], v[118:121]
	v_mfma_f32_16x16x32_bf16 v[114:117], v[198:201], v[174:177], v[114:117]
	v_mfma_f32_16x16x32_bf16 v[110:113], v[206:209], v[166:169], v[110:113]
	v_mfma_f32_16x16x32_bf16 v[106:109], v[206:209], v[174:177], v[106:109]
	s_waitcnt lgkmcnt(0)
	v_mfma_f32_16x16x32_bf16 v[102:105], v[214:217], v[166:169], v[102:105]
	v_mfma_f32_16x16x32_bf16 v[98:101], v[214:217], v[174:177], v[98:101]
	s_barrier
	v_readfirstlane_b32 s26, v146
	s_add_i32 s25, s24, 0x180
	s_mov_b32 m0, s26
	v_readfirstlane_b32 s26, v147
	ds_read_b128 v[218:221], v144
	ds_read_b128 v[222:225], v144 offset:1024
	ds_read_b128 v[226:229], v144 offset:2048
	ds_read_b128 v[230:233], v144 offset:3072
	buffer_load_dwordx4 v32, s[76:79], s25 offen lds
	s_mov_b32 m0, s26
	s_nop 0
	buffer_load_dwordx4 v131, s[76:79], s25 offen lds
	s_barrier
	s_waitcnt lgkmcnt(0)
	s_waitcnt lgkmcnt(3)
	v_mfma_f32_16x16x32_bf16 v[94:97], v[186:189], v[218:221], v[94:97]
	s_waitcnt lgkmcnt(1)
	v_mfma_f32_16x16x32_bf16 v[90:93], v[186:189], v[226:229], v[90:93]
	v_mfma_f32_16x16x32_bf16 v[86:89], v[194:197], v[218:221], v[86:89]
	v_mfma_f32_16x16x32_bf16 v[82:85], v[194:197], v[226:229], v[82:85]
	v_mfma_f32_16x16x32_bf16 v[78:81], v[202:205], v[218:221], v[78:81]
	v_mfma_f32_16x16x32_bf16 v[74:77], v[202:205], v[226:229], v[74:77]
	v_mfma_f32_16x16x32_bf16 v[70:73], v[210:213], v[218:221], v[70:73]
	v_mfma_f32_16x16x32_bf16 v[66:69], v[210:213], v[226:229], v[66:69]
	v_mfma_f32_16x16x32_bf16 v[94:97], v[190:193], v[222:225], v[94:97]
	s_waitcnt lgkmcnt(0)
	v_mfma_f32_16x16x32_bf16 v[90:93], v[190:193], v[230:233], v[90:93]
	v_mfma_f32_16x16x32_bf16 v[86:89], v[198:201], v[222:225], v[86:89]
	v_mfma_f32_16x16x32_bf16 v[82:85], v[198:201], v[230:233], v[82:85]
	v_mfma_f32_16x16x32_bf16 v[78:81], v[206:209], v[222:225], v[78:81]
	v_mfma_f32_16x16x32_bf16 v[74:77], v[206:209], v[230:233], v[74:77]
	v_mfma_f32_16x16x32_bf16 v[70:73], v[214:217], v[222:225], v[70:73]
	v_mfma_f32_16x16x32_bf16 v[66:69], v[214:217], v[230:233], v[66:69]
	v_readfirstlane_b32 s25, v148
	s_addk_i32 s23, 0x180
	s_mov_b32 m0, s25
	v_readfirstlane_b32 s25, v150
	s_barrier
	ds_read_b128 v[186:189], v143 offset:49152
	ds_read_b128 v[190:193], v143 offset:50176
	ds_read_b128 v[194:197], v142 offset:49152
	ds_read_b128 v[198:201], v142 offset:50176
	ds_read_b128 v[202:205], v141 offset:49152
	ds_read_b128 v[206:209], v141 offset:50176
	ds_read_b128 v[210:213], v140 offset:49152
	ds_read_b128 v[214:217], v140 offset:50176
	buffer_load_dwordx4 v32, s[4:7], s23 offen lds
	s_mov_b32 m0, s25
	s_nop 0
	buffer_load_dwordx4 v131, s[4:7], s23 offen lds
	s_barrier
; #define STAGE(P, BASE, br, kt) do { int _so = ((br) * K + (kt) * BK) * 2; \
;     __builtin_amdgcn_raw_ptr_buffer_load_lds(rs_##BASE, (__attribute__((address_space(3))) void*)((char*)(P) + tx * 16), 16, voff0, _so, 0, 0); \
;     __builtin_amdgcn_raw_ptr_buffer_load_lds(rs_##BASE, (__attribute__((address_space(3))) void*)((char*)(P) + tx * 16 + 8192), 16, voff1, _so, 0, 0); } while (0)
; #define LDA(dst, b, h) _Pragma("unroll") for (int m = 0; m < 4; ++m) _Pragma("unroll") for (int k = 0; k < 2; ++k) \
;     dst[m][k] = *reinterpret_cast<const bf16x8*>((char*)SA(b, h) + lds_byte(wr * 64 + m * 16 + fr, k * 32 + fq * 8))
; #define LDB(dst, b, h) _Pragma("unroll") for (int n = 0; n < 2; ++n) _Pragma("unroll") for (int k = 0; k < 2; ++k) \
;     dst[n][k] = *reinterpret_cast<const bf16x8*>((char*)SB(b, h) + lds_byte(wc * 32 + n * 16 + fr, k * 32 + fq * 8))
; #define MMA(ai, bj, At, Bt_) do { __builtin_amdgcn_s_setprio(1); \
;     _Pragma("unroll") for (int m = 0; m < 4; ++m) _Pragma("unroll") for (int n = 0; n < 2; ++n) _Pragma("unroll") for (int k = 0; k < 2; ++k) \
;       acc[ai][bj][m][n] = __builtin_amdgcn_mfma_f32_16x16x32_bf16(At[m][k], Bt_[n][k], acc[ai][bj][m][n], 0, 0, 0); \
;     __builtin_amdgcn_s_setprio(0); } while (0)
; #define WAIT_V(n) asm volatile("s_waitcnt vmcnt(" #n ")" ::: "memory")
; #define WAIT_L(n) asm volatile("s_waitcnt lgkmcnt(" #n ")" ::: "memory")
; #define BAR __builtin_amdgcn_s_barrier()
; #define SCHED __builtin_amdgcn_sched_barrier(0)
; template <class Epi> ...
;     ...
;     LDB(B0, 0, 0); SCHED; LDA(At, 0, 0); STAGE(SA(1, 1), A, brow + HALF, t + 1);
;     WAIT_L(8); BAR; WAIT_L(0); MMA(0, 0, At, B0); BAR; SCHED;
;     LDB(B1, 0, 1); STAGE(SB(0, 0), Bt, bcol, t + 2);
;     ...
;     BAR; WAIT_L(0); MMA(1, 0, At, B0); BAR; SCHED;
;     STAGE(SB(1, 1), Bt, bcol + HALF, t + 3);
;     WAIT_V(6); BAR; MMA(1, 1, At, B1); BAR;
;   }
	s_waitcnt lgkmcnt(0)
	s_waitcnt lgkmcnt(7)
	v_mfma_f32_16x16x32_bf16 v[62:65], v[186:189], v[156:159], v[62:65]
	v_mfma_f32_16x16x32_bf16 v[58:61], v[186:189], v[170:173], v[58:61]
	s_waitcnt lgkmcnt(5)
	v_mfma_f32_16x16x32_bf16 v[54:57], v[194:197], v[156:159], v[54:57]
	v_mfma_f32_16x16x32_bf16 v[50:53], v[194:197], v[170:173], v[50:53]
	s_waitcnt lgkmcnt(3)
	v_mfma_f32_16x16x32_bf16 v[46:49], v[202:205], v[156:159], v[46:49]
	v_mfma_f32_16x16x32_bf16 v[42:45], v[202:205], v[170:173], v[42:45]
	s_waitcnt lgkmcnt(1)
	v_mfma_f32_16x16x32_bf16 v[38:41], v[210:213], v[156:159], v[38:41]
	v_mfma_f32_16x16x32_bf16 v[34:37], v[210:213], v[170:173], v[34:37]
	v_mfma_f32_16x16x32_bf16 v[62:65], v[190:193], v[166:169], v[62:65]
	v_mfma_f32_16x16x32_bf16 v[58:61], v[190:193], v[174:177], v[58:61]
	v_mfma_f32_16x16x32_bf16 v[54:57], v[198:201], v[166:169], v[54:57]
	v_mfma_f32_16x16x32_bf16 v[50:53], v[198:201], v[174:177], v[50:53]
	v_mfma_f32_16x16x32_bf16 v[46:49], v[206:209], v[166:169], v[46:49]
	v_mfma_f32_16x16x32_bf16 v[42:45], v[206:209], v[174:177], v[42:45]
	s_waitcnt lgkmcnt(0)
	v_mfma_f32_16x16x32_bf16 v[38:41], v[214:217], v[166:169], v[38:41]
	v_mfma_f32_16x16x32_bf16 v[34:37], v[214:217], v[174:177], v[34:37]
	s_barrier
	v_readfirstlane_b32 s23, v153
	s_add_i32 s24, s24, 0xb0180
	s_mov_b32 m0, s23
	v_readfirstlane_b32 s23, v154
	buffer_load_dwordx4 v32, s[76:79], s24 offen lds
	s_mov_b32 m0, s23
	s_nop 0
	buffer_load_dwordx4 v131, s[76:79], s24 offen lds
	s_waitcnt vmcnt(6)
	s_barrier
	v_mfma_f32_16x16x32_bf16 v[28:31], v[186:189], v[218:221], v[28:31]
	v_mfma_f32_16x16x32_bf16 v[24:27], v[186:189], v[226:229], v[24:27]
	v_mfma_f32_16x16x32_bf16 v[20:23], v[194:197], v[218:221], v[20:23]
	v_mfma_f32_16x16x32_bf16 v[16:19], v[194:197], v[226:229], v[16:19]
	v_mfma_f32_16x16x32_bf16 v[12:15], v[202:205], v[218:221], v[12:15]
	v_mfma_f32_16x16x32_bf16 v[8:11], v[202:205], v[226:229], v[8:11]
	v_mfma_f32_16x16x32_bf16 v[4:7], v[210:213], v[218:221], v[4:7]
	v_mfma_f32_16x16x32_bf16 v[0:3], v[210:213], v[226:229], v[0:3]
	v_mfma_f32_16x16x32_bf16 v[28:31], v[190:193], v[222:225], v[28:31]
	v_mfma_f32_16x16x32_bf16 v[24:27], v[190:193], v[230:233], v[24:27]
	v_mfma_f32_16x16x32_bf16 v[20:23], v[198:201], v[222:225], v[20:23]
	v_mfma_f32_16x16x32_bf16 v[16:19], v[198:201], v[230:233], v[16:19]
	v_mfma_f32_16x16x32_bf16 v[12:15], v[206:209], v[222:225], v[12:15]
	v_mfma_f32_16x16x32_bf16 v[8:11], v[206:209], v[230:233], v[8:11]
	v_mfma_f32_16x16x32_bf16 v[4:7], v[214:217], v[222:225], v[4:7]
	v_mfma_f32_16x16x32_bf16 v[0:3], v[214:217], v[230:233], v[0:3]
	s_add_i32 s14, s14, 2
	s_addk_i32 s15, 0x100
	s_cmp_lt_u32 s14, 40
	s_barrier
	s_cbranch_scc1 .LBB0_2336
	s_branch .Lpx8
.LBB0_2336:
	ds_read_b128 v[156:159], v155
	ds_read_b128 v[166:169], v155 offset:1024
	ds_read_b128 v[170:173], v155 offset:2048
	ds_read_b128 v[174:177], v155 offset:3072
	s_add_i32 s23, s21, s15
	v_readfirstlane_b32 s25, v152
	s_add_i32 s24, s23, 0xb0080
	s_mov_b32 m0, s25
	v_readfirstlane_b32 s25, v151
	ds_read_b128 v[186:189], v143
	ds_read_b128 v[190:193], v143 offset:1024
	ds_read_b128 v[194:197], v142
	ds_read_b128 v[198:201], v142 offset:1024
	ds_read_b128 v[202:205], v141
	ds_read_b128 v[206:209], v141 offset:1024
	ds_read_b128 v[210:213], v140
	ds_read_b128 v[214:217], v140 offset:1024
	buffer_load_dwordx4 v32, s[4:7], s24 offen lds
	s_mov_b32 m0, s25
	s_nop 0
	buffer_load_dwordx4 v131, s[4:7], s24 offen lds
	s_waitcnt lgkmcnt(8)
	s_barrier
	s_waitcnt lgkmcnt(0)
	s_waitcnt lgkmcnt(7)
	v_mfma_f32_16x16x32_bf16 v[126:129], v[186:189], v[156:159], v[126:129]
	v_mfma_f32_16x16x32_bf16 v[122:125], v[186:189], v[170:173], v[122:125]
	s_waitcnt lgkmcnt(5)
	v_mfma_f32_16x16x32_bf16 v[118:121], v[194:197], v[156:159], v[118:121]
	v_mfma_f32_16x16x32_bf16 v[114:117], v[194:197], v[170:173], v[114:117]
	s_waitcnt lgkmcnt(3)
	v_mfma_f32_16x16x32_bf16 v[110:113], v[202:205], v[156:159], v[110:113]
	v_mfma_f32_16x16x32_bf16 v[106:109], v[202:205], v[170:173], v[106:109]
	s_waitcnt lgkmcnt(1)
	v_mfma_f32_16x16x32_bf16 v[102:105], v[210:213], v[156:159], v[102:105]
	v_mfma_f32_16x16x32_bf16 v[98:101], v[210:213], v[170:173], v[98:101]
	v_mfma_f32_16x16x32_bf16 v[126:129], v[190:193], v[166:169], v[126:129]
	v_mfma_f32_16x16x32_bf16 v[122:125], v[190:193], v[174:177], v[122:125]
	v_mfma_f32_16x16x32_bf16 v[118:121], v[198:201], v[166:169], v[118:121]
	v_mfma_f32_16x16x32_bf16 v[114:117], v[198:201], v[174:177], v[114:117]
	v_mfma_f32_16x16x32_bf16 v[110:113], v[206:209], v[166:169], v[110:113]
	v_mfma_f32_16x16x32_bf16 v[106:109], v[206:209], v[174:177], v[106:109]
	s_waitcnt lgkmcnt(0)
	v_mfma_f32_16x16x32_bf16 v[102:105], v[214:217], v[166:169], v[102:105]
	v_mfma_f32_16x16x32_bf16 v[98:101], v[214:217], v[174:177], v[98:101]
	s_barrier
	s_add_i32 s24, s22, s15
	v_readfirstlane_b32 s26, v137
	s_add_i32 s25, s24, 0x100
	s_mov_b32 m0, s26
	v_readfirstlane_b32 s26, v139
	ds_read_b128 v[218:221], v149
	ds_read_b128 v[222:225], v149 offset:1024
	ds_read_b128 v[226:229], v149 offset:2048
	ds_read_b128 v[230:233], v149 offset:3072
	buffer_load_dwordx4 v32, s[76:79], s25 offen lds
	s_mov_b32 m0, s26
	s_nop 0
	buffer_load_dwordx4 v131, s[76:79], s25 offen lds
	s_barrier
; #define STAGE(P, BASE, br, kt) do { int _so = ((br) * K + (kt) * BK) * 2; \
;     __builtin_amdgcn_raw_ptr_buffer_load_lds(rs_##BASE, (__attribute__((address_space(3))) void*)((char*)(P) + tx * 16), 16, voff0, _so, 0, 0); \
;     __builtin_amdgcn_raw_ptr_buffer_load_lds(rs_##BASE, (__attribute__((address_space(3))) void*)((char*)(P) + tx * 16 + 8192), 16, voff1, _so, 0, 0); } while (0)
; #define LDA(dst, b, h) _Pragma("unroll") for (int m = 0; m < 4; ++m) _Pragma("unroll") for (int k = 0; k < 2; ++k) \
;     dst[m][k] = *reinterpret_cast<const bf16x8*>((char*)SA(b, h) + lds_byte(wr * 64 + m * 16 + fr, k * 32 + fq * 8))
; #define LDB(dst, b, h) _Pragma("unroll") for (int n = 0; n < 2; ++n) _Pragma("unroll") for (int k = 0; k < 2; ++k) \
;     dst[n][k] = *reinterpret_cast<const bf16x8*>((char*)SB(b, h) + lds_byte(wc * 32 + n * 16 + fr, k * 32 + fq * 8))
; #define MMA(ai, bj, At, Bt_) do { __builtin_amdgcn_s_setprio(1); \
;     _Pragma("unroll") for (int m = 0; m < 4; ++m) _Pragma("unroll") for (int n = 0; n < 2; ++n) _Pragma("unroll") for (int k = 0; k < 2; ++k) \
;       acc[ai][bj][m][n] = __builtin_amdgcn_mfma_f32_16x16x32_bf16(At[m][k], Bt_[n][k], acc[ai][bj][m][n], 0, 0, 0); \
;     __builtin_amdgcn_s_setprio(0); } while (0)
; #define WAIT_V(n) asm volatile("s_waitcnt vmcnt(" #n ")" ::: "memory")
; #define WAIT_L(n) asm volatile("s_waitcnt lgkmcnt(" #n ")" ::: "memory")
; #define BAR __builtin_amdgcn_s_barrier()
; #define SCHED __builtin_amdgcn_sched_barrier(0)
; template <class Epi> ...
;     ...
;     BAR; WAIT_L(0); MMA(0, 1, At, B1); BAR;
;     LDA(At, 0, 1); STAGE(SA(0, 0), A, brow, t + 2);
;     BAR; WAIT_L(0); MMA(1, 0, At, B0); BAR; SCHED;
;     STAGE(SB(0, 1), Bt, bcol + HALF, t + 2);
;     WAIT_V(6); BAR; MMA(1, 1, At, B1); BAR;
;     LDB(B0, 1, 0); SCHED; LDA(At, 1, 0); STAGE(SA(0, 1), A, brow + HALF, t + 2);
;     WAIT_L(8); BAR; WAIT_L(0); MMA(0, 0, At, B0); BAR; SCHED;
	s_waitcnt lgkmcnt(0)
	s_waitcnt lgkmcnt(3)
	v_mfma_f32_16x16x32_bf16 v[94:97], v[186:189], v[218:221], v[94:97]
	s_waitcnt lgkmcnt(1)
	v_mfma_f32_16x16x32_bf16 v[90:93], v[186:189], v[226:229], v[90:93]
	v_mfma_f32_16x16x32_bf16 v[86:89], v[194:197], v[218:221], v[86:89]
	v_mfma_f32_16x16x32_bf16 v[82:85], v[194:197], v[226:229], v[82:85]
	v_mfma_f32_16x16x32_bf16 v[78:81], v[202:205], v[218:221], v[78:81]
	v_mfma_f32_16x16x32_bf16 v[74:77], v[202:205], v[226:229], v[74:77]
	v_mfma_f32_16x16x32_bf16 v[70:73], v[210:213], v[218:221], v[70:73]
	v_mfma_f32_16x16x32_bf16 v[66:69], v[210:213], v[226:229], v[66:69]
	v_mfma_f32_16x16x32_bf16 v[94:97], v[190:193], v[222:225], v[94:97]
	s_waitcnt lgkmcnt(0)
	v_mfma_f32_16x16x32_bf16 v[90:93], v[190:193], v[230:233], v[90:93]
	v_mfma_f32_16x16x32_bf16 v[86:89], v[198:201], v[222:225], v[86:89]
	v_mfma_f32_16x16x32_bf16 v[82:85], v[198:201], v[230:233], v[82:85]
	v_mfma_f32_16x16x32_bf16 v[78:81], v[206:209], v[222:225], v[78:81]
	v_mfma_f32_16x16x32_bf16 v[74:77], v[206:209], v[230:233], v[74:77]
	v_mfma_f32_16x16x32_bf16 v[70:73], v[214:217], v[222:225], v[70:73]
	v_mfma_f32_16x16x32_bf16 v[66:69], v[214:217], v[230:233], v[66:69]
	v_readfirstlane_b32 s26, v136
	s_add_i32 s25, s23, 0x100
	s_mov_b32 m0, s26
	v_readfirstlane_b32 s26, v135
	s_barrier
	ds_read_b128 v[186:189], v143 offset:16384
	ds_read_b128 v[190:193], v143 offset:17408
	ds_read_b128 v[194:197], v142 offset:16384
	ds_read_b128 v[198:201], v142 offset:17408
	ds_read_b128 v[202:205], v141 offset:16384
	ds_read_b128 v[206:209], v141 offset:17408
	ds_read_b128 v[210:213], v140 offset:16384
	ds_read_b128 v[214:217], v140 offset:17408
	buffer_load_dwordx4 v32, s[4:7], s25 offen lds
	s_mov_b32 m0, s26
	s_nop 0
	buffer_load_dwordx4 v131, s[4:7], s25 offen lds
	s_barrier
	s_waitcnt lgkmcnt(0)
	s_waitcnt lgkmcnt(7)
	v_mfma_f32_16x16x32_bf16 v[62:65], v[186:189], v[156:159], v[62:65]
	v_mfma_f32_16x16x32_bf16 v[58:61], v[186:189], v[170:173], v[58:61]
	s_waitcnt lgkmcnt(5)
	v_mfma_f32_16x16x32_bf16 v[54:57], v[194:197], v[156:159], v[54:57]
	v_mfma_f32_16x16x32_bf16 v[50:53], v[194:197], v[170:173], v[50:53]
	s_waitcnt lgkmcnt(3)
	v_mfma_f32_16x16x32_bf16 v[46:49], v[202:205], v[156:159], v[46:49]
	v_mfma_f32_16x16x32_bf16 v[42:45], v[202:205], v[170:173], v[42:45]
	s_waitcnt lgkmcnt(1)
	v_mfma_f32_16x16x32_bf16 v[38:41], v[210:213], v[156:159], v[38:41]
	v_mfma_f32_16x16x32_bf16 v[34:37], v[210:213], v[170:173], v[34:37]
	v_mfma_f32_16x16x32_bf16 v[62:65], v[190:193], v[166:169], v[62:65]
	v_mfma_f32_16x16x32_bf16 v[58:61], v[190:193], v[174:177], v[58:61]
	v_mfma_f32_16x16x32_bf16 v[54:57], v[198:201], v[166:169], v[54:57]
	v_mfma_f32_16x16x32_bf16 v[50:53], v[198:201], v[174:177], v[50:53]
	v_mfma_f32_16x16x32_bf16 v[46:49], v[206:209], v[166:169], v[46:49]
	v_mfma_f32_16x16x32_bf16 v[42:45], v[206:209], v[174:177], v[42:45]
	s_waitcnt lgkmcnt(0)
	v_mfma_f32_16x16x32_bf16 v[38:41], v[214:217], v[166:169], v[38:41]
	v_mfma_f32_16x16x32_bf16 v[34:37], v[214:217], v[174:177], v[34:37]
	s_barrier
	v_readfirstlane_b32 s26, v134
	s_add_i32 s25, s24, 0xb0100
	s_mov_b32 m0, s26
	v_readfirstlane_b32 s26, v138
	buffer_load_dwordx4 v32, s[76:79], s25 offen lds
	s_mov_b32 m0, s26
	s_nop 0
	buffer_load_dwordx4 v131, s[76:79], s25 offen lds
	s_waitcnt vmcnt(6)
	s_barrier
	v_mfma_f32_16x16x32_bf16 v[28:31], v[186:189], v[218:221], v[28:31]
	v_mfma_f32_16x16x32_bf16 v[24:27], v[186:189], v[226:229], v[24:27]
	v_mfma_f32_16x16x32_bf16 v[20:23], v[194:197], v[218:221], v[20:23]
	v_mfma_f32_16x16x32_bf16 v[16:19], v[194:197], v[226:229], v[16:19]
	v_mfma_f32_16x16x32_bf16 v[12:15], v[202:205], v[218:221], v[12:15]
	v_mfma_f32_16x16x32_bf16 v[8:11], v[202:205], v[226:229], v[8:11]
	v_mfma_f32_16x16x32_bf16 v[4:7], v[210:213], v[218:221], v[4:7]
	v_mfma_f32_16x16x32_bf16 v[0:3], v[210:213], v[226:229], v[0:3]
	v_mfma_f32_16x16x32_bf16 v[28:31], v[190:193], v[222:225], v[28:31]
	v_mfma_f32_16x16x32_bf16 v[24:27], v[190:193], v[230:233], v[24:27]
	v_mfma_f32_16x16x32_bf16 v[20:23], v[198:201], v[222:225], v[20:23]
	v_mfma_f32_16x16x32_bf16 v[16:19], v[198:201], v[230:233], v[16:19]
	v_mfma_f32_16x16x32_bf16 v[12:15], v[206:209], v[222:225], v[12:15]
	v_mfma_f32_16x16x32_bf16 v[8:11], v[206:209], v[230:233], v[8:11]
	v_mfma_f32_16x16x32_bf16 v[4:7], v[214:217], v[222:225], v[4:7]
	v_mfma_f32_16x16x32_bf16 v[0:3], v[214:217], v[230:233], v[0:3]
	s_barrier
	ds_read_b128 v[156:159], v145
	ds_read_b128 v[166:169], v145 offset:1024
	ds_read_b128 v[170:173], v145 offset:2048
	ds_read_b128 v[174:177], v145 offset:3072
	v_readfirstlane_b32 s26, v133
	s_add_i32 s25, s23, 0xb0100
	s_mov_b32 m0, s26
	v_readfirstlane_b32 s26, v132
	ds_read_b128 v[186:189], v143 offset:32768
	ds_read_b128 v[190:193], v143 offset:33792
	ds_read_b128 v[194:197], v142 offset:32768
	ds_read_b128 v[198:201], v142 offset:33792
	ds_read_b128 v[202:205], v141 offset:32768
	ds_read_b128 v[206:209], v141 offset:33792
	ds_read_b128 v[210:213], v140 offset:32768
	ds_read_b128 v[214:217], v140 offset:33792
	buffer_load_dwordx4 v32, s[4:7], s25 offen lds
	s_mov_b32 m0, s26
	s_nop 0
	buffer_load_dwordx4 v131, s[4:7], s25 offen lds
	s_waitcnt lgkmcnt(8)
	s_barrier
; #define STAGE(P, BASE, br, kt) do { int _so = ((br) * K + (kt) * BK) * 2; \
;     __builtin_amdgcn_raw_ptr_buffer_load_lds(rs_##BASE, (__attribute__((address_space(3))) void*)((char*)(P) + tx * 16), 16, voff0, _so, 0, 0); \
;     __builtin_amdgcn_raw_ptr_buffer_load_lds(rs_##BASE, (__attribute__((address_space(3))) void*)((char*)(P) + tx * 16 + 8192), 16, voff1, _so, 0, 0); } while (0)
; #define LDA(dst, b, h) _Pragma("unroll") for (int m = 0; m < 4; ++m) _Pragma("unroll") for (int k = 0; k < 2; ++k) \
;     dst[m][k] = *reinterpret_cast<const bf16x8*>((char*)SA(b, h) + lds_byte(wr * 64 + m * 16 + fr, k * 32 + fq * 8))
; #define LDB(dst, b, h) _Pragma("unroll") for (int n = 0; n < 2; ++n) _Pragma("unroll") for (int k = 0; k < 2; ++k) \
;     dst[n][k] = *reinterpret_cast<const bf16x8*>((char*)SB(b, h) + lds_byte(wc * 32 + n * 16 + fr, k * 32 + fq * 8))
; #define MMA(ai, bj, At, Bt_) do { __builtin_amdgcn_s_setprio(1); \
;     _Pragma("unroll") for (int m = 0; m < 4; ++m) _Pragma("unroll") for (int n = 0; n < 2; ++n) _Pragma("unroll") for (int k = 0; k < 2; ++k) \
;       acc[ai][bj][m][n] = __builtin_amdgcn_mfma_f32_16x16x32_bf16(At[m][k], Bt_[n][k], acc[ai][bj][m][n], 0, 0, 0); \
;     __builtin_amdgcn_s_setprio(0); } while (0)
; #define WAIT_V(n) asm volatile("s_waitcnt vmcnt(" #n ")" ::: "memory")
; #define WAIT_L(n) asm volatile("s_waitcnt lgkmcnt(" #n ")" ::: "memory")
; #define BAR __builtin_amdgcn_s_barrier()
; #define SCHED __builtin_amdgcn_sched_barrier(0)
; template <class Epi> ...
;     ...
;     WAIT_L(8); BAR; WAIT_L(0); MMA(0, 0, At, B0); BAR; SCHED;
;     LDB(B1, 1, 1); STAGE(SB(1, 0), Bt, bcol, t + 3);
;     BAR; WAIT_L(0); MMA(0, 1, At, B1); BAR;
;     LDA(At, 1, 1); STAGE(SA(1, 0), A, brow, t + 3);
;     BAR; WAIT_L(0); MMA(1, 0, At, B0); BAR; SCHED;
;     STAGE(SB(1, 1), Bt, bcol + HALF, t + 3);
;     WAIT_V(6); BAR; MMA(1, 1, At, B1); BAR;
;   }
	s_waitcnt lgkmcnt(0)
	s_waitcnt lgkmcnt(7)
	v_mfma_f32_16x16x32_bf16 v[126:129], v[186:189], v[156:159], v[126:129]
	v_mfma_f32_16x16x32_bf16 v[122:125], v[186:189], v[170:173], v[122:125]
	s_waitcnt lgkmcnt(5)
	v_mfma_f32_16x16x32_bf16 v[118:121], v[194:197], v[156:159], v[118:121]
	v_mfma_f32_16x16x32_bf16 v[114:117], v[194:197], v[170:173], v[114:117]
	s_waitcnt lgkmcnt(3)
	v_mfma_f32_16x16x32_bf16 v[110:113], v[202:205], v[156:159], v[110:113]
	v_mfma_f32_16x16x32_bf16 v[106:109], v[202:205], v[170:173], v[106:109]
	s_waitcnt lgkmcnt(1)
	v_mfma_f32_16x16x32_bf16 v[102:105], v[210:213], v[156:159], v[102:105]
	v_mfma_f32_16x16x32_bf16 v[98:101], v[210:213], v[170:173], v[98:101]
	v_mfma_f32_16x16x32_bf16 v[126:129], v[190:193], v[166:169], v[126:129]
	v_mfma_f32_16x16x32_bf16 v[122:125], v[190:193], v[174:177], v[122:125]
	v_mfma_f32_16x16x32_bf16 v[118:121], v[198:201], v[166:169], v[118:121]
	v_mfma_f32_16x16x32_bf16 v[114:117], v[198:201], v[174:177], v[114:117]
	v_mfma_f32_16x16x32_bf16 v[110:113], v[206:209], v[166:169], v[110:113]
	v_mfma_f32_16x16x32_bf16 v[106:109], v[206:209], v[174:177], v[106:109]
	s_waitcnt lgkmcnt(0)
	v_mfma_f32_16x16x32_bf16 v[102:105], v[214:217], v[166:169], v[102:105]
	v_mfma_f32_16x16x32_bf16 v[98:101], v[214:217], v[174:177], v[98:101]
	s_barrier
	v_readfirstlane_b32 s26, v146
	s_add_i32 s25, s24, 0x180
	s_mov_b32 m0, s26
	v_readfirstlane_b32 s26, v147
	ds_read_b128 v[218:221], v144
	ds_read_b128 v[222:225], v144 offset:1024
	ds_read_b128 v[226:229], v144 offset:2048
	ds_read_b128 v[230:233], v144 offset:3072
	buffer_load_dwordx4 v32, s[76:79], s25 offen lds
	s_mov_b32 m0, s26
	s_nop 0
	buffer_load_dwordx4 v131, s[76:79], s25 offen lds
	s_barrier
	s_waitcnt lgkmcnt(0)
	s_waitcnt lgkmcnt(3)
	v_mfma_f32_16x16x32_bf16 v[94:97], v[186:189], v[218:221], v[94:97]
	s_waitcnt lgkmcnt(1)
	v_mfma_f32_16x16x32_bf16 v[90:93], v[186:189], v[226:229], v[90:93]
	v_mfma_f32_16x16x32_bf16 v[86:89], v[194:197], v[218:221], v[86:89]
	v_mfma_f32_16x16x32_bf16 v[82:85], v[194:197], v[226:229], v[82:85]
	v_mfma_f32_16x16x32_bf16 v[78:81], v[202:205], v[218:221], v[78:81]
	v_mfma_f32_16x16x32_bf16 v[74:77], v[202:205], v[226:229], v[74:77]
	v_mfma_f32_16x16x32_bf16 v[70:73], v[210:213], v[218:221], v[70:73]
	v_mfma_f32_16x16x32_bf16 v[66:69], v[210:213], v[226:229], v[66:69]
	v_mfma_f32_16x16x32_bf16 v[94:97], v[190:193], v[222:225], v[94:97]
	s_waitcnt lgkmcnt(0)
	v_mfma_f32_16x16x32_bf16 v[90:93], v[190:193], v[230:233], v[90:93]
	v_mfma_f32_16x16x32_bf16 v[86:89], v[198:201], v[222:225], v[86:89]
	v_mfma_f32_16x16x32_bf16 v[82:85], v[198:201], v[230:233], v[82:85]
	v_mfma_f32_16x16x32_bf16 v[78:81], v[206:209], v[222:225], v[78:81]
	v_mfma_f32_16x16x32_bf16 v[74:77], v[206:209], v[230:233], v[74:77]
	v_mfma_f32_16x16x32_bf16 v[70:73], v[214:217], v[222:225], v[70:73]
	v_mfma_f32_16x16x32_bf16 v[66:69], v[214:217], v[230:233], v[66:69]
	v_readfirstlane_b32 s25, v148
	s_addk_i32 s23, 0x180
	s_mov_b32 m0, s25
	v_readfirstlane_b32 s25, v150
	s_barrier
	ds_read_b128 v[186:189], v143 offset:49152
	ds_read_b128 v[190:193], v143 offset:50176
	ds_read_b128 v[194:197], v142 offset:49152
	ds_read_b128 v[198:201], v142 offset:50176
	ds_read_b128 v[202:205], v141 offset:49152
	ds_read_b128 v[206:209], v141 offset:50176
	ds_read_b128 v[210:213], v140 offset:49152
	ds_read_b128 v[214:217], v140 offset:50176
	buffer_load_dwordx4 v32, s[4:7], s23 offen lds
	s_mov_b32 m0, s25
	s_nop 0
	buffer_load_dwordx4 v131, s[4:7], s23 offen lds
	s_barrier
	s_waitcnt lgkmcnt(0)
	s_waitcnt lgkmcnt(7)
	v_mfma_f32_16x16x32_bf16 v[62:65], v[186:189], v[156:159], v[62:65]
	v_mfma_f32_16x16x32_bf16 v[58:61], v[186:189], v[170:173], v[58:61]
	s_waitcnt lgkmcnt(5)
	v_mfma_f32_16x16x32_bf16 v[54:57], v[194:197], v[156:159], v[54:57]
	v_mfma_f32_16x16x32_bf16 v[50:53], v[194:197], v[170:173], v[50:53]
	s_waitcnt lgkmcnt(3)
	v_mfma_f32_16x16x32_bf16 v[46:49], v[202:205], v[156:159], v[46:49]
	v_mfma_f32_16x16x32_bf16 v[42:45], v[202:205], v[170:173], v[42:45]
	s_waitcnt lgkmcnt(1)
	v_mfma_f32_16x16x32_bf16 v[38:41], v[210:213], v[156:159], v[38:41]
	v_mfma_f32_16x16x32_bf16 v[34:37], v[210:213], v[170:173], v[34:37]
	v_mfma_f32_16x16x32_bf16 v[62:65], v[190:193], v[166:169], v[62:65]
	v_mfma_f32_16x16x32_bf16 v[58:61], v[190:193], v[174:177], v[58:61]
	v_mfma_f32_16x16x32_bf16 v[54:57], v[198:201], v[166:169], v[54:57]
	v_mfma_f32_16x16x32_bf16 v[50:53], v[198:201], v[174:177], v[50:53]
	v_mfma_f32_16x16x32_bf16 v[46:49], v[206:209], v[166:169], v[46:49]
	v_mfma_f32_16x16x32_bf16 v[42:45], v[206:209], v[174:177], v[42:45]
	s_waitcnt lgkmcnt(0)
	v_mfma_f32_16x16x32_bf16 v[38:41], v[214:217], v[166:169], v[38:41]
	v_mfma_f32_16x16x32_bf16 v[34:37], v[214:217], v[174:177], v[34:37]
	s_barrier
	v_readfirstlane_b32 s23, v153
	s_add_i32 s24, s24, 0xb0180
	s_mov_b32 m0, s23
	v_readfirstlane_b32 s23, v154
	buffer_load_dwordx4 v32, s[76:79], s24 offen lds
	s_mov_b32 m0, s23
	s_nop 0
	buffer_load_dwordx4 v131, s[76:79], s24 offen lds
	s_waitcnt vmcnt(6)
	s_barrier
	v_mfma_f32_16x16x32_bf16 v[28:31], v[186:189], v[218:221], v[28:31]
	v_mfma_f32_16x16x32_bf16 v[24:27], v[186:189], v[226:229], v[24:27]
	v_mfma_f32_16x16x32_bf16 v[20:23], v[194:197], v[218:221], v[20:23]
	v_mfma_f32_16x16x32_bf16 v[16:19], v[194:197], v[226:229], v[16:19]
	v_mfma_f32_16x16x32_bf16 v[12:15], v[202:205], v[218:221], v[12:15]
	v_mfma_f32_16x16x32_bf16 v[8:11], v[202:205], v[226:229], v[8:11]
	v_mfma_f32_16x16x32_bf16 v[4:7], v[210:213], v[218:221], v[4:7]
	v_mfma_f32_16x16x32_bf16 v[0:3], v[210:213], v[226:229], v[0:3]
	v_mfma_f32_16x16x32_bf16 v[28:31], v[190:193], v[222:225], v[28:31]
	v_mfma_f32_16x16x32_bf16 v[24:27], v[190:193], v[230:233], v[24:27]
	v_mfma_f32_16x16x32_bf16 v[20:23], v[198:201], v[222:225], v[20:23]
	v_mfma_f32_16x16x32_bf16 v[16:19], v[198:201], v[230:233], v[16:19]
	v_mfma_f32_16x16x32_bf16 v[12:15], v[206:209], v[222:225], v[12:15]
	v_mfma_f32_16x16x32_bf16 v[8:11], v[206:209], v[230:233], v[8:11]
	v_mfma_f32_16x16x32_bf16 v[4:7], v[214:217], v[222:225], v[4:7]
	v_mfma_f32_16x16x32_bf16 v[0:3], v[214:217], v[230:233], v[0:3]
	s_add_i32 s14, s14, 2
	s_addk_i32 s15, 0x100
	s_cmp_lt_u32 s14, 40
	s_barrier
	s_cbranch_scc1 .LBB0_2336
; #define STAGE(P, BASE, br, kt) do { int _so = ((br) * K + (kt) * BK) * 2; \
;     __builtin_amdgcn_raw_ptr_buffer_load_lds(rs_##BASE, (__attribute__((address_space(3))) void*)((char*)(P) + tx * 16), 16, voff0, _so, 0, 0); \
;     __builtin_amdgcn_raw_ptr_buffer_load_lds(rs_##BASE, (__attribute__((address_space(3))) void*)((char*)(P) + tx * 16 + 8192), 16, voff1, _so, 0, 0); } while (0)
; #define LDA(dst, b, h) _Pragma("unroll") for (int m = 0; m < 4; ++m) _Pragma("unroll") for (int k = 0; k < 2; ++k) \
;     dst[m][k] = *reinterpret_cast<const bf16x8*>((char*)SA(b, h) + lds_byte(wr * 64 + m * 16 + fr, k * 32 + fq * 8))
; #define LDB(dst, b, h) _Pragma("unroll") for (int n = 0; n < 2; ++n) _Pragma("unroll") for (int k = 0; k < 2; ++k) \
;     dst[n][k] = *reinterpret_cast<const bf16x8*>((char*)SB(b, h) + lds_byte(wc * 32 + n * 16 + fr, k * 32 + fq * 8))
; #define MMA(ai, bj, At, Bt_) do { __builtin_amdgcn_s_setprio(1); \
;     _Pragma("unroll") for (int m = 0; m < 4; ++m) _Pragma("unroll") for (int n = 0; n < 2; ++n) _Pragma("unroll") for (int k = 0; k < 2; ++k) \
;       acc[ai][bj][m][n] = __builtin_amdgcn_mfma_f32_16x16x32_bf16(At[m][k], Bt_[n][k], acc[ai][bj][m][n], 0, 0, 0); \
;     __builtin_amdgcn_s_setprio(0); } while (0)
; #define WAIT_V(n) asm volatile("s_waitcnt vmcnt(" #n ")" ::: "memory")
; #define WAIT_L(n) asm volatile("s_waitcnt lgkmcnt(" #n ")" ::: "memory")
; #define BAR __builtin_amdgcn_s_barrier()
; template <class Epi> ...
;     ...
;   { LDB(B0, 0, 0); LDA(At, 0, 0); STAGE(SA(1, 1), A, brow + HALF, nt - 1);
;     BAR; WAIT_L(0); MMA(0, 0, At, B0); BAR;
;     LDB(B1, 0, 1); BAR; WAIT_L(0); MMA(0, 1, At, B1); BAR;
;     LDA(At, 0, 1); WAIT_V(4); BAR; WAIT_L(0); MMA(1, 0, At, B0); MMA(1, 1, At, B1); BAR; }
.Lpx8:
	v_readfirstlane_b32 s14, v152
	s_add_i32 s21, s21, 0xb1580
	s_mov_b32 s6, s78
	s_mov_b32 s7, s79
	s_mov_b32 m0, s14
	v_readfirstlane_b32 s14, v151
	ds_read_b128 v[156:159], v155
	ds_read_b128 v[166:169], v155 offset:1024
	ds_read_b128 v[170:173], v155 offset:2048
	ds_read_b128 v[174:177], v155 offset:3072
	ds_read_b128 v[186:189], v143
	ds_read_b128 v[190:193], v143 offset:1024
	ds_read_b128 v[194:197], v142
	ds_read_b128 v[198:201], v142 offset:1024
	ds_read_b128 v[202:205], v141
	ds_read_b128 v[206:209], v141 offset:1024
	ds_read_b128 v[210:213], v140
	ds_read_b128 v[214:217], v140 offset:1024
	buffer_load_dwordx4 v32, s[4:7], s21 offen lds
	s_mov_b32 m0, s14
	s_nop 0
	buffer_load_dwordx4 v131, s[4:7], s21 offen lds
	s_barrier
	s_waitcnt lgkmcnt(0)
	s_waitcnt lgkmcnt(7)
	v_mfma_f32_16x16x32_bf16 v[126:129], v[186:189], v[156:159], v[126:129]
	v_mfma_f32_16x16x32_bf16 v[122:125], v[186:189], v[170:173], v[122:125]
	s_waitcnt lgkmcnt(5)
	v_mfma_f32_16x16x32_bf16 v[118:121], v[194:197], v[156:159], v[118:121]
	v_mfma_f32_16x16x32_bf16 v[114:117], v[194:197], v[170:173], v[114:117]
	s_waitcnt lgkmcnt(3)
	v_mfma_f32_16x16x32_bf16 v[110:113], v[202:205], v[156:159], v[110:113]
	v_mfma_f32_16x16x32_bf16 v[106:109], v[202:205], v[170:173], v[106:109]
	s_waitcnt lgkmcnt(1)
	v_mfma_f32_16x16x32_bf16 v[102:105], v[210:213], v[156:159], v[102:105]
	v_mfma_f32_16x16x32_bf16 v[98:101], v[210:213], v[170:173], v[98:101]
	v_mfma_f32_16x16x32_bf16 v[126:129], v[190:193], v[166:169], v[126:129]
	v_mfma_f32_16x16x32_bf16 v[122:125], v[190:193], v[174:177], v[122:125]
	v_mfma_f32_16x16x32_bf16 v[118:121], v[198:201], v[166:169], v[118:121]
	v_mfma_f32_16x16x32_bf16 v[114:117], v[198:201], v[174:177], v[114:117]
	v_mfma_f32_16x16x32_bf16 v[110:113], v[206:209], v[166:169], v[110:113]
	v_mfma_f32_16x16x32_bf16 v[106:109], v[206:209], v[174:177], v[106:109]
	s_waitcnt lgkmcnt(0)
	v_mfma_f32_16x16x32_bf16 v[102:105], v[214:217], v[166:169], v[102:105]
	v_mfma_f32_16x16x32_bf16 v[98:101], v[214:217], v[174:177], v[98:101]
	s_barrier
	ds_read_b128 v[150:153], v149
	ds_read_b128 v[218:221], v149 offset:1024
	ds_read_b128 v[222:225], v149 offset:2048
	ds_read_b128 v[146:149], v149 offset:3072
	s_barrier
	s_waitcnt lgkmcnt(0)
	s_waitcnt lgkmcnt(3)
	v_mfma_f32_16x16x32_bf16 v[78:81], v[202:205], v[150:153], v[78:81]
	s_waitcnt lgkmcnt(1)
	v_mfma_f32_16x16x32_bf16 v[74:77], v[202:205], v[222:225], v[74:77]
	v_mfma_f32_16x16x32_bf16 v[70:73], v[210:213], v[150:153], v[70:73]
	v_mfma_f32_16x16x32_bf16 v[66:69], v[210:213], v[222:225], v[66:69]
	v_mfma_f32_16x16x32_bf16 v[94:97], v[186:189], v[150:153], v[94:97]
	v_mfma_f32_16x16x32_bf16 v[90:93], v[186:189], v[222:225], v[90:93]
	v_mfma_f32_16x16x32_bf16 v[86:89], v[194:197], v[150:153], v[86:89]
	v_mfma_f32_16x16x32_bf16 v[82:85], v[194:197], v[222:225], v[82:85]
	v_mfma_f32_16x16x32_bf16 v[78:81], v[206:209], v[218:221], v[78:81]
	s_waitcnt lgkmcnt(0)
	v_mfma_f32_16x16x32_bf16 v[74:77], v[206:209], v[146:149], v[74:77]
	v_mfma_f32_16x16x32_bf16 v[70:73], v[214:217], v[218:221], v[70:73]
	v_mfma_f32_16x16x32_bf16 v[66:69], v[214:217], v[146:149], v[66:69]
	v_mfma_f32_16x16x32_bf16 v[226:229], v[190:193], v[218:221], v[94:97]
	v_mfma_f32_16x16x32_bf16 v[186:189], v[190:193], v[146:149], v[90:93]
	v_mfma_f32_16x16x32_bf16 v[190:193], v[198:201], v[218:221], v[86:89]
	v_mfma_f32_16x16x32_bf16 v[194:197], v[198:201], v[146:149], v[82:85]
	s_barrier
	s_nop 0
	ds_read_b128 v[82:85], v143 offset:16384
	ds_read_b128 v[86:89], v143 offset:17408
	ds_read_b128 v[90:93], v142 offset:16384
	ds_read_b128 v[94:97], v142 offset:17408
	ds_read_b128 v[198:201], v141 offset:16384
	ds_read_b128 v[202:205], v141 offset:17408
	ds_read_b128 v[206:209], v140 offset:16384
	ds_read_b128 v[210:213], v140 offset:17408
	s_waitcnt vmcnt(4)
	s_barrier
	s_waitcnt lgkmcnt(0)
	s_waitcnt lgkmcnt(3)
	v_mfma_f32_16x16x32_bf16 v[46:49], v[198:201], v[156:159], v[46:49]
	v_mfma_f32_16x16x32_bf16 v[42:45], v[198:201], v[170:173], v[42:45]
	s_waitcnt lgkmcnt(1)
	v_mfma_f32_16x16x32_bf16 v[38:41], v[206:209], v[156:159], v[38:41]
	v_mfma_f32_16x16x32_bf16 v[34:37], v[206:209], v[170:173], v[34:37]
	v_mfma_f32_16x16x32_bf16 v[62:65], v[82:85], v[156:159], v[62:65]
	v_mfma_f32_16x16x32_bf16 v[58:61], v[82:85], v[170:173], v[58:61]
	v_mfma_f32_16x16x32_bf16 v[54:57], v[90:93], v[156:159], v[54:57]
	v_mfma_f32_16x16x32_bf16 v[50:53], v[90:93], v[170:173], v[50:53]
	v_mfma_f32_16x16x32_bf16 v[46:49], v[202:205], v[166:169], v[46:49]
	v_mfma_f32_16x16x32_bf16 v[42:45], v[202:205], v[174:177], v[42:45]
	s_waitcnt lgkmcnt(0)
	v_mfma_f32_16x16x32_bf16 v[38:41], v[210:213], v[166:169], v[38:41]
	v_mfma_f32_16x16x32_bf16 v[34:37], v[210:213], v[174:177], v[34:37]
	v_mfma_f32_16x16x32_bf16 v[214:217], v[86:89], v[166:169], v[62:65]
	v_mfma_f32_16x16x32_bf16 v[230:233], v[86:89], v[174:177], v[58:61]
	v_mfma_f32_16x16x32_bf16 v[234:237], v[94:97], v[166:169], v[54:57]
	v_mfma_f32_16x16x32_bf16 v[238:241], v[94:97], v[174:177], v[50:53]
	v_mfma_f32_16x16x32_bf16 v[0:3], v[206:209], v[222:225], v[0:3]
	v_mfma_f32_16x16x32_bf16 v[28:31], v[82:85], v[150:153], v[28:31]
	v_mfma_f32_16x16x32_bf16 v[24:27], v[82:85], v[222:225], v[24:27]
	v_mfma_f32_16x16x32_bf16 v[20:23], v[90:93], v[150:153], v[20:23]
	v_mfma_f32_16x16x32_bf16 v[16:19], v[90:93], v[222:225], v[16:19]
	v_mfma_f32_16x16x32_bf16 v[12:15], v[198:201], v[150:153], v[12:15]
	v_mfma_f32_16x16x32_bf16 v[8:11], v[198:201], v[222:225], v[8:11]
	v_mfma_f32_16x16x32_bf16 v[4:7], v[206:209], v[150:153], v[4:7]
	v_mfma_f32_16x16x32_bf16 v[0:3], v[210:213], v[146:149], v[0:3]
	v_mfma_f32_16x16x32_bf16 v[154:157], v[86:89], v[218:221], v[28:31]
	v_mfma_f32_16x16x32_bf16 v[158:161], v[86:89], v[146:149], v[24:27]
	v_mfma_f32_16x16x32_bf16 v[166:169], v[94:97], v[218:221], v[20:23]
	v_mfma_f32_16x16x32_bf16 v[170:173], v[94:97], v[146:149], v[16:19]
	v_mfma_f32_16x16x32_bf16 v[174:177], v[202:205], v[218:221], v[12:15]
	v_mfma_f32_16x16x32_bf16 v[198:201], v[202:205], v[146:149], v[8:11]
	v_mfma_f32_16x16x32_bf16 v[150:153], v[210:213], v[218:221], v[4:7]
	s_barrier
; #define LDA(dst, b, h) _Pragma("unroll") for (int m = 0; m < 4; ++m) _Pragma("unroll") for (int k = 0; k < 2; ++k) \
;     dst[m][k] = *reinterpret_cast<const bf16x8*>((char*)SA(b, h) + lds_byte(wr * 64 + m * 16 + fr, k * 32 + fq * 8))
; #define LDB(dst, b, h) _Pragma("unroll") for (int n = 0; n < 2; ++n) _Pragma("unroll") for (int k = 0; k < 2; ++k) \
;     dst[n][k] = *reinterpret_cast<const bf16x8*>((char*)SB(b, h) + lds_byte(wc * 32 + n * 16 + fr, k * 32 + fq * 8))
; #define MMA(ai, bj, At, Bt_) do { __builtin_amdgcn_s_setprio(1); \
;     _Pragma("unroll") for (int m = 0; m < 4; ++m) _Pragma("unroll") for (int n = 0; n < 2; ++n) _Pragma("unroll") for (int k = 0; k < 2; ++k) \
;       acc[ai][bj][m][n] = __builtin_amdgcn_mfma_f32_16x16x32_bf16(At[m][k], Bt_[n][k], acc[ai][bj][m][n], 0, 0, 0); \
;     __builtin_amdgcn_s_setprio(0); } while (0)
; #define WAIT_V(n) asm volatile("s_waitcnt vmcnt(" #n ")" ::: "memory")
; #define WAIT_L(n) asm volatile("s_waitcnt lgkmcnt(" #n ")" ::: "memory")
; #define BAR __builtin_amdgcn_s_barrier()
; template <class Epi> ...
;     ...
;   { LDB(B0, 1, 0); LDA(At, 1, 0); WAIT_V(2); BAR; WAIT_L(0); MMA(0, 0, At, B0); BAR;
;     LDB(B1, 1, 1); WAIT_V(0); BAR; WAIT_L(0); MMA(0, 1, At, B1); BAR;
;     LDA(At, 1, 1); BAR; WAIT_L(0); MMA(1, 0, At, B0); MMA(1, 1, At, B1); BAR; }
;   if (wr == 0) BAR;
	s_nop 0
	ds_read_b128 v[4:7], v145
	ds_read_b128 v[8:11], v145 offset:1024
	ds_read_b128 v[12:15], v145 offset:2048
	ds_read_b128 v[146:149], v145 offset:3072
	ds_read_b128 v[16:19], v143 offset:32768
	ds_read_b128 v[20:23], v143 offset:33792
	ds_read_b128 v[24:27], v142 offset:32768
	ds_read_b128 v[50:53], v142 offset:33792
	ds_read_b128 v[202:205], v141 offset:32768
	ds_read_b128 v[206:209], v141 offset:33792
	ds_read_b128 v[210:213], v140 offset:32768
	ds_read_b128 v[218:221], v140 offset:33792
	s_waitcnt vmcnt(2)
	s_barrier
	s_waitcnt lgkmcnt(0)
	s_waitcnt lgkmcnt(7)
	v_mfma_f32_16x16x32_bf16 v[28:31], v[16:19], v[4:7], v[126:129]
	s_waitcnt lgkmcnt(6)
	v_mfma_f32_16x16x32_bf16 v[126:129], v[20:23], v[8:11], v[28:31]
	v_mfma_f32_16x16x32_bf16 v[28:31], v[16:19], v[12:15], v[122:125]
	v_mfma_f32_16x16x32_bf16 v[94:97], v[20:23], v[146:149], v[28:31]
	s_waitcnt lgkmcnt(5)
	v_mfma_f32_16x16x32_bf16 v[28:31], v[24:27], v[4:7], v[118:121]
	s_waitcnt lgkmcnt(4)
	v_mfma_f32_16x16x32_bf16 v[122:125], v[50:53], v[8:11], v[28:31]
	v_mfma_f32_16x16x32_bf16 v[28:31], v[24:27], v[12:15], v[114:117]
	v_mfma_f32_16x16x32_bf16 v[90:93], v[50:53], v[146:149], v[28:31]
	s_waitcnt lgkmcnt(3)
	v_mfma_f32_16x16x32_bf16 v[28:31], v[202:205], v[4:7], v[110:113]
	s_waitcnt lgkmcnt(2)
	v_mfma_f32_16x16x32_bf16 v[118:121], v[206:209], v[8:11], v[28:31]
	v_mfma_f32_16x16x32_bf16 v[28:31], v[202:205], v[12:15], v[106:109]
	v_mfma_f32_16x16x32_bf16 v[86:89], v[206:209], v[146:149], v[28:31]
	s_waitcnt lgkmcnt(1)
	v_mfma_f32_16x16x32_bf16 v[28:31], v[210:213], v[4:7], v[102:105]
	s_waitcnt lgkmcnt(0)
	v_mfma_f32_16x16x32_bf16 v[114:117], v[218:221], v[8:11], v[28:31]
	v_mfma_f32_16x16x32_bf16 v[28:31], v[210:213], v[12:15], v[98:101]
	v_mfma_f32_16x16x32_bf16 v[82:85], v[218:221], v[146:149], v[28:31]
	s_barrier
	ds_read_b128 v[222:225], v144
	ds_read_b128 v[242:245], v144 offset:1024
	ds_read_b128 v[246:249], v144 offset:2048
	ds_read_b128 v[250:253], v144 offset:3072
	s_waitcnt vmcnt(0)
	s_barrier
	s_waitcnt lgkmcnt(0)
	s_waitcnt lgkmcnt(3)
	v_mfma_f32_16x16x32_bf16 v[28:31], v[16:19], v[222:225], v[226:229]
	s_waitcnt lgkmcnt(1)
	v_mfma_f32_16x16x32_bf16 v[16:19], v[16:19], v[246:249], v[186:189]
	v_mfma_f32_16x16x32_bf16 v[62:65], v[20:23], v[242:245], v[28:31]
	s_waitcnt lgkmcnt(0)
	v_mfma_f32_16x16x32_bf16 v[28:31], v[20:23], v[250:253], v[16:19]
	v_mfma_f32_16x16x32_bf16 v[16:19], v[24:27], v[222:225], v[190:193]
	v_mfma_f32_16x16x32_bf16 v[58:61], v[50:53], v[242:245], v[16:19]
	v_mfma_f32_16x16x32_bf16 v[16:19], v[24:27], v[246:249], v[194:197]
	v_mfma_f32_16x16x32_bf16 v[24:27], v[50:53], v[250:253], v[16:19]
	v_mfma_f32_16x16x32_bf16 v[16:19], v[202:205], v[222:225], v[78:81]
	v_mfma_f32_16x16x32_bf16 v[54:57], v[206:209], v[242:245], v[16:19]
	v_mfma_f32_16x16x32_bf16 v[16:19], v[202:205], v[246:249], v[74:77]
	v_mfma_f32_16x16x32_bf16 v[20:23], v[206:209], v[250:253], v[16:19]
	v_mfma_f32_16x16x32_bf16 v[16:19], v[210:213], v[222:225], v[70:73]
	v_mfma_f32_16x16x32_bf16 v[50:53], v[218:221], v[242:245], v[16:19]
	v_mfma_f32_16x16x32_bf16 v[16:19], v[210:213], v[246:249], v[66:69]
	v_mfma_f32_16x16x32_bf16 v[16:19], v[218:221], v[250:253], v[16:19]
	s_barrier
	ds_read_b128 v[186:189], v143 offset:49152
	ds_read_b128 v[190:193], v143 offset:50176
	ds_read_b128 v[194:197], v142 offset:49152
	ds_read_b128 v[142:145], v142 offset:50176
	ds_read_b128 v[202:205], v141 offset:49152
	ds_read_b128 v[206:209], v141 offset:50176
	ds_read_b128 v[210:213], v140 offset:49152
	ds_read_b128 v[218:221], v140 offset:50176
	s_barrier
	s_waitcnt lgkmcnt(0)
	s_waitcnt lgkmcnt(7)
	v_mfma_f32_16x16x32_bf16 v[66:69], v[186:189], v[4:7], v[214:217]
	s_waitcnt lgkmcnt(6)
	v_mfma_f32_16x16x32_bf16 v[110:113], v[190:193], v[8:11], v[66:69]
	v_mfma_f32_16x16x32_bf16 v[66:69], v[186:189], v[12:15], v[230:233]
	v_mfma_f32_16x16x32_bf16 v[78:81], v[190:193], v[146:149], v[66:69]
	s_waitcnt lgkmcnt(5)
	v_mfma_f32_16x16x32_bf16 v[66:69], v[194:197], v[4:7], v[234:237]
	s_waitcnt lgkmcnt(3)
	v_mfma_f32_16x16x32_bf16 v[46:49], v[202:205], v[4:7], v[46:49]
	s_waitcnt lgkmcnt(1)
	v_mfma_f32_16x16x32_bf16 v[4:7], v[210:213], v[4:7], v[38:41]
	v_mfma_f32_16x16x32_bf16 v[106:109], v[142:145], v[8:11], v[66:69]
	v_mfma_f32_16x16x32_bf16 v[66:69], v[194:197], v[12:15], v[238:241]
	v_mfma_f32_16x16x32_bf16 v[42:45], v[202:205], v[12:15], v[42:45]
	s_waitcnt lgkmcnt(0)
	v_mfma_f32_16x16x32_bf16 v[98:101], v[218:221], v[8:11], v[4:7]
	v_mfma_f32_16x16x32_bf16 v[4:7], v[210:213], v[12:15], v[34:37]
	v_mfma_f32_16x16x32_bf16 v[74:77], v[142:145], v[146:149], v[66:69]
	v_mfma_f32_16x16x32_bf16 v[102:105], v[206:209], v[8:11], v[46:49]
	v_mfma_f32_16x16x32_bf16 v[70:73], v[206:209], v[146:149], v[42:45]
	v_mfma_f32_16x16x32_bf16 v[66:69], v[218:221], v[146:149], v[4:7]
	v_mfma_f32_16x16x32_bf16 v[4:7], v[186:189], v[222:225], v[154:157]
	v_mfma_f32_16x16x32_bf16 v[46:49], v[190:193], v[242:245], v[4:7]
	v_mfma_f32_16x16x32_bf16 v[4:7], v[186:189], v[246:249], v[158:161]
	v_mfma_f32_16x16x32_bf16 v[12:15], v[190:193], v[250:253], v[4:7]
	v_mfma_f32_16x16x32_bf16 v[4:7], v[194:197], v[222:225], v[166:169]
	v_mfma_f32_16x16x32_bf16 v[42:45], v[142:145], v[242:245], v[4:7]
	v_mfma_f32_16x16x32_bf16 v[4:7], v[194:197], v[246:249], v[170:173]
	v_mfma_f32_16x16x32_bf16 v[8:11], v[142:145], v[250:253], v[4:7]
	v_mfma_f32_16x16x32_bf16 v[4:7], v[202:205], v[222:225], v[174:177]
	v_mfma_f32_16x16x32_bf16 v[38:41], v[206:209], v[242:245], v[4:7]
	v_mfma_f32_16x16x32_bf16 v[4:7], v[202:205], v[246:249], v[198:201]
	v_mfma_f32_16x16x32_bf16 v[34:37], v[210:213], v[222:225], v[150:153]
	v_mfma_f32_16x16x32_bf16 v[0:3], v[210:213], v[246:249], v[0:3]
	v_mfma_f32_16x16x32_bf16 v[4:7], v[206:209], v[250:253], v[4:7]
	v_mfma_f32_16x16x32_bf16 v[34:37], v[218:221], v[242:245], v[34:37]
	v_mfma_f32_16x16x32_bf16 v[0:3], v[218:221], v[250:253], v[0:3]
	v_cmp_gt_u32_e32 vcc, s59, v130
	s_barrier
	s_and_saveexec_b64 s[6:7], vcc
	s_cbranch_execz .LBB0_2339
	s_barrier
